# P8/P9 K-loops: saddr LDS-DMA, hoisted LDS bases, scalar bookkeeping under MFMA; duplicate lgkmcnt waits removed
# speedup vs baseline: 1.0551x; 1.0041x over previous
; #define PG8_STAGE(bufoff, gbase) PG8_STAGE_(bufoff, gbase, voffA)
; #define PG8_STAGEB(bufoff, gbase) PG8_STAGE_(bufoff, gbase, voffB)
; #define PG8_LDA(dst, b, h) do { _Pragma("unroll") for (int m = 0; m < 4; ++m) _Pragma("unroll") for (int k = 0; k < 2; ++k) dst[m][k] = *(const LAS bf16x8*)(lds + PG8_SA(b, h) + aoff + m * 2048 + k * 1024); } while (0)
; #define PG8_LDB(dst, b, h) do { _Pragma("unroll") for (int n = 0; n < 2; ++n) _Pragma("unroll") for (int k = 0; k < 2; ++k) dst[n][k] = *(const LAS bf16x8*)(lds + PG8_SB(b, h) + boff + n * 2048 + k * 1024); } while (0)
; #define PG8_MMA(ai, bj, At, Bt) do { __builtin_amdgcn_s_setprio(1); _Pragma("unroll") for (int m = 0; m < 4; ++m) _Pragma("unroll") for (int n = 0; n < 2; ++n) _Pragma("unroll") for (int k = 0; k < 2; ++k) \
;         acc[ai][bj][m][n] = __builtin_amdgcn_mfma_f32_16x16x32_bf16(Bt[n][k], At[m][k], acc[ai][bj][m][n], 0, 0, 0); __builtin_amdgcn_s_setprio(0); } while (0)
; #define PG8_WAIT_V(n) asm volatile("s_waitcnt vmcnt(" #n ")" ::: "memory")
; #define PG8_WAIT_L(n) asm volatile("s_waitcnt lgkmcnt(" #n ")" ::: "memory")
; #define PG8_BAR __builtin_amdgcn_s_barrier()
; #define PG8_SCHED __builtin_amdgcn_sched_barrier(0)
; template <class Epi>
; __device__ __forceinline__ void gemm_phase(LAS unsigned char* lds, const Gemm g, const StaticOrder& S, const Epi& E) {
;     ...
;             PG8_LDB(B0, 0, 0); PG8_SCHED; PG8_LDA(At, 0, 0); PG8_STAGE(PG8_SA(1, 1), a1 + hstep);
;             PG8_WAIT_L(8); PG8_BAR; PG8_WAIT_L(0); PG8_MMA(0, 0, At, B0); PG8_BAR; PG8_SCHED;
;             PG8_LDB(B1, 0, 1); PG8_STAGEB(PG8_SB(0, 0), b2);
;             PG8_BAR; PG8_WAIT_L(0); PG8_MMA(0, 1, At, B1); PG8_BAR;
;             PG8_LDA(At, 0, 1); PG8_STAGE(PG8_SA(0, 0), a2);
;             PG8_BAR; PG8_WAIT_L(0); PG8_MMA(1, 0, At, B0); PG8_BAR; PG8_SCHED;
;             PG8_STAGEB(PG8_SB(0, 1), b2 + hstep);
;             PG8_WAIT_V(6); PG8_BAR; PG8_MMA(1, 1, At, B1); PG8_BAR;
.LBB0_426:
	ds_read_b128 v[74:77], v148
	ds_read_b128 v[86:89], v148 offset:1024
	ds_read_b128 v[90:93], v148 offset:2048
	ds_read_b128 v[94:97], v148 offset:3072
	ds_read_b128 v[166:169], v171
	ds_read_b128 v[172:175], v171 offset:1024
	ds_read_b128 v[176:179], v171 offset:2048
	ds_read_b128 v[206:209], v171 offset:3072
	ds_read_b128 v[210:213], v171 offset:4096
	ds_read_b128 v[214:217], v171 offset:5120
	ds_read_b128 v[218:221], v171 offset:6144
	global_load_lds_dwordx4 v162, s[30:31]
	s_add_i32 m0, s62, 0xe000
	ds_read_b128 v[222:225], v171 offset:7168
	global_load_lds_dwordx4 v164, s[30:31]
	s_waitcnt lgkmcnt(8)
	s_barrier
	s_waitcnt lgkmcnt(0)
	s_setprio 1
	v_mfma_f32_16x16x32_bf16 v[138:141], v[74:77], v[166:169], v[138:141]
	v_mfma_f32_16x16x32_bf16 v[142:145], v[90:93], v[166:169], v[142:145]
	s_add_i32 s59, 0, 0x14000
	v_mfma_f32_16x16x32_bf16 v[122:125], v[74:77], v[176:179], v[122:125]
	s_add_i32 s58, s58, s55
	v_mfma_f32_16x16x32_bf16 v[126:129], v[90:93], v[176:179], v[126:129]
	s_mov_b32 m0, s58
	v_mfma_f32_16x16x32_bf16 v[106:109], v[74:77], v[210:213], v[106:109]
	v_mfma_f32_16x16x32_bf16 v[110:113], v[90:93], v[210:213], v[110:113]
	v_mfma_f32_16x16x32_bf16 v[78:81], v[74:77], v[218:221], v[78:81]
	v_mfma_f32_16x16x32_bf16 v[82:85], v[90:93], v[218:221], v[82:85]
	v_mfma_f32_16x16x32_bf16 v[138:141], v[86:89], v[172:175], v[138:141]
	v_mfma_f32_16x16x32_bf16 v[142:145], v[94:97], v[172:175], v[142:145]
	v_mfma_f32_16x16x32_bf16 v[122:125], v[86:89], v[206:209], v[122:125]
	v_mfma_f32_16x16x32_bf16 v[126:129], v[94:97], v[206:209], v[126:129]
	v_mfma_f32_16x16x32_bf16 v[106:109], v[86:89], v[214:217], v[106:109]
	v_mfma_f32_16x16x32_bf16 v[110:113], v[94:97], v[214:217], v[110:113]
	v_mfma_f32_16x16x32_bf16 v[78:81], v[86:89], v[222:225], v[78:81]
	v_mfma_f32_16x16x32_bf16 v[82:85], v[94:97], v[222:225], v[82:85]
	s_setprio 0
	s_barrier
	ds_read_b128 v[226:229], v149
	ds_read_b128 v[230:233], v149 offset:1024
	ds_read_b128 v[234:237], v149 offset:2048
	global_load_lds_dwordx4 v0, s[20:21]
	s_add_i32 m0, s58, 0x2000
	ds_read_b128 v[238:241], v149 offset:3072
	global_load_lds_dwordx4 v156, s[20:21]
	s_barrier
	s_waitcnt lgkmcnt(0)
	s_setprio 1
	v_mfma_f32_16x16x32_bf16 v[130:133], v[226:229], v[166:169], v[130:133]
	v_mfma_f32_16x16x32_bf16 v[134:137], v[234:237], v[166:169], v[134:137]
	v_mfma_f32_16x16x32_bf16 v[114:117], v[226:229], v[176:179], v[114:117]
	v_mfma_f32_16x16x32_bf16 v[118:121], v[234:237], v[176:179], v[118:121]
	v_mfma_f32_16x16x32_bf16 v[98:101], v[226:229], v[210:213], v[98:101]
	v_mfma_f32_16x16x32_bf16 v[102:105], v[234:237], v[210:213], v[102:105]
	v_mfma_f32_16x16x32_bf16 v[66:69], v[226:229], v[218:221], v[66:69]
	v_mfma_f32_16x16x32_bf16 v[70:73], v[234:237], v[218:221], v[70:73]
	v_mfma_f32_16x16x32_bf16 v[130:133], v[230:233], v[172:175], v[130:133]
	v_mfma_f32_16x16x32_bf16 v[134:137], v[238:241], v[172:175], v[134:137]
	v_mfma_f32_16x16x32_bf16 v[114:117], v[230:233], v[206:209], v[114:117]
	v_mfma_f32_16x16x32_bf16 v[118:121], v[238:241], v[206:209], v[118:121]
	v_mfma_f32_16x16x32_bf16 v[98:101], v[230:233], v[214:217], v[98:101]
	v_mfma_f32_16x16x32_bf16 v[102:105], v[238:241], v[214:217], v[102:105]
	v_mfma_f32_16x16x32_bf16 v[66:69], v[230:233], v[222:225], v[66:69]
	v_mfma_f32_16x16x32_bf16 v[70:73], v[238:241], v[222:225], v[70:73]
	s_setprio 0
	s_mov_b32 m0, s62
	s_barrier
	ds_read_b128 v[166:169], v171 offset:16384
	ds_read_b128 v[172:175], v171 offset:17408
	ds_read_b128 v[176:179], v171 offset:18432
	ds_read_b128 v[206:209], v171 offset:19456
	ds_read_b128 v[210:213], v171 offset:20480
	ds_read_b128 v[214:217], v171 offset:21504
	ds_read_b128 v[218:221], v171 offset:22528
	global_load_lds_dwordx4 v160, s[44:45]
	s_mov_b32 m0, s63
	ds_read_b128 v[222:225], v171 offset:23552
	global_load_lds_dwordx4 v158, s[44:45]
	s_barrier
	s_waitcnt lgkmcnt(0)
	s_setprio 1
	v_mfma_f32_16x16x32_bf16 v[58:61], v[74:77], v[166:169], v[58:61]
	v_mfma_f32_16x16x32_bf16 v[62:65], v[90:93], v[166:169], v[62:65]
	s_add_u32 s90, s20, 0x80000
	v_mfma_f32_16x16x32_bf16 v[42:45], v[74:77], v[176:179], v[42:45]
	s_addc_u32 s91, s21, 0
	v_mfma_f32_16x16x32_bf16 v[46:49], v[90:93], v[176:179], v[46:49]
	s_add_i32 s58, s59, s55
	v_mfma_f32_16x16x32_bf16 v[26:29], v[74:77], v[210:213], v[26:29]
	s_mov_b32 m0, s58
	v_mfma_f32_16x16x32_bf16 v[30:33], v[90:93], v[210:213], v[30:33]
	v_mfma_f32_16x16x32_bf16 v[10:13], v[74:77], v[218:221], v[10:13]
	v_mfma_f32_16x16x32_bf16 v[14:17], v[90:93], v[218:221], v[14:17]
	v_mfma_f32_16x16x32_bf16 v[58:61], v[86:89], v[172:175], v[58:61]
	v_mfma_f32_16x16x32_bf16 v[62:65], v[94:97], v[172:175], v[62:65]
	v_mfma_f32_16x16x32_bf16 v[42:45], v[86:89], v[206:209], v[42:45]
	v_mfma_f32_16x16x32_bf16 v[46:49], v[94:97], v[206:209], v[46:49]
	v_mfma_f32_16x16x32_bf16 v[26:29], v[86:89], v[214:217], v[26:29]
	v_mfma_f32_16x16x32_bf16 v[30:33], v[94:97], v[214:217], v[30:33]
	v_mfma_f32_16x16x32_bf16 v[10:13], v[86:89], v[222:225], v[10:13]
	v_mfma_f32_16x16x32_bf16 v[14:17], v[94:97], v[222:225], v[14:17]
	s_setprio 0
	s_barrier
	global_load_lds_dwordx4 v0, s[90:91]
	s_add_i32 m0, s58, 0x2000
	s_nop 0
	global_load_lds_dwordx4 v156, s[90:91]
	s_waitcnt vmcnt(6)
	s_barrier
; #define PG8_STAGE(bufoff, gbase) PG8_STAGE_(bufoff, gbase, voffA)
; #define PG8_STAGEB(bufoff, gbase) PG8_STAGE_(bufoff, gbase, voffB)
; #define PG8_LDA(dst, b, h) do { _Pragma("unroll") for (int m = 0; m < 4; ++m) _Pragma("unroll") for (int k = 0; k < 2; ++k) dst[m][k] = *(const LAS bf16x8*)(lds + PG8_SA(b, h) + aoff + m * 2048 + k * 1024); } while (0)
; #define PG8_LDB(dst, b, h) do { _Pragma("unroll") for (int n = 0; n < 2; ++n) _Pragma("unroll") for (int k = 0; k < 2; ++k) dst[n][k] = *(const LAS bf16x8*)(lds + PG8_SB(b, h) + boff + n * 2048 + k * 1024); } while (0)
; #define PG8_MMA(ai, bj, At, Bt) do { __builtin_amdgcn_s_setprio(1); _Pragma("unroll") for (int m = 0; m < 4; ++m) _Pragma("unroll") for (int n = 0; n < 2; ++n) _Pragma("unroll") for (int k = 0; k < 2; ++k) \
;         acc[ai][bj][m][n] = __builtin_amdgcn_mfma_f32_16x16x32_bf16(Bt[n][k], At[m][k], acc[ai][bj][m][n], 0, 0, 0); __builtin_amdgcn_s_setprio(0); } while (0)
; #define PG8_WAIT_V(n) asm volatile("s_waitcnt vmcnt(" #n ")" ::: "memory")
; #define PG8_WAIT_L(n) asm volatile("s_waitcnt lgkmcnt(" #n ")" ::: "memory")
; #define PG8_BAR __builtin_amdgcn_s_barrier()
; #define PG8_SCHED __builtin_amdgcn_sched_barrier(0)
; template <class Epi>
; __device__ __forceinline__ void gemm_phase(LAS unsigned char* lds, const Gemm g, const StaticOrder& S, const Epi& E) {
;     ...
;             PG8_WAIT_V(6); PG8_BAR; PG8_MMA(1, 1, At, B1); PG8_BAR;
;             PG8_LDB(B0, 1, 0); PG8_SCHED; PG8_LDA(At, 1, 0); PG8_STAGE(PG8_SA(0, 1), a2 + hstep);
;             PG8_WAIT_L(8); PG8_BAR; PG8_WAIT_L(0); PG8_MMA(0, 0, At, B0); PG8_BAR; PG8_SCHED;
;             PG8_LDB(B1, 1, 1); PG8_STAGEB(PG8_SB(1, 0), b3);
;             PG8_BAR; PG8_WAIT_L(0); PG8_MMA(0, 1, At, B1); PG8_BAR;
;             PG8_LDA(At, 1, 1); PG8_STAGE(PG8_SA(1, 0), a3);
;             PG8_BAR; PG8_WAIT_L(0); PG8_MMA(1, 0, At, B0); PG8_BAR; PG8_SCHED;
	s_setprio 1
	v_mfma_f32_16x16x32_bf16 v[50:53], v[226:229], v[166:169], v[50:53]
	v_mfma_f32_16x16x32_bf16 v[54:57], v[234:237], v[166:169], v[54:57]
	s_add_i32 s58, 0, 0x18000
	v_mfma_f32_16x16x32_bf16 v[34:37], v[226:229], v[176:179], v[34:37]
	s_add_u32 s44, s44, 0x80000
	v_mfma_f32_16x16x32_bf16 v[38:41], v[234:237], v[176:179], v[38:41]
	s_addc_u32 s45, s45, 0
	v_mfma_f32_16x16x32_bf16 v[18:21], v[226:229], v[210:213], v[18:21]
	s_mov_b32 m0, s66
	v_mfma_f32_16x16x32_bf16 v[22:25], v[234:237], v[210:213], v[22:25]
	s_add_u32 s90, s20, s16
	v_mfma_f32_16x16x32_bf16 v[6:9], v[226:229], v[218:221], v[6:9]
	s_addc_u32 s91, s21, s17
	v_mfma_f32_16x16x32_bf16 v[2:5], v[234:237], v[218:221], v[2:5]
	v_mfma_f32_16x16x32_bf16 v[50:53], v[230:233], v[172:175], v[50:53]
	v_mfma_f32_16x16x32_bf16 v[54:57], v[238:241], v[172:175], v[54:57]
	v_mfma_f32_16x16x32_bf16 v[34:37], v[230:233], v[206:209], v[34:37]
	v_mfma_f32_16x16x32_bf16 v[38:41], v[238:241], v[206:209], v[38:41]
	v_mfma_f32_16x16x32_bf16 v[18:21], v[230:233], v[214:217], v[18:21]
	v_mfma_f32_16x16x32_bf16 v[22:25], v[238:241], v[214:217], v[22:25]
	v_mfma_f32_16x16x32_bf16 v[6:9], v[230:233], v[222:225], v[6:9]
	v_mfma_f32_16x16x32_bf16 v[2:5], v[238:241], v[222:225], v[2:5]
	s_setprio 0
	s_barrier
	ds_read_b128 v[74:77], v150
	ds_read_b128 v[86:89], v150 offset:1024
	ds_read_b128 v[90:93], v150 offset:2048
	ds_read_b128 v[94:97], v150 offset:3072
	ds_read_b128 v[166:169], v171 offset:32768
	ds_read_b128 v[172:175], v171 offset:33792
	ds_read_b128 v[176:179], v171 offset:34816
	ds_read_b128 v[206:209], v171 offset:35840
	ds_read_b128 v[210:213], v171 offset:36864
	ds_read_b128 v[214:217], v171 offset:37888
	ds_read_b128 v[218:221], v171 offset:38912
	global_load_lds_dwordx4 v160, s[44:45]
	s_mov_b32 m0, s67
	ds_read_b128 v[222:225], v171 offset:39936
	global_load_lds_dwordx4 v158, s[44:45]
	s_waitcnt lgkmcnt(8)
	s_barrier
	s_waitcnt lgkmcnt(0)
	s_setprio 1
	v_mfma_f32_16x16x32_bf16 v[138:141], v[74:77], v[166:169], v[138:141]
	v_mfma_f32_16x16x32_bf16 v[142:145], v[90:93], v[166:169], v[142:145]
	s_add_i32 s44, 0, 0x1c000
	v_mfma_f32_16x16x32_bf16 v[122:125], v[74:77], v[176:179], v[122:125]
	s_add_i32 s45, s58, s55
	v_mfma_f32_16x16x32_bf16 v[126:129], v[90:93], v[176:179], v[126:129]
	s_mov_b32 m0, s45
	v_mfma_f32_16x16x32_bf16 v[106:109], v[74:77], v[210:213], v[106:109]
	v_mfma_f32_16x16x32_bf16 v[110:113], v[90:93], v[210:213], v[110:113]
	v_mfma_f32_16x16x32_bf16 v[78:81], v[74:77], v[218:221], v[78:81]
	v_mfma_f32_16x16x32_bf16 v[82:85], v[90:93], v[218:221], v[82:85]
	v_mfma_f32_16x16x32_bf16 v[138:141], v[86:89], v[172:175], v[138:141]
	v_mfma_f32_16x16x32_bf16 v[142:145], v[94:97], v[172:175], v[142:145]
	v_mfma_f32_16x16x32_bf16 v[122:125], v[86:89], v[206:209], v[122:125]
	v_mfma_f32_16x16x32_bf16 v[126:129], v[94:97], v[206:209], v[126:129]
	v_mfma_f32_16x16x32_bf16 v[106:109], v[86:89], v[214:217], v[106:109]
	v_mfma_f32_16x16x32_bf16 v[110:113], v[94:97], v[214:217], v[110:113]
	v_mfma_f32_16x16x32_bf16 v[78:81], v[86:89], v[222:225], v[78:81]
	v_mfma_f32_16x16x32_bf16 v[82:85], v[94:97], v[222:225], v[82:85]
	s_setprio 0
	s_barrier
	ds_read_b128 v[226:229], v151
	ds_read_b128 v[230:233], v151 offset:1024
	ds_read_b128 v[234:237], v151 offset:2048
	global_load_lds_dwordx4 v0, s[90:91]
	s_add_i32 m0, s45, 0x2000
	ds_read_b128 v[238:241], v151 offset:3072
	global_load_lds_dwordx4 v156, s[90:91]
	s_barrier
	s_waitcnt lgkmcnt(0)
	s_setprio 1
	v_mfma_f32_16x16x32_bf16 v[130:133], v[226:229], v[166:169], v[130:133]
	v_mfma_f32_16x16x32_bf16 v[134:137], v[234:237], v[166:169], v[134:137]
	v_mfma_f32_16x16x32_bf16 v[114:117], v[226:229], v[176:179], v[114:117]
	v_mfma_f32_16x16x32_bf16 v[118:121], v[234:237], v[176:179], v[118:121]
	v_mfma_f32_16x16x32_bf16 v[98:101], v[226:229], v[210:213], v[98:101]
	v_mfma_f32_16x16x32_bf16 v[102:105], v[234:237], v[210:213], v[102:105]
	v_mfma_f32_16x16x32_bf16 v[66:69], v[226:229], v[218:221], v[66:69]
	v_mfma_f32_16x16x32_bf16 v[70:73], v[234:237], v[218:221], v[70:73]
	v_mfma_f32_16x16x32_bf16 v[130:133], v[230:233], v[172:175], v[130:133]
	v_mfma_f32_16x16x32_bf16 v[134:137], v[238:241], v[172:175], v[134:137]
	v_mfma_f32_16x16x32_bf16 v[114:117], v[230:233], v[206:209], v[114:117]
	v_mfma_f32_16x16x32_bf16 v[118:121], v[238:241], v[206:209], v[118:121]
	v_mfma_f32_16x16x32_bf16 v[98:101], v[230:233], v[214:217], v[98:101]
	v_mfma_f32_16x16x32_bf16 v[102:105], v[238:241], v[214:217], v[102:105]
	v_mfma_f32_16x16x32_bf16 v[66:69], v[230:233], v[222:225], v[66:69]
	v_mfma_f32_16x16x32_bf16 v[70:73], v[238:241], v[222:225], v[70:73]
	s_setprio 0
	s_mov_b32 m0, s38
	s_barrier
; #define PG8_STAGE(bufoff, gbase) PG8_STAGE_(bufoff, gbase, voffA)
; #define PG8_STAGEB(bufoff, gbase) PG8_STAGE_(bufoff, gbase, voffB)
; #define PG8_LDA(dst, b, h) do { _Pragma("unroll") for (int m = 0; m < 4; ++m) _Pragma("unroll") for (int k = 0; k < 2; ++k) dst[m][k] = *(const LAS bf16x8*)(lds + PG8_SA(b, h) + aoff + m * 2048 + k * 1024); } while (0)
; #define PG8_MMA(ai, bj, At, Bt) do { __builtin_amdgcn_s_setprio(1); _Pragma("unroll") for (int m = 0; m < 4; ++m) _Pragma("unroll") for (int n = 0; n < 2; ++n) _Pragma("unroll") for (int k = 0; k < 2; ++k) \
;         acc[ai][bj][m][n] = __builtin_amdgcn_mfma_f32_16x16x32_bf16(Bt[n][k], At[m][k], acc[ai][bj][m][n], 0, 0, 0); __builtin_amdgcn_s_setprio(0); } while (0)
; #define PG8_WAIT_V(n) asm volatile("s_waitcnt vmcnt(" #n ")" ::: "memory")
; #define PG8_WAIT_L(n) asm volatile("s_waitcnt lgkmcnt(" #n ")" ::: "memory")
; #define PG8_BAR __builtin_amdgcn_s_barrier()
; #define PG8_SCHED __builtin_amdgcn_sched_barrier(0)
; template <class Epi>
; __device__ __forceinline__ void gemm_phase(LAS unsigned char* lds, const Gemm g, const StaticOrder& S, const Epi& E) {
;     ...
;             PG8_LDA(At, 1, 1); PG8_STAGE(PG8_SA(1, 0), a3);
;             PG8_BAR; PG8_WAIT_L(0); PG8_MMA(1, 0, At, B0); PG8_BAR; PG8_SCHED;
;             PG8_STAGEB(PG8_SB(1, 1), b3 + hstep);
;             PG8_WAIT_V(6); PG8_BAR; PG8_MMA(1, 1, At, B1); PG8_BAR;
;     __device__ __forceinline__ void operator()(AccT& acc, const Unit& u, int wr, int wc, int fr, int fq) const {
;         int row0 = u.pm * 256 + wr * 64 + fr, col0 = u.pn * 256 + wc * 32 + 8 * fq;
;         asm volatile("" : "+v"(row0), "+v"(col0));
;         const bool gate = u.pn >= 37;
;         f32x4 bv[2][2];
; #pragma unroll
;         for (int bj = 0; bj < 2; ++bj)
; #pragma unroll
;             for (int n = 0; n < 2; ++n) bv[bj][n] = gate ? *(const f32x4*)(mb + (col0 - GATE0) + bj * 128 + n * 4) : (f32x4){0.f, 0.f, 0.f, 0.f};
	ds_read_b128 v[166:169], v171 offset:49152
	ds_read_b128 v[172:175], v171 offset:50176
	ds_read_b128 v[176:179], v171 offset:51200
	ds_read_b128 v[206:209], v171 offset:52224
	ds_read_b128 v[210:213], v171 offset:53248
	ds_read_b128 v[214:217], v171 offset:54272
	ds_read_b128 v[218:221], v171 offset:55296
	global_load_lds_dwordx4 v160, s[100:101]
	s_mov_b32 m0, s80
	ds_read_b128 v[222:225], v171 offset:56320
	global_load_lds_dwordx4 v158, s[100:101]
	s_barrier
	s_waitcnt lgkmcnt(0)
	s_setprio 1
	v_mfma_f32_16x16x32_bf16 v[58:61], v[74:77], v[166:169], v[58:61]
	v_mfma_f32_16x16x32_bf16 v[62:65], v[90:93], v[166:169], v[62:65]
	s_add_u32 s20, s20, 0x80080
	v_mfma_f32_16x16x32_bf16 v[42:45], v[74:77], v[176:179], v[42:45]
	s_addc_u32 s21, s21, 0
	v_mfma_f32_16x16x32_bf16 v[46:49], v[90:93], v[176:179], v[46:49]
	s_add_i32 s44, s44, s55
	v_mfma_f32_16x16x32_bf16 v[26:29], v[74:77], v[210:213], v[26:29]
	s_mov_b32 m0, s44
	v_mfma_f32_16x16x32_bf16 v[30:33], v[90:93], v[210:213], v[30:33]
	v_mfma_f32_16x16x32_bf16 v[10:13], v[74:77], v[218:221], v[10:13]
	v_mfma_f32_16x16x32_bf16 v[14:17], v[90:93], v[218:221], v[14:17]
	v_mfma_f32_16x16x32_bf16 v[58:61], v[86:89], v[172:175], v[58:61]
	v_mfma_f32_16x16x32_bf16 v[62:65], v[94:97], v[172:175], v[62:65]
	v_mfma_f32_16x16x32_bf16 v[42:45], v[86:89], v[206:209], v[42:45]
	v_mfma_f32_16x16x32_bf16 v[46:49], v[94:97], v[206:209], v[46:49]
	v_mfma_f32_16x16x32_bf16 v[26:29], v[86:89], v[214:217], v[26:29]
	v_mfma_f32_16x16x32_bf16 v[30:33], v[94:97], v[214:217], v[30:33]
	v_mfma_f32_16x16x32_bf16 v[10:13], v[86:89], v[222:225], v[10:13]
	v_mfma_f32_16x16x32_bf16 v[14:17], v[94:97], v[222:225], v[14:17]
	s_setprio 0
	s_barrier
	global_load_lds_dwordx4 v0, s[20:21]
	s_add_i32 m0, s44, 0x2000
	s_nop 0
	global_load_lds_dwordx4 v156, s[20:21]
	s_waitcnt vmcnt(6)
	s_barrier
	s_setprio 1
	v_mfma_f32_16x16x32_bf16 v[50:53], v[226:229], v[166:169], v[50:53]
	v_mfma_f32_16x16x32_bf16 v[54:57], v[234:237], v[166:169], v[54:57]
	s_add_i32 s88, s88, 2
	v_mfma_f32_16x16x32_bf16 v[34:37], v[226:229], v[176:179], v[34:37]
	s_add_u32 s30, s30, 0x100
	v_mfma_f32_16x16x32_bf16 v[38:41], v[234:237], v[176:179], v[38:41]
	s_addc_u32 s31, s31, 0
	v_mfma_f32_16x16x32_bf16 v[18:21], v[226:229], v[210:213], v[18:21]
	s_add_u32 s86, s86, 0x100
	v_mfma_f32_16x16x32_bf16 v[22:25], v[234:237], v[210:213], v[22:25]
	s_addc_u32 s87, s87, 0
	v_mfma_f32_16x16x32_bf16 v[6:9], v[226:229], v[218:221], v[6:9]
	s_add_u32 s20, s30, 0xfff80080
	v_mfma_f32_16x16x32_bf16 v[2:5], v[234:237], v[218:221], v[2:5]
	s_addc_u32 s21, s31, -1
	v_mfma_f32_16x16x32_bf16 v[50:53], v[230:233], v[172:175], v[50:53]
	s_add_i32 s58, 0, 0x10000
	v_mfma_f32_16x16x32_bf16 v[54:57], v[238:241], v[172:175], v[54:57]
	s_cmp_eq_u32 s88, 28
	v_mfma_f32_16x16x32_bf16 v[34:37], v[230:233], v[206:209], v[34:37]
	s_cselect_b32 s45, s35, s21
	v_mfma_f32_16x16x32_bf16 v[38:41], v[238:241], v[206:209], v[38:41]
	s_cselect_b32 s44, s84, s20
	v_mfma_f32_16x16x32_bf16 v[18:21], v[230:233], v[214:217], v[18:21]
	s_cselect_b32 s21, s25, s87
	v_mfma_f32_16x16x32_bf16 v[22:25], v[238:241], v[214:217], v[22:25]
	s_cselect_b32 s20, s85, s86
	v_mfma_f32_16x16x32_bf16 v[6:9], v[230:233], v[222:225], v[6:9]
	s_add_u32 s100, s44, s16
	v_mfma_f32_16x16x32_bf16 v[2:5], v[238:241], v[222:225], v[2:5]
	s_addc_u32 s101, s45, s17
	s_add_i32 m0, s62, 0xc000
	s_setprio 0
	s_cmp_gt_u32 s88, 29
	s_barrier
	s_cbranch_scc0 .LBB0_426
	v_mov_b32_e32 v74, v250
	s_lshl_b32 s21, s83, 8
	v_readfirstlane_b32 s20, v74
	s_ashr_i32 s25, s20, 2
	s_andn2_b32 s25, s25, 63
	s_lshr_b32 s20, s20, 1
	s_add_i32 s25, s25, s21
	s_lshl_b32 s21, s82, 8
	s_and_b32 s20, s20, 0x60
	v_and_or_b32 v172, v74, 15, s25
	s_or_b32 s20, s20, s21
	v_lshrrev_b32_e32 v74, 1, v74
	v_and_or_b32 v166, v74, 24, s20
	s_cmp_gt_i32 s82, 36
	v_ashrrev_i32_e32 v167, 31, v166
	v_mov_b32_e32 v90, 0
	s_cselect_b64 s[20:21], -1, 0
	s_cmp_lt_i32 s82, 37
	v_lshl_add_u64 v[168:169], v[166:167], 2, s[6:7]
	v_mov_b32_e32 v94, 0
	v_mov_b32_e32 v95, v90
	v_mov_b32_e32 v96, 0
	v_mov_b32_e32 v97, 0
	s_cbranch_scc1 .LBB0_429
	v_add_co_u32_e32 v74, vcc, 0xffff7000, v168
	s_nop 1
	v_addc_co_u32_e32 v75, vcc, -1, v169, vcc
	global_load_dwordx4 v[94:97], v[74:75], off offset:-1024

; #define PG8_STAGE(bufoff, gbase) PG8_STAGE_(bufoff, gbase, voffA)
; #define PG8_STAGEB(bufoff, gbase) PG8_STAGE_(bufoff, gbase, voffB)
; #define PG8_LDA(dst, b, h) do { _Pragma("unroll") for (int m = 0; m < 4; ++m) _Pragma("unroll") for (int k = 0; k < 2; ++k) dst[m][k] = *(const LAS bf16x8*)(lds + PG8_SA(b, h) + aoff + m * 2048 + k * 1024); } while (0)
; #define PG8_LDB(dst, b, h) do { _Pragma("unroll") for (int n = 0; n < 2; ++n) _Pragma("unroll") for (int k = 0; k < 2; ++k) dst[n][k] = *(const LAS bf16x8*)(lds + PG8_SB(b, h) + boff + n * 2048 + k * 1024); } while (0)
; #define PG8_MMA(ai, bj, At, Bt) do { __builtin_amdgcn_s_setprio(1); _Pragma("unroll") for (int m = 0; m < 4; ++m) _Pragma("unroll") for (int n = 0; n < 2; ++n) _Pragma("unroll") for (int k = 0; k < 2; ++k) \
;         acc[ai][bj][m][n] = __builtin_amdgcn_mfma_f32_16x16x32_bf16(Bt[n][k], At[m][k], acc[ai][bj][m][n], 0, 0, 0); __builtin_amdgcn_s_setprio(0); } while (0)
; #define PG8_WAIT_V(n) asm volatile("s_waitcnt vmcnt(" #n ")" ::: "memory")
; #define PG8_WAIT_L(n) asm volatile("s_waitcnt lgkmcnt(" #n ")" ::: "memory")
; #define PG8_BAR __builtin_amdgcn_s_barrier()
; #define PG8_SCHED __builtin_amdgcn_sched_barrier(0)
; template <class Epi>
; __device__ __forceinline__ void gemm_phase(LAS unsigned char* lds, const Gemm g, const StaticOrder& S, const Epi& E) {
;     ...
;             PG8_LDB(B0, 0, 0); PG8_SCHED; PG8_LDA(At, 0, 0); PG8_STAGE(PG8_SA(1, 1), a1 + hstep);
;             PG8_WAIT_L(8); PG8_BAR; PG8_WAIT_L(0); PG8_MMA(0, 0, At, B0); PG8_BAR; PG8_SCHED;
;             PG8_LDB(B1, 0, 1); PG8_STAGEB(PG8_SB(0, 0), b2);
;             PG8_BAR; PG8_WAIT_L(0); PG8_MMA(0, 1, At, B1); PG8_BAR;
;             PG8_LDA(At, 0, 1); PG8_STAGE(PG8_SA(0, 0), a2);
;             PG8_BAR; PG8_WAIT_L(0); PG8_MMA(1, 0, At, B0); PG8_BAR; PG8_SCHED;
;             PG8_STAGEB(PG8_SB(0, 1), b2 + hstep);
;             PG8_WAIT_V(6); PG8_BAR; PG8_MMA(1, 1, At, B1); PG8_BAR;
;             PG8_LDB(B0, 1, 0); PG8_SCHED; PG8_LDA(At, 1, 0); PG8_STAGE(PG8_SA(0, 1), a2 + hstep);
;             PG8_WAIT_L(8); PG8_BAR; PG8_WAIT_L(0); PG8_MMA(0, 0, At, B0); PG8_BAR; PG8_SCHED;
.LBB0_964:
	s_add_u32 s0, s30, 0xfffe0080
	s_addc_u32 s1, s31, -1
	s_add_i32 s58, 0, 0x10000
	v_add_u32_e32 v146, s58, v144
	ds_read_b128 v[140:143], v146
	ds_read_b128 v[156:159], v146 offset:1024
	ds_read_b128 v[160:163], v146 offset:2048
	ds_read_b128 v[164:167], v146 offset:3072
	s_cmp_eq_u32 vcc_hi, 4
	s_cselect_b32 s51, s45, s1
	s_cselect_b32 s50, s91, s0
	s_cselect_b32 s21, s35, vcc_lo
	s_cselect_b32 s20, s92, s93
	v_lshl_add_u64 v[146:147], s[30:31], 0, v[136:137]
	s_add_i32 m0, s82, 0xc000
	ds_read_b128 v[168:171], v145
	ds_read_b128 v[172:175], v145 offset:1024
	ds_read_b128 v[176:179], v145 offset:2048
	ds_read_b128 v[206:209], v145 offset:3072
	ds_read_b128 v[210:213], v145 offset:4096
	ds_read_b128 v[214:217], v145 offset:5120
	ds_read_b128 v[218:221], v145 offset:6144
	ds_read_b128 v[222:225], v145 offset:7168
	global_load_lds_dwordx4 v[146:147], off
	v_lshl_add_u64 v[146:147], s[30:31], 0, v[138:139]
	s_add_i32 m0, s82, 0xe000
	s_nop 0
	global_load_lds_dwordx4 v[146:147], off
	s_waitcnt lgkmcnt(8)
	s_barrier
	s_waitcnt lgkmcnt(0)
	s_setprio 1
	v_mfma_f32_16x16x32_bf16 v[126:129], v[140:143], v[168:171], v[126:129]
	v_mfma_f32_16x16x32_bf16 v[122:125], v[160:163], v[168:171], v[122:125]
	v_mfma_f32_16x16x32_bf16 v[118:121], v[140:143], v[176:179], v[118:121]
	v_mfma_f32_16x16x32_bf16 v[110:113], v[160:163], v[176:179], v[110:113]
	v_mfma_f32_16x16x32_bf16 v[102:105], v[140:143], v[210:213], v[102:105]
	v_mfma_f32_16x16x32_bf16 v[94:97], v[160:163], v[210:213], v[94:97]
	v_mfma_f32_16x16x32_bf16 v[86:89], v[140:143], v[218:221], v[86:89]
	v_mfma_f32_16x16x32_bf16 v[78:81], v[160:163], v[218:221], v[78:81]
	v_mfma_f32_16x16x32_bf16 v[126:129], v[156:159], v[172:175], v[126:129]
	v_mfma_f32_16x16x32_bf16 v[122:125], v[164:167], v[172:175], v[122:125]
	v_mfma_f32_16x16x32_bf16 v[118:121], v[156:159], v[206:209], v[118:121]
	v_mfma_f32_16x16x32_bf16 v[110:113], v[164:167], v[206:209], v[110:113]
	v_mfma_f32_16x16x32_bf16 v[102:105], v[156:159], v[214:217], v[102:105]
	v_mfma_f32_16x16x32_bf16 v[94:97], v[164:167], v[214:217], v[94:97]
	v_mfma_f32_16x16x32_bf16 v[86:89], v[156:159], v[222:225], v[86:89]
	v_mfma_f32_16x16x32_bf16 v[78:81], v[164:167], v[222:225], v[78:81]
	s_setprio 0
	s_barrier
	s_add_i32 s59, 0, 0x14000
	v_add_u32_e32 v146, s59, v144
	s_add_i32 s0, s58, s81
	ds_read_b128 v[226:229], v146
	ds_read_b128 v[230:233], v146 offset:1024
	ds_read_b128 v[234:237], v146 offset:2048
	ds_read_b128 v[238:241], v146 offset:3072
	v_lshl_add_u64 v[146:147], s[20:21], 0, v[0:1]
	s_mov_b32 m0, s0
	v_lshl_add_u64 v[148:149], s[20:21], 0, v[130:131]
	global_load_lds_dwordx4 v[146:147], off
	s_add_i32 m0, s0, 0x2000
	s_nop 0
	global_load_lds_dwordx4 v[148:149], off
	s_barrier
	s_waitcnt lgkmcnt(0)
	s_setprio 1
	v_mfma_f32_16x16x32_bf16 v[114:117], v[226:229], v[168:171], v[114:117]
	v_mfma_f32_16x16x32_bf16 v[106:109], v[234:237], v[168:171], v[106:109]
	v_mfma_f32_16x16x32_bf16 v[98:101], v[226:229], v[176:179], v[98:101]
	v_mfma_f32_16x16x32_bf16 v[90:93], v[234:237], v[176:179], v[90:93]
	v_mfma_f32_16x16x32_bf16 v[82:85], v[226:229], v[210:213], v[82:85]
	v_mfma_f32_16x16x32_bf16 v[74:77], v[234:237], v[210:213], v[74:77]
	v_mfma_f32_16x16x32_bf16 v[70:73], v[226:229], v[218:221], v[70:73]
	v_mfma_f32_16x16x32_bf16 v[66:69], v[234:237], v[218:221], v[66:69]
	v_mfma_f32_16x16x32_bf16 v[114:117], v[230:233], v[172:175], v[114:117]
	v_mfma_f32_16x16x32_bf16 v[106:109], v[238:241], v[172:175], v[106:109]
	v_mfma_f32_16x16x32_bf16 v[98:101], v[230:233], v[206:209], v[98:101]
	v_mfma_f32_16x16x32_bf16 v[90:93], v[238:241], v[206:209], v[90:93]
	v_mfma_f32_16x16x32_bf16 v[82:85], v[230:233], v[214:217], v[82:85]
	v_mfma_f32_16x16x32_bf16 v[74:77], v[238:241], v[214:217], v[74:77]
	v_mfma_f32_16x16x32_bf16 v[70:73], v[230:233], v[222:225], v[70:73]
	v_mfma_f32_16x16x32_bf16 v[66:69], v[238:241], v[222:225], v[66:69]
	s_setprio 0
	s_mov_b32 m0, s82
	v_lshl_add_u64 v[150:151], s[50:51], 0, v[134:135]
	s_barrier
	ds_read_b128 v[168:171], v145 offset:16384
	ds_read_b128 v[172:175], v145 offset:17408
	ds_read_b128 v[176:179], v145 offset:18432
	ds_read_b128 v[206:209], v145 offset:19456
	ds_read_b128 v[210:213], v145 offset:20480
	ds_read_b128 v[214:217], v145 offset:21504
	ds_read_b128 v[218:221], v145 offset:22528
	ds_read_b128 v[222:225], v145 offset:23552
	global_load_lds_dwordx4 v[150:151], off
	v_lshl_add_u64 v[152:153], s[50:51], 0, v[132:133]
	s_mov_b32 m0, s83
	s_nop 0
	global_load_lds_dwordx4 v[152:153], off
	s_barrier
	s_waitcnt lgkmcnt(0)
	s_setprio 1
	v_mfma_f32_16x16x32_bf16 v[62:65], v[140:143], v[168:171], v[62:65]
	v_mfma_f32_16x16x32_bf16 v[58:61], v[160:163], v[168:171], v[58:61]
	v_mfma_f32_16x16x32_bf16 v[54:57], v[140:143], v[176:179], v[54:57]
	v_mfma_f32_16x16x32_bf16 v[46:49], v[160:163], v[176:179], v[46:49]
	v_mfma_f32_16x16x32_bf16 v[38:41], v[140:143], v[210:213], v[38:41]
	v_mfma_f32_16x16x32_bf16 v[30:33], v[160:163], v[210:213], v[30:33]
	v_mfma_f32_16x16x32_bf16 v[22:25], v[140:143], v[218:221], v[22:25]
	v_mfma_f32_16x16x32_bf16 v[14:17], v[160:163], v[218:221], v[14:17]
	v_mfma_f32_16x16x32_bf16 v[62:65], v[156:159], v[172:175], v[62:65]
	v_mfma_f32_16x16x32_bf16 v[58:61], v[164:167], v[172:175], v[58:61]
	v_mfma_f32_16x16x32_bf16 v[54:57], v[156:159], v[206:209], v[54:57]
	v_mfma_f32_16x16x32_bf16 v[46:49], v[164:167], v[206:209], v[46:49]
	v_mfma_f32_16x16x32_bf16 v[38:41], v[156:159], v[214:217], v[38:41]
	v_mfma_f32_16x16x32_bf16 v[30:33], v[164:167], v[214:217], v[30:33]
	v_mfma_f32_16x16x32_bf16 v[22:25], v[156:159], v[222:225], v[22:25]
	v_mfma_f32_16x16x32_bf16 v[14:17], v[164:167], v[222:225], v[14:17]
	s_setprio 0
	s_barrier
; #define PG8_STAGE(bufoff, gbase) PG8_STAGE_(bufoff, gbase, voffA)
; #define PG8_STAGEB(bufoff, gbase) PG8_STAGE_(bufoff, gbase, voffB)
; #define PG8_LDA(dst, b, h) do { _Pragma("unroll") for (int m = 0; m < 4; ++m) _Pragma("unroll") for (int k = 0; k < 2; ++k) dst[m][k] = *(const LAS bf16x8*)(lds + PG8_SA(b, h) + aoff + m * 2048 + k * 1024); } while (0)
; #define PG8_LDB(dst, b, h) do { _Pragma("unroll") for (int n = 0; n < 2; ++n) _Pragma("unroll") for (int k = 0; k < 2; ++k) dst[n][k] = *(const LAS bf16x8*)(lds + PG8_SB(b, h) + boff + n * 2048 + k * 1024); } while (0)
; #define PG8_MMA(ai, bj, At, Bt) do { __builtin_amdgcn_s_setprio(1); _Pragma("unroll") for (int m = 0; m < 4; ++m) _Pragma("unroll") for (int n = 0; n < 2; ++n) _Pragma("unroll") for (int k = 0; k < 2; ++k) \
;         acc[ai][bj][m][n] = __builtin_amdgcn_mfma_f32_16x16x32_bf16(Bt[n][k], At[m][k], acc[ai][bj][m][n], 0, 0, 0); __builtin_amdgcn_s_setprio(0); } while (0)
; #define PG8_WAIT_V(n) asm volatile("s_waitcnt vmcnt(" #n ")" ::: "memory")
; #define PG8_WAIT_L(n) asm volatile("s_waitcnt lgkmcnt(" #n ")" ::: "memory")
; #define PG8_BAR __builtin_amdgcn_s_barrier()
; #define PG8_SCHED __builtin_amdgcn_sched_barrier(0)
; template <class Epi>
; __device__ __forceinline__ void gemm_phase(LAS unsigned char* lds, const Gemm g, const StaticOrder& S, const Epi& E) {
;     ...
;             PG8_STAGEB(PG8_SB(0, 1), b2 + hstep);
;             PG8_WAIT_V(6); PG8_BAR; PG8_MMA(1, 1, At, B1); PG8_BAR;
;             PG8_LDB(B0, 1, 0); PG8_SCHED; PG8_LDA(At, 1, 0); PG8_STAGE(PG8_SA(0, 1), a2 + hstep);
;             PG8_WAIT_L(8); PG8_BAR; PG8_WAIT_L(0); PG8_MMA(0, 0, At, B0); PG8_BAR; PG8_SCHED;
;             PG8_LDB(B1, 1, 1); PG8_STAGEB(PG8_SB(1, 0), b3);
;             PG8_BAR; PG8_WAIT_L(0); PG8_MMA(0, 1, At, B1); PG8_BAR;
;             PG8_LDA(At, 1, 1); PG8_STAGE(PG8_SA(1, 0), a3);
;             PG8_BAR; PG8_WAIT_L(0); PG8_MMA(1, 0, At, B0); PG8_BAR; PG8_SCHED;
	s_add_u32 s0, s20, 0x20000
	s_addc_u32 s1, s21, 0
	s_add_i32 s58, s59, s81
	v_lshl_add_u64 v[140:141], s[0:1], 0, v[0:1]
	s_mov_b32 m0, s58
	s_nop 0
	global_load_lds_dwordx4 v[140:141], off
	v_lshl_add_u64 v[140:141], s[0:1], 0, v[130:131]
	s_add_i32 m0, s58, 0x2000
	s_nop 0
	global_load_lds_dwordx4 v[140:141], off
	s_waitcnt vmcnt(6)
	s_barrier
	s_setprio 1
	v_mfma_f32_16x16x32_bf16 v[50:53], v[226:229], v[168:171], v[50:53]
	v_mfma_f32_16x16x32_bf16 v[42:45], v[234:237], v[168:171], v[42:45]
	v_mfma_f32_16x16x32_bf16 v[34:37], v[226:229], v[176:179], v[34:37]
	v_mfma_f32_16x16x32_bf16 v[26:29], v[234:237], v[176:179], v[26:29]
	v_mfma_f32_16x16x32_bf16 v[18:21], v[226:229], v[210:213], v[18:21]
	v_mfma_f32_16x16x32_bf16 v[10:13], v[234:237], v[210:213], v[10:13]
	v_mfma_f32_16x16x32_bf16 v[6:9], v[226:229], v[218:221], v[6:9]
	v_mfma_f32_16x16x32_bf16 v[2:5], v[234:237], v[218:221], v[2:5]
	v_mfma_f32_16x16x32_bf16 v[50:53], v[230:233], v[172:175], v[50:53]
	v_mfma_f32_16x16x32_bf16 v[42:45], v[238:241], v[172:175], v[42:45]
	v_mfma_f32_16x16x32_bf16 v[34:37], v[230:233], v[206:209], v[34:37]
	v_mfma_f32_16x16x32_bf16 v[26:29], v[238:241], v[206:209], v[26:29]
	v_mfma_f32_16x16x32_bf16 v[18:21], v[230:233], v[214:217], v[18:21]
	v_mfma_f32_16x16x32_bf16 v[10:13], v[238:241], v[214:217], v[10:13]
	v_mfma_f32_16x16x32_bf16 v[6:9], v[230:233], v[222:225], v[6:9]
	v_mfma_f32_16x16x32_bf16 v[2:5], v[238:241], v[222:225], v[2:5]
	s_setprio 0
	s_add_i32 s58, 0, 0x18000
	v_add_u32_e32 v154, s58, v144
	s_barrier
	ds_read_b128 v[140:143], v154
	ds_read_b128 v[156:159], v154 offset:1024
	ds_read_b128 v[160:163], v154 offset:2048
	ds_read_b128 v[164:167], v154 offset:3072
	s_add_u32 s0, s50, 0x20000
	s_addc_u32 s1, s51, 0
	s_mov_b32 m0, s84
	v_lshl_add_u64 v[154:155], s[0:1], 0, v[134:135]
	ds_read_b128 v[168:171], v145 offset:32768
	ds_read_b128 v[172:175], v145 offset:33792
	ds_read_b128 v[176:179], v145 offset:34816
	ds_read_b128 v[206:209], v145 offset:35840
	ds_read_b128 v[210:213], v145 offset:36864
	ds_read_b128 v[214:217], v145 offset:37888
	ds_read_b128 v[218:221], v145 offset:38912
	ds_read_b128 v[222:225], v145 offset:39936
	global_load_lds_dwordx4 v[154:155], off
	v_lshl_add_u64 v[154:155], s[0:1], 0, v[132:133]
	s_mov_b32 m0, s85
	s_nop 0
	global_load_lds_dwordx4 v[154:155], off
	s_waitcnt lgkmcnt(8)
	s_barrier
	s_waitcnt lgkmcnt(0)
	s_setprio 1
	v_mfma_f32_16x16x32_bf16 v[126:129], v[140:143], v[168:171], v[126:129]
	v_mfma_f32_16x16x32_bf16 v[122:125], v[160:163], v[168:171], v[122:125]
	v_mfma_f32_16x16x32_bf16 v[118:121], v[140:143], v[176:179], v[118:121]
	v_mfma_f32_16x16x32_bf16 v[110:113], v[160:163], v[176:179], v[110:113]
	v_mfma_f32_16x16x32_bf16 v[102:105], v[140:143], v[210:213], v[102:105]
	v_mfma_f32_16x16x32_bf16 v[94:97], v[160:163], v[210:213], v[94:97]
	v_mfma_f32_16x16x32_bf16 v[86:89], v[140:143], v[218:221], v[86:89]
	v_mfma_f32_16x16x32_bf16 v[78:81], v[160:163], v[218:221], v[78:81]
	v_mfma_f32_16x16x32_bf16 v[126:129], v[156:159], v[172:175], v[126:129]
	v_mfma_f32_16x16x32_bf16 v[122:125], v[164:167], v[172:175], v[122:125]
	v_mfma_f32_16x16x32_bf16 v[118:121], v[156:159], v[206:209], v[118:121]
	v_mfma_f32_16x16x32_bf16 v[110:113], v[164:167], v[206:209], v[110:113]
	v_mfma_f32_16x16x32_bf16 v[102:105], v[156:159], v[214:217], v[102:105]
	v_mfma_f32_16x16x32_bf16 v[94:97], v[164:167], v[214:217], v[94:97]
	v_mfma_f32_16x16x32_bf16 v[86:89], v[156:159], v[222:225], v[86:89]
	v_mfma_f32_16x16x32_bf16 v[78:81], v[164:167], v[222:225], v[78:81]
	s_setprio 0
	s_barrier
	s_add_i32 s50, 0, 0x1c000
	s_add_i32 s0, s58, s81
	v_add_u32_e32 v154, s50, v144
	v_lshl_add_u64 v[146:147], v[146:147], 0, s[16:17]
	s_mov_b32 m0, s0
	ds_read_b128 v[226:229], v154
	ds_read_b128 v[230:233], v154 offset:1024
	ds_read_b128 v[234:237], v154 offset:2048
	ds_read_b128 v[238:241], v154 offset:3072
	global_load_lds_dwordx4 v[146:147], off
	v_lshl_add_u64 v[146:147], v[148:149], 0, s[16:17]
	s_add_i32 m0, s0, 0x2000
	s_nop 0
	global_load_lds_dwordx4 v[146:147], off
	s_barrier
	s_waitcnt lgkmcnt(0)
	s_setprio 1
	v_mfma_f32_16x16x32_bf16 v[114:117], v[226:229], v[168:171], v[114:117]
	v_mfma_f32_16x16x32_bf16 v[106:109], v[234:237], v[168:171], v[106:109]
	v_mfma_f32_16x16x32_bf16 v[98:101], v[226:229], v[176:179], v[98:101]
	v_mfma_f32_16x16x32_bf16 v[90:93], v[234:237], v[176:179], v[90:93]
	v_mfma_f32_16x16x32_bf16 v[82:85], v[226:229], v[210:213], v[82:85]
	v_mfma_f32_16x16x32_bf16 v[74:77], v[234:237], v[210:213], v[74:77]
	v_mfma_f32_16x16x32_bf16 v[70:73], v[226:229], v[218:221], v[70:73]
	v_mfma_f32_16x16x32_bf16 v[66:69], v[234:237], v[218:221], v[66:69]
	v_mfma_f32_16x16x32_bf16 v[114:117], v[230:233], v[172:175], v[114:117]
	v_mfma_f32_16x16x32_bf16 v[106:109], v[238:241], v[172:175], v[106:109]
	v_mfma_f32_16x16x32_bf16 v[98:101], v[230:233], v[206:209], v[98:101]
	v_mfma_f32_16x16x32_bf16 v[90:93], v[238:241], v[206:209], v[90:93]
	v_mfma_f32_16x16x32_bf16 v[82:85], v[230:233], v[214:217], v[82:85]
	v_mfma_f32_16x16x32_bf16 v[74:77], v[238:241], v[214:217], v[74:77]
	v_mfma_f32_16x16x32_bf16 v[70:73], v[230:233], v[222:225], v[70:73]
	v_mfma_f32_16x16x32_bf16 v[66:69], v[238:241], v[222:225], v[66:69]
	s_setprio 0
	s_mov_b32 m0, s86
	v_lshl_add_u64 v[146:147], v[150:151], 0, s[16:17]
	s_barrier
	ds_read_b128 v[168:171], v145 offset:49152
	ds_read_b128 v[172:175], v145 offset:50176
	ds_read_b128 v[176:179], v145 offset:51200
	ds_read_b128 v[206:209], v145 offset:52224
	ds_read_b128 v[210:213], v145 offset:53248
	ds_read_b128 v[214:217], v145 offset:54272
	ds_read_b128 v[218:221], v145 offset:55296
	ds_read_b128 v[222:225], v145 offset:56320
	global_load_lds_dwordx4 v[146:147], off
	v_lshl_add_u64 v[146:147], v[152:153], 0, s[16:17]
	s_mov_b32 m0, s87
	s_nop 0
	global_load_lds_dwordx4 v[146:147], off
	s_barrier
; #define PG8_STAGEB(bufoff, gbase) PG8_STAGE_(bufoff, gbase, voffB)
; #define PG8_MMA(ai, bj, At, Bt) do { __builtin_amdgcn_s_setprio(1); _Pragma("unroll") for (int m = 0; m < 4; ++m) _Pragma("unroll") for (int n = 0; n < 2; ++n) _Pragma("unroll") for (int k = 0; k < 2; ++k) \
;         acc[ai][bj][m][n] = __builtin_amdgcn_mfma_f32_16x16x32_bf16(Bt[n][k], At[m][k], acc[ai][bj][m][n], 0, 0, 0); __builtin_amdgcn_s_setprio(0); } while (0)
; #define PG8_WAIT_V(n) asm volatile("s_waitcnt vmcnt(" #n ")" ::: "memory")
; #define PG8_WAIT_L(n) asm volatile("s_waitcnt lgkmcnt(" #n ")" ::: "memory")
; #define PG8_BAR __builtin_amdgcn_s_barrier()
; #define PG8_SCHED __builtin_amdgcn_sched_barrier(0)
; template <class Epi>
; __device__ __forceinline__ void gemm_phase(LAS unsigned char* lds, const Gemm g, const StaticOrder& S, const Epi& E) {
;     ...
;             PG8_BAR; PG8_WAIT_L(0); PG8_MMA(1, 0, At, B0); PG8_BAR; PG8_SCHED;
;             PG8_STAGEB(PG8_SB(1, 1), b3 + hstep);
;             PG8_WAIT_V(6); PG8_BAR; PG8_MMA(1, 1, At, B1); PG8_BAR;
	s_waitcnt lgkmcnt(0)
	s_setprio 1
	v_mfma_f32_16x16x32_bf16 v[62:65], v[140:143], v[168:171], v[62:65]
	v_mfma_f32_16x16x32_bf16 v[58:61], v[160:163], v[168:171], v[58:61]
	v_mfma_f32_16x16x32_bf16 v[54:57], v[140:143], v[176:179], v[54:57]
	v_mfma_f32_16x16x32_bf16 v[46:49], v[160:163], v[176:179], v[46:49]
	v_mfma_f32_16x16x32_bf16 v[38:41], v[140:143], v[210:213], v[38:41]
	v_mfma_f32_16x16x32_bf16 v[30:33], v[160:163], v[210:213], v[30:33]
	v_mfma_f32_16x16x32_bf16 v[22:25], v[140:143], v[218:221], v[22:25]
	v_mfma_f32_16x16x32_bf16 v[14:17], v[160:163], v[218:221], v[14:17]
	v_mfma_f32_16x16x32_bf16 v[62:65], v[156:159], v[172:175], v[62:65]
	v_mfma_f32_16x16x32_bf16 v[58:61], v[164:167], v[172:175], v[58:61]
	v_mfma_f32_16x16x32_bf16 v[54:57], v[156:159], v[206:209], v[54:57]
	v_mfma_f32_16x16x32_bf16 v[46:49], v[164:167], v[206:209], v[46:49]
	v_mfma_f32_16x16x32_bf16 v[38:41], v[156:159], v[214:217], v[38:41]
	v_mfma_f32_16x16x32_bf16 v[30:33], v[164:167], v[214:217], v[30:33]
	v_mfma_f32_16x16x32_bf16 v[22:25], v[156:159], v[222:225], v[22:25]
	v_mfma_f32_16x16x32_bf16 v[14:17], v[164:167], v[222:225], v[14:17]
	s_setprio 0
	s_barrier
	s_add_u32 s0, s20, 0x20080
	s_addc_u32 s1, s21, 0
	s_add_i32 s20, s50, s81
	v_lshl_add_u64 v[140:141], s[0:1], 0, v[0:1]
	s_mov_b32 m0, s20
	s_nop 0
	global_load_lds_dwordx4 v[140:141], off
	v_lshl_add_u64 v[140:141], s[0:1], 0, v[130:131]
	s_add_i32 m0, s20, 0x2000
	s_nop 0
	global_load_lds_dwordx4 v[140:141], off
	s_waitcnt vmcnt(6)
	s_barrier
	s_setprio 1
	v_mfma_f32_16x16x32_bf16 v[50:53], v[226:229], v[168:171], v[50:53]
	v_mfma_f32_16x16x32_bf16 v[42:45], v[234:237], v[168:171], v[42:45]
	v_mfma_f32_16x16x32_bf16 v[34:37], v[226:229], v[176:179], v[34:37]
	v_mfma_f32_16x16x32_bf16 v[26:29], v[234:237], v[176:179], v[26:29]
	v_mfma_f32_16x16x32_bf16 v[18:21], v[226:229], v[210:213], v[18:21]
	v_mfma_f32_16x16x32_bf16 v[10:13], v[234:237], v[210:213], v[10:13]
	v_mfma_f32_16x16x32_bf16 v[6:9], v[226:229], v[218:221], v[6:9]
	v_mfma_f32_16x16x32_bf16 v[2:5], v[234:237], v[218:221], v[2:5]
	v_mfma_f32_16x16x32_bf16 v[50:53], v[230:233], v[172:175], v[50:53]
	v_mfma_f32_16x16x32_bf16 v[42:45], v[238:241], v[172:175], v[42:45]
	v_mfma_f32_16x16x32_bf16 v[34:37], v[230:233], v[206:209], v[34:37]
	v_mfma_f32_16x16x32_bf16 v[26:29], v[238:241], v[206:209], v[26:29]
	v_mfma_f32_16x16x32_bf16 v[18:21], v[230:233], v[214:217], v[18:21]
	v_mfma_f32_16x16x32_bf16 v[10:13], v[238:241], v[214:217], v[10:13]
	v_mfma_f32_16x16x32_bf16 v[6:9], v[230:233], v[222:225], v[6:9]
	v_mfma_f32_16x16x32_bf16 v[2:5], v[238:241], v[222:225], v[2:5]
	s_setprio 0
	s_add_i32 vcc_hi, vcc_hi, 2
	s_add_u32 s30, s30, 0x100
	s_addc_u32 s31, s31, 0
	s_add_u32 s93, s93, 0x100
	s_addc_u32 vcc_lo, vcc_lo, 0
	s_cmp_gt_u32 vcc_hi, 5
	s_barrier
	s_cbranch_scc0 .LBB0_964
; __device__ __forceinline__ unsigned cvt_pk_bf16(float lo, float hi) { unsigned r; asm volatile("s_nop 0\n\tv_cvt_pk_bf16_f32 %0, %1, %2" : "=v"(r) : "v"(lo), "v"(hi)); return r; }
;     __device__ __forceinline__ void operator()(AccT& acc, const Unit& u, int wr, int wc, int fr, int fq) const {
;         int row0 = u.pm * 256 + wr * 64 + fr, col0 = u.pn * 256 + wc * 32 + 8 * fq;
;         asm volatile("" : "+v"(row0), "+v"(col0));
; #pragma unroll
;         for (int ai = 0; ai < 2; ++ai)
; #pragma unroll
;             for (int m = 0; m < 4; ++m) { bf16_t* rowp = O + (size_t)(row0 + ai * 128 + m * 16) * ldc + col0;
; #pragma unroll
;                 for (int bj = 0; bj < 2; ++bj) { const f32x4 v0 = acc[ai][bj][m][0], v1 = acc[ai][bj][m][1];
;                     u32x4 w; w.x = cvt_pk_bf16(v0[0], v0[1]); w.y = cvt_pk_bf16(v0[2], v0[3]); w.z = cvt_pk_bf16(v1[0], v1[1]); w.w = cvt_pk_bf16(v1[2], v1[3]);
;                     *(u32x4*)(rowp + bj * 128) = w; } }
	v_mov_b32_e32 v140, v250
	s_lshl_b32 s1, s90, 8
	v_readfirstlane_b32 s0, v140
	s_ashr_i32 s20, s0, 2
	s_andn2_b32 s20, s20, 63
	s_lshr_b32 s0, s0, 1
	s_add_i32 s20, s20, s1
	s_lshl_b32 s1, s89, 8
	s_and_b32 s0, s0, 0x60
	v_and_or_b32 v148, v140, 15, s20
	s_or_b32 s0, s0, s1
	v_lshrrev_b32_e32 v140, 1, v140
	v_and_or_b32 v142, v140, 24, s0
	v_mov_b64_e32 v[140:141], s[24:25]
	v_ashrrev_i32_e32 v143, 31, v142
	s_movk_i32 s4, 0x600
	v_mad_i64_i32 v[146:147], s[0:1], v148, s4, v[140:141]
	v_lshlrev_b64 v[142:143], 1, v[142:143]
	v_lshl_add_u64 v[146:147], v[146:147], 0, v[142:143]
	s_nop 0
	v_cvt_pk_bf16_f32 v126, v126, v127
	s_nop 0
	v_cvt_pk_bf16_f32 v127, v128, v129
	s_nop 0
	v_cvt_pk_bf16_f32 v128, v122, v123
	s_nop 0
	v_cvt_pk_bf16_f32 v129, v124, v125
	global_store_dwordx4 v[146:147], v[126:129], off
	s_nop 0
	v_cvt_pk_bf16_f32 v114, v114, v115
	s_nop 0
	v_cvt_pk_bf16_f32 v115, v116, v117
	s_nop 0
	v_cvt_pk_bf16_f32 v116, v106, v107
	v_add_u32_e32 v106, 16, v148
	v_mad_i64_i32 v[106:107], s[0:1], v106, s4, v[140:141]
	s_nop 0
	v_cvt_pk_bf16_f32 v117, v108, v109
	global_store_dwordx4 v[146:147], v[114:117], off offset:256
	s_and_b64 vcc, exec, s[42:43]
	s_mov_b32 s89, s34
	v_lshl_add_u64 v[114:115], v[106:107], 0, v[142:143]
	s_nop 0
	v_cvt_pk_bf16_f32 v106, v118, v119
	s_nop 0
	v_cvt_pk_bf16_f32 v107, v120, v121
	s_nop 0
	v_cvt_pk_bf16_f32 v108, v110, v111
	s_nop 0
	v_cvt_pk_bf16_f32 v109, v112, v113
	global_store_dwordx4 v[114:115], v[106:109], off
	s_nop 0
	v_cvt_pk_bf16_f32 v98, v98, v99
	s_nop 0
	v_cvt_pk_bf16_f32 v99, v100, v101
	s_nop 0
	v_cvt_pk_bf16_f32 v100, v90, v91
	v_add_u32_e32 v90, 32, v148
	v_mad_i64_i32 v[90:91], s[0:1], v90, s4, v[140:141]
	s_nop 0
	v_cvt_pk_bf16_f32 v101, v92, v93
	global_store_dwordx4 v[114:115], v[98:101], off offset:256
	s_mov_b32 s90, s44
	s_mov_b64 s[20:21], s[48:49]
	v_lshl_add_u64 v[98:99], v[90:91], 0, v[142:143]
	s_nop 0
	v_cvt_pk_bf16_f32 v90, v102, v103
	s_nop 0
	v_cvt_pk_bf16_f32 v91, v104, v105
	s_nop 0
	v_cvt_pk_bf16_f32 v92, v94, v95
	s_nop 0
	v_cvt_pk_bf16_f32 v93, v96, v97
	global_store_dwordx4 v[98:99], v[90:93], off
	s_nop 0
	v_cvt_pk_bf16_f32 v82, v82, v83
	s_nop 0
	v_cvt_pk_bf16_f32 v83, v84, v85
	s_nop 0
	v_cvt_pk_bf16_f32 v84, v74, v75
	v_add_u32_e32 v74, 48, v148
	v_mad_i64_i32 v[74:75], s[0:1], v74, s4, v[140:141]
	s_nop 0
	v_cvt_pk_bf16_f32 v85, v76, v77
	global_store_dwordx4 v[98:99], v[82:85], off offset:256
	s_mov_b64 s[30:31], s[46:47]
	s_nop 0
	v_lshl_add_u64 v[82:83], v[74:75], 0, v[142:143]
	s_nop 0
	v_cvt_pk_bf16_f32 v74, v86, v87
	s_nop 0
	v_cvt_pk_bf16_f32 v75, v88, v89
	s_nop 0
	v_cvt_pk_bf16_f32 v76, v78, v79
	s_nop 0
	v_cvt_pk_bf16_f32 v77, v80, v81
	global_store_dwordx4 v[82:83], v[74:77], off
	s_nop 0
	v_cvt_pk_bf16_f32 v70, v70, v71
	s_nop 0
	v_cvt_pk_bf16_f32 v71, v72, v73
	s_nop 0
	v_cvt_pk_bf16_f32 v72, v66, v67
	v_add_u32_e32 v66, 0x80, v148
	v_mad_i64_i32 v[66:67], s[0:1], v66, s4, v[140:141]
	v_lshl_add_u64 v[66:67], v[66:67], 0, v[142:143]
	s_nop 0
	v_cvt_pk_bf16_f32 v73, v68, v69
	global_store_dwordx4 v[82:83], v[70:73], off offset:256
	s_nop 0
	v_cvt_pk_bf16_f32 v62, v62, v63
	s_nop 0
	v_cvt_pk_bf16_f32 v63, v64, v65
	s_nop 0
	v_cvt_pk_bf16_f32 v64, v58, v59
	s_nop 0
	v_cvt_pk_bf16_f32 v65, v60, v61
	global_store_dwordx4 v[66:67], v[62:65], off
	s_nop 0
	v_cvt_pk_bf16_f32 v50, v50, v51
	s_nop 0
	v_cvt_pk_bf16_f32 v51, v52, v53
	s_nop 0
	v_cvt_pk_bf16_f32 v52, v42, v43
	v_add_u32_e32 v42, 0x90, v148
	v_mad_i64_i32 v[42:43], s[0:1], v42, s4, v[140:141]
	s_nop 0
	v_cvt_pk_bf16_f32 v53, v44, v45
	global_store_dwordx4 v[66:67], v[50:53], off offset:256
	s_nop 1
	v_lshl_add_u64 v[50:51], v[42:43], 0, v[142:143]
	s_nop 0
	v_cvt_pk_bf16_f32 v42, v54, v55
	s_nop 0
	v_cvt_pk_bf16_f32 v43, v56, v57
	s_nop 0
	v_cvt_pk_bf16_f32 v44, v46, v47
	s_nop 0
	v_cvt_pk_bf16_f32 v45, v48, v49
	global_store_dwordx4 v[50:51], v[42:45], off
	s_nop 0
	v_cvt_pk_bf16_f32 v34, v34, v35
	s_nop 0
	v_cvt_pk_bf16_f32 v35, v36, v37
	s_nop 0
	v_cvt_pk_bf16_f32 v36, v26, v27
	v_add_u32_e32 v26, 0xa0, v148
	v_mad_i64_i32 v[26:27], s[0:1], v26, s4, v[140:141]
	s_nop 0
	v_cvt_pk_bf16_f32 v37, v28, v29
	global_store_dwordx4 v[50:51], v[34:37], off offset:256
	s_nop 1
	v_lshl_add_u64 v[34:35], v[26:27], 0, v[142:143]
	s_nop 0
	v_cvt_pk_bf16_f32 v26, v38, v39
	s_nop 0
	v_cvt_pk_bf16_f32 v27, v40, v41
	s_nop 0
	v_cvt_pk_bf16_f32 v28, v30, v31
	s_nop 0
	v_cvt_pk_bf16_f32 v29, v32, v33
	global_store_dwordx4 v[34:35], v[26:29], off
	s_nop 0
	v_cvt_pk_bf16_f32 v18, v18, v19
	s_nop 0
	v_cvt_pk_bf16_f32 v19, v20, v21
	s_nop 0
	v_cvt_pk_bf16_f32 v20, v10, v11
	v_add_u32_e32 v10, 0xb0, v148
	v_mad_i64_i32 v[10:11], s[0:1], v10, s4, v[140:141]
	s_nop 0
	v_cvt_pk_bf16_f32 v21, v12, v13
	global_store_dwordx4 v[34:35], v[18:21], off offset:256
	s_nop 1
	v_lshl_add_u64 v[18:19], v[10:11], 0, v[142:143]
	s_nop 0
	v_cvt_pk_bf16_f32 v10, v22, v23
	s_nop 0
	v_cvt_pk_bf16_f32 v11, v24, v25
	s_nop 0
	v_cvt_pk_bf16_f32 v12, v14, v15
	s_nop 0
	v_cvt_pk_bf16_f32 v13, v16, v17
	global_store_dwordx4 v[18:19], v[10:13], off
	s_nop 0
	v_cvt_pk_bf16_f32 v6, v6, v7
	s_nop 0
	v_cvt_pk_bf16_f32 v7, v8, v9
	s_nop 0
	v_cvt_pk_bf16_f32 v8, v2, v3
	s_nop 0
	v_cvt_pk_bf16_f32 v9, v4, v5
	global_store_dwordx4 v[18:19], v[6:9], off offset:256
	s_cbranch_vccz .LBB0_961
	s_waitcnt vmcnt(0)
	v_readlane_b32 s44, v255, 52
	s_cmpk_gt_u32 s38, 0xff
	s_mov_b32 s86, 0x3fb8aa3b
	s_mov_b32 s89, 0x42b17218
	s_brev_b32 s90, 18
	v_readlane_b32 s45, v255, 53
	s_cbranch_scc1 .LBB0_968
	s_barrier

; __device__ __forceinline__ int fresh_tid() { int t = threadIdx.x; asm volatile("" : "+v"(t)); return t; }
; #define PG8_STAGE(bufoff, gbase) PG8_STAGE_(bufoff, gbase, voffA)
; #define PG8_STAGEB(bufoff, gbase) PG8_STAGE_(bufoff, gbase, voffB)
; #define PG8_WAIT_V(n) asm volatile("s_waitcnt vmcnt(" #n ")" ::: "memory")
; template <class Epi>
; __device__ __forceinline__ void gemm_phase(LAS unsigned char* lds, const Gemm g, const StaticOrder& S, const Epi& E) {
;     ...
;     const char* cA = (const char*)g.A + (size_t)cur.pm * tstep; const char* cB = (const char*)g.Bt + (size_t)cur.pn * tstep;
;     PG8_STAGEB(PG8_SB(0, 0), cB); PG8_STAGE(PG8_SA(0, 0), cA); PG8_STAGEB(PG8_SB(0, 1), cB + hstep); PG8_STAGE(PG8_SA(0, 1), cA + hstep);
;     if (wr == 1) PG8_BAR;
;     PG8_WAIT_V(4); PG8_BAR;
;     PG8_STAGEB(PG8_SB(1, 0), cB + kstep); PG8_STAGE(PG8_SA(1, 0), cA + kstep); PG8_STAGEB(PG8_SB(1, 1), cB + hstep + kstep);
;     PG8_WAIT_V(6); PG8_BAR;
;     for (;;) {
;         const bool has_next = S.next(ui + 1, nxt);
;         const char* nA = has_next ? (const char*)g.A + (size_t)nxt.pm * tstep : cA; const char* nB = has_next ? (const char*)g.Bt + (size_t)nxt.pn * tstep : cB;
;         for (int t = 0; t < nt; t += 2) {
;             const bool last = (t == nt - 2);
;             const char* a1 = cA + (size_t)(t + 1) * kstep;
;             const char* a2 = last ? nA : cA + (size_t)(t + 2) * kstep; const char* b2 = last ? nB : cB + (size_t)(t + 2) * kstep;
;             const char* a3 = a2 + kstep; const char* b3 = b2 + kstep;
;             if constexpr (Epi::RESCALE) { if (t != 0 && (t & 7) == 0) { const int t2 = fresh_tid(); const int w2 = __builtin_amdgcn_readfirstlane(t2 >> 6); E.rescale(acc, cur, t >> 3, w2 >> 2, w2 & 3, t2 & 15, (t2 >> 4) & 3); } }
;             PG8_LDB(B0, 0, 0); PG8_SCHED; PG8_LDA(At, 0, 0); PG8_STAGE(PG8_SA(1, 1), a1 + hstep);
;             PG8_WAIT_L(8); PG8_BAR; PG8_WAIT_L(0); PG8_MMA(0, 0, At, B0); PG8_BAR; PG8_SCHED;
;             PG8_LDB(B1, 0, 1); PG8_STAGEB(PG8_SB(0, 0), b2);
;             PG8_BAR; PG8_WAIT_L(0); PG8_MMA(0, 1, At, B1); PG8_BAR;
;             PG8_LDA(At, 0, 1); PG8_STAGE(PG8_SA(0, 0), a2);
;             PG8_BAR; PG8_WAIT_L(0); PG8_MMA(1, 0, At, B0); PG8_BAR; PG8_SCHED;
;             PG8_STAGEB(PG8_SB(0, 1), b2 + hstep);
;             PG8_WAIT_V(6); PG8_BAR; PG8_MMA(1, 1, At, B1); PG8_BAR;
.LBB0_976:
	s_ashr_i32 s47, s46, 31
	s_lshl_b64 s[0:1], s[46:47], 17
	v_mov_b64_e32 v[2:3], 0x80
	s_add_u32 s48, s81, s0
	v_cmp_lt_i64_e32 vcc, s[34:35], v[2:3]
	s_addc_u32 s49, s82, s1
	s_and_b64 s[0:1], vcc, exec
	s_cselect_b32 s21, s49, s53
	s_cselect_b32 s20, s48, s52
	s_ashr_i32 s45, s44, 31
	s_lshl_b64 s[0:1], s[44:45], 17
	s_add_u32 s30, s83, s0
	s_addc_u32 s31, s84, s1
	s_and_b64 s[0:1], vcc, exec
	s_cselect_b32 vcc_hi, s31, s55
	s_cselect_b32 vcc_lo, s30, s54
	s_add_i32 s47, 0, 0x10000
	v_add_u32_e32 v152, s47, v122
	ds_read_b128 v[2:5], v152
	ds_read_b128 v[6:9], v152 offset:1024
	ds_read_b128 v[10:13], v152 offset:2048
	ds_read_b128 v[14:17], v152 offset:3072
	v_mov_b32_e32 v186, v250
	v_mov_b32_e32 v180, v181
	v_mov_b32_e32 v181, v204
	v_mov_b32_e32 v204, v245
	s_mov_b32 s4, s65
	s_mov_b32 s65, s69
	s_mov_b32 s69, s79
	s_mov_b32 s79, s22
	s_mov_b64 s[18:19], s[96:97]
	s_mov_b64 s[22:23], s[94:95]
	v_mov_b32_e32 v184, v243
	s_add_u32 s94, s52, 0x10080
	s_addc_u32 s95, s53, 0
	s_add_i32 s1, s51, 0xc000
	v_lshl_add_u64 v[50:51], s[94:95], 0, v[98:99]
	s_mov_b32 m0, s1
	s_add_i32 s45, s51, 0xe000
	ds_read_b128 v[18:21], v123
	ds_read_b128 v[22:25], v123 offset:1024
	ds_read_b128 v[26:29], v123 offset:2048
	ds_read_b128 v[30:33], v123 offset:3072
	ds_read_b128 v[34:37], v123 offset:4096
	ds_read_b128 v[38:41], v123 offset:5120
	ds_read_b128 v[42:45], v123 offset:6144
	ds_read_b128 v[46:49], v123 offset:7168
	global_load_lds_dwordx4 v[50:51], off
	v_lshl_add_u64 v[50:51], s[94:95], 0, v[100:101]
	s_mov_b32 m0, s45
	s_nop 0
	global_load_lds_dwordx4 v[50:51], off
	s_waitcnt lgkmcnt(8)
	s_barrier
	s_waitcnt lgkmcnt(0)
	s_setprio 1
	v_mfma_f32_16x16x32_bf16 v[50:53], v[2:5], v[18:21], 0
	v_mfma_f32_16x16x32_bf16 v[54:57], v[10:13], v[18:21], 0
	v_mfma_f32_16x16x32_bf16 v[58:61], v[2:5], v[26:29], 0
	v_mfma_f32_16x16x32_bf16 v[62:65], v[10:13], v[26:29], 0
	v_mfma_f32_16x16x32_bf16 v[66:69], v[2:5], v[34:37], 0
	v_mfma_f32_16x16x32_bf16 v[70:73], v[10:13], v[34:37], 0
	v_mfma_f32_16x16x32_bf16 v[74:77], v[2:5], v[42:45], 0
	v_mfma_f32_16x16x32_bf16 v[78:81], v[10:13], v[42:45], 0
	v_mfma_f32_16x16x32_bf16 v[50:53], v[6:9], v[22:25], v[50:53]
	v_mfma_f32_16x16x32_bf16 v[54:57], v[14:17], v[22:25], v[54:57]
	v_mfma_f32_16x16x32_bf16 v[58:61], v[6:9], v[30:33], v[58:61]
	v_mfma_f32_16x16x32_bf16 v[62:65], v[14:17], v[30:33], v[62:65]
	v_mfma_f32_16x16x32_bf16 v[66:69], v[6:9], v[38:41], v[66:69]
	v_mfma_f32_16x16x32_bf16 v[70:73], v[14:17], v[38:41], v[70:73]
	v_mfma_f32_16x16x32_bf16 v[74:77], v[6:9], v[46:49], v[74:77]
	v_mfma_f32_16x16x32_bf16 v[78:81], v[14:17], v[46:49], v[78:81]
	s_setprio 0
	s_barrier
	s_add_i32 s93, 0, 0x14000
	v_lshl_add_u64 v[120:121], s[54:55], 0, v[0:1]
	s_mov_b64 s[58:59], 0x100
	s_add_i32 s47, s47, s85
	v_add_u32_e32 v153, s93, v122
	v_lshl_add_u64 v[104:105], v[120:121], 0, s[58:59]
	s_mov_b32 m0, s47
	v_lshl_add_u64 v[144:145], s[54:55], 0, v[102:103]
	s_add_i32 s0, s47, 0x2000
	ds_read_b128 v[82:85], v153
	ds_read_b128 v[86:89], v153 offset:1024
	ds_read_b128 v[90:93], v153 offset:2048
	ds_read_b128 v[94:97], v153 offset:3072
	global_load_lds_dwordx4 v[104:105], off
	v_lshl_add_u64 v[104:105], v[144:145], 0, s[58:59]
	s_mov_b32 m0, s0
	s_nop 0
	global_load_lds_dwordx4 v[104:105], off
	s_barrier
	s_waitcnt lgkmcnt(0)
	s_setprio 1
	v_mfma_f32_16x16x32_bf16 v[104:107], v[82:85], v[18:21], 0
	v_mfma_f32_16x16x32_bf16 v[18:21], v[90:93], v[18:21], 0
	v_mfma_f32_16x16x32_bf16 v[104:107], v[86:89], v[22:25], v[104:107]
	v_mfma_f32_16x16x32_bf16 v[18:21], v[94:97], v[22:25], v[18:21]
	v_mfma_f32_16x16x32_bf16 v[22:25], v[82:85], v[26:29], 0
	v_mfma_f32_16x16x32_bf16 v[26:29], v[90:93], v[26:29], 0
	v_mfma_f32_16x16x32_bf16 v[22:25], v[86:89], v[30:33], v[22:25]
	v_mfma_f32_16x16x32_bf16 v[26:29], v[94:97], v[30:33], v[26:29]
	v_mfma_f32_16x16x32_bf16 v[30:33], v[82:85], v[34:37], 0
	v_mfma_f32_16x16x32_bf16 v[34:37], v[90:93], v[34:37], 0
	v_mfma_f32_16x16x32_bf16 v[30:33], v[86:89], v[38:41], v[30:33]
	v_mfma_f32_16x16x32_bf16 v[34:37], v[94:97], v[38:41], v[34:37]
	v_mfma_f32_16x16x32_bf16 v[38:41], v[82:85], v[42:45], 0
	v_mfma_f32_16x16x32_bf16 v[42:45], v[90:93], v[42:45], 0
	v_mfma_f32_16x16x32_bf16 v[38:41], v[86:89], v[46:49], v[38:41]
	v_mfma_f32_16x16x32_bf16 v[42:45], v[94:97], v[46:49], v[42:45]
	s_setprio 0
	v_lshl_add_u64 v[146:147], s[52:53], 0, v[98:99]
	s_mov_b32 m0, s51
	v_lshl_add_u64 v[140:141], v[146:147], 0, s[58:59]
	v_lshl_add_u64 v[148:149], s[52:53], 0, v[100:101]
	s_barrier
	ds_read_b128 v[46:49], v123 offset:16384
	ds_read_b128 v[108:111], v123 offset:17408
	ds_read_b128 v[112:115], v123 offset:18432
	ds_read_b128 v[116:119], v123 offset:19456
	ds_read_b128 v[124:127], v123 offset:20480
	ds_read_b128 v[128:131], v123 offset:21504
	ds_read_b128 v[132:135], v123 offset:22528
	ds_read_b128 v[136:139], v123 offset:23552
	global_load_lds_dwordx4 v[140:141], off
	v_lshl_add_u64 v[140:141], v[148:149], 0, s[58:59]
	s_mov_b32 m0, s86
	s_nop 0
	global_load_lds_dwordx4 v[140:141], off
	s_barrier
	s_waitcnt lgkmcnt(0)
	s_setprio 1
	v_mfma_f32_16x16x32_bf16 v[140:143], v[2:5], v[46:49], 0
	v_mfma_f32_16x16x32_bf16 v[160:163], v[2:5], v[112:115], 0
	v_mfma_f32_16x16x32_bf16 v[168:171], v[2:5], v[124:127], 0
	v_mfma_f32_16x16x32_bf16 v[2:5], v[2:5], v[132:135], 0
	v_mfma_f32_16x16x32_bf16 v[140:143], v[6:9], v[108:111], v[140:143]
	v_mfma_f32_16x16x32_bf16 v[156:159], v[10:13], v[46:49], 0
	v_mfma_f32_16x16x32_bf16 v[160:163], v[6:9], v[116:119], v[160:163]
	v_mfma_f32_16x16x32_bf16 v[164:167], v[10:13], v[112:115], 0
	v_mfma_f32_16x16x32_bf16 v[168:171], v[6:9], v[128:131], v[168:171]
	v_mfma_f32_16x16x32_bf16 v[172:175], v[10:13], v[124:127], 0
	v_mfma_f32_16x16x32_bf16 v[2:5], v[6:9], v[136:139], v[2:5]
	v_mfma_f32_16x16x32_bf16 v[6:9], v[10:13], v[132:135], 0
	v_mfma_f32_16x16x32_bf16 v[156:159], v[14:17], v[108:111], v[156:159]
	v_mfma_f32_16x16x32_bf16 v[164:167], v[14:17], v[116:119], v[164:167]
	v_mfma_f32_16x16x32_bf16 v[172:175], v[14:17], v[128:131], v[172:175]
	v_mfma_f32_16x16x32_bf16 v[6:9], v[14:17], v[136:139], v[6:9]
	s_setprio 0
	s_barrier
; #define PG8_STAGE(bufoff, gbase) PG8_STAGE_(bufoff, gbase, voffA)
; #define PG8_STAGEB(bufoff, gbase) PG8_STAGE_(bufoff, gbase, voffB)
; #define PG8_LDA(dst, b, h) do { _Pragma("unroll") for (int m = 0; m < 4; ++m) _Pragma("unroll") for (int k = 0; k < 2; ++k) dst[m][k] = *(const LAS bf16x8*)(lds + PG8_SA(b, h) + aoff + m * 2048 + k * 1024); } while (0)
; #define PG8_LDB(dst, b, h) do { _Pragma("unroll") for (int n = 0; n < 2; ++n) _Pragma("unroll") for (int k = 0; k < 2; ++k) dst[n][k] = *(const LAS bf16x8*)(lds + PG8_SB(b, h) + boff + n * 2048 + k * 1024); } while (0)
; #define PG8_MMA(ai, bj, At, Bt) do { __builtin_amdgcn_s_setprio(1); _Pragma("unroll") for (int m = 0; m < 4; ++m) _Pragma("unroll") for (int n = 0; n < 2; ++n) _Pragma("unroll") for (int k = 0; k < 2; ++k) \
;         acc[ai][bj][m][n] = __builtin_amdgcn_mfma_f32_16x16x32_bf16(Bt[n][k], At[m][k], acc[ai][bj][m][n], 0, 0, 0); __builtin_amdgcn_s_setprio(0); } while (0)
; #define PG8_WAIT_V(n) asm volatile("s_waitcnt vmcnt(" #n ")" ::: "memory")
; #define PG8_WAIT_L(n) asm volatile("s_waitcnt lgkmcnt(" #n ")" ::: "memory")
; #define PG8_BAR __builtin_amdgcn_s_barrier()
; #define PG8_SCHED __builtin_amdgcn_sched_barrier(0)
; template <class Epi>
; __device__ __forceinline__ void gemm_phase(LAS unsigned char* lds, const Gemm g, const StaticOrder& S, const Epi& E) {
;     ...
;             PG8_STAGEB(PG8_SB(0, 1), b2 + hstep);
;             PG8_WAIT_V(6); PG8_BAR; PG8_MMA(1, 1, At, B1); PG8_BAR;
;             PG8_LDB(B0, 1, 0); PG8_SCHED; PG8_LDA(At, 1, 0); PG8_STAGE(PG8_SA(0, 1), a2 + hstep);
;             PG8_WAIT_L(8); PG8_BAR; PG8_WAIT_L(0); PG8_MMA(0, 0, At, B0); PG8_BAR; PG8_SCHED;
;             PG8_LDB(B1, 1, 1); PG8_STAGEB(PG8_SB(1, 0), b3);
;             PG8_BAR; PG8_WAIT_L(0); PG8_MMA(0, 1, At, B1); PG8_BAR;
;             PG8_LDA(At, 1, 1); PG8_STAGE(PG8_SA(1, 0), a3);
;             PG8_BAR; PG8_WAIT_L(0); PG8_MMA(1, 0, At, B0); PG8_BAR; PG8_SCHED;
	s_add_u32 s94, s54, 0x10100
	s_addc_u32 s95, s55, 0
	s_add_i32 s93, s93, s85
	v_lshl_add_u64 v[10:11], s[94:95], 0, v[0:1]
	s_mov_b32 m0, s93
	s_nop 0
	global_load_lds_dwordx4 v[10:11], off
	v_lshl_add_u64 v[10:11], s[94:95], 0, v[102:103]
	s_add_i32 s94, s93, 0x2000
	s_mov_b32 m0, s94
	s_nop 0
	global_load_lds_dwordx4 v[10:11], off
	s_waitcnt vmcnt(6)
	s_barrier
	s_setprio 1
	v_mfma_f32_16x16x32_bf16 v[10:13], v[82:85], v[46:49], 0
	v_mfma_f32_16x16x32_bf16 v[14:17], v[90:93], v[46:49], 0
	v_mfma_f32_16x16x32_bf16 v[10:13], v[86:89], v[108:111], v[10:13]
	v_mfma_f32_16x16x32_bf16 v[14:17], v[94:97], v[108:111], v[14:17]
	v_mfma_f32_16x16x32_bf16 v[46:49], v[82:85], v[112:115], 0
	v_mfma_f32_16x16x32_bf16 v[108:111], v[90:93], v[112:115], 0
	v_mfma_f32_16x16x32_bf16 v[112:115], v[82:85], v[124:127], 0
	v_mfma_f32_16x16x32_bf16 v[82:85], v[82:85], v[132:135], 0
	v_mfma_f32_16x16x32_bf16 v[46:49], v[86:89], v[116:119], v[46:49]
	v_mfma_f32_16x16x32_bf16 v[108:111], v[94:97], v[116:119], v[108:111]
	v_mfma_f32_16x16x32_bf16 v[112:115], v[86:89], v[128:131], v[112:115]
	v_mfma_f32_16x16x32_bf16 v[116:119], v[90:93], v[124:127], 0
	v_mfma_f32_16x16x32_bf16 v[82:85], v[86:89], v[136:139], v[82:85]
	v_mfma_f32_16x16x32_bf16 v[86:89], v[90:93], v[132:135], 0
	v_mfma_f32_16x16x32_bf16 v[116:119], v[94:97], v[128:131], v[116:119]
	v_mfma_f32_16x16x32_bf16 v[86:89], v[94:97], v[136:139], v[86:89]
	s_setprio 0
	s_add_i32 s95, 0, 0x18000
	v_add_u32_e32 v154, s95, v122
	s_barrier
	ds_read_b128 v[90:93], v154
	ds_read_b128 v[94:97], v154 offset:1024
	ds_read_b128 v[124:127], v154 offset:2048
	ds_read_b128 v[128:131], v154 offset:3072
	s_add_u32 s96, s52, 0x10100
	s_addc_u32 s97, s53, 0
	s_mov_b32 m0, s87
	v_lshl_add_u64 v[150:151], s[96:97], 0, v[98:99]
	ds_read_b128 v[132:135], v123 offset:32768
	ds_read_b128 v[136:139], v123 offset:33792
	ds_read_b128 v[176:179], v123 offset:34816
	ds_read_b128 v[206:209], v123 offset:35840
	ds_read_b128 v[210:213], v123 offset:36864
	ds_read_b128 v[214:217], v123 offset:37888
	ds_read_b128 v[218:221], v123 offset:38912
	ds_read_b128 v[222:225], v123 offset:39936
	global_load_lds_dwordx4 v[150:151], off
	v_lshl_add_u64 v[150:151], s[96:97], 0, v[100:101]
	s_mov_b32 m0, s88
	s_nop 0
	global_load_lds_dwordx4 v[150:151], off
	s_waitcnt lgkmcnt(8)
	s_barrier
	s_waitcnt lgkmcnt(0)
	s_setprio 1
	v_mfma_f32_16x16x32_bf16 v[50:53], v[90:93], v[132:135], v[50:53]
	v_mfma_f32_16x16x32_bf16 v[54:57], v[124:127], v[132:135], v[54:57]
	v_mfma_f32_16x16x32_bf16 v[58:61], v[90:93], v[176:179], v[58:61]
	v_mfma_f32_16x16x32_bf16 v[62:65], v[124:127], v[176:179], v[62:65]
	v_mfma_f32_16x16x32_bf16 v[66:69], v[90:93], v[210:213], v[66:69]
	v_mfma_f32_16x16x32_bf16 v[70:73], v[124:127], v[210:213], v[70:73]
	v_mfma_f32_16x16x32_bf16 v[74:77], v[90:93], v[218:221], v[74:77]
	v_mfma_f32_16x16x32_bf16 v[78:81], v[124:127], v[218:221], v[78:81]
	v_mfma_f32_16x16x32_bf16 v[50:53], v[94:97], v[136:139], v[50:53]
	v_mfma_f32_16x16x32_bf16 v[54:57], v[128:131], v[136:139], v[54:57]
	v_mfma_f32_16x16x32_bf16 v[58:61], v[94:97], v[206:209], v[58:61]
	v_mfma_f32_16x16x32_bf16 v[62:65], v[128:131], v[206:209], v[62:65]
	v_mfma_f32_16x16x32_bf16 v[66:69], v[94:97], v[214:217], v[66:69]
	v_mfma_f32_16x16x32_bf16 v[70:73], v[128:131], v[214:217], v[70:73]
	v_mfma_f32_16x16x32_bf16 v[74:77], v[94:97], v[222:225], v[74:77]
	v_mfma_f32_16x16x32_bf16 v[78:81], v[128:131], v[222:225], v[78:81]
	s_setprio 0
	s_barrier
	s_add_i32 s97, 0, 0x1c000
	s_mov_b64 s[58:59], 0x180
	s_add_i32 s95, s95, s85
	v_add_u32_e32 v155, s97, v122
	v_lshl_add_u64 v[120:121], v[120:121], 0, s[58:59]
	s_mov_b32 m0, s95
	s_add_i32 s96, s95, 0x2000
	ds_read_b128 v[226:229], v155
	ds_read_b128 v[230:233], v155 offset:1024
	ds_read_b128 v[234:237], v155 offset:2048
	ds_read_b128 v[238:241], v155 offset:3072
	global_load_lds_dwordx4 v[120:121], off
	v_lshl_add_u64 v[120:121], v[144:145], 0, s[58:59]
	s_mov_b32 m0, s96
	s_nop 0
	global_load_lds_dwordx4 v[120:121], off
	s_barrier
	s_waitcnt lgkmcnt(0)
	s_setprio 1
	v_mfma_f32_16x16x32_bf16 v[104:107], v[226:229], v[132:135], v[104:107]
	v_mfma_f32_16x16x32_bf16 v[18:21], v[234:237], v[132:135], v[18:21]
	v_mfma_f32_16x16x32_bf16 v[22:25], v[226:229], v[176:179], v[22:25]
	v_mfma_f32_16x16x32_bf16 v[26:29], v[234:237], v[176:179], v[26:29]
	v_mfma_f32_16x16x32_bf16 v[30:33], v[226:229], v[210:213], v[30:33]
	v_mfma_f32_16x16x32_bf16 v[34:37], v[234:237], v[210:213], v[34:37]
	v_mfma_f32_16x16x32_bf16 v[38:41], v[226:229], v[218:221], v[38:41]
	v_mfma_f32_16x16x32_bf16 v[42:45], v[234:237], v[218:221], v[42:45]
	v_mfma_f32_16x16x32_bf16 v[104:107], v[230:233], v[136:139], v[104:107]
	v_mfma_f32_16x16x32_bf16 v[18:21], v[238:241], v[136:139], v[18:21]
	v_mfma_f32_16x16x32_bf16 v[22:25], v[230:233], v[206:209], v[22:25]
	v_mfma_f32_16x16x32_bf16 v[26:29], v[238:241], v[206:209], v[26:29]
	v_mfma_f32_16x16x32_bf16 v[30:33], v[230:233], v[214:217], v[30:33]
	v_mfma_f32_16x16x32_bf16 v[34:37], v[238:241], v[214:217], v[34:37]
	v_mfma_f32_16x16x32_bf16 v[38:41], v[230:233], v[222:225], v[38:41]
	v_mfma_f32_16x16x32_bf16 v[42:45], v[238:241], v[222:225], v[42:45]
	s_setprio 0
	s_mov_b32 m0, s89
	v_lshl_add_u64 v[120:121], v[146:147], 0, s[58:59]
	s_barrier
	ds_read_b128 v[132:135], v123 offset:49152
	ds_read_b128 v[136:139], v123 offset:50176
	ds_read_b128 v[176:179], v123 offset:51200
	ds_read_b128 v[206:209], v123 offset:52224
	ds_read_b128 v[210:213], v123 offset:53248
	ds_read_b128 v[214:217], v123 offset:54272
	ds_read_b128 v[218:221], v123 offset:55296
	ds_read_b128 v[222:225], v123 offset:56320
	global_load_lds_dwordx4 v[120:121], off
	v_lshl_add_u64 v[120:121], v[148:149], 0, s[58:59]
	s_mov_b32 m0, s90
	s_nop 0
	global_load_lds_dwordx4 v[120:121], off
	s_barrier
; #define PG8_STAGE(bufoff, gbase) PG8_STAGE_(bufoff, gbase, voffA)
; #define PG8_STAGEB(bufoff, gbase) PG8_STAGE_(bufoff, gbase, voffB)
; #define PG8_LDA(dst, b, h) do { _Pragma("unroll") for (int m = 0; m < 4; ++m) _Pragma("unroll") for (int k = 0; k < 2; ++k) dst[m][k] = *(const LAS bf16x8*)(lds + PG8_SA(b, h) + aoff + m * 2048 + k * 1024); } while (0)
; #define PG8_LDB(dst, b, h) do { _Pragma("unroll") for (int n = 0; n < 2; ++n) _Pragma("unroll") for (int k = 0; k < 2; ++k) dst[n][k] = *(const LAS bf16x8*)(lds + PG8_SB(b, h) + boff + n * 2048 + k * 1024); } while (0)
; #define PG8_MMA(ai, bj, At, Bt) do { __builtin_amdgcn_s_setprio(1); _Pragma("unroll") for (int m = 0; m < 4; ++m) _Pragma("unroll") for (int n = 0; n < 2; ++n) _Pragma("unroll") for (int k = 0; k < 2; ++k) \
;         acc[ai][bj][m][n] = __builtin_amdgcn_mfma_f32_16x16x32_bf16(Bt[n][k], At[m][k], acc[ai][bj][m][n], 0, 0, 0); __builtin_amdgcn_s_setprio(0); } while (0)
; #define PG8_WAIT_V(n) asm volatile("s_waitcnt vmcnt(" #n ")" ::: "memory")
; template <class Epi>
; __device__ __forceinline__ void gemm_phase(LAS unsigned char* lds, const Gemm g, const StaticOrder& S, const Epi& E) {
;     ...
;             PG8_LDB(B0, 0, 0); PG8_SCHED; PG8_LDA(At, 0, 0); PG8_STAGE(PG8_SA(1, 1), a1 + hstep);
;             PG8_WAIT_L(8); PG8_BAR; PG8_WAIT_L(0); PG8_MMA(0, 0, At, B0); PG8_BAR; PG8_SCHED;
;             PG8_LDB(B1, 0, 1); PG8_STAGEB(PG8_SB(0, 0), b2);
;             PG8_BAR; PG8_WAIT_L(0); PG8_MMA(0, 1, At, B1); PG8_BAR;
;             PG8_LDA(At, 0, 1); PG8_STAGE(PG8_SA(0, 0), a2);
;             PG8_BAR; PG8_WAIT_L(0); PG8_MMA(1, 0, At, B0); PG8_BAR; PG8_SCHED;
;             PG8_STAGEB(PG8_SB(0, 1), b2 + hstep);
;             PG8_WAIT_V(6); PG8_BAR; PG8_MMA(1, 1, At, B1); PG8_BAR;
;             PG8_LDB(B0, 1, 0); PG8_SCHED; PG8_LDA(At, 1, 0); PG8_STAGE(PG8_SA(0, 1), a2 + hstep);
;             PG8_WAIT_L(8); PG8_BAR; PG8_WAIT_L(0); PG8_MMA(0, 0, At, B0); PG8_BAR; PG8_SCHED;
;             PG8_LDB(B1, 1, 1); PG8_STAGEB(PG8_SB(1, 0), b3);
;             PG8_BAR; PG8_WAIT_L(0); PG8_MMA(0, 1, At, B1); PG8_BAR;
;             PG8_LDA(At, 1, 1); PG8_STAGE(PG8_SA(1, 0), a3);
;             PG8_BAR; PG8_WAIT_L(0); PG8_MMA(1, 0, At, B0); PG8_BAR; PG8_SCHED;
;             PG8_STAGEB(PG8_SB(1, 1), b3 + hstep);
;             PG8_WAIT_V(6); PG8_BAR; PG8_MMA(1, 1, At, B1); PG8_BAR;
	s_waitcnt lgkmcnt(0)
	s_setprio 1
	v_mfma_f32_16x16x32_bf16 v[140:143], v[90:93], v[132:135], v[140:143]
	v_mfma_f32_16x16x32_bf16 v[156:159], v[124:127], v[132:135], v[156:159]
	v_mfma_f32_16x16x32_bf16 v[160:163], v[90:93], v[176:179], v[160:163]
	v_mfma_f32_16x16x32_bf16 v[164:167], v[124:127], v[176:179], v[164:167]
	v_mfma_f32_16x16x32_bf16 v[168:171], v[90:93], v[210:213], v[168:171]
	v_mfma_f32_16x16x32_bf16 v[172:175], v[124:127], v[210:213], v[172:175]
	v_mfma_f32_16x16x32_bf16 v[2:5], v[90:93], v[218:221], v[2:5]
	v_mfma_f32_16x16x32_bf16 v[6:9], v[124:127], v[218:221], v[6:9]
	v_mfma_f32_16x16x32_bf16 v[140:143], v[94:97], v[136:139], v[140:143]
	v_mfma_f32_16x16x32_bf16 v[156:159], v[128:131], v[136:139], v[156:159]
	v_mfma_f32_16x16x32_bf16 v[160:163], v[94:97], v[206:209], v[160:163]
	v_mfma_f32_16x16x32_bf16 v[164:167], v[128:131], v[206:209], v[164:167]
	v_mfma_f32_16x16x32_bf16 v[168:171], v[94:97], v[214:217], v[168:171]
	v_mfma_f32_16x16x32_bf16 v[172:175], v[128:131], v[214:217], v[172:175]
	v_mfma_f32_16x16x32_bf16 v[2:5], v[94:97], v[222:225], v[2:5]
	v_mfma_f32_16x16x32_bf16 v[6:9], v[128:131], v[222:225], v[6:9]
	s_setprio 0
	s_barrier
	s_add_u32 s58, s54, 0x10180
	s_addc_u32 s59, s55, 0
	s_add_i32 s55, s97, s85
	v_lshl_add_u64 v[90:91], s[58:59], 0, v[0:1]
	s_mov_b32 m0, s55
	s_add_i32 s54, s55, 0x2000
	global_load_lds_dwordx4 v[90:91], off
	v_lshl_add_u64 v[90:91], s[58:59], 0, v[102:103]
	s_mov_b32 m0, s54
	s_nop 0
	global_load_lds_dwordx4 v[90:91], off
	s_waitcnt vmcnt(6)
	s_barrier
	s_setprio 1
	v_mfma_f32_16x16x32_bf16 v[10:13], v[226:229], v[132:135], v[10:13]
	v_mfma_f32_16x16x32_bf16 v[14:17], v[234:237], v[132:135], v[14:17]
	v_mfma_f32_16x16x32_bf16 v[46:49], v[226:229], v[176:179], v[46:49]
	v_mfma_f32_16x16x32_bf16 v[90:93], v[234:237], v[176:179], v[108:111]
	v_mfma_f32_16x16x32_bf16 v[94:97], v[226:229], v[210:213], v[112:115]
	v_mfma_f32_16x16x32_bf16 v[108:111], v[234:237], v[210:213], v[116:119]
	v_mfma_f32_16x16x32_bf16 v[82:85], v[226:229], v[218:221], v[82:85]
	v_mfma_f32_16x16x32_bf16 v[86:89], v[234:237], v[218:221], v[86:89]
	v_mfma_f32_16x16x32_bf16 v[10:13], v[230:233], v[136:139], v[10:13]
	v_mfma_f32_16x16x32_bf16 v[14:17], v[238:241], v[136:139], v[14:17]
	v_mfma_f32_16x16x32_bf16 v[46:49], v[230:233], v[206:209], v[46:49]
	v_mfma_f32_16x16x32_bf16 v[90:93], v[238:241], v[206:209], v[90:93]
	v_mfma_f32_16x16x32_bf16 v[94:97], v[230:233], v[214:217], v[94:97]
	v_mfma_f32_16x16x32_bf16 v[108:111], v[238:241], v[214:217], v[108:111]
	v_mfma_f32_16x16x32_bf16 v[82:85], v[230:233], v[222:225], v[82:85]
	v_mfma_f32_16x16x32_bf16 v[86:89], v[238:241], v[222:225], v[86:89]
	s_setprio 0
	s_barrier
	ds_read_b128 v[112:115], v152
	ds_read_b128 v[116:119], v152 offset:1024
	ds_read_b128 v[124:127], v152 offset:2048
	ds_read_b128 v[128:131], v152 offset:3072
	s_add_u32 s52, s52, 0x10180
	s_addc_u32 s53, s53, 0
	s_mov_b32 m0, s1
	v_lshl_add_u64 v[120:121], s[52:53], 0, v[98:99]
	ds_read_b128 v[132:135], v123
	ds_read_b128 v[136:139], v123 offset:1024
	ds_read_b128 v[176:179], v123 offset:2048
	ds_read_b128 v[206:209], v123 offset:3072
	ds_read_b128 v[210:213], v123 offset:4096
	ds_read_b128 v[214:217], v123 offset:5120
	ds_read_b128 v[218:221], v123 offset:6144
	ds_read_b128 v[222:225], v123 offset:7168
	global_load_lds_dwordx4 v[120:121], off
	v_lshl_add_u64 v[120:121], s[52:53], 0, v[100:101]
	s_mov_b32 m0, s45
	s_nop 0
	global_load_lds_dwordx4 v[120:121], off
	s_waitcnt lgkmcnt(8)
	s_barrier
	s_waitcnt lgkmcnt(0)
	s_setprio 1
	v_mfma_f32_16x16x32_bf16 v[50:53], v[112:115], v[132:135], v[50:53]
	v_mfma_f32_16x16x32_bf16 v[54:57], v[124:127], v[132:135], v[54:57]
	v_mfma_f32_16x16x32_bf16 v[58:61], v[112:115], v[176:179], v[58:61]
	v_mfma_f32_16x16x32_bf16 v[62:65], v[124:127], v[176:179], v[62:65]
	v_mfma_f32_16x16x32_bf16 v[66:69], v[112:115], v[210:213], v[66:69]
	v_mfma_f32_16x16x32_bf16 v[70:73], v[124:127], v[210:213], v[70:73]
	v_mfma_f32_16x16x32_bf16 v[74:77], v[112:115], v[218:221], v[74:77]
	v_mfma_f32_16x16x32_bf16 v[78:81], v[124:127], v[218:221], v[78:81]
	v_mfma_f32_16x16x32_bf16 v[50:53], v[116:119], v[136:139], v[50:53]
	v_mfma_f32_16x16x32_bf16 v[54:57], v[128:131], v[136:139], v[54:57]
	v_mfma_f32_16x16x32_bf16 v[58:61], v[116:119], v[206:209], v[58:61]
	v_mfma_f32_16x16x32_bf16 v[62:65], v[128:131], v[206:209], v[62:65]
	v_mfma_f32_16x16x32_bf16 v[66:69], v[116:119], v[214:217], v[66:69]
	v_mfma_f32_16x16x32_bf16 v[70:73], v[128:131], v[214:217], v[70:73]
	v_mfma_f32_16x16x32_bf16 v[74:77], v[116:119], v[222:225], v[74:77]
	v_mfma_f32_16x16x32_bf16 v[78:81], v[128:131], v[222:225], v[78:81]
	s_setprio 0
	s_barrier
	s_mov_b32 m0, s47
	v_lshl_add_u64 v[120:121], vcc, 0, v[0:1]
	ds_read_b128 v[226:229], v153
	ds_read_b128 v[230:233], v153 offset:1024
	ds_read_b128 v[234:237], v153 offset:2048
	ds_read_b128 v[238:241], v153 offset:3072
	global_load_lds_dwordx4 v[120:121], off
	v_lshl_add_u64 v[188:189], vcc, 0, v[102:103]
	s_mov_b32 m0, s0
	s_nop 0
	global_load_lds_dwordx4 v[188:189], off
	s_barrier
; #define PG8_STAGE(bufoff, gbase) PG8_STAGE_(bufoff, gbase, voffA)
; #define PG8_STAGEB(bufoff, gbase) PG8_STAGE_(bufoff, gbase, voffB)
; #define PG8_LDA(dst, b, h) do { _Pragma("unroll") for (int m = 0; m < 4; ++m) _Pragma("unroll") for (int k = 0; k < 2; ++k) dst[m][k] = *(const LAS bf16x8*)(lds + PG8_SA(b, h) + aoff + m * 2048 + k * 1024); } while (0)
; #define PG8_LDB(dst, b, h) do { _Pragma("unroll") for (int n = 0; n < 2; ++n) _Pragma("unroll") for (int k = 0; k < 2; ++k) dst[n][k] = *(const LAS bf16x8*)(lds + PG8_SB(b, h) + boff + n * 2048 + k * 1024); } while (0)
; #define PG8_MMA(ai, bj, At, Bt) do { __builtin_amdgcn_s_setprio(1); _Pragma("unroll") for (int m = 0; m < 4; ++m) _Pragma("unroll") for (int n = 0; n < 2; ++n) _Pragma("unroll") for (int k = 0; k < 2; ++k) \
;         acc[ai][bj][m][n] = __builtin_amdgcn_mfma_f32_16x16x32_bf16(Bt[n][k], At[m][k], acc[ai][bj][m][n], 0, 0, 0); __builtin_amdgcn_s_setprio(0); } while (0)
; #define PG8_WAIT_V(n) asm volatile("s_waitcnt vmcnt(" #n ")" ::: "memory")
; template <class Epi>
; __device__ __forceinline__ void gemm_phase(LAS unsigned char* lds, const Gemm g, const StaticOrder& S, const Epi& E) {
;     ...
;             PG8_LDB(B0, 0, 0); PG8_SCHED; PG8_LDA(At, 0, 0); PG8_STAGE(PG8_SA(1, 1), a1 + hstep);
;             PG8_WAIT_L(8); PG8_BAR; PG8_WAIT_L(0); PG8_MMA(0, 0, At, B0); PG8_BAR; PG8_SCHED;
;             PG8_LDB(B1, 0, 1); PG8_STAGEB(PG8_SB(0, 0), b2);
;             PG8_BAR; PG8_WAIT_L(0); PG8_MMA(0, 1, At, B1); PG8_BAR;
;             PG8_LDA(At, 0, 1); PG8_STAGE(PG8_SA(0, 0), a2);
;             PG8_BAR; PG8_WAIT_L(0); PG8_MMA(1, 0, At, B0); PG8_BAR; PG8_SCHED;
;             PG8_STAGEB(PG8_SB(0, 1), b2 + hstep);
;             PG8_WAIT_V(6); PG8_BAR; PG8_MMA(1, 1, At, B1); PG8_BAR;
;             PG8_LDB(B0, 1, 0); PG8_SCHED; PG8_LDA(At, 1, 0); PG8_STAGE(PG8_SA(0, 1), a2 + hstep);
;             PG8_WAIT_L(8); PG8_BAR; PG8_WAIT_L(0); PG8_MMA(0, 0, At, B0); PG8_BAR; PG8_SCHED;
;             PG8_LDB(B1, 1, 1); PG8_STAGEB(PG8_SB(1, 0), b3);
;             PG8_BAR; PG8_WAIT_L(0); PG8_MMA(0, 1, At, B1); PG8_BAR;
;             PG8_LDA(At, 1, 1); PG8_STAGE(PG8_SA(1, 0), a3);
;             PG8_BAR; PG8_WAIT_L(0); PG8_MMA(1, 0, At, B0); PG8_BAR; PG8_SCHED;
;             PG8_STAGEB(PG8_SB(1, 1), b3 + hstep);
;             PG8_WAIT_V(6); PG8_BAR; PG8_MMA(1, 1, At, B1); PG8_BAR;
	s_waitcnt lgkmcnt(0)
	s_setprio 1
	v_mfma_f32_16x16x32_bf16 v[104:107], v[226:229], v[132:135], v[104:107]
	v_mfma_f32_16x16x32_bf16 v[18:21], v[234:237], v[132:135], v[18:21]
	v_mfma_f32_16x16x32_bf16 v[22:25], v[226:229], v[176:179], v[22:25]
	v_mfma_f32_16x16x32_bf16 v[26:29], v[234:237], v[176:179], v[26:29]
	v_mfma_f32_16x16x32_bf16 v[30:33], v[226:229], v[210:213], v[30:33]
	v_mfma_f32_16x16x32_bf16 v[34:37], v[234:237], v[210:213], v[34:37]
	v_mfma_f32_16x16x32_bf16 v[38:41], v[226:229], v[218:221], v[38:41]
	v_mfma_f32_16x16x32_bf16 v[42:45], v[234:237], v[218:221], v[42:45]
	v_mfma_f32_16x16x32_bf16 v[104:107], v[230:233], v[136:139], v[104:107]
	v_mfma_f32_16x16x32_bf16 v[18:21], v[238:241], v[136:139], v[18:21]
	v_mfma_f32_16x16x32_bf16 v[22:25], v[230:233], v[206:209], v[22:25]
	v_mfma_f32_16x16x32_bf16 v[26:29], v[238:241], v[206:209], v[26:29]
	v_mfma_f32_16x16x32_bf16 v[30:33], v[230:233], v[214:217], v[30:33]
	v_mfma_f32_16x16x32_bf16 v[34:37], v[238:241], v[214:217], v[34:37]
	v_mfma_f32_16x16x32_bf16 v[38:41], v[230:233], v[222:225], v[38:41]
	v_mfma_f32_16x16x32_bf16 v[42:45], v[238:241], v[222:225], v[42:45]
	s_setprio 0
	s_mov_b32 m0, s51
	v_lshl_add_u64 v[182:183], s[20:21], 0, v[98:99]
	s_barrier
	ds_read_b128 v[132:135], v123 offset:16384
	ds_read_b128 v[136:139], v123 offset:17408
	ds_read_b128 v[176:179], v123 offset:18432
	ds_read_b128 v[206:209], v123 offset:19456
	ds_read_b128 v[210:213], v123 offset:20480
	ds_read_b128 v[214:217], v123 offset:21504
	ds_read_b128 v[218:221], v123 offset:22528
	ds_read_b128 v[222:225], v123 offset:23552
	global_load_lds_dwordx4 v[182:183], off
	v_lshl_add_u64 v[250:251], s[20:21], 0, v[100:101]
	s_mov_b32 m0, s86
	s_nop 0
	global_load_lds_dwordx4 v[250:251], off
	s_barrier
	s_waitcnt lgkmcnt(0)
	s_setprio 1
	v_mfma_f32_16x16x32_bf16 v[140:143], v[112:115], v[132:135], v[140:143]
	v_mfma_f32_16x16x32_bf16 v[156:159], v[124:127], v[132:135], v[156:159]
	v_mfma_f32_16x16x32_bf16 v[160:163], v[112:115], v[176:179], v[160:163]
	v_mfma_f32_16x16x32_bf16 v[164:167], v[124:127], v[176:179], v[164:167]
	v_mfma_f32_16x16x32_bf16 v[168:171], v[112:115], v[210:213], v[168:171]
	v_mfma_f32_16x16x32_bf16 v[172:175], v[124:127], v[210:213], v[172:175]
	v_mfma_f32_16x16x32_bf16 v[2:5], v[112:115], v[218:221], v[2:5]
	v_mfma_f32_16x16x32_bf16 v[6:9], v[124:127], v[218:221], v[6:9]
	v_mfma_f32_16x16x32_bf16 v[140:143], v[116:119], v[136:139], v[140:143]
	v_mfma_f32_16x16x32_bf16 v[156:159], v[128:131], v[136:139], v[156:159]
	v_mfma_f32_16x16x32_bf16 v[160:163], v[116:119], v[206:209], v[160:163]
	v_mfma_f32_16x16x32_bf16 v[164:167], v[128:131], v[206:209], v[164:167]
	v_mfma_f32_16x16x32_bf16 v[168:171], v[116:119], v[214:217], v[168:171]
	v_mfma_f32_16x16x32_bf16 v[172:175], v[128:131], v[214:217], v[172:175]
	v_mfma_f32_16x16x32_bf16 v[2:5], v[116:119], v[222:225], v[2:5]
	v_mfma_f32_16x16x32_bf16 v[112:115], v[128:131], v[222:225], v[6:9]
	s_setprio 0
	s_barrier
	s_add_u32 s0, vcc_lo, 0x10000
	s_addc_u32 s1, vcc_hi, 0
	s_mov_b32 m0, s93
	v_lshl_add_u64 v[6:7], s[0:1], 0, v[0:1]
	global_load_lds_dwordx4 v[6:7], off
	v_lshl_add_u64 v[6:7], s[0:1], 0, v[102:103]
	s_mov_b32 m0, s94
	s_nop 0
	global_load_lds_dwordx4 v[6:7], off
	s_waitcnt vmcnt(6)
	s_barrier
	s_setprio 1
	v_mfma_f32_16x16x32_bf16 v[6:9], v[226:229], v[132:135], v[10:13]
	v_mfma_f32_16x16x32_bf16 v[10:13], v[230:233], v[136:139], v[6:9]
	v_mfma_f32_16x16x32_bf16 v[6:9], v[234:237], v[132:135], v[14:17]
	v_mfma_f32_16x16x32_bf16 v[14:17], v[238:241], v[136:139], v[6:9]
	v_mfma_f32_16x16x32_bf16 v[6:9], v[226:229], v[176:179], v[46:49]
	v_mfma_f32_16x16x32_bf16 v[46:49], v[230:233], v[206:209], v[6:9]
	v_mfma_f32_16x16x32_bf16 v[6:9], v[234:237], v[176:179], v[90:93]
	v_mfma_f32_16x16x32_bf16 v[116:119], v[238:241], v[206:209], v[6:9]
	v_mfma_f32_16x16x32_bf16 v[6:9], v[226:229], v[210:213], v[94:97]
	v_mfma_f32_16x16x32_bf16 v[124:127], v[230:233], v[214:217], v[6:9]
	v_mfma_f32_16x16x32_bf16 v[6:9], v[234:237], v[210:213], v[108:111]
	v_mfma_f32_16x16x32_bf16 v[108:111], v[238:241], v[214:217], v[6:9]
	v_mfma_f32_16x16x32_bf16 v[6:9], v[226:229], v[218:221], v[82:85]
	v_mfma_f32_16x16x32_bf16 v[128:131], v[230:233], v[222:225], v[6:9]
	v_mfma_f32_16x16x32_bf16 v[6:9], v[234:237], v[218:221], v[86:89]
	v_mfma_f32_16x16x32_bf16 v[132:135], v[238:241], v[222:225], v[6:9]
	s_setprio 0
	s_barrier
	s_nop 4
	ds_read_b128 v[6:9], v154
	ds_read_b128 v[136:139], v154 offset:1024
	ds_read_b128 v[176:179], v154 offset:2048
	ds_read_b128 v[206:209], v154 offset:3072
	s_add_u32 s0, s20, 0x10000
	s_addc_u32 s1, s21, 0
	s_mov_b32 m0, s87
	v_lshl_add_u64 v[82:83], s[0:1], 0, v[98:99]
	ds_read_b128 v[90:93], v123 offset:32768
	ds_read_b128 v[94:97], v123 offset:33792
	ds_read_b128 v[210:213], v123 offset:34816
	ds_read_b128 v[214:217], v123 offset:35840
	ds_read_b128 v[218:221], v123 offset:36864
	ds_read_b128 v[222:225], v123 offset:37888
	ds_read_b128 v[226:229], v123 offset:38912
	ds_read_b128 v[230:233], v123 offset:39936
	global_load_lds_dwordx4 v[82:83], off
	v_lshl_add_u64 v[82:83], s[0:1], 0, v[100:101]
	s_mov_b32 m0, s88
	s_nop 0
	global_load_lds_dwordx4 v[82:83], off
	s_waitcnt lgkmcnt(8)
	s_barrier
; #define PG8_STAGE(bufoff, gbase) PG8_STAGE_(bufoff, gbase, voffA)
; #define PG8_STAGEB(bufoff, gbase) PG8_STAGE_(bufoff, gbase, voffB)
; #define PG8_LDA(dst, b, h) do { _Pragma("unroll") for (int m = 0; m < 4; ++m) _Pragma("unroll") for (int k = 0; k < 2; ++k) dst[m][k] = *(const LAS bf16x8*)(lds + PG8_SA(b, h) + aoff + m * 2048 + k * 1024); } while (0)
; #define PG8_LDB(dst, b, h) do { _Pragma("unroll") for (int n = 0; n < 2; ++n) _Pragma("unroll") for (int k = 0; k < 2; ++k) dst[n][k] = *(const LAS bf16x8*)(lds + PG8_SB(b, h) + boff + n * 2048 + k * 1024); } while (0)
; #define PG8_MMA(ai, bj, At, Bt) do { __builtin_amdgcn_s_setprio(1); _Pragma("unroll") for (int m = 0; m < 4; ++m) _Pragma("unroll") for (int n = 0; n < 2; ++n) _Pragma("unroll") for (int k = 0; k < 2; ++k) \
;         acc[ai][bj][m][n] = __builtin_amdgcn_mfma_f32_16x16x32_bf16(Bt[n][k], At[m][k], acc[ai][bj][m][n], 0, 0, 0); __builtin_amdgcn_s_setprio(0); } while (0)
; #define PG8_WAIT_V(n) asm volatile("s_waitcnt vmcnt(" #n ")" ::: "memory")
; #define PG8_WAIT_L(n) asm volatile("s_waitcnt lgkmcnt(" #n ")" ::: "memory")
; #define PG8_BAR __builtin_amdgcn_s_barrier()
; #define PG8_SCHED __builtin_amdgcn_sched_barrier(0)
; template <class Epi>
; __device__ __forceinline__ void gemm_phase(LAS unsigned char* lds, const Gemm g, const StaticOrder& S, const Epi& E) {
;     ...
;             PG8_WAIT_V(6); PG8_BAR; PG8_MMA(1, 1, At, B1); PG8_BAR;
;             PG8_LDB(B0, 1, 0); PG8_SCHED; PG8_LDA(At, 1, 0); PG8_STAGE(PG8_SA(0, 1), a2 + hstep);
;             PG8_WAIT_L(8); PG8_BAR; PG8_WAIT_L(0); PG8_MMA(0, 0, At, B0); PG8_BAR; PG8_SCHED;
;             PG8_LDB(B1, 1, 1); PG8_STAGEB(PG8_SB(1, 0), b3);
;             PG8_BAR; PG8_WAIT_L(0); PG8_MMA(0, 1, At, B1); PG8_BAR;
;             PG8_LDA(At, 1, 1); PG8_STAGE(PG8_SA(1, 0), a3);
;             PG8_BAR; PG8_WAIT_L(0); PG8_MMA(1, 0, At, B0); PG8_BAR; PG8_SCHED;
;             PG8_STAGEB(PG8_SB(1, 1), b3 + hstep);
;             PG8_WAIT_V(6); PG8_BAR; PG8_MMA(1, 1, At, B1); PG8_BAR;
	s_waitcnt lgkmcnt(0)
	s_setprio 1
	v_mfma_f32_16x16x32_bf16 v[50:53], v[6:9], v[90:93], v[50:53]
	v_mfma_f32_16x16x32_bf16 v[234:237], v[136:139], v[94:97], v[50:53]
	v_mfma_f32_16x16x32_bf16 v[50:53], v[176:179], v[90:93], v[54:57]
	v_mfma_f32_16x16x32_bf16 v[238:241], v[206:209], v[94:97], v[50:53]
	v_mfma_f32_16x16x32_bf16 v[50:53], v[6:9], v[210:213], v[58:61]
	v_mfma_f32_16x16x32_bf16 v[242:245], v[136:139], v[214:217], v[50:53]
	v_mfma_f32_16x16x32_bf16 v[50:53], v[176:179], v[210:213], v[62:65]
	v_mfma_f32_16x16x32_bf16 v[246:249], v[206:209], v[214:217], v[50:53]
	v_mfma_f32_16x16x32_bf16 v[50:53], v[6:9], v[218:221], v[66:69]
	v_mfma_f32_16x16x32_bf16 v[86:89], v[136:139], v[222:225], v[50:53]
	v_mfma_f32_16x16x32_bf16 v[50:53], v[176:179], v[218:221], v[70:73]
	v_mfma_f32_16x16x32_bf16 v[82:85], v[206:209], v[222:225], v[50:53]
	v_mfma_f32_16x16x32_bf16 v[50:53], v[6:9], v[226:229], v[74:77]
	v_mfma_f32_16x16x32_bf16 v[54:57], v[136:139], v[230:233], v[50:53]
	v_mfma_f32_16x16x32_bf16 v[50:53], v[176:179], v[226:229], v[78:81]
	v_mfma_f32_16x16x32_bf16 v[50:53], v[206:209], v[230:233], v[50:53]
	s_setprio 0
	s_barrier
	s_mov_b32 m0, s95
	v_lshl_add_u64 v[58:59], v[120:121], 0, s[16:17]
	ds_read_b128 v[200:203], v155
	ds_read_b128 v[144:147], v155 offset:1024
	ds_read_b128 v[148:151], v155 offset:2048
	ds_read_b128 v[152:155], v155 offset:3072
	global_load_lds_dwordx4 v[58:59], off
	v_lshl_add_u64 v[58:59], v[188:189], 0, s[16:17]
	s_mov_b32 m0, s96
	s_nop 0
	global_load_lds_dwordx4 v[58:59], off
	s_barrier
	s_waitcnt lgkmcnt(0)
	s_setprio 1
	v_mfma_f32_16x16x32_bf16 v[18:21], v[148:151], v[90:93], v[18:21]
	v_mfma_f32_16x16x32_bf16 v[196:199], v[152:155], v[94:97], v[18:21]
	v_mfma_f32_16x16x32_bf16 v[18:21], v[200:203], v[210:213], v[22:25]
	v_mfma_f32_16x16x32_bf16 v[188:191], v[144:147], v[214:217], v[18:21]
	v_mfma_f32_16x16x32_bf16 v[18:21], v[148:151], v[210:213], v[26:29]
	v_mfma_f32_16x16x32_bf16 v[58:61], v[200:203], v[90:93], v[104:107]
	v_mfma_f32_16x16x32_bf16 v[210:213], v[152:155], v[214:217], v[18:21]
	v_mfma_f32_16x16x32_bf16 v[18:21], v[200:203], v[218:221], v[30:33]
	v_mfma_f32_16x16x32_bf16 v[192:195], v[144:147], v[94:97], v[58:61]
	v_mfma_f32_16x16x32_bf16 v[94:97], v[144:147], v[222:225], v[18:21]
	v_mfma_f32_16x16x32_bf16 v[18:21], v[148:151], v[218:221], v[34:37]
	v_mfma_f32_16x16x32_bf16 v[90:93], v[152:155], v[222:225], v[18:21]
	v_mfma_f32_16x16x32_bf16 v[18:21], v[200:203], v[226:229], v[38:41]
	v_mfma_f32_16x16x32_bf16 v[62:65], v[144:147], v[230:233], v[18:21]
	v_mfma_f32_16x16x32_bf16 v[18:21], v[148:151], v[226:229], v[42:45]
	v_mfma_f32_16x16x32_bf16 v[58:61], v[152:155], v[230:233], v[18:21]
	s_setprio 0
	s_mov_b32 m0, s89
	s_nop 4
	v_lshl_add_u64 v[18:19], v[182:183], 0, s[16:17]
	s_barrier
	ds_read_b128 v[26:29], v123 offset:49152
	ds_read_b128 v[30:33], v123 offset:50176
	ds_read_b128 v[42:45], v123 offset:51200
	ds_read_b128 v[104:107], v123 offset:52224
	ds_read_b128 v[214:217], v123 offset:53248
	ds_read_b128 v[218:221], v123 offset:54272
	ds_read_b128 v[222:225], v123 offset:55296
	ds_read_b128 v[226:229], v123 offset:56320
	global_load_lds_dwordx4 v[18:19], off
	v_lshl_add_u64 v[18:19], v[250:251], 0, s[16:17]
	s_mov_b32 m0, s90
	s_nop 0
	global_load_lds_dwordx4 v[18:19], off
	s_barrier
	s_waitcnt lgkmcnt(0)
	s_setprio 1
	v_mfma_f32_16x16x32_bf16 v[18:21], v[6:9], v[26:29], v[140:143]
	v_mfma_f32_16x16x32_bf16 v[70:73], v[136:139], v[30:33], v[18:21]
	v_mfma_f32_16x16x32_bf16 v[18:21], v[176:179], v[26:29], v[156:159]
	v_mfma_f32_16x16x32_bf16 v[66:69], v[206:209], v[30:33], v[18:21]
	v_mfma_f32_16x16x32_bf16 v[18:21], v[6:9], v[42:45], v[160:163]
	v_mfma_f32_16x16x32_bf16 v[38:41], v[136:139], v[104:107], v[18:21]
	v_mfma_f32_16x16x32_bf16 v[18:21], v[176:179], v[42:45], v[164:167]
	v_mfma_f32_16x16x32_bf16 v[34:37], v[206:209], v[104:107], v[18:21]
	v_mfma_f32_16x16x32_bf16 v[18:21], v[6:9], v[214:217], v[168:171]
	v_mfma_f32_16x16x32_bf16 v[2:5], v[6:9], v[222:225], v[2:5]
	v_mfma_f32_16x16x32_bf16 v[22:25], v[136:139], v[218:221], v[18:21]
	v_mfma_f32_16x16x32_bf16 v[18:21], v[176:179], v[214:217], v[172:175]
	v_mfma_f32_16x16x32_bf16 v[6:9], v[136:139], v[226:229], v[2:5]
	v_mfma_f32_16x16x32_bf16 v[2:5], v[176:179], v[222:225], v[112:115]
	v_mfma_f32_16x16x32_bf16 v[18:21], v[206:209], v[218:221], v[18:21]
	v_mfma_f32_16x16x32_bf16 v[2:5], v[206:209], v[226:229], v[2:5]
	s_setprio 0
	s_barrier
	s_add_u32 s0, vcc_lo, 0x10080
	s_addc_u32 s1, vcc_hi, 0
	s_mov_b32 m0, s55
	v_lshl_add_u64 v[74:75], s[0:1], 0, v[0:1]
	global_load_lds_dwordx4 v[74:75], off
	v_lshl_add_u64 v[74:75], s[0:1], 0, v[102:103]
	s_mov_b32 m0, s54
	s_nop 0
	global_load_lds_dwordx4 v[74:75], off
	s_waitcnt vmcnt(6)
	s_barrier
	s_setprio 1
	v_mfma_f32_16x16x32_bf16 v[10:13], v[200:203], v[26:29], v[10:13]
	v_mfma_f32_16x16x32_bf16 v[78:81], v[144:147], v[30:33], v[10:13]
	v_mfma_f32_16x16x32_bf16 v[10:13], v[148:151], v[26:29], v[14:17]
	v_mfma_f32_16x16x32_bf16 v[74:77], v[152:155], v[30:33], v[10:13]
	v_mfma_f32_16x16x32_bf16 v[10:13], v[200:203], v[42:45], v[46:49]
	v_mfma_f32_16x16x32_bf16 v[46:49], v[144:147], v[104:107], v[10:13]
	v_mfma_f32_16x16x32_bf16 v[10:13], v[148:151], v[42:45], v[116:119]
	v_mfma_f32_16x16x32_bf16 v[42:45], v[152:155], v[104:107], v[10:13]
	v_mfma_f32_16x16x32_bf16 v[10:13], v[200:203], v[214:217], v[124:127]
	v_mfma_f32_16x16x32_bf16 v[30:33], v[144:147], v[218:221], v[10:13]
	v_mfma_f32_16x16x32_bf16 v[10:13], v[148:151], v[214:217], v[108:111]
	v_mfma_f32_16x16x32_bf16 v[26:29], v[152:155], v[218:221], v[10:13]
	v_mfma_f32_16x16x32_bf16 v[10:13], v[200:203], v[222:225], v[128:131]
	v_mfma_f32_16x16x32_bf16 v[14:17], v[144:147], v[226:229], v[10:13]
	v_mfma_f32_16x16x32_bf16 v[10:13], v[148:151], v[222:225], v[132:135]
	v_mfma_f32_16x16x32_bf16 v[10:13], v[152:155], v[226:229], v[10:13]
	s_setprio 0
	v_mov_b32_e32 v104, v186
	s_barrier
; __device__ __forceinline__ unsigned cvt_pk_bf16(float lo, float hi) { unsigned r; asm volatile("s_nop 0\n\tv_cvt_pk_bf16_f32 %0, %1, %2" : "=v"(r) : "v"(lo), "v"(hi)); return r; }
;     __device__ __forceinline__ void operator()(AccT& acc, const Unit& u, int wr, int wc, int fr, int fq) const {
;         int row0 = u.pm * 256 + wr * 64 + fr, cl = wc * 32 + 8 * fq;
;         asm volatile("" : "+v"(row0), "+v"(cl));
; #pragma unroll
;         for (int ai = 0; ai < 2; ++ai)
; #pragma unroll
;             for (int m = 0; m < 4; ++m) { const int row = row0 + ai * 128 + m * 16;
;                 { const f32x4 v0 = acc[ai][0][m][0], v1 = acc[ai][0][m][1];
;                   u32x4 w; w.x = cvt_pk_bf16(v0[0], v0[1]); w.y = cvt_pk_bf16(v0[2], v0[3]); w.z = cvt_pk_bf16(v1[0], v1[1]); w.w = cvt_pk_bf16(v1[2], v1[3]);
;                   *(u32x4*)(O + (size_t)row * 1024 + u.pn * 256 + cl) = w; }
; #pragma unroll
;                 for (int n = 0; n < 2; ++n) { const f32x4 v = acc[ai][1][m][n];
;                     const unsigned w0 = cvt_pk_bf16(v[0], v[1]), w1 = cvt_pk_bf16(v[2], v[3]);
;                     bf16_t* vp = VT + (size_t)(u.pn * 128 + cl + n * 4) * SEQ + row;
;                     vp[0] = (bf16_t)(w0 & 0xffffu); vp[SEQ] = (bf16_t)(w0 >> 16); vp[2 * SEQ] = (bf16_t)(w1 & 0xffffu); vp[3 * SEQ] = (bf16_t)(w1 >> 16); } }
	s_lshl_b32 s1, s50, 8
	v_readfirstlane_b32 s0, v104
	s_ashr_i32 s20, s0, 2
	s_andn2_b32 s20, s20, 63
	s_add_i32 s20, s20, s1
	s_lshr_b32 s0, s0, 1
	v_and_or_b32 v110, v104, 15, s20
	s_and_b32 s0, s0, 0x60
	v_lshrrev_b32_e32 v104, 1, v104
	v_and_or_b32 v104, v104, 24, s0
	s_lshl_b32 s0, s92, 8
	v_ashrrev_i32_e32 v111, 31, v110
	v_lshlrev_b64 v[114:115], 11, v[110:111]
	s_ashr_i32 s1, s0, 31
	v_lshl_add_u64 v[114:115], s[24:25], 0, v[114:115]
	v_ashrrev_i32_e32 v105, 31, v104
	v_lshl_add_u32 v112, s92, 7, v104
	v_lshl_add_u64 v[114:115], s[0:1], 1, v[114:115]
	s_nop 0
	v_cvt_pk_bf16_f32 v106, v234, v235
	s_nop 0
	v_cvt_pk_bf16_f32 v107, v236, v237
	v_lshl_add_u64 v[104:105], v[104:105], 1, v[114:115]
	v_ashrrev_i32_e32 v113, 31, v112
	s_nop 0
	v_cvt_pk_bf16_f32 v108, v238, v239
	s_nop 0
	v_cvt_pk_bf16_f32 v109, v240, v241
	global_store_dwordx4 v[104:105], v[106:109], off
	s_mov_b32 s21, 0x8000
	s_mov_b32 s0, 0xc000
	v_lshlrev_b64 v[106:107], 14, v[112:113]
	v_lshl_add_u64 v[106:107], s[6:7], 0, v[106:107]
	v_lshl_add_u64 v[106:107], v[110:111], 1, v[106:107]
	v_add_co_u32_e32 v108, vcc, s12, v106
	s_nop 0
	v_cvt_pk_bf16_f32 v114, v192, v193
	s_nop 0
	v_cvt_pk_bf16_f32 v115, v194, v195
	global_store_short v[106:107], v114, off
	s_nop 0
	v_addc_co_u32_e32 v109, vcc, 0, v107, vcc
	v_add_co_u32_e32 v110, vcc, s21, v106
	global_store_short_d16_hi v[108:109], v114, off
	s_nop 0
	v_addc_co_u32_e32 v111, vcc, 0, v107, vcc
	v_add_co_u32_e32 v112, vcc, s0, v106
	s_mov_b64 s[0:1], 0x10000
	s_nop 0
	v_addc_co_u32_e32 v113, vcc, 0, v107, vcc
	global_store_short v[110:111], v115, off
	global_store_short_d16_hi v[112:113], v115, off
	v_lshl_add_u64 v[114:115], v[106:107], 0, s[0:1]
	s_mov_b32 s1, 0x10000
	v_add_co_u32_e32 v116, vcc, s1, v106
	s_mov_b32 s0, 0x14000
	s_nop 0
	v_addc_co_u32_e32 v117, vcc, 0, v107, vcc
	s_nop 0
	v_cvt_pk_bf16_f32 v118, v196, v197
	s_nop 0
	v_cvt_pk_bf16_f32 v124, v198, v199
	global_store_short v[116:117], v118, off
	v_add_co_u32_e32 v116, vcc, s0, v106
	s_mov_b32 s20, 0x18000
	s_nop 0
	v_addc_co_u32_e32 v117, vcc, 0, v107, vcc
	global_store_short_d16_hi v[116:117], v118, off
	v_add_co_u32_e32 v118, vcc, s20, v106
	s_mov_b32 s0, 0x1c000
	s_nop 0
	v_addc_co_u32_e32 v119, vcc, 0, v107, vcc
	v_add_co_u32_e32 v120, vcc, s0, v106
	global_store_short v[118:119], v124, off
	s_nop 0
	v_addc_co_u32_e32 v121, vcc, 0, v107, vcc
	v_add_co_u32_e32 v128, vcc, s21, v104
	global_store_short_d16_hi v[120:121], v124, off
	s_nop 0
	v_cvt_pk_bf16_f32 v124, v242, v243
	s_nop 0
	v_addc_co_u32_e32 v129, vcc, 0, v105, vcc
	s_nop 0
	v_cvt_pk_bf16_f32 v125, v244, v245
	s_nop 0
	v_cvt_pk_bf16_f32 v126, v246, v247
	s_nop 0
	v_cvt_pk_bf16_f32 v127, v248, v249
	global_store_dwordx4 v[128:129], v[124:127], off
	s_mov_b32 s0, 0x40000
	s_mov_b64 s[96:97], s[18:19]
	s_nop 0
	v_cvt_pk_bf16_f32 v124, v188, v189
	s_nop 0
	v_cvt_pk_bf16_f32 v125, v190, v191
	global_store_short v[106:107], v124, off offset:32
	global_store_short_d16_hi v[108:109], v124, off offset:32
	global_store_short v[110:111], v125, off offset:32
	global_store_short_d16_hi v[112:113], v125, off offset:32
	s_nop 0
	v_cvt_pk_bf16_f32 v124, v210, v211
	s_nop 0
	v_cvt_pk_bf16_f32 v125, v212, v213
	global_store_short v[114:115], v124, off offset:32
	global_store_short_d16_hi v[116:117], v124, off offset:32
	global_store_short v[118:119], v125, off offset:32
	global_store_short_d16_hi v[120:121], v125, off offset:32
	s_nop 0
	v_cvt_pk_bf16_f32 v86, v86, v87
	s_nop 0
	v_cvt_pk_bf16_f32 v87, v88, v89
	s_nop 0
	v_cvt_pk_bf16_f32 v88, v82, v83
	v_add_co_u32_e32 v82, vcc, s1, v104
	s_nop 0
	v_cvt_pk_bf16_f32 v89, v84, v85
	v_readlane_b32 s18, v255, 37
	s_nop 0
	v_addc_co_u32_e32 v83, vcc, 0, v105, vcc
	global_store_dwordx4 v[82:83], v[86:89], off
	s_nop 0
	v_cvt_pk_bf16_f32 v82, v94, v95
	s_nop 0
	v_cvt_pk_bf16_f32 v83, v96, v97
	global_store_short v[106:107], v82, off offset:64
	global_store_short_d16_hi v[108:109], v82, off offset:64
	global_store_short v[110:111], v83, off offset:64
	global_store_short_d16_hi v[112:113], v83, off offset:64
	s_nop 0
	v_cvt_pk_bf16_f32 v82, v90, v91
	s_nop 0
	v_cvt_pk_bf16_f32 v83, v92, v93
	global_store_short v[114:115], v82, off offset:64
	global_store_short_d16_hi v[116:117], v82, off offset:64
	global_store_short v[118:119], v83, off offset:64
	global_store_short_d16_hi v[120:121], v83, off offset:64
	s_nop 0
	v_cvt_pk_bf16_f32 v54, v54, v55
	s_nop 0
	v_cvt_pk_bf16_f32 v55, v56, v57
	s_nop 0
	v_cvt_pk_bf16_f32 v56, v50, v51
	v_add_co_u32_e32 v50, vcc, s20, v104
	s_nop 0
	v_cvt_pk_bf16_f32 v57, v52, v53
	v_mov_b32_e32 v250, v186
	s_nop 0
	v_addc_co_u32_e32 v51, vcc, 0, v105, vcc
	global_store_dwordx4 v[50:51], v[54:57], off
	s_nop 0
	v_cvt_pk_bf16_f32 v50, v62, v63
	s_nop 0
	v_cvt_pk_bf16_f32 v51, v64, v65
	global_store_short v[106:107], v50, off offset:96
; __device__ __forceinline__ unsigned cvt_pk_bf16(float lo, float hi) { unsigned r; asm volatile("s_nop 0\n\tv_cvt_pk_bf16_f32 %0, %1, %2" : "=v"(r) : "v"(lo), "v"(hi)); return r; }
;     __device__ __forceinline__ void operator()(AccT& acc, const Unit& u, int wr, int wc, int fr, int fq) const {
;     ...
;         for (int ai = 0; ai < 2; ++ai)
; #pragma unroll
;             for (int m = 0; m < 4; ++m) { const int row = row0 + ai * 128 + m * 16;
;                 { const f32x4 v0 = acc[ai][0][m][0], v1 = acc[ai][0][m][1];
;                   u32x4 w; w.x = cvt_pk_bf16(v0[0], v0[1]); w.y = cvt_pk_bf16(v0[2], v0[3]); w.z = cvt_pk_bf16(v1[0], v1[1]); w.w = cvt_pk_bf16(v1[2], v1[3]);
;                   *(u32x4*)(O + (size_t)row * 1024 + u.pn * 256 + cl) = w; }
; #pragma unroll
;                 for (int n = 0; n < 2; ++n) { const f32x4 v = acc[ai][1][m][n];
;                     const unsigned w0 = cvt_pk_bf16(v[0], v[1]), w1 = cvt_pk_bf16(v[2], v[3]);
;                     bf16_t* vp = VT + (size_t)(u.pn * 128 + cl + n * 4) * SEQ + row;
;                     vp[0] = (bf16_t)(w0 & 0xffffu); vp[SEQ] = (bf16_t)(w0 >> 16); vp[2 * SEQ] = (bf16_t)(w1 & 0xffffu); vp[3 * SEQ] = (bf16_t)(w1 >> 16); } }
	global_store_short_d16_hi v[108:109], v50, off offset:96
	global_store_short v[110:111], v51, off offset:96
	global_store_short_d16_hi v[112:113], v51, off offset:96
	s_nop 0
	v_cvt_pk_bf16_f32 v50, v58, v59
	v_add_co_u32_e32 v54, vcc, s0, v104
	s_nop 0
	v_cvt_pk_bf16_f32 v51, v60, v61
	global_store_short v[114:115], v50, off offset:96
	global_store_short_d16_hi v[116:117], v50, off offset:96
	global_store_short v[118:119], v51, off offset:96
	global_store_short_d16_hi v[120:121], v51, off offset:96
	s_nop 0
	v_cvt_pk_bf16_f32 v50, v70, v71
	v_addc_co_u32_e32 v55, vcc, 0, v105, vcc
	s_nop 0
	v_cvt_pk_bf16_f32 v51, v72, v73
	s_nop 0
	v_cvt_pk_bf16_f32 v52, v66, v67
	s_nop 0
	v_cvt_pk_bf16_f32 v53, v68, v69
	global_store_dwordx4 v[54:55], v[50:53], off
	s_mov_b32 s0, 0x48000
	s_add_i32 s91, s91, s41
	s_nop 0
	v_cvt_pk_bf16_f32 v50, v78, v79
	s_nop 0
	v_cvt_pk_bf16_f32 v51, v80, v81
	global_store_short v[106:107], v50, off offset:256
	global_store_short_d16_hi v[108:109], v50, off offset:256
	global_store_short v[110:111], v51, off offset:256
	global_store_short_d16_hi v[112:113], v51, off offset:256
	s_nop 0
	v_cvt_pk_bf16_f32 v50, v74, v75
	s_nop 0
	v_cvt_pk_bf16_f32 v51, v76, v77
	global_store_short v[114:115], v50, off offset:256
	global_store_short_d16_hi v[116:117], v50, off offset:256
	global_store_short v[118:119], v51, off offset:256
	global_store_short_d16_hi v[120:121], v51, off offset:256
	s_nop 0
	v_cvt_pk_bf16_f32 v38, v38, v39
	s_nop 0
	v_cvt_pk_bf16_f32 v39, v40, v41
	s_nop 0
	v_cvt_pk_bf16_f32 v40, v34, v35
	v_add_co_u32_e32 v34, vcc, s0, v104
	s_nop 0
	v_cvt_pk_bf16_f32 v41, v36, v37
	s_mov_b32 s0, 0x50000
	s_nop 0
	v_addc_co_u32_e32 v35, vcc, 0, v105, vcc
	global_store_dwordx4 v[34:35], v[38:41], off
	s_nop 0
	v_cvt_pk_bf16_f32 v34, v46, v47
	s_nop 0
	v_cvt_pk_bf16_f32 v35, v48, v49
	global_store_short v[106:107], v34, off offset:288
	global_store_short_d16_hi v[108:109], v34, off offset:288
	global_store_short v[110:111], v35, off offset:288
	global_store_short_d16_hi v[112:113], v35, off offset:288
	s_nop 0
	v_cvt_pk_bf16_f32 v34, v42, v43
	s_nop 0
	v_cvt_pk_bf16_f32 v35, v44, v45
	global_store_short v[114:115], v34, off offset:288
	global_store_short_d16_hi v[116:117], v34, off offset:288
	global_store_short v[118:119], v35, off offset:288
	global_store_short_d16_hi v[120:121], v35, off offset:288
	s_nop 0
	v_cvt_pk_bf16_f32 v22, v22, v23
	s_nop 0
	v_cvt_pk_bf16_f32 v23, v24, v25
	s_nop 0
	v_cvt_pk_bf16_f32 v24, v18, v19
	v_add_co_u32_e32 v18, vcc, s0, v104
	s_nop 0
	v_cvt_pk_bf16_f32 v25, v20, v21
	s_mov_b32 s0, 0x58000
	s_nop 0
	v_addc_co_u32_e32 v19, vcc, 0, v105, vcc
	global_store_dwordx4 v[18:19], v[22:25], off
	s_nop 0
	v_cvt_pk_bf16_f32 v18, v30, v31
	s_nop 0
	v_cvt_pk_bf16_f32 v19, v32, v33
	global_store_short v[106:107], v18, off offset:320
	global_store_short_d16_hi v[108:109], v18, off offset:320
	global_store_short v[110:111], v19, off offset:320
	global_store_short_d16_hi v[112:113], v19, off offset:320
	s_nop 0
	v_cvt_pk_bf16_f32 v18, v26, v27
	s_nop 0
	v_cvt_pk_bf16_f32 v19, v28, v29
	global_store_short v[114:115], v18, off offset:320
	global_store_short_d16_hi v[116:117], v18, off offset:320
	global_store_short v[118:119], v19, off offset:320
	global_store_short_d16_hi v[120:121], v19, off offset:320
	s_nop 0
	v_cvt_pk_bf16_f32 v6, v6, v7
	s_nop 0
	v_cvt_pk_bf16_f32 v7, v8, v9
	s_nop 0
	v_cvt_pk_bf16_f32 v8, v2, v3
	v_add_co_u32_e32 v2, vcc, s0, v104
	s_nop 0
	v_cvt_pk_bf16_f32 v9, v4, v5
	s_mov_b32 s92, s44
	s_nop 0
	v_addc_co_u32_e32 v3, vcc, 0, v105, vcc
	global_store_dwordx4 v[2:3], v[6:9], off
	s_nop 0
	v_cvt_pk_bf16_f32 v2, v14, v15
	s_nop 0
	v_cvt_pk_bf16_f32 v3, v16, v17
	global_store_short v[106:107], v2, off offset:352
	global_store_short_d16_hi v[108:109], v2, off offset:352
	global_store_short v[110:111], v3, off offset:352
	global_store_short_d16_hi v[112:113], v3, off offset:352
	s_nop 0
	v_cvt_pk_bf16_f32 v2, v10, v11
	s_andn2_b64 vcc, exec, s[42:43]
	s_mov_b32 s50, s46
	s_mov_b64 s[54:55], s[30:31]
	s_mov_b64 s[52:53], s[48:49]
	s_mov_b64 s[94:95], s[22:23]
	v_readlane_b32 s19, v255, 38
	s_mov_b32 s22, s79
	s_mov_b32 s79, s69
	s_mov_b32 s69, s65
	s_mov_b32 s65, s4
	v_mov_b32_e32 v242, 0x358637bd
	v_mov_b32_e32 v244, 0x3c0881c4
	v_mov_b32_e32 v186, 0xbab64f3b
	v_mov_b32_e32 v243, v184
	v_mov_b32_e32 v245, v204
	v_mov_b32_e32 v204, v181
	v_mov_b32_e32 v181, v180
	v_mov_b32_e32 v180, 0x7f800000
	v_not_b32_e32 v246, 63
	v_not_b32_e32 v247, 31
	v_mov_b32_e32 v248, 0x7fc00000
	v_mov_b32_e32 v249, 0x41b17218
	v_mov_b32_e32 v251, 0x42800000
	s_nop 0
	v_cvt_pk_bf16_f32 v3, v12, v13
	global_store_short v[114:115], v2, off offset:352
	global_store_short_d16_hi v[116:117], v2, off offset:352
	global_store_short v[118:119], v3, off offset:352
	global_store_short_d16_hi v[120:121], v3, off offset:352
	s_cbranch_vccz .LBB0_982

; #define PG8_STAGE(bufoff, gbase) PG8_STAGE_(bufoff, gbase, voffA)
; #define PG8_STAGEB(bufoff, gbase) PG8_STAGE_(bufoff, gbase, voffB)
; #define PG8_LDA(dst, b, h) do { _Pragma("unroll") for (int m = 0; m < 4; ++m) _Pragma("unroll") for (int k = 0; k < 2; ++k) dst[m][k] = *(const LAS bf16x8*)(lds + PG8_SA(b, h) + aoff + m * 2048 + k * 1024); } while (0)
; #define PG8_LDB(dst, b, h) do { _Pragma("unroll") for (int n = 0; n < 2; ++n) _Pragma("unroll") for (int k = 0; k < 2; ++k) dst[n][k] = *(const LAS bf16x8*)(lds + PG8_SB(b, h) + boff + n * 2048 + k * 1024); } while (0)
; #define PG8_MMA(ai, bj, At, Bt) do { __builtin_amdgcn_s_setprio(1); _Pragma("unroll") for (int m = 0; m < 4; ++m) _Pragma("unroll") for (int n = 0; n < 2; ++n) _Pragma("unroll") for (int k = 0; k < 2; ++k) \
;         acc[ai][bj][m][n] = __builtin_amdgcn_mfma_f32_16x16x32_bf16(Bt[n][k], At[m][k], acc[ai][bj][m][n], 0, 0, 0); __builtin_amdgcn_s_setprio(0); } while (0)
; #define PG8_WAIT_V(n) asm volatile("s_waitcnt vmcnt(" #n ")" ::: "memory")
; #define PG8_WAIT_L(n) asm volatile("s_waitcnt lgkmcnt(" #n ")" ::: "memory")
; #define PG8_BAR __builtin_amdgcn_s_barrier()
; #define PG8_SCHED __builtin_amdgcn_sched_barrier(0)
; template <class Epi>
; __device__ __forceinline__ void gemm_phase(LAS unsigned char* lds, const Gemm g, const StaticOrder& S, const Epi& E) {
;     ...
;             PG8_LDB(B0, 0, 0); PG8_SCHED; PG8_LDA(At, 0, 0); PG8_STAGE(PG8_SA(1, 1), a1 + hstep);
;             PG8_WAIT_L(8); PG8_BAR; PG8_WAIT_L(0); PG8_MMA(0, 0, At, B0); PG8_BAR; PG8_SCHED;
;             PG8_LDB(B1, 0, 1); PG8_STAGEB(PG8_SB(0, 0), b2);
;             PG8_BAR; PG8_WAIT_L(0); PG8_MMA(0, 1, At, B1); PG8_BAR;
;             PG8_LDA(At, 0, 1); PG8_STAGE(PG8_SA(0, 0), a2);
;             PG8_BAR; PG8_WAIT_L(0); PG8_MMA(1, 0, At, B0); PG8_BAR; PG8_SCHED;
;             PG8_STAGEB(PG8_SB(0, 1), b2 + hstep);
;             PG8_WAIT_V(6); PG8_BAR; PG8_MMA(1, 1, At, B1); PG8_BAR;
;             PG8_LDB(B0, 1, 0); PG8_SCHED; PG8_LDA(At, 1, 0); PG8_STAGE(PG8_SA(0, 1), a2 + hstep);
;             PG8_WAIT_L(8); PG8_BAR; PG8_WAIT_L(0); PG8_MMA(0, 0, At, B0); PG8_BAR; PG8_SCHED;
.LBB0_1302:
	s_add_u32 s20, s6, 0xfffe0080
	s_addc_u32 s21, s7, -1
	s_add_i32 s58, 0, 0x10000
	v_add_u32_e32 v142, s58, v206
	ds_read_b128 v[130:133], v142
	ds_read_b128 v[134:137], v142 offset:1024
	ds_read_b128 v[138:141], v142 offset:2048
	ds_read_b128 v[142:145], v142 offset:3072
	s_cmp_eq_u32 s89, 4
	s_cselect_b32 s25, s30, s21
	s_cselect_b32 s24, s31, s20
	s_cselect_b32 s21, s53, s88
	s_cselect_b32 s20, s55, s87
	v_lshl_add_u64 v[154:155], s[6:7], 0, v[162:163]
	s_add_i32 m0, s43, 0xc000
	ds_read_b128 v[146:149], v207
	ds_read_b128 v[150:153], v207 offset:1024
	ds_read_b128 v[166:169], v207 offset:2048
	ds_read_b128 v[170:173], v207 offset:3072
	ds_read_b128 v[174:177], v207 offset:4096
	ds_read_b128 v[188:191], v207 offset:5120
	ds_read_b128 v[192:195], v207 offset:6144
	ds_read_b128 v[196:199], v207 offset:7168
	global_load_lds_dwordx4 v[154:155], off
	v_lshl_add_u64 v[154:155], s[6:7], 0, v[164:165]
	s_add_i32 m0, s43, 0xe000
	s_nop 0
	global_load_lds_dwordx4 v[154:155], off
	s_waitcnt lgkmcnt(8)
	s_barrier
	s_waitcnt lgkmcnt(0)
	s_setprio 1
	v_mfma_f32_16x16x32_bf16 v[126:129], v[130:133], v[146:149], v[126:129]
	v_mfma_f32_16x16x32_bf16 v[122:125], v[138:141], v[146:149], v[122:125]
	v_mfma_f32_16x16x32_bf16 v[110:113], v[130:133], v[166:169], v[110:113]
	v_mfma_f32_16x16x32_bf16 v[106:109], v[138:141], v[166:169], v[106:109]
	v_mfma_f32_16x16x32_bf16 v[94:97], v[130:133], v[174:177], v[94:97]
	v_mfma_f32_16x16x32_bf16 v[90:93], v[138:141], v[174:177], v[90:93]
	v_mfma_f32_16x16x32_bf16 v[78:81], v[130:133], v[192:195], v[78:81]
	v_mfma_f32_16x16x32_bf16 v[74:77], v[138:141], v[192:195], v[74:77]
	v_mfma_f32_16x16x32_bf16 v[126:129], v[134:137], v[150:153], v[126:129]
	v_mfma_f32_16x16x32_bf16 v[122:125], v[142:145], v[150:153], v[122:125]
	v_mfma_f32_16x16x32_bf16 v[110:113], v[134:137], v[170:173], v[110:113]
	v_mfma_f32_16x16x32_bf16 v[106:109], v[142:145], v[170:173], v[106:109]
	v_mfma_f32_16x16x32_bf16 v[94:97], v[134:137], v[188:191], v[94:97]
	v_mfma_f32_16x16x32_bf16 v[90:93], v[142:145], v[188:191], v[90:93]
	v_mfma_f32_16x16x32_bf16 v[78:81], v[134:137], v[196:199], v[78:81]
	v_mfma_f32_16x16x32_bf16 v[74:77], v[142:145], v[196:199], v[74:77]
	s_setprio 0
	s_barrier
	s_add_i32 s90, 0, 0x14000
	v_add_u32_e32 v154, s90, v206
	s_add_i32 s58, s58, s42
	ds_read_b128 v[200:203], v154
	ds_read_b128 v[208:211], v154 offset:1024
	ds_read_b128 v[212:215], v154 offset:2048
	ds_read_b128 v[216:219], v154 offset:3072
	v_lshl_add_u64 v[154:155], s[20:21], 0, v[0:1]
	s_mov_b32 m0, s58
	v_lshl_add_u64 v[178:179], s[20:21], 0, v[156:157]
	global_load_lds_dwordx4 v[154:155], off
	s_add_i32 m0, s58, 0x2000
	s_nop 0
	global_load_lds_dwordx4 v[178:179], off
	s_barrier
	s_waitcnt lgkmcnt(0)
	s_setprio 1
	v_mfma_f32_16x16x32_bf16 v[118:121], v[200:203], v[146:149], v[118:121]
	v_mfma_f32_16x16x32_bf16 v[114:117], v[212:215], v[146:149], v[114:117]
	v_mfma_f32_16x16x32_bf16 v[102:105], v[200:203], v[166:169], v[102:105]
	v_mfma_f32_16x16x32_bf16 v[98:101], v[212:215], v[166:169], v[98:101]
	v_mfma_f32_16x16x32_bf16 v[86:89], v[200:203], v[174:177], v[86:89]
	v_mfma_f32_16x16x32_bf16 v[82:85], v[212:215], v[174:177], v[82:85]
	v_mfma_f32_16x16x32_bf16 v[70:73], v[200:203], v[192:195], v[70:73]
	v_mfma_f32_16x16x32_bf16 v[66:69], v[212:215], v[192:195], v[66:69]
	v_mfma_f32_16x16x32_bf16 v[118:121], v[208:211], v[150:153], v[118:121]
	v_mfma_f32_16x16x32_bf16 v[114:117], v[216:219], v[150:153], v[114:117]
	v_mfma_f32_16x16x32_bf16 v[102:105], v[208:211], v[170:173], v[102:105]
	v_mfma_f32_16x16x32_bf16 v[98:101], v[216:219], v[170:173], v[98:101]
	v_mfma_f32_16x16x32_bf16 v[86:89], v[208:211], v[188:191], v[86:89]
	v_mfma_f32_16x16x32_bf16 v[82:85], v[216:219], v[188:191], v[82:85]
	v_mfma_f32_16x16x32_bf16 v[70:73], v[208:211], v[196:199], v[70:73]
	v_mfma_f32_16x16x32_bf16 v[66:69], v[216:219], v[196:199], v[66:69]
	s_setprio 0
	s_mov_b32 m0, s43
	v_lshl_add_u64 v[182:183], s[24:25], 0, v[160:161]
	s_barrier
	ds_read_b128 v[146:149], v207 offset:16384
	ds_read_b128 v[150:153], v207 offset:17408
	ds_read_b128 v[166:169], v207 offset:18432
	ds_read_b128 v[170:173], v207 offset:19456
	ds_read_b128 v[174:177], v207 offset:20480
	ds_read_b128 v[188:191], v207 offset:21504
	ds_read_b128 v[192:195], v207 offset:22528
	ds_read_b128 v[196:199], v207 offset:23552
	global_load_lds_dwordx4 v[182:183], off
	v_lshl_add_u64 v[220:221], s[24:25], 0, v[158:159]
	s_mov_b32 m0, s80
	s_nop 0
	global_load_lds_dwordx4 v[220:221], off
	s_barrier
	s_waitcnt lgkmcnt(0)
	s_setprio 1
	v_mfma_f32_16x16x32_bf16 v[62:65], v[130:133], v[146:149], v[62:65]
	v_mfma_f32_16x16x32_bf16 v[58:61], v[138:141], v[146:149], v[58:61]
	v_mfma_f32_16x16x32_bf16 v[46:49], v[130:133], v[166:169], v[46:49]
	v_mfma_f32_16x16x32_bf16 v[42:45], v[138:141], v[166:169], v[42:45]
	v_mfma_f32_16x16x32_bf16 v[30:33], v[130:133], v[174:177], v[30:33]
	v_mfma_f32_16x16x32_bf16 v[26:29], v[138:141], v[174:177], v[26:29]
	v_mfma_f32_16x16x32_bf16 v[14:17], v[130:133], v[192:195], v[14:17]
	v_mfma_f32_16x16x32_bf16 v[10:13], v[138:141], v[192:195], v[10:13]
	v_mfma_f32_16x16x32_bf16 v[62:65], v[134:137], v[150:153], v[62:65]
	v_mfma_f32_16x16x32_bf16 v[58:61], v[142:145], v[150:153], v[58:61]
	v_mfma_f32_16x16x32_bf16 v[46:49], v[134:137], v[170:173], v[46:49]
	v_mfma_f32_16x16x32_bf16 v[42:45], v[142:145], v[170:173], v[42:45]
	v_mfma_f32_16x16x32_bf16 v[30:33], v[134:137], v[188:191], v[30:33]
	v_mfma_f32_16x16x32_bf16 v[26:29], v[142:145], v[188:191], v[26:29]
	v_mfma_f32_16x16x32_bf16 v[14:17], v[134:137], v[196:199], v[14:17]
	v_mfma_f32_16x16x32_bf16 v[10:13], v[142:145], v[196:199], v[10:13]
	s_setprio 0
	s_barrier
; #define PG8_STAGE(bufoff, gbase) PG8_STAGE_(bufoff, gbase, voffA)
; #define PG8_STAGEB(bufoff, gbase) PG8_STAGE_(bufoff, gbase, voffB)
; #define PG8_LDA(dst, b, h) do { _Pragma("unroll") for (int m = 0; m < 4; ++m) _Pragma("unroll") for (int k = 0; k < 2; ++k) dst[m][k] = *(const LAS bf16x8*)(lds + PG8_SA(b, h) + aoff + m * 2048 + k * 1024); } while (0)
; #define PG8_LDB(dst, b, h) do { _Pragma("unroll") for (int n = 0; n < 2; ++n) _Pragma("unroll") for (int k = 0; k < 2; ++k) dst[n][k] = *(const LAS bf16x8*)(lds + PG8_SB(b, h) + boff + n * 2048 + k * 1024); } while (0)
; #define PG8_MMA(ai, bj, At, Bt) do { __builtin_amdgcn_s_setprio(1); _Pragma("unroll") for (int m = 0; m < 4; ++m) _Pragma("unroll") for (int n = 0; n < 2; ++n) _Pragma("unroll") for (int k = 0; k < 2; ++k) \
;         acc[ai][bj][m][n] = __builtin_amdgcn_mfma_f32_16x16x32_bf16(Bt[n][k], At[m][k], acc[ai][bj][m][n], 0, 0, 0); __builtin_amdgcn_s_setprio(0); } while (0)
; #define PG8_WAIT_V(n) asm volatile("s_waitcnt vmcnt(" #n ")" ::: "memory")
; #define PG8_WAIT_L(n) asm volatile("s_waitcnt lgkmcnt(" #n ")" ::: "memory")
; #define PG8_BAR __builtin_amdgcn_s_barrier()
; #define PG8_SCHED __builtin_amdgcn_sched_barrier(0)
; template <class Epi>
; __device__ __forceinline__ void gemm_phase(LAS unsigned char* lds, const Gemm g, const StaticOrder& S, const Epi& E) {
;     ...
;             PG8_STAGEB(PG8_SB(0, 1), b2 + hstep);
;             PG8_WAIT_V(6); PG8_BAR; PG8_MMA(1, 1, At, B1); PG8_BAR;
;             PG8_LDB(B0, 1, 0); PG8_SCHED; PG8_LDA(At, 1, 0); PG8_STAGE(PG8_SA(0, 1), a2 + hstep);
;             PG8_WAIT_L(8); PG8_BAR; PG8_WAIT_L(0); PG8_MMA(0, 0, At, B0); PG8_BAR; PG8_SCHED;
;             PG8_LDB(B1, 1, 1); PG8_STAGEB(PG8_SB(1, 0), b3);
;             PG8_BAR; PG8_WAIT_L(0); PG8_MMA(0, 1, At, B1); PG8_BAR;
;             PG8_LDA(At, 1, 1); PG8_STAGE(PG8_SA(1, 0), a3);
;             PG8_BAR; PG8_WAIT_L(0); PG8_MMA(1, 0, At, B0); PG8_BAR; PG8_SCHED;
	s_add_u32 s58, s20, 0x20000
	s_addc_u32 s59, s21, 0
	s_add_i32 s90, s90, s42
	v_lshl_add_u64 v[130:131], s[58:59], 0, v[0:1]
	s_mov_b32 m0, s90
	s_nop 0
	global_load_lds_dwordx4 v[130:131], off
	v_lshl_add_u64 v[130:131], s[58:59], 0, v[156:157]
	s_add_i32 m0, s90, 0x2000
	s_nop 0
	global_load_lds_dwordx4 v[130:131], off
	s_waitcnt vmcnt(6)
	s_barrier
	s_setprio 1
	v_mfma_f32_16x16x32_bf16 v[54:57], v[200:203], v[146:149], v[54:57]
	v_mfma_f32_16x16x32_bf16 v[50:53], v[212:215], v[146:149], v[50:53]
	v_mfma_f32_16x16x32_bf16 v[38:41], v[200:203], v[166:169], v[38:41]
	v_mfma_f32_16x16x32_bf16 v[34:37], v[212:215], v[166:169], v[34:37]
	v_mfma_f32_16x16x32_bf16 v[22:25], v[200:203], v[174:177], v[22:25]
	v_mfma_f32_16x16x32_bf16 v[18:21], v[212:215], v[174:177], v[18:21]
	v_mfma_f32_16x16x32_bf16 v[6:9], v[200:203], v[192:195], v[6:9]
	v_mfma_f32_16x16x32_bf16 v[2:5], v[212:215], v[192:195], v[2:5]
	v_mfma_f32_16x16x32_bf16 v[54:57], v[208:211], v[150:153], v[54:57]
	v_mfma_f32_16x16x32_bf16 v[50:53], v[216:219], v[150:153], v[50:53]
	v_mfma_f32_16x16x32_bf16 v[38:41], v[208:211], v[170:173], v[38:41]
	v_mfma_f32_16x16x32_bf16 v[34:37], v[216:219], v[170:173], v[34:37]
	v_mfma_f32_16x16x32_bf16 v[22:25], v[208:211], v[188:191], v[22:25]
	v_mfma_f32_16x16x32_bf16 v[18:21], v[216:219], v[188:191], v[18:21]
	v_mfma_f32_16x16x32_bf16 v[6:9], v[208:211], v[196:199], v[6:9]
	v_mfma_f32_16x16x32_bf16 v[2:5], v[216:219], v[196:199], v[2:5]
	s_setprio 0
	s_add_i32 s58, 0, 0x18000
	v_add_u32_e32 v142, s58, v206
	s_barrier
	ds_read_b128 v[130:133], v142
	ds_read_b128 v[134:137], v142 offset:1024
	ds_read_b128 v[138:141], v142 offset:2048
	ds_read_b128 v[142:145], v142 offset:3072
	s_add_u32 s24, s24, 0x20000
	s_addc_u32 s25, s25, 0
	s_mov_b32 m0, s81
	v_lshl_add_u64 v[200:201], s[24:25], 0, v[160:161]
	ds_read_b128 v[146:149], v207 offset:32768
	ds_read_b128 v[150:153], v207 offset:33792
	ds_read_b128 v[166:169], v207 offset:34816
	ds_read_b128 v[170:173], v207 offset:35840
	ds_read_b128 v[174:177], v207 offset:36864
	ds_read_b128 v[188:191], v207 offset:37888
	ds_read_b128 v[192:195], v207 offset:38912
	ds_read_b128 v[196:199], v207 offset:39936
	global_load_lds_dwordx4 v[200:201], off
	v_lshl_add_u64 v[200:201], s[24:25], 0, v[158:159]
	s_mov_b32 m0, s34
	s_nop 0
	global_load_lds_dwordx4 v[200:201], off
	s_waitcnt lgkmcnt(8)
	s_barrier
	s_waitcnt lgkmcnt(0)
	s_setprio 1
	v_mfma_f32_16x16x32_bf16 v[126:129], v[130:133], v[146:149], v[126:129]
	v_mfma_f32_16x16x32_bf16 v[122:125], v[138:141], v[146:149], v[122:125]
	v_mfma_f32_16x16x32_bf16 v[110:113], v[130:133], v[166:169], v[110:113]
	v_mfma_f32_16x16x32_bf16 v[106:109], v[138:141], v[166:169], v[106:109]
	v_mfma_f32_16x16x32_bf16 v[94:97], v[130:133], v[174:177], v[94:97]
	v_mfma_f32_16x16x32_bf16 v[90:93], v[138:141], v[174:177], v[90:93]
	v_mfma_f32_16x16x32_bf16 v[78:81], v[130:133], v[192:195], v[78:81]
	v_mfma_f32_16x16x32_bf16 v[74:77], v[138:141], v[192:195], v[74:77]
	v_mfma_f32_16x16x32_bf16 v[126:129], v[134:137], v[150:153], v[126:129]
	v_mfma_f32_16x16x32_bf16 v[122:125], v[142:145], v[150:153], v[122:125]
	v_mfma_f32_16x16x32_bf16 v[110:113], v[134:137], v[170:173], v[110:113]
	v_mfma_f32_16x16x32_bf16 v[106:109], v[142:145], v[170:173], v[106:109]
	v_mfma_f32_16x16x32_bf16 v[94:97], v[134:137], v[188:191], v[94:97]
	v_mfma_f32_16x16x32_bf16 v[90:93], v[142:145], v[188:191], v[90:93]
	v_mfma_f32_16x16x32_bf16 v[78:81], v[134:137], v[196:199], v[78:81]
	v_mfma_f32_16x16x32_bf16 v[74:77], v[142:145], v[196:199], v[74:77]
	s_setprio 0
	s_barrier
	s_add_i32 s24, 0, 0x1c000
	s_add_i32 s25, s58, s42
	v_add_u32_e32 v216, s24, v206
	v_lshl_add_u64 v[154:155], v[154:155], 0, s[16:17]
	s_mov_b32 m0, s25
	ds_read_b128 v[200:203], v216
	ds_read_b128 v[208:211], v216 offset:1024
	ds_read_b128 v[212:215], v216 offset:2048
	ds_read_b128 v[216:219], v216 offset:3072
	global_load_lds_dwordx4 v[154:155], off
	v_lshl_add_u64 v[154:155], v[178:179], 0, s[16:17]
	s_add_i32 m0, s25, 0x2000
	s_nop 0
	global_load_lds_dwordx4 v[154:155], off
	s_barrier
	s_waitcnt lgkmcnt(0)
	s_setprio 1
	v_mfma_f32_16x16x32_bf16 v[118:121], v[200:203], v[146:149], v[118:121]
	v_mfma_f32_16x16x32_bf16 v[114:117], v[212:215], v[146:149], v[114:117]
	v_mfma_f32_16x16x32_bf16 v[102:105], v[200:203], v[166:169], v[102:105]
	v_mfma_f32_16x16x32_bf16 v[98:101], v[212:215], v[166:169], v[98:101]
	v_mfma_f32_16x16x32_bf16 v[86:89], v[200:203], v[174:177], v[86:89]
	v_mfma_f32_16x16x32_bf16 v[82:85], v[212:215], v[174:177], v[82:85]
	v_mfma_f32_16x16x32_bf16 v[70:73], v[200:203], v[192:195], v[70:73]
	v_mfma_f32_16x16x32_bf16 v[66:69], v[212:215], v[192:195], v[66:69]
	v_mfma_f32_16x16x32_bf16 v[118:121], v[208:211], v[150:153], v[118:121]
	v_mfma_f32_16x16x32_bf16 v[114:117], v[216:219], v[150:153], v[114:117]
	v_mfma_f32_16x16x32_bf16 v[102:105], v[208:211], v[170:173], v[102:105]
	v_mfma_f32_16x16x32_bf16 v[98:101], v[216:219], v[170:173], v[98:101]
	v_mfma_f32_16x16x32_bf16 v[86:89], v[208:211], v[188:191], v[86:89]
	v_mfma_f32_16x16x32_bf16 v[82:85], v[216:219], v[188:191], v[82:85]
	v_mfma_f32_16x16x32_bf16 v[70:73], v[208:211], v[196:199], v[70:73]
	v_mfma_f32_16x16x32_bf16 v[66:69], v[216:219], v[196:199], v[66:69]
	s_setprio 0
	s_mov_b32 m0, s82
	v_lshl_add_u64 v[154:155], v[182:183], 0, s[16:17]
	s_barrier
	ds_read_b128 v[146:149], v207 offset:49152
	ds_read_b128 v[150:153], v207 offset:50176
	ds_read_b128 v[166:169], v207 offset:51200
	ds_read_b128 v[170:173], v207 offset:52224
	ds_read_b128 v[174:177], v207 offset:53248
	ds_read_b128 v[188:191], v207 offset:54272
	ds_read_b128 v[192:195], v207 offset:55296
	ds_read_b128 v[196:199], v207 offset:56320
	global_load_lds_dwordx4 v[154:155], off
	v_lshl_add_u64 v[154:155], v[220:221], 0, s[16:17]
	s_mov_b32 m0, s83
	s_nop 0
	global_load_lds_dwordx4 v[154:155], off
	s_barrier
; __device__ __forceinline__ float sigmoidf_(float x) { return __builtin_amdgcn_rcpf(1.f + __expf(-x)); }
; __device__ __forceinline__ float siluf_(float x) { return x * sigmoidf_(x); }
; #define PG8_STAGEB(bufoff, gbase) PG8_STAGE_(bufoff, gbase, voffB)
; #define PG8_MMA(ai, bj, At, Bt) do { __builtin_amdgcn_s_setprio(1); _Pragma("unroll") for (int m = 0; m < 4; ++m) _Pragma("unroll") for (int n = 0; n < 2; ++n) _Pragma("unroll") for (int k = 0; k < 2; ++k) \
;         acc[ai][bj][m][n] = __builtin_amdgcn_mfma_f32_16x16x32_bf16(Bt[n][k], At[m][k], acc[ai][bj][m][n], 0, 0, 0); __builtin_amdgcn_s_setprio(0); } while (0)
; #define PG8_WAIT_V(n) asm volatile("s_waitcnt vmcnt(" #n ")" ::: "memory")
; #define PG8_WAIT_L(n) asm volatile("s_waitcnt lgkmcnt(" #n ")" ::: "memory")
; #define PG8_BAR __builtin_amdgcn_s_barrier()
; #define PG8_SCHED __builtin_amdgcn_sched_barrier(0)
; template <class Epi>
; __device__ __forceinline__ void gemm_phase(LAS unsigned char* lds, const Gemm g, const StaticOrder& S, const Epi& E) {
;     ...
;             PG8_BAR; PG8_WAIT_L(0); PG8_MMA(1, 0, At, B0); PG8_BAR; PG8_SCHED;
;             PG8_STAGEB(PG8_SB(1, 1), b3 + hstep);
;             PG8_WAIT_V(6); PG8_BAR; PG8_MMA(1, 1, At, B1); PG8_BAR;
;     __device__ __forceinline__ void operator()(AccT& acc, const Unit& u, int wr, int wc, int fr, int fq) const {
;         int row0 = u.pm * 256 + wr * 64 + fr, col0 = u.pn * 256 + wc * 32 + 8 * fq;
;         asm volatile("" : "+v"(row0), "+v"(col0));
; #pragma unroll
;         for (int ai = 0; ai < 2; ++ai)
; #pragma unroll
;             for (int m = 0; m < 4; ++m) { const size_t row = (size_t)(row0 + ai * 128 + m * 16);
; #pragma unroll
;                 for (int bj = 0; bj < 2; ++bj) { const int c = col0 + bj * 128;
;                     float y8[8], z8[8], o8[8]; ld8(yd + row * 512 + c, y8); ld8(proj + row * NP + O_DZ + c, z8);
;                     const f32x4 b0 = *(const f32x4*)(gb + c), b1 = *(const f32x4*)(gb + c + 4);
; #pragma unroll
;                     for (int e = 0; e < 4; ++e) { o8[e] = y8[e] * sigmoidf_(acc[ai][bj][m][0][e] + b0[e]) * siluf_(z8[e]); o8[4 + e] = y8[4 + e] * sigmoidf_(acc[ai][bj][m][1][e] + b1[e]) * siluf_(z8[4 + e]); }
;                     st8(ys + row * DM + 1536 + c, o8); } }
	s_waitcnt lgkmcnt(0)
	s_setprio 1
	v_mfma_f32_16x16x32_bf16 v[62:65], v[130:133], v[146:149], v[62:65]
	v_mfma_f32_16x16x32_bf16 v[58:61], v[138:141], v[146:149], v[58:61]
	v_mfma_f32_16x16x32_bf16 v[46:49], v[130:133], v[166:169], v[46:49]
	v_mfma_f32_16x16x32_bf16 v[42:45], v[138:141], v[166:169], v[42:45]
	v_mfma_f32_16x16x32_bf16 v[30:33], v[130:133], v[174:177], v[30:33]
	v_mfma_f32_16x16x32_bf16 v[26:29], v[138:141], v[174:177], v[26:29]
	v_mfma_f32_16x16x32_bf16 v[14:17], v[130:133], v[192:195], v[14:17]
	v_mfma_f32_16x16x32_bf16 v[10:13], v[138:141], v[192:195], v[10:13]
	v_mfma_f32_16x16x32_bf16 v[62:65], v[134:137], v[150:153], v[62:65]
	v_mfma_f32_16x16x32_bf16 v[58:61], v[142:145], v[150:153], v[58:61]
	v_mfma_f32_16x16x32_bf16 v[46:49], v[134:137], v[170:173], v[46:49]
	v_mfma_f32_16x16x32_bf16 v[42:45], v[142:145], v[170:173], v[42:45]
	v_mfma_f32_16x16x32_bf16 v[30:33], v[134:137], v[188:191], v[30:33]
	v_mfma_f32_16x16x32_bf16 v[26:29], v[142:145], v[188:191], v[26:29]
	v_mfma_f32_16x16x32_bf16 v[14:17], v[134:137], v[196:199], v[14:17]
	v_mfma_f32_16x16x32_bf16 v[10:13], v[142:145], v[196:199], v[10:13]
	s_setprio 0
	s_barrier
	s_add_u32 s20, s20, 0x20080
	s_addc_u32 s21, s21, 0
	s_add_i32 s24, s24, s42
	v_lshl_add_u64 v[130:131], s[20:21], 0, v[0:1]
	s_mov_b32 m0, s24
	s_nop 0
	global_load_lds_dwordx4 v[130:131], off
	v_lshl_add_u64 v[130:131], s[20:21], 0, v[156:157]
	s_add_i32 m0, s24, 0x2000
	s_nop 0
	global_load_lds_dwordx4 v[130:131], off
	s_waitcnt vmcnt(6)
	s_barrier
	s_setprio 1
	v_mfma_f32_16x16x32_bf16 v[54:57], v[200:203], v[146:149], v[54:57]
	v_mfma_f32_16x16x32_bf16 v[50:53], v[212:215], v[146:149], v[50:53]
	v_mfma_f32_16x16x32_bf16 v[38:41], v[200:203], v[166:169], v[38:41]
	v_mfma_f32_16x16x32_bf16 v[34:37], v[212:215], v[166:169], v[34:37]
	v_mfma_f32_16x16x32_bf16 v[22:25], v[200:203], v[174:177], v[22:25]
	v_mfma_f32_16x16x32_bf16 v[18:21], v[212:215], v[174:177], v[18:21]
	v_mfma_f32_16x16x32_bf16 v[6:9], v[200:203], v[192:195], v[6:9]
	v_mfma_f32_16x16x32_bf16 v[2:5], v[212:215], v[192:195], v[2:5]
	v_mfma_f32_16x16x32_bf16 v[54:57], v[208:211], v[150:153], v[54:57]
	v_mfma_f32_16x16x32_bf16 v[50:53], v[216:219], v[150:153], v[50:53]
	v_mfma_f32_16x16x32_bf16 v[38:41], v[208:211], v[170:173], v[38:41]
	v_mfma_f32_16x16x32_bf16 v[34:37], v[216:219], v[170:173], v[34:37]
	v_mfma_f32_16x16x32_bf16 v[22:25], v[208:211], v[188:191], v[22:25]
	v_mfma_f32_16x16x32_bf16 v[18:21], v[216:219], v[188:191], v[18:21]
	v_mfma_f32_16x16x32_bf16 v[6:9], v[208:211], v[196:199], v[6:9]
	v_mfma_f32_16x16x32_bf16 v[2:5], v[216:219], v[196:199], v[2:5]
	s_setprio 0
	s_add_i32 s89, s89, 2
	s_add_u32 s6, s6, 0x100
	s_addc_u32 s7, s7, 0
	s_add_u32 s87, s87, 0x100
	s_addc_u32 s88, s88, 0
	s_cmp_gt_u32 s89, 5
	s_barrier
	s_cbranch_scc0 .LBB0_1302
	v_mov_b32_e32 v130, v250
	s_lshl_b32 s7, s86, 8
	v_readfirstlane_b32 s6, v130
	s_ashr_i32 s20, s6, 2
	s_andn2_b32 s20, s20, 63
	s_lshr_b32 s6, s6, 1
	s_add_i32 s20, s20, s7
	s_lshl_b32 s7, s85, 8
	s_and_b32 s6, s6, 0x60
	v_and_or_b32 v170, v130, 15, s20
	s_or_b32 s6, s6, s7
	v_lshrrev_b32_e32 v130, 1, v130
	v_and_or_b32 v138, v130, 24, s6
	v_mov_b64_e32 v[172:173], s[44:45]
	v_ashrrev_i32_e32 v171, 31, v170
	v_lshlrev_b64 v[130:131], 10, v[170:171]
	v_ashrrev_i32_e32 v139, 31, v138
	v_lshl_add_u64 v[130:131], s[0:1], 0, v[130:131]
	v_lshlrev_b64 v[166:167], 1, v[138:139]
	v_lshl_add_u64 v[174:175], v[130:131], 0, v[166:167]
	v_mad_i64_i32 v[130:131], s[6:7], v170, s26, v[172:173]
	v_lshl_add_u64 v[130:131], v[130:131], 0, v[166:167]
	s_mov_b64 s[20:21], 0x4510
	v_lshl_add_u64 v[178:179], v[130:131], 0, s[20:21]
	v_add_co_u32_e32 v130, vcc, s12, v130
	v_lshl_add_u64 v[168:169], v[138:139], 2, s[46:47]
	s_nop 0
	v_addc_co_u32_e32 v131, vcc, 0, v131, vcc
	global_load_dwordx4 v[134:137], v[174:175], off
	v_lshlrev_b64 v[176:177], 12, v[170:171]
	global_load_dwordx4 v[130:133], v[130:131], off offset:1296
	s_nop 0
	global_load_dwordx4 v[138:141], v[168:169], off offset:16
	global_load_dwordx4 v[142:145], v[168:169], off
	s_mov_b32 s85, s52
	s_mov_b32 s86, s54
	s_mov_b32 s89, 0x42b17218
	s_brev_b32 s90, 18
	s_waitcnt vmcnt(0)
	v_lshlrev_b32_e32 v149, 16, v134
	v_lshlrev_b32_e32 v148, 16, v130
	v_add_f32_e32 v126, v126, v142
	v_mul_f32_e32 v126, 0xbfb8aa3b, v126
	v_exp_f32_e32 v126, v126
	v_add_f32_e32 v122, v122, v138
	v_mul_f32_e32 v122, 0xbfb8aa3b, v122
	v_exp_f32_e32 v122, v122
	v_add_f32_e32 v126, 1.0, v126
	v_rcp_f32_e32 v147, v126
	v_mul_f32_e32 v126, 0xbfb8aa3b, v148
	v_exp_f32_e32 v126, v126
	v_add_f32_e32 v122, 1.0, v122
	v_add_f32_e32 v127, v127, v143
	v_mul_f32_e32 v127, 0xbfb8aa3b, v127
	v_add_f32_e32 v126, 1.0, v126
	v_rcp_f32_e32 v146, v126
	v_exp_f32_e32 v127, v127
	v_add_f32_e32 v123, v123, v139
	v_mul_f32_e32 v123, 0xbfb8aa3b, v123
	v_pk_mul_f32 v[146:147], v[146:147], v[148:149]
	v_lshlrev_b32_e32 v148, 16, v132
	v_mul_f32_e32 v126, v146, v147
	v_rcp_f32_e32 v147, v122
	v_mul_f32_e32 v122, 0xbfb8aa3b, v148
	v_exp_f32_e32 v122, v122
	v_lshlrev_b32_e32 v149, 16, v136
	v_add_f32_e32 v127, 1.0, v127
	v_rcp_f32_e32 v143, v127
	v_add_f32_e32 v122, 1.0, v122
	v_rcp_f32_e32 v146, v122
	v_exp_f32_e32 v123, v123
	v_add_f32_e32 v128, v128, v144
	v_mul_f32_e32 v128, 0xbfb8aa3b, v128
	v_pk_mul_f32 v[146:147], v[146:147], v[148:149]
	v_add_f32_e32 v123, 1.0, v123
	v_mul_f32_e32 v122, v146, v147
	v_and_b32_e32 v146, 0xffff0000, v130
	v_mul_f32_e32 v127, 0xbfb8aa3b, v146
	v_exp_f32_e32 v127, v127
	v_and_b32_e32 v147, 0xffff0000, v134
	v_rcp_f32_e32 v139, v123
	v_exp_f32_e32 v128, v128
	v_add_f32_e32 v127, 1.0, v127
	v_rcp_f32_e32 v142, v127
	v_add_f32_e32 v124, v124, v140
; __device__ __forceinline__ float sigmoidf_(float x) { return __builtin_amdgcn_rcpf(1.f + __expf(-x)); }
; __device__ __forceinline__ float siluf_(float x) { return x * sigmoidf_(x); }
;     __device__ __forceinline__ void operator()(AccT& acc, const Unit& u, int wr, int wc, int fr, int fq) const {
;     ...
;         for (int ai = 0; ai < 2; ++ai)
; #pragma unroll
;             for (int m = 0; m < 4; ++m) { const size_t row = (size_t)(row0 + ai * 128 + m * 16);
; #pragma unroll
;                 for (int bj = 0; bj < 2; ++bj) { const int c = col0 + bj * 128;
;                     float y8[8], z8[8], o8[8]; ld8(yd + row * 512 + c, y8); ld8(proj + row * NP + O_DZ + c, z8);
;                     const f32x4 b0 = *(const f32x4*)(gb + c), b1 = *(const f32x4*)(gb + c + 4);
; #pragma unroll
;                     for (int e = 0; e < 4; ++e) { o8[e] = y8[e] * sigmoidf_(acc[ai][bj][m][0][e] + b0[e]) * siluf_(z8[e]); o8[4 + e] = y8[4 + e] * sigmoidf_(acc[ai][bj][m][1][e] + b1[e]) * siluf_(z8[4 + e]); }
;                     st8(ys + row * DM + 1536 + c, o8); } }
	v_add_f32_e32 v128, 1.0, v128
	v_mul_f32_e32 v124, 0xbfb8aa3b, v124
	v_pk_mul_f32 v[142:143], v[142:143], v[146:147]
	v_exp_f32_e32 v124, v124
	v_mul_f32_e32 v127, v142, v143
	v_and_b32_e32 v142, 0xffff0000, v132
	v_mul_f32_e32 v123, 0xbfb8aa3b, v142
	v_exp_f32_e32 v123, v123
	v_and_b32_e32 v143, 0xffff0000, v136
	v_add_f32_e32 v124, 1.0, v124
	v_and_b32_e32 v134, 0xffff0000, v131
	v_add_f32_e32 v123, 1.0, v123
	v_rcp_f32_e32 v138, v123
	s_nop 0
	v_pk_mul_f32 v[138:139], v[138:139], v[142:143]
	v_lshlrev_b32_e32 v142, 16, v131
	v_mul_f32_e32 v123, v138, v139
	v_rcp_f32_e32 v139, v128
	v_mul_f32_e32 v128, 0xbfb8aa3b, v142
	v_exp_f32_e32 v128, v128
	v_lshlrev_b32_e32 v143, 16, v135
	v_and_b32_e32 v135, 0xffff0000, v135
	v_add_f32_e32 v128, 1.0, v128
	v_rcp_f32_e32 v138, v128
	s_nop 0
	v_pk_mul_f32 v[138:139], v[138:139], v[142:143]
	v_lshlrev_b32_e32 v142, 16, v133
	v_mul_f32_e32 v130, v138, v139
	v_rcp_f32_e32 v139, v124
	v_mul_f32_e32 v124, 0xbfb8aa3b, v142
	v_exp_f32_e32 v124, v124
	v_lshlrev_b32_e32 v143, 16, v137
	v_add_f32_e32 v124, 1.0, v124
	v_rcp_f32_e32 v138, v124
	v_add_f32_e32 v124, v129, v145
	v_mul_f32_e32 v124, 0xbfb8aa3b, v124
	v_exp_f32_e32 v124, v124
	v_pk_mul_f32 v[138:139], v[138:139], v[142:143]
	v_add_f32_e32 v124, 1.0, v124
	v_rcp_f32_e32 v129, v124
	v_mul_f32_e32 v124, 0xbfb8aa3b, v134
	v_exp_f32_e32 v124, v124
	v_mul_f32_e32 v132, v138, v139
	v_add_f32_e32 v124, 1.0, v124
	v_rcp_f32_e32 v128, v124
	v_add_f32_e32 v124, v125, v141
	v_mul_f32_e32 v124, 0xbfb8aa3b, v124
	v_exp_f32_e32 v124, v124
	v_pk_mul_f32 v[128:129], v[128:129], v[134:135]
	v_add_f32_e32 v124, 1.0, v124
	v_mul_f32_e32 v131, v128, v129
	v_and_b32_e32 v128, 0xffff0000, v133
	v_rcp_f32_e32 v125, v124
	v_mul_f32_e32 v124, 0xbfb8aa3b, v128
	v_exp_f32_e32 v124, v124
	v_and_b32_e32 v129, 0xffff0000, v137
	v_add_f32_e32 v124, 1.0, v124
	v_rcp_f32_e32 v124, v124
	s_nop 0
	v_pk_mul_f32 v[124:125], v[124:125], v[128:129]
	s_nop 0
	v_mul_f32_e32 v128, v124, v125
	v_lshl_add_u64 v[124:125], s[48:49], 0, v[176:177]
	v_lshl_add_u64 v[138:139], v[124:125], 0, v[166:167]
	s_nop 0
	v_cvt_pk_bf16_f32 v124, v126, v127
	s_nop 0
	v_cvt_pk_bf16_f32 v125, v130, v131
	s_nop 0
	v_cvt_pk_bf16_f32 v126, v122, v123
	s_nop 0
	v_cvt_pk_bf16_f32 v127, v132, v128
	global_store_dwordx4 v[138:139], v[124:127], off offset:3072
	global_load_dwordx4 v[126:129], v[174:175], off offset:256
	s_nop 0
	global_load_dwordx4 v[122:125], v[178:179], off offset:256
	global_load_dwordx4 v[130:133], v[168:169], off offset:528
	global_load_dwordx4 v[134:137], v[168:169], off offset:512
	s_waitcnt vmcnt(0)
	v_lshlrev_b32_e32 v143, 16, v126
	v_lshlrev_b32_e32 v142, 16, v122
	v_add_f32_e32 v114, v114, v130
	v_add_f32_e32 v118, v118, v134
	v_mul_f32_e32 v118, 0xbfb8aa3b, v118
	v_exp_f32_e32 v118, v118
	v_mul_f32_e32 v114, 0xbfb8aa3b, v114
	v_exp_f32_e32 v114, v114
	v_and_b32_e32 v130, 0xffff0000, v124
	v_add_f32_e32 v118, 1.0, v118
	v_rcp_f32_e32 v141, v118
	v_mul_f32_e32 v118, 0xbfb8aa3b, v142
	v_exp_f32_e32 v118, v118
	v_add_f32_e32 v114, 1.0, v114
	v_add_f32_e32 v118, 1.0, v118
	v_rcp_f32_e32 v140, v118
	s_nop 0
	v_pk_mul_f32 v[140:141], v[140:141], v[142:143]
	v_lshlrev_b32_e32 v142, 16, v124
	v_mul_f32_e32 v118, v140, v141
	v_rcp_f32_e32 v141, v114
	v_mul_f32_e32 v114, 0xbfb8aa3b, v142
	v_exp_f32_e32 v114, v114
	v_lshlrev_b32_e32 v143, 16, v128
	v_add_f32_e32 v114, 1.0, v114
	v_rcp_f32_e32 v140, v114
	v_add_f32_e32 v114, v119, v135
	v_mul_f32_e32 v114, 0xbfb8aa3b, v114
	v_exp_f32_e32 v114, v114
	v_pk_mul_f32 v[140:141], v[140:141], v[142:143]
	v_add_f32_e32 v114, 1.0, v114
	v_mul_f32_e32 v142, v140, v141
	v_and_b32_e32 v140, 0xffff0000, v122
	v_rcp_f32_e32 v135, v114
	v_mul_f32_e32 v114, 0xbfb8aa3b, v140
	v_exp_f32_e32 v114, v114
	v_and_b32_e32 v141, 0xffff0000, v126
	v_add_f32_e32 v114, 1.0, v114
	v_rcp_f32_e32 v134, v114
	v_add_f32_e32 v114, v115, v131
	v_mul_f32_e32 v114, 0xbfb8aa3b, v114
	v_exp_f32_e32 v114, v114
	v_and_b32_e32 v131, 0xffff0000, v128
	v_pk_mul_f32 v[134:135], v[134:135], v[140:141]
	v_add_f32_e32 v114, 1.0, v114
	v_rcp_f32_e32 v115, v114
	v_mul_f32_e32 v114, 0xbfb8aa3b, v130
	v_exp_f32_e32 v114, v114
	v_mul_f32_e32 v119, v134, v135
	v_add_f32_e32 v114, 1.0, v114
	v_rcp_f32_e32 v114, v114
	s_nop 0
	v_pk_mul_f32 v[114:115], v[114:115], v[130:131]
	s_nop 0
	v_mul_f32_e32 v122, v114, v115
	v_add_f32_e32 v114, v120, v136
	v_mul_f32_e32 v114, 0xbfb8aa3b, v114
	v_exp_f32_e32 v114, v114
	v_lshlrev_b32_e32 v130, 16, v123
	v_lshlrev_b32_e32 v131, 16, v127
	v_and_b32_e32 v120, 0xffff0000, v123
	v_add_f32_e32 v114, 1.0, v114
	v_rcp_f32_e32 v115, v114
	v_mul_f32_e32 v114, 0xbfb8aa3b, v130
	v_exp_f32_e32 v114, v114
	s_nop 0
	v_add_f32_e32 v114, 1.0, v114
	v_rcp_f32_e32 v114, v114
	s_nop 0
	v_pk_mul_f32 v[114:115], v[114:115], v[130:131]
	s_nop 0
	v_mul_f32_e32 v124, v114, v115
	v_add_f32_e32 v114, v116, v132
	v_mul_f32_e32 v114, 0xbfb8aa3b, v114
	v_exp_f32_e32 v114, v114
	v_lshlrev_b32_e32 v130, 16, v125
	v_lshlrev_b32_e32 v131, 16, v129
	v_and_b32_e32 v116, 0xffff0000, v125
	v_add_f32_e32 v114, 1.0, v114
	v_rcp_f32_e32 v115, v114
	v_mul_f32_e32 v114, 0xbfb8aa3b, v130
	v_exp_f32_e32 v114, v114
	s_nop 0
	v_add_f32_e32 v114, 1.0, v114
	v_rcp_f32_e32 v114, v114
	s_nop 0
	v_pk_mul_f32 v[114:115], v[114:115], v[130:131]
	s_nop 0
	v_mul_f32_e32 v126, v114, v115
	v_add_f32_e32 v114, v121, v137
	v_mul_f32_e32 v114, 0xbfb8aa3b, v114
	v_exp_f32_e32 v114, v114
	v_and_b32_e32 v121, 0xffff0000, v127
	v_add_f32_e32 v114, 1.0, v114
	v_rcp_f32_e32 v115, v114
	v_mul_f32_e32 v114, 0xbfb8aa3b, v120
	v_exp_f32_e32 v114, v114
	s_nop 0
	v_add_f32_e32 v114, 1.0, v114
	v_rcp_f32_e32 v114, v114
	s_nop 0
; __device__ __forceinline__ float sigmoidf_(float x) { return __builtin_amdgcn_rcpf(1.f + __expf(-x)); }
; __device__ __forceinline__ float siluf_(float x) { return x * sigmoidf_(x); }
;     __device__ __forceinline__ void operator()(AccT& acc, const Unit& u, int wr, int wc, int fr, int fq) const {
;     ...
;         for (int ai = 0; ai < 2; ++ai)
; #pragma unroll
;             for (int m = 0; m < 4; ++m) { const size_t row = (size_t)(row0 + ai * 128 + m * 16);
; #pragma unroll
;                 for (int bj = 0; bj < 2; ++bj) { const int c = col0 + bj * 128;
;                     float y8[8], z8[8], o8[8]; ld8(yd + row * 512 + c, y8); ld8(proj + row * NP + O_DZ + c, z8);
;                     const f32x4 b0 = *(const f32x4*)(gb + c), b1 = *(const f32x4*)(gb + c + 4);
; #pragma unroll
;                     for (int e = 0; e < 4; ++e) { o8[e] = y8[e] * sigmoidf_(acc[ai][bj][m][0][e] + b0[e]) * siluf_(z8[e]); o8[4 + e] = y8[4 + e] * sigmoidf_(acc[ai][bj][m][1][e] + b1[e]) * siluf_(z8[4 + e]); }
;                     st8(ys + row * DM + 1536 + c, o8); } }
	v_pk_mul_f32 v[114:115], v[114:115], v[120:121]
	s_nop 0
	v_mul_f32_e32 v120, v114, v115
	v_add_f32_e32 v114, v117, v133
	v_mul_f32_e32 v114, 0xbfb8aa3b, v114
	v_exp_f32_e32 v114, v114
	v_and_b32_e32 v117, 0xffff0000, v129
	v_add_f32_e32 v114, 1.0, v114
	v_rcp_f32_e32 v115, v114
	v_mul_f32_e32 v114, 0xbfb8aa3b, v116
	v_exp_f32_e32 v114, v114
	s_nop 0
	v_add_f32_e32 v114, 1.0, v114
	v_rcp_f32_e32 v114, v114
	s_nop 0
	v_pk_mul_f32 v[114:115], v[114:115], v[116:117]
	s_nop 0
	v_mul_f32_e32 v117, v114, v115
	s_nop 0
	v_cvt_pk_bf16_f32 v114, v118, v119
	v_add_u32_e32 v118, 16, v170
	s_nop 0
	v_cvt_pk_bf16_f32 v115, v124, v120
	v_ashrrev_i32_e32 v119, 31, v118
	s_nop 0
	v_cvt_pk_bf16_f32 v116, v142, v122
	s_nop 0
	v_cvt_pk_bf16_f32 v117, v126, v117
	global_store_dwordx4 v[138:139], v[114:117], off offset:3328
	v_lshlrev_b64 v[132:133], 12, v[118:119]
	s_nop 0
	v_lshlrev_b64 v[114:115], 10, v[118:119]
	v_mad_i64_i32 v[118:119], s[6:7], v118, s26, v[172:173]
	v_lshl_add_u64 v[118:119], v[118:119], 0, v[166:167]
	v_lshl_add_u64 v[114:115], s[0:1], 0, v[114:115]
	v_lshl_add_u64 v[134:135], v[118:119], 0, s[20:21]
	v_add_co_u32_e32 v118, vcc, s12, v118
	v_lshl_add_u64 v[130:131], v[114:115], 0, v[166:167]
	s_nop 0
	v_addc_co_u32_e32 v119, vcc, 0, v119, vcc
	global_load_dwordx4 v[114:117], v[130:131], off
	s_nop 0
	global_load_dwordx4 v[118:121], v[118:119], off offset:1296
	s_nop 0
	global_load_dwordx4 v[122:125], v[168:169], off offset:16
	global_load_dwordx4 v[126:129], v[168:169], off
	s_waitcnt vmcnt(0)
	v_lshlrev_b32_e32 v138, 16, v118
	v_add_f32_e32 v106, v106, v122
	v_add_f32_e32 v110, v110, v126
	v_mul_f32_e32 v110, 0xbfb8aa3b, v110
	v_exp_f32_e32 v110, v110
	v_mul_f32_e32 v106, 0xbfb8aa3b, v106
	v_exp_f32_e32 v106, v106
	v_lshlrev_b32_e32 v139, 16, v114
	v_add_f32_e32 v110, 1.0, v110
	v_rcp_f32_e32 v137, v110
	v_mul_f32_e32 v110, 0xbfb8aa3b, v138
	v_exp_f32_e32 v110, v110
	v_add_f32_e32 v106, 1.0, v106
	v_and_b32_e32 v126, 0xffff0000, v118
	v_add_f32_e32 v110, 1.0, v110
	v_rcp_f32_e32 v136, v110
	s_nop 0
	v_pk_mul_f32 v[136:137], v[136:137], v[138:139]
	v_lshlrev_b32_e32 v138, 16, v120
	v_mul_f32_e32 v140, v136, v137
	v_rcp_f32_e32 v137, v106
	v_mul_f32_e32 v106, 0xbfb8aa3b, v138
	v_exp_f32_e32 v106, v106
	v_lshlrev_b32_e32 v139, 16, v116
	v_add_f32_e32 v106, 1.0, v106
	v_rcp_f32_e32 v136, v106
	v_add_f32_e32 v106, v111, v127
	v_mul_f32_e32 v106, 0xbfb8aa3b, v106
	v_exp_f32_e32 v106, v106
	v_and_b32_e32 v127, 0xffff0000, v114
	v_pk_mul_f32 v[136:137], v[136:137], v[138:139]
	v_add_f32_e32 v106, 1.0, v106
	v_rcp_f32_e32 v111, v106
	v_mul_f32_e32 v106, 0xbfb8aa3b, v126
	v_exp_f32_e32 v106, v106
	v_mul_f32_e32 v136, v136, v137
	v_add_f32_e32 v106, 1.0, v106
	v_rcp_f32_e32 v110, v106
	v_add_f32_e32 v106, v107, v123
	v_mul_f32_e32 v106, 0xbfb8aa3b, v106
	v_exp_f32_e32 v106, v106
	v_pk_mul_f32 v[110:111], v[110:111], v[126:127]
	v_add_f32_e32 v106, 1.0, v106
	v_mul_f32_e32 v114, v110, v111
	v_and_b32_e32 v110, 0xffff0000, v120
	v_rcp_f32_e32 v107, v106
	v_mul_f32_e32 v106, 0xbfb8aa3b, v110
	v_exp_f32_e32 v106, v106
	v_and_b32_e32 v111, 0xffff0000, v116
	v_add_f32_e32 v106, 1.0, v106
	v_rcp_f32_e32 v106, v106
	s_nop 0
	v_pk_mul_f32 v[106:107], v[106:107], v[110:111]
	s_nop 0
	v_mul_f32_e32 v116, v106, v107
	v_add_f32_e32 v106, v112, v128
	v_mul_f32_e32 v106, 0xbfb8aa3b, v106
	v_exp_f32_e32 v106, v106
	v_lshlrev_b32_e32 v110, 16, v119
	v_lshlrev_b32_e32 v111, 16, v115
	v_add_f32_e32 v106, 1.0, v106
	v_rcp_f32_e32 v107, v106
	v_mul_f32_e32 v106, 0xbfb8aa3b, v110
	v_exp_f32_e32 v106, v106
	s_nop 0
	v_add_f32_e32 v106, 1.0, v106
	v_rcp_f32_e32 v106, v106
	s_nop 0
	v_pk_mul_f32 v[106:107], v[106:107], v[110:111]
	s_nop 0
	v_mul_f32_e32 v112, v106, v107
	v_add_f32_e32 v106, v108, v124
	v_mul_f32_e32 v106, 0xbfb8aa3b, v106
	v_exp_f32_e32 v106, v106
	v_lshlrev_b32_e32 v110, 16, v121
	v_lshlrev_b32_e32 v111, 16, v117
	v_and_b32_e32 v108, 0xffff0000, v121
	v_add_f32_e32 v106, 1.0, v106
	v_rcp_f32_e32 v107, v106
	v_mul_f32_e32 v106, 0xbfb8aa3b, v110
	v_exp_f32_e32 v106, v106
	s_nop 0
	v_add_f32_e32 v106, 1.0, v106
	v_rcp_f32_e32 v106, v106
	s_nop 0
	v_pk_mul_f32 v[106:107], v[106:107], v[110:111]
	s_nop 0
	v_mul_f32_e32 v118, v106, v107
	v_add_f32_e32 v106, v113, v129
	v_mul_f32_e32 v106, 0xbfb8aa3b, v106
	v_exp_f32_e32 v106, v106
	v_and_b32_e32 v110, 0xffff0000, v119
	v_and_b32_e32 v111, 0xffff0000, v115
	v_add_f32_e32 v106, 1.0, v106
	v_rcp_f32_e32 v107, v106
	v_mul_f32_e32 v106, 0xbfb8aa3b, v110
	v_exp_f32_e32 v106, v106
	s_nop 0
	v_add_f32_e32 v106, 1.0, v106
	v_rcp_f32_e32 v106, v106
	s_nop 0
	v_pk_mul_f32 v[106:107], v[106:107], v[110:111]
	s_nop 0
	v_mul_f32_e32 v110, v106, v107
	v_add_f32_e32 v106, v109, v125
	v_mul_f32_e32 v106, 0xbfb8aa3b, v106
	v_exp_f32_e32 v106, v106
	v_and_b32_e32 v109, 0xffff0000, v117
	v_add_f32_e32 v106, 1.0, v106
	v_rcp_f32_e32 v107, v106
	v_mul_f32_e32 v106, 0xbfb8aa3b, v108
	v_exp_f32_e32 v106, v106
	s_nop 0
	v_add_f32_e32 v106, 1.0, v106
	v_rcp_f32_e32 v106, v106
	s_nop 0
	v_pk_mul_f32 v[106:107], v[106:107], v[108:109]
	s_nop 0
	v_mul_f32_e32 v109, v106, v107
	v_lshl_add_u64 v[106:107], s[48:49], 0, v[132:133]
	v_lshl_add_u64 v[122:123], v[106:107], 0, v[166:167]
	s_nop 0
	v_cvt_pk_bf16_f32 v106, v140, v114
	s_nop 0
	v_cvt_pk_bf16_f32 v107, v112, v110
	s_nop 0
	v_cvt_pk_bf16_f32 v108, v136, v116
	s_nop 0
	v_cvt_pk_bf16_f32 v109, v118, v109
	global_store_dwordx4 v[122:123], v[106:109], off offset:3072
	global_load_dwordx4 v[110:113], v[130:131], off offset:256
	s_nop 0
	global_load_dwordx4 v[106:109], v[134:135], off offset:256
	global_load_dwordx4 v[114:117], v[168:169], off offset:528
	global_load_dwordx4 v[118:121], v[168:169], off offset:512
	s_waitcnt vmcnt(0)
; __device__ __forceinline__ float sigmoidf_(float x) { return __builtin_amdgcn_rcpf(1.f + __expf(-x)); }
; __device__ __forceinline__ float siluf_(float x) { return x * sigmoidf_(x); }
;     __device__ __forceinline__ void operator()(AccT& acc, const Unit& u, int wr, int wc, int fr, int fq) const {
;     ...
;             for (int m = 0; m < 4; ++m) { const size_t row = (size_t)(row0 + ai * 128 + m * 16);
; #pragma unroll
;                 for (int bj = 0; bj < 2; ++bj) { const int c = col0 + bj * 128;
;                     float y8[8], z8[8], o8[8]; ld8(yd + row * 512 + c, y8); ld8(proj + row * NP + O_DZ + c, z8);
;                     const f32x4 b0 = *(const f32x4*)(gb + c), b1 = *(const f32x4*)(gb + c + 4);
; #pragma unroll
;                     for (int e = 0; e < 4; ++e) { o8[e] = y8[e] * sigmoidf_(acc[ai][bj][m][0][e] + b0[e]) * siluf_(z8[e]); o8[4 + e] = y8[4 + e] * sigmoidf_(acc[ai][bj][m][1][e] + b1[e]) * siluf_(z8[4 + e]); }
;                     st8(ys + row * DM + 1536 + c, o8); } }
	v_lshlrev_b32_e32 v127, 16, v110
	v_lshlrev_b32_e32 v126, 16, v106
	v_add_f32_e32 v98, v98, v114
	v_add_f32_e32 v102, v102, v118
	v_mul_f32_e32 v102, 0xbfb8aa3b, v102
	v_exp_f32_e32 v102, v102
	v_mul_f32_e32 v98, 0xbfb8aa3b, v98
	v_exp_f32_e32 v98, v98
	v_and_b32_e32 v118, 0xffff0000, v106
	v_add_f32_e32 v102, 1.0, v102
	v_rcp_f32_e32 v125, v102
	v_mul_f32_e32 v102, 0xbfb8aa3b, v126
	v_exp_f32_e32 v102, v102
	v_add_f32_e32 v98, 1.0, v98
	v_add_f32_e32 v102, 1.0, v102
	v_rcp_f32_e32 v124, v102
	s_nop 0
	v_pk_mul_f32 v[124:125], v[124:125], v[126:127]
	v_lshlrev_b32_e32 v126, 16, v108
	v_mul_f32_e32 v128, v124, v125
	v_rcp_f32_e32 v125, v98
	v_mul_f32_e32 v98, 0xbfb8aa3b, v126
	v_exp_f32_e32 v98, v98
	v_lshlrev_b32_e32 v127, 16, v112
	v_add_f32_e32 v98, 1.0, v98
	v_rcp_f32_e32 v124, v98
	v_add_f32_e32 v98, v103, v119
	v_mul_f32_e32 v98, 0xbfb8aa3b, v98
	v_exp_f32_e32 v98, v98
	v_and_b32_e32 v119, 0xffff0000, v110
	v_pk_mul_f32 v[124:125], v[124:125], v[126:127]
	v_add_f32_e32 v98, 1.0, v98
	v_rcp_f32_e32 v103, v98
	v_mul_f32_e32 v98, 0xbfb8aa3b, v118
	v_exp_f32_e32 v98, v98
	v_mul_f32_e32 v114, v124, v125
	v_add_f32_e32 v98, 1.0, v98
	v_rcp_f32_e32 v102, v98
	v_add_f32_e32 v98, v99, v115
	v_mul_f32_e32 v98, 0xbfb8aa3b, v98
	v_exp_f32_e32 v98, v98
	v_pk_mul_f32 v[102:103], v[102:103], v[118:119]
	v_add_f32_e32 v98, 1.0, v98
	v_mul_f32_e32 v106, v102, v103
	v_and_b32_e32 v102, 0xffff0000, v108
	v_rcp_f32_e32 v99, v98
	v_mul_f32_e32 v98, 0xbfb8aa3b, v102
	v_exp_f32_e32 v98, v98
	v_and_b32_e32 v103, 0xffff0000, v112
	v_add_f32_e32 v98, 1.0, v98
	v_rcp_f32_e32 v98, v98
	s_nop 0
	v_pk_mul_f32 v[98:99], v[98:99], v[102:103]
	s_nop 0
	v_mul_f32_e32 v108, v98, v99
	v_add_f32_e32 v98, v104, v120
	v_mul_f32_e32 v98, 0xbfb8aa3b, v98
	v_exp_f32_e32 v98, v98
	v_lshlrev_b32_e32 v102, 16, v107
	v_lshlrev_b32_e32 v103, 16, v111
	v_add_f32_e32 v98, 1.0, v98
	v_rcp_f32_e32 v99, v98
	v_mul_f32_e32 v98, 0xbfb8aa3b, v102
	v_exp_f32_e32 v98, v98
	s_nop 0
	v_add_f32_e32 v98, 1.0, v98
	v_rcp_f32_e32 v98, v98
	s_nop 0
	v_pk_mul_f32 v[98:99], v[98:99], v[102:103]
	s_nop 0
	v_mul_f32_e32 v104, v98, v99
	v_add_f32_e32 v98, v100, v116
	v_mul_f32_e32 v98, 0xbfb8aa3b, v98
	v_exp_f32_e32 v98, v98
	v_lshlrev_b32_e32 v102, 16, v109
	v_lshlrev_b32_e32 v103, 16, v113
	v_and_b32_e32 v100, 0xffff0000, v109
	v_add_f32_e32 v98, 1.0, v98
	v_rcp_f32_e32 v99, v98
	v_mul_f32_e32 v98, 0xbfb8aa3b, v102
	v_exp_f32_e32 v98, v98
	s_nop 0
	v_add_f32_e32 v98, 1.0, v98
	v_rcp_f32_e32 v98, v98
	s_nop 0
	v_pk_mul_f32 v[98:99], v[98:99], v[102:103]
	s_nop 0
	v_mul_f32_e32 v110, v98, v99
	v_add_f32_e32 v98, v105, v121
	v_mul_f32_e32 v98, 0xbfb8aa3b, v98
	v_exp_f32_e32 v98, v98
	v_and_b32_e32 v102, 0xffff0000, v107
	v_and_b32_e32 v103, 0xffff0000, v111
	v_add_f32_e32 v98, 1.0, v98
	v_rcp_f32_e32 v99, v98
	v_mul_f32_e32 v98, 0xbfb8aa3b, v102
	v_exp_f32_e32 v98, v98
	s_nop 0
	v_add_f32_e32 v98, 1.0, v98
	v_rcp_f32_e32 v98, v98
	s_nop 0
	v_pk_mul_f32 v[98:99], v[98:99], v[102:103]
	s_nop 0
	v_mul_f32_e32 v102, v98, v99
	v_add_f32_e32 v98, v101, v117
	v_mul_f32_e32 v98, 0xbfb8aa3b, v98
	v_exp_f32_e32 v98, v98
	v_and_b32_e32 v101, 0xffff0000, v113
	v_add_f32_e32 v98, 1.0, v98
	v_rcp_f32_e32 v99, v98
	v_mul_f32_e32 v98, 0xbfb8aa3b, v100
	v_exp_f32_e32 v98, v98
	s_nop 0
	v_add_f32_e32 v98, 1.0, v98
	v_rcp_f32_e32 v98, v98
	s_nop 0
	v_pk_mul_f32 v[98:99], v[98:99], v[100:101]
	s_nop 0
	v_mul_f32_e32 v101, v98, v99
	s_nop 0
	v_cvt_pk_bf16_f32 v98, v128, v106
	s_nop 0
	v_cvt_pk_bf16_f32 v99, v104, v102
	v_add_u32_e32 v102, 32, v170
	v_ashrrev_i32_e32 v103, 31, v102
	s_nop 0
	v_cvt_pk_bf16_f32 v100, v114, v108
	s_nop 0
	v_cvt_pk_bf16_f32 v101, v110, v101
	global_store_dwordx4 v[122:123], v[98:101], off offset:3328
	v_lshlrev_b64 v[116:117], 12, v[102:103]
	s_nop 0
	v_lshlrev_b64 v[98:99], 10, v[102:103]
	v_mad_i64_i32 v[102:103], s[6:7], v102, s26, v[172:173]
	v_lshl_add_u64 v[102:103], v[102:103], 0, v[166:167]
	v_lshl_add_u64 v[98:99], s[0:1], 0, v[98:99]
	v_lshl_add_u64 v[118:119], v[102:103], 0, s[20:21]
	v_add_co_u32_e32 v102, vcc, s12, v102
	v_lshl_add_u64 v[114:115], v[98:99], 0, v[166:167]
	s_nop 0
	v_addc_co_u32_e32 v103, vcc, 0, v103, vcc
	global_load_dwordx4 v[98:101], v[114:115], off
	s_nop 0
	global_load_dwordx4 v[102:105], v[102:103], off offset:1296
	s_nop 0
	global_load_dwordx4 v[106:109], v[168:169], off offset:16
	global_load_dwordx4 v[110:113], v[168:169], off
	s_waitcnt vmcnt(0)
; __device__ __forceinline__ float sigmoidf_(float x) { return __builtin_amdgcn_rcpf(1.f + __expf(-x)); }
; __device__ __forceinline__ float siluf_(float x) { return x * sigmoidf_(x); }
;     __device__ __forceinline__ void operator()(AccT& acc, const Unit& u, int wr, int wc, int fr, int fq) const {
;     ...
;             for (int m = 0; m < 4; ++m) { const size_t row = (size_t)(row0 + ai * 128 + m * 16);
; #pragma unroll
;                 for (int bj = 0; bj < 2; ++bj) { const int c = col0 + bj * 128;
;                     float y8[8], z8[8], o8[8]; ld8(yd + row * 512 + c, y8); ld8(proj + row * NP + O_DZ + c, z8);
;                     const f32x4 b0 = *(const f32x4*)(gb + c), b1 = *(const f32x4*)(gb + c + 4);
; #pragma unroll
;                     for (int e = 0; e < 4; ++e) { o8[e] = y8[e] * sigmoidf_(acc[ai][bj][m][0][e] + b0[e]) * siluf_(z8[e]); o8[4 + e] = y8[4 + e] * sigmoidf_(acc[ai][bj][m][1][e] + b1[e]) * siluf_(z8[4 + e]); }
;                     st8(ys + row * DM + 1536 + c, o8); } }
	v_lshlrev_b32_e32 v122, 16, v102
	v_add_f32_e32 v90, v90, v106
	v_add_f32_e32 v94, v94, v110
	v_mul_f32_e32 v94, 0xbfb8aa3b, v94
	v_exp_f32_e32 v94, v94
	v_mul_f32_e32 v90, 0xbfb8aa3b, v90
	v_exp_f32_e32 v90, v90
	v_lshlrev_b32_e32 v123, 16, v98
	v_add_f32_e32 v94, 1.0, v94
	v_rcp_f32_e32 v121, v94
	v_mul_f32_e32 v94, 0xbfb8aa3b, v122
	v_exp_f32_e32 v94, v94
	v_add_f32_e32 v90, 1.0, v90
	v_and_b32_e32 v110, 0xffff0000, v102
	v_add_f32_e32 v94, 1.0, v94
	v_rcp_f32_e32 v120, v94
	s_nop 0
	v_pk_mul_f32 v[120:121], v[120:121], v[122:123]
	v_lshlrev_b32_e32 v122, 16, v104
	v_mul_f32_e32 v124, v120, v121
	v_rcp_f32_e32 v121, v90
	v_mul_f32_e32 v90, 0xbfb8aa3b, v122
	v_exp_f32_e32 v90, v90
	v_lshlrev_b32_e32 v123, 16, v100
	v_add_f32_e32 v90, 1.0, v90
	v_rcp_f32_e32 v120, v90
	v_add_f32_e32 v90, v95, v111
	v_mul_f32_e32 v90, 0xbfb8aa3b, v90
	v_exp_f32_e32 v90, v90
	v_and_b32_e32 v111, 0xffff0000, v98
	v_pk_mul_f32 v[120:121], v[120:121], v[122:123]
	v_add_f32_e32 v90, 1.0, v90
	v_rcp_f32_e32 v95, v90
	v_mul_f32_e32 v90, 0xbfb8aa3b, v110
	v_exp_f32_e32 v90, v90
	v_mul_f32_e32 v120, v120, v121
	v_add_f32_e32 v90, 1.0, v90
	v_rcp_f32_e32 v94, v90
	v_add_f32_e32 v90, v91, v107
	v_mul_f32_e32 v90, 0xbfb8aa3b, v90
	v_exp_f32_e32 v90, v90
	v_pk_mul_f32 v[94:95], v[94:95], v[110:111]
	v_add_f32_e32 v90, 1.0, v90
	v_mul_f32_e32 v98, v94, v95
	v_and_b32_e32 v94, 0xffff0000, v104
	v_rcp_f32_e32 v91, v90
	v_mul_f32_e32 v90, 0xbfb8aa3b, v94
	v_exp_f32_e32 v90, v90
	v_and_b32_e32 v95, 0xffff0000, v100
	v_add_f32_e32 v90, 1.0, v90
	v_rcp_f32_e32 v90, v90
	s_nop 0
	v_pk_mul_f32 v[90:91], v[90:91], v[94:95]
	s_nop 0
	v_mul_f32_e32 v100, v90, v91
	v_add_f32_e32 v90, v96, v112
	v_mul_f32_e32 v90, 0xbfb8aa3b, v90
	v_exp_f32_e32 v90, v90
	v_lshlrev_b32_e32 v94, 16, v103
	v_lshlrev_b32_e32 v95, 16, v99
	v_add_f32_e32 v90, 1.0, v90
	v_rcp_f32_e32 v91, v90
	v_mul_f32_e32 v90, 0xbfb8aa3b, v94
	v_exp_f32_e32 v90, v90
	s_nop 0
	v_add_f32_e32 v90, 1.0, v90
	v_rcp_f32_e32 v90, v90
	s_nop 0
	v_pk_mul_f32 v[90:91], v[90:91], v[94:95]
	s_nop 0
	v_mul_f32_e32 v96, v90, v91
	v_add_f32_e32 v90, v92, v108
	v_mul_f32_e32 v90, 0xbfb8aa3b, v90
	v_exp_f32_e32 v90, v90
	v_lshlrev_b32_e32 v94, 16, v105
	v_lshlrev_b32_e32 v95, 16, v101
	v_and_b32_e32 v92, 0xffff0000, v105
	v_add_f32_e32 v90, 1.0, v90
	v_rcp_f32_e32 v91, v90
	v_mul_f32_e32 v90, 0xbfb8aa3b, v94
	v_exp_f32_e32 v90, v90
	s_nop 0
	v_add_f32_e32 v90, 1.0, v90
	v_rcp_f32_e32 v90, v90
	s_nop 0
	v_pk_mul_f32 v[90:91], v[90:91], v[94:95]
	s_nop 0
	v_mul_f32_e32 v102, v90, v91
	v_add_f32_e32 v90, v97, v113
	v_mul_f32_e32 v90, 0xbfb8aa3b, v90
	v_exp_f32_e32 v90, v90
	v_and_b32_e32 v94, 0xffff0000, v103
	v_and_b32_e32 v95, 0xffff0000, v99
	v_add_f32_e32 v90, 1.0, v90
	v_rcp_f32_e32 v91, v90
	v_mul_f32_e32 v90, 0xbfb8aa3b, v94
	v_exp_f32_e32 v90, v90
	s_nop 0
	v_add_f32_e32 v90, 1.0, v90
	v_rcp_f32_e32 v90, v90
	s_nop 0
	v_pk_mul_f32 v[90:91], v[90:91], v[94:95]
	s_nop 0
	v_mul_f32_e32 v94, v90, v91
	v_add_f32_e32 v90, v93, v109
	v_mul_f32_e32 v90, 0xbfb8aa3b, v90
	v_exp_f32_e32 v90, v90
	v_and_b32_e32 v93, 0xffff0000, v101
	v_add_f32_e32 v90, 1.0, v90
	v_rcp_f32_e32 v91, v90
	v_mul_f32_e32 v90, 0xbfb8aa3b, v92
	v_exp_f32_e32 v90, v90
	s_nop 0
	v_add_f32_e32 v90, 1.0, v90
	v_rcp_f32_e32 v90, v90
	s_nop 0
	v_pk_mul_f32 v[90:91], v[90:91], v[92:93]
	s_nop 0
	v_mul_f32_e32 v93, v90, v91
	v_lshl_add_u64 v[90:91], s[48:49], 0, v[116:117]
	v_lshl_add_u64 v[106:107], v[90:91], 0, v[166:167]
	s_nop 0
	v_cvt_pk_bf16_f32 v90, v124, v98
	s_nop 0
	v_cvt_pk_bf16_f32 v91, v96, v94
	s_nop 0
	v_cvt_pk_bf16_f32 v92, v120, v100
	s_nop 0
	v_cvt_pk_bf16_f32 v93, v102, v93
	global_store_dwordx4 v[106:107], v[90:93], off offset:3072
	global_load_dwordx4 v[94:97], v[114:115], off offset:256
	s_nop 0
	global_load_dwordx4 v[90:93], v[118:119], off offset:256
	global_load_dwordx4 v[98:101], v[168:169], off offset:528
	global_load_dwordx4 v[102:105], v[168:169], off offset:512
	s_waitcnt vmcnt(0)
	v_lshlrev_b32_e32 v111, 16, v94
	v_lshlrev_b32_e32 v110, 16, v90
	v_add_f32_e32 v82, v82, v98
	v_add_f32_e32 v86, v86, v102
	v_mul_f32_e32 v86, 0xbfb8aa3b, v86
	v_exp_f32_e32 v86, v86
	v_mul_f32_e32 v82, 0xbfb8aa3b, v82
	v_exp_f32_e32 v82, v82
	v_and_b32_e32 v102, 0xffff0000, v90
	v_add_f32_e32 v86, 1.0, v86
	v_rcp_f32_e32 v109, v86
	v_mul_f32_e32 v86, 0xbfb8aa3b, v110
	v_exp_f32_e32 v86, v86
	v_add_f32_e32 v82, 1.0, v82
	v_add_f32_e32 v86, 1.0, v86
	v_rcp_f32_e32 v108, v86
	s_nop 0
	v_pk_mul_f32 v[108:109], v[108:109], v[110:111]
	v_lshlrev_b32_e32 v110, 16, v92
	v_mul_f32_e32 v112, v108, v109
	v_rcp_f32_e32 v109, v82
	v_mul_f32_e32 v82, 0xbfb8aa3b, v110
	v_exp_f32_e32 v82, v82
	v_lshlrev_b32_e32 v111, 16, v96
	v_add_f32_e32 v82, 1.0, v82
	v_rcp_f32_e32 v108, v82
	v_add_f32_e32 v82, v87, v103
	v_mul_f32_e32 v82, 0xbfb8aa3b, v82
	v_exp_f32_e32 v82, v82
	v_and_b32_e32 v103, 0xffff0000, v94
	v_pk_mul_f32 v[108:109], v[108:109], v[110:111]
	v_add_f32_e32 v82, 1.0, v82
	v_rcp_f32_e32 v87, v82
	v_mul_f32_e32 v82, 0xbfb8aa3b, v102
	v_exp_f32_e32 v82, v82
	v_mul_f32_e32 v98, v108, v109
	v_add_f32_e32 v82, 1.0, v82
	v_rcp_f32_e32 v86, v82
	v_add_f32_e32 v82, v83, v99
	v_mul_f32_e32 v82, 0xbfb8aa3b, v82
	v_exp_f32_e32 v82, v82
	v_pk_mul_f32 v[86:87], v[86:87], v[102:103]
	v_add_f32_e32 v82, 1.0, v82
	v_mul_f32_e32 v90, v86, v87
	v_and_b32_e32 v86, 0xffff0000, v92
	v_rcp_f32_e32 v83, v82
	v_mul_f32_e32 v82, 0xbfb8aa3b, v86
	v_exp_f32_e32 v82, v82
	v_and_b32_e32 v87, 0xffff0000, v96
	v_add_f32_e32 v82, 1.0, v82
	v_rcp_f32_e32 v82, v82
	s_nop 0
	v_pk_mul_f32 v[82:83], v[82:83], v[86:87]
	s_nop 0
	v_mul_f32_e32 v92, v82, v83
	v_add_f32_e32 v82, v88, v104
	v_mul_f32_e32 v82, 0xbfb8aa3b, v82
; __device__ __forceinline__ float sigmoidf_(float x) { return __builtin_amdgcn_rcpf(1.f + __expf(-x)); }
; __device__ __forceinline__ float siluf_(float x) { return x * sigmoidf_(x); }
;     __device__ __forceinline__ void operator()(AccT& acc, const Unit& u, int wr, int wc, int fr, int fq) const {
;     ...
;             for (int m = 0; m < 4; ++m) { const size_t row = (size_t)(row0 + ai * 128 + m * 16);
; #pragma unroll
;                 for (int bj = 0; bj < 2; ++bj) { const int c = col0 + bj * 128;
;                     float y8[8], z8[8], o8[8]; ld8(yd + row * 512 + c, y8); ld8(proj + row * NP + O_DZ + c, z8);
;                     const f32x4 b0 = *(const f32x4*)(gb + c), b1 = *(const f32x4*)(gb + c + 4);
; #pragma unroll
;                     for (int e = 0; e < 4; ++e) { o8[e] = y8[e] * sigmoidf_(acc[ai][bj][m][0][e] + b0[e]) * siluf_(z8[e]); o8[4 + e] = y8[4 + e] * sigmoidf_(acc[ai][bj][m][1][e] + b1[e]) * siluf_(z8[4 + e]); }
;                     st8(ys + row * DM + 1536 + c, o8); } }
	v_exp_f32_e32 v82, v82
	v_lshlrev_b32_e32 v86, 16, v91
	v_lshlrev_b32_e32 v87, 16, v95
	v_add_f32_e32 v82, 1.0, v82
	v_rcp_f32_e32 v83, v82
	v_mul_f32_e32 v82, 0xbfb8aa3b, v86
	v_exp_f32_e32 v82, v82
	s_nop 0
	v_add_f32_e32 v82, 1.0, v82
	v_rcp_f32_e32 v82, v82
	s_nop 0
	v_pk_mul_f32 v[82:83], v[82:83], v[86:87]
	s_nop 0
	v_mul_f32_e32 v88, v82, v83
	v_add_f32_e32 v82, v84, v100
	v_mul_f32_e32 v82, 0xbfb8aa3b, v82
	v_exp_f32_e32 v82, v82
	v_lshlrev_b32_e32 v86, 16, v93
	v_lshlrev_b32_e32 v87, 16, v97
	v_and_b32_e32 v84, 0xffff0000, v93
	v_add_f32_e32 v82, 1.0, v82
	v_rcp_f32_e32 v83, v82
	v_mul_f32_e32 v82, 0xbfb8aa3b, v86
	v_exp_f32_e32 v82, v82
	s_nop 0
	v_add_f32_e32 v82, 1.0, v82
	v_rcp_f32_e32 v82, v82
	s_nop 0
	v_pk_mul_f32 v[82:83], v[82:83], v[86:87]
	s_nop 0
	v_mul_f32_e32 v94, v82, v83
	v_add_f32_e32 v82, v89, v105
	v_mul_f32_e32 v82, 0xbfb8aa3b, v82
	v_exp_f32_e32 v82, v82
	v_and_b32_e32 v86, 0xffff0000, v91
	v_and_b32_e32 v87, 0xffff0000, v95
	v_add_f32_e32 v82, 1.0, v82
	v_rcp_f32_e32 v83, v82
	v_mul_f32_e32 v82, 0xbfb8aa3b, v86
	v_exp_f32_e32 v82, v82
	s_nop 0
	v_add_f32_e32 v82, 1.0, v82
	v_rcp_f32_e32 v82, v82
	s_nop 0
	v_pk_mul_f32 v[82:83], v[82:83], v[86:87]
	s_nop 0
	v_mul_f32_e32 v86, v82, v83
	v_add_f32_e32 v82, v85, v101
	v_mul_f32_e32 v82, 0xbfb8aa3b, v82
	v_exp_f32_e32 v82, v82
	v_and_b32_e32 v85, 0xffff0000, v97
	v_add_f32_e32 v82, 1.0, v82
	v_rcp_f32_e32 v83, v82
	v_mul_f32_e32 v82, 0xbfb8aa3b, v84
	v_exp_f32_e32 v82, v82
	s_nop 0
	v_add_f32_e32 v82, 1.0, v82
	v_rcp_f32_e32 v82, v82
	s_nop 0
	v_pk_mul_f32 v[82:83], v[82:83], v[84:85]
	s_nop 0
	v_mul_f32_e32 v85, v82, v83
	s_nop 0
	v_cvt_pk_bf16_f32 v82, v112, v90
	s_nop 0
	v_cvt_pk_bf16_f32 v83, v88, v86
	v_add_u32_e32 v86, 48, v170
	v_ashrrev_i32_e32 v87, 31, v86
	s_nop 0
	v_cvt_pk_bf16_f32 v84, v98, v92
	s_nop 0
	v_cvt_pk_bf16_f32 v85, v94, v85
	global_store_dwordx4 v[106:107], v[82:85], off offset:3328
	v_lshlrev_b64 v[100:101], 12, v[86:87]
	s_nop 0
	v_lshlrev_b64 v[82:83], 10, v[86:87]
	v_mad_i64_i32 v[86:87], s[6:7], v86, s26, v[172:173]
	v_lshl_add_u64 v[86:87], v[86:87], 0, v[166:167]
	v_lshl_add_u64 v[82:83], s[0:1], 0, v[82:83]
	v_lshl_add_u64 v[102:103], v[86:87], 0, s[20:21]
	v_add_co_u32_e32 v86, vcc, s12, v86
	v_lshl_add_u64 v[98:99], v[82:83], 0, v[166:167]
	s_nop 0
	v_addc_co_u32_e32 v87, vcc, 0, v87, vcc
	global_load_dwordx4 v[82:85], v[98:99], off
	s_nop 0
	global_load_dwordx4 v[86:89], v[86:87], off offset:1296
	s_nop 0
	global_load_dwordx4 v[90:93], v[168:169], off offset:16
	global_load_dwordx4 v[94:97], v[168:169], off
	s_waitcnt vmcnt(0)
	v_lshlrev_b32_e32 v106, 16, v86
	v_add_f32_e32 v74, v74, v90
	v_add_f32_e32 v78, v78, v94
	v_mul_f32_e32 v78, 0xbfb8aa3b, v78
	v_exp_f32_e32 v78, v78
	v_mul_f32_e32 v74, 0xbfb8aa3b, v74
	v_exp_f32_e32 v74, v74
	v_lshlrev_b32_e32 v107, 16, v82
	v_add_f32_e32 v78, 1.0, v78
	v_rcp_f32_e32 v105, v78
	v_mul_f32_e32 v78, 0xbfb8aa3b, v106
	v_exp_f32_e32 v78, v78
	v_add_f32_e32 v74, 1.0, v74
	v_and_b32_e32 v94, 0xffff0000, v86
	v_add_f32_e32 v78, 1.0, v78
	v_rcp_f32_e32 v104, v78
	s_nop 0
	v_pk_mul_f32 v[104:105], v[104:105], v[106:107]
	v_lshlrev_b32_e32 v106, 16, v88
	v_mul_f32_e32 v108, v104, v105
	v_rcp_f32_e32 v105, v74
	v_mul_f32_e32 v74, 0xbfb8aa3b, v106
	v_exp_f32_e32 v74, v74
	v_lshlrev_b32_e32 v107, 16, v84
	v_add_f32_e32 v74, 1.0, v74
	v_rcp_f32_e32 v104, v74
	v_add_f32_e32 v74, v79, v95
	v_mul_f32_e32 v74, 0xbfb8aa3b, v74
	v_exp_f32_e32 v74, v74
	v_and_b32_e32 v95, 0xffff0000, v82
	v_pk_mul_f32 v[104:105], v[104:105], v[106:107]
	v_add_f32_e32 v74, 1.0, v74
	v_rcp_f32_e32 v79, v74
	v_mul_f32_e32 v74, 0xbfb8aa3b, v94
	v_exp_f32_e32 v74, v74
	v_mul_f32_e32 v104, v104, v105
	v_add_f32_e32 v74, 1.0, v74
	v_rcp_f32_e32 v78, v74
	v_add_f32_e32 v74, v75, v91
	v_mul_f32_e32 v74, 0xbfb8aa3b, v74
	v_exp_f32_e32 v74, v74
	v_pk_mul_f32 v[78:79], v[78:79], v[94:95]
	v_add_f32_e32 v74, 1.0, v74
	v_mul_f32_e32 v82, v78, v79
	v_and_b32_e32 v78, 0xffff0000, v88
	v_rcp_f32_e32 v75, v74
	v_mul_f32_e32 v74, 0xbfb8aa3b, v78
	v_exp_f32_e32 v74, v74
	v_and_b32_e32 v79, 0xffff0000, v84
	v_add_f32_e32 v74, 1.0, v74
	v_rcp_f32_e32 v74, v74
	s_nop 0
	v_pk_mul_f32 v[74:75], v[74:75], v[78:79]
	s_nop 0
	v_mul_f32_e32 v84, v74, v75
	v_add_f32_e32 v74, v80, v96
	v_mul_f32_e32 v74, 0xbfb8aa3b, v74
	v_exp_f32_e32 v74, v74
	v_lshlrev_b32_e32 v78, 16, v87
	v_lshlrev_b32_e32 v79, 16, v83
	v_add_f32_e32 v74, 1.0, v74
	v_rcp_f32_e32 v75, v74
	v_mul_f32_e32 v74, 0xbfb8aa3b, v78
	v_exp_f32_e32 v74, v74
	s_nop 0
	v_add_f32_e32 v74, 1.0, v74
	v_rcp_f32_e32 v74, v74
	s_nop 0
	v_pk_mul_f32 v[74:75], v[74:75], v[78:79]
	s_nop 0
	v_mul_f32_e32 v80, v74, v75
	v_add_f32_e32 v74, v76, v92
	v_mul_f32_e32 v74, 0xbfb8aa3b, v74
	v_exp_f32_e32 v74, v74
	v_lshlrev_b32_e32 v78, 16, v89
	v_lshlrev_b32_e32 v79, 16, v85
	v_and_b32_e32 v76, 0xffff0000, v89
	v_add_f32_e32 v74, 1.0, v74
	v_rcp_f32_e32 v75, v74
	v_mul_f32_e32 v74, 0xbfb8aa3b, v78
	v_exp_f32_e32 v74, v74
	s_nop 0
	v_add_f32_e32 v74, 1.0, v74
	v_rcp_f32_e32 v74, v74
	s_nop 0
	v_pk_mul_f32 v[74:75], v[74:75], v[78:79]
	s_nop 0
	v_mul_f32_e32 v86, v74, v75
	v_add_f32_e32 v74, v81, v97
	v_mul_f32_e32 v74, 0xbfb8aa3b, v74
	v_exp_f32_e32 v74, v74
	v_and_b32_e32 v78, 0xffff0000, v87
	v_and_b32_e32 v79, 0xffff0000, v83
	v_add_f32_e32 v74, 1.0, v74
	v_rcp_f32_e32 v75, v74
	v_mul_f32_e32 v74, 0xbfb8aa3b, v78
	v_exp_f32_e32 v74, v74
	s_nop 0
	v_add_f32_e32 v74, 1.0, v74
	v_rcp_f32_e32 v74, v74
	s_nop 0
	v_pk_mul_f32 v[74:75], v[74:75], v[78:79]
	s_nop 0
	v_mul_f32_e32 v78, v74, v75
	v_add_f32_e32 v74, v77, v93
	v_mul_f32_e32 v74, 0xbfb8aa3b, v74
	v_exp_f32_e32 v74, v74
	v_and_b32_e32 v77, 0xffff0000, v85
	v_add_f32_e32 v74, 1.0, v74
	v_rcp_f32_e32 v75, v74
	v_mul_f32_e32 v74, 0xbfb8aa3b, v76
	v_exp_f32_e32 v74, v74
	s_nop 0
	v_add_f32_e32 v74, 1.0, v74
	v_rcp_f32_e32 v74, v74
	s_nop 0
	v_pk_mul_f32 v[74:75], v[74:75], v[76:77]
	s_nop 0
	v_mul_f32_e32 v77, v74, v75
	v_lshl_add_u64 v[74:75], s[48:49], 0, v[100:101]
	v_lshl_add_u64 v[90:91], v[74:75], 0, v[166:167]
	s_nop 0
	v_cvt_pk_bf16_f32 v74, v108, v82
	s_nop 0
	v_cvt_pk_bf16_f32 v75, v80, v78
	s_nop 0
	v_cvt_pk_bf16_f32 v76, v104, v84
	s_nop 0
	v_cvt_pk_bf16_f32 v77, v86, v77
	global_store_dwordx4 v[90:91], v[74:77], off offset:3072
	global_load_dwordx4 v[78:81], v[98:99], off offset:256
	s_nop 0
	global_load_dwordx4 v[74:77], v[102:103], off offset:256
	global_load_dwordx4 v[82:85], v[168:169], off offset:528
	global_load_dwordx4 v[86:89], v[168:169], off offset:512
	s_waitcnt vmcnt(0)
; __device__ __forceinline__ float sigmoidf_(float x) { return __builtin_amdgcn_rcpf(1.f + __expf(-x)); }
; __device__ __forceinline__ float siluf_(float x) { return x * sigmoidf_(x); }
;     __device__ __forceinline__ void operator()(AccT& acc, const Unit& u, int wr, int wc, int fr, int fq) const {
;     ...
;             for (int m = 0; m < 4; ++m) { const size_t row = (size_t)(row0 + ai * 128 + m * 16);
; #pragma unroll
;                 for (int bj = 0; bj < 2; ++bj) { const int c = col0 + bj * 128;
;                     float y8[8], z8[8], o8[8]; ld8(yd + row * 512 + c, y8); ld8(proj + row * NP + O_DZ + c, z8);
;                     const f32x4 b0 = *(const f32x4*)(gb + c), b1 = *(const f32x4*)(gb + c + 4);
; #pragma unroll
;                     for (int e = 0; e < 4; ++e) { o8[e] = y8[e] * sigmoidf_(acc[ai][bj][m][0][e] + b0[e]) * siluf_(z8[e]); o8[4 + e] = y8[4 + e] * sigmoidf_(acc[ai][bj][m][1][e] + b1[e]) * siluf_(z8[4 + e]); }
;                     st8(ys + row * DM + 1536 + c, o8); } }
	v_lshlrev_b32_e32 v95, 16, v78
	v_lshlrev_b32_e32 v94, 16, v74
	v_add_f32_e32 v66, v66, v82
	v_add_f32_e32 v70, v70, v86
	v_mul_f32_e32 v70, 0xbfb8aa3b, v70
	v_exp_f32_e32 v70, v70
	v_mul_f32_e32 v66, 0xbfb8aa3b, v66
	v_exp_f32_e32 v66, v66
	v_and_b32_e32 v86, 0xffff0000, v74
	v_add_f32_e32 v70, 1.0, v70
	v_rcp_f32_e32 v93, v70
	v_mul_f32_e32 v70, 0xbfb8aa3b, v94
	v_exp_f32_e32 v70, v70
	v_add_f32_e32 v66, 1.0, v66
	v_add_f32_e32 v70, 1.0, v70
	v_rcp_f32_e32 v92, v70
	s_nop 0
	v_pk_mul_f32 v[92:93], v[92:93], v[94:95]
	v_lshlrev_b32_e32 v94, 16, v76
	v_mul_f32_e32 v96, v92, v93
	v_rcp_f32_e32 v93, v66
	v_mul_f32_e32 v66, 0xbfb8aa3b, v94
	v_exp_f32_e32 v66, v66
	v_lshlrev_b32_e32 v95, 16, v80
	v_add_f32_e32 v66, 1.0, v66
	v_rcp_f32_e32 v92, v66
	v_add_f32_e32 v66, v71, v87
	v_mul_f32_e32 v66, 0xbfb8aa3b, v66
	v_exp_f32_e32 v66, v66
	v_and_b32_e32 v87, 0xffff0000, v78
	v_pk_mul_f32 v[92:93], v[92:93], v[94:95]
	v_add_f32_e32 v66, 1.0, v66
	v_rcp_f32_e32 v71, v66
	v_mul_f32_e32 v66, 0xbfb8aa3b, v86
	v_exp_f32_e32 v66, v66
	v_mul_f32_e32 v82, v92, v93
	v_add_f32_e32 v66, 1.0, v66
	v_rcp_f32_e32 v70, v66
	v_add_f32_e32 v66, v67, v83
	v_mul_f32_e32 v66, 0xbfb8aa3b, v66
	v_exp_f32_e32 v66, v66
	v_pk_mul_f32 v[70:71], v[70:71], v[86:87]
	v_add_f32_e32 v66, 1.0, v66
	v_mul_f32_e32 v74, v70, v71
	v_and_b32_e32 v70, 0xffff0000, v76
	v_rcp_f32_e32 v67, v66
	v_mul_f32_e32 v66, 0xbfb8aa3b, v70
	v_exp_f32_e32 v66, v66
	v_and_b32_e32 v71, 0xffff0000, v80
	v_add_f32_e32 v66, 1.0, v66
	v_rcp_f32_e32 v66, v66
	s_nop 0
	v_pk_mul_f32 v[66:67], v[66:67], v[70:71]
	s_nop 0
	v_mul_f32_e32 v76, v66, v67
	v_add_f32_e32 v66, v72, v88
	v_mul_f32_e32 v66, 0xbfb8aa3b, v66
	v_exp_f32_e32 v66, v66
	v_lshlrev_b32_e32 v70, 16, v75
	v_lshlrev_b32_e32 v71, 16, v79
	v_add_f32_e32 v66, 1.0, v66
	v_rcp_f32_e32 v67, v66
	v_mul_f32_e32 v66, 0xbfb8aa3b, v70
	v_exp_f32_e32 v66, v66
	s_nop 0
	v_add_f32_e32 v66, 1.0, v66
	v_rcp_f32_e32 v66, v66
	s_nop 0
	v_pk_mul_f32 v[66:67], v[66:67], v[70:71]
	s_nop 0
	v_mul_f32_e32 v72, v66, v67
	v_add_f32_e32 v66, v68, v84
	v_mul_f32_e32 v66, 0xbfb8aa3b, v66
	v_exp_f32_e32 v66, v66
	v_lshlrev_b32_e32 v70, 16, v77
	v_lshlrev_b32_e32 v71, 16, v81
	v_and_b32_e32 v68, 0xffff0000, v77
	v_add_f32_e32 v66, 1.0, v66
	v_rcp_f32_e32 v67, v66
	v_mul_f32_e32 v66, 0xbfb8aa3b, v70
	v_exp_f32_e32 v66, v66
	s_nop 0
	v_add_f32_e32 v66, 1.0, v66
	v_rcp_f32_e32 v66, v66
	s_nop 0
	v_pk_mul_f32 v[66:67], v[66:67], v[70:71]
	s_nop 0
	v_mul_f32_e32 v78, v66, v67
	v_add_f32_e32 v66, v73, v89
	v_mul_f32_e32 v66, 0xbfb8aa3b, v66
	v_exp_f32_e32 v66, v66
	v_and_b32_e32 v70, 0xffff0000, v75
	v_and_b32_e32 v71, 0xffff0000, v79
	v_add_f32_e32 v66, 1.0, v66
	v_rcp_f32_e32 v67, v66
	v_mul_f32_e32 v66, 0xbfb8aa3b, v70
	v_exp_f32_e32 v66, v66
	s_nop 0
	v_add_f32_e32 v66, 1.0, v66
	v_rcp_f32_e32 v66, v66
	s_nop 0
	v_pk_mul_f32 v[66:67], v[66:67], v[70:71]
	s_nop 0
	v_mul_f32_e32 v70, v66, v67
	v_add_f32_e32 v66, v69, v85
	v_mul_f32_e32 v66, 0xbfb8aa3b, v66
	v_exp_f32_e32 v66, v66
	v_and_b32_e32 v69, 0xffff0000, v81
	v_add_f32_e32 v66, 1.0, v66
	v_rcp_f32_e32 v67, v66
	v_mul_f32_e32 v66, 0xbfb8aa3b, v68
	v_exp_f32_e32 v66, v66
	s_nop 0
	v_add_f32_e32 v66, 1.0, v66
	v_rcp_f32_e32 v66, v66
	s_nop 0
	v_pk_mul_f32 v[66:67], v[66:67], v[68:69]
	s_nop 0
	v_mul_f32_e32 v69, v66, v67
	s_nop 0
	v_cvt_pk_bf16_f32 v66, v96, v74
	s_nop 0
	v_cvt_pk_bf16_f32 v67, v72, v70
	v_add_u32_e32 v70, 0x80, v170
	v_ashrrev_i32_e32 v71, 31, v70
	s_nop 0
	v_cvt_pk_bf16_f32 v68, v82, v76
	s_nop 0
	v_cvt_pk_bf16_f32 v69, v78, v69
	global_store_dwordx4 v[90:91], v[66:69], off offset:3328
	v_lshlrev_b64 v[84:85], 12, v[70:71]
	s_nop 0
	v_lshlrev_b64 v[66:67], 10, v[70:71]
	v_mad_i64_i32 v[70:71], s[6:7], v70, s26, v[172:173]
	v_lshl_add_u64 v[70:71], v[70:71], 0, v[166:167]
	v_lshl_add_u64 v[66:67], s[0:1], 0, v[66:67]
	v_lshl_add_u64 v[86:87], v[70:71], 0, s[20:21]
	v_add_co_u32_e32 v70, vcc, s12, v70
	v_lshl_add_u64 v[82:83], v[66:67], 0, v[166:167]
	s_nop 0
	v_addc_co_u32_e32 v71, vcc, 0, v71, vcc
	global_load_dwordx4 v[66:69], v[82:83], off
	s_nop 0
	global_load_dwordx4 v[70:73], v[70:71], off offset:1296
	s_nop 0
	global_load_dwordx4 v[74:77], v[168:169], off offset:16
	global_load_dwordx4 v[78:81], v[168:169], off
	s_waitcnt vmcnt(0)
; __device__ __forceinline__ float sigmoidf_(float x) { return __builtin_amdgcn_rcpf(1.f + __expf(-x)); }
; __device__ __forceinline__ float siluf_(float x) { return x * sigmoidf_(x); }
;     __device__ __forceinline__ void operator()(AccT& acc, const Unit& u, int wr, int wc, int fr, int fq) const {
;     ...
;             for (int m = 0; m < 4; ++m) { const size_t row = (size_t)(row0 + ai * 128 + m * 16);
; #pragma unroll
;                 for (int bj = 0; bj < 2; ++bj) { const int c = col0 + bj * 128;
;                     float y8[8], z8[8], o8[8]; ld8(yd + row * 512 + c, y8); ld8(proj + row * NP + O_DZ + c, z8);
;                     const f32x4 b0 = *(const f32x4*)(gb + c), b1 = *(const f32x4*)(gb + c + 4);
; #pragma unroll
;                     for (int e = 0; e < 4; ++e) { o8[e] = y8[e] * sigmoidf_(acc[ai][bj][m][0][e] + b0[e]) * siluf_(z8[e]); o8[4 + e] = y8[4 + e] * sigmoidf_(acc[ai][bj][m][1][e] + b1[e]) * siluf_(z8[4 + e]); }
;                     st8(ys + row * DM + 1536 + c, o8); } }
	v_lshlrev_b32_e32 v90, 16, v70
	v_add_f32_e32 v58, v58, v74
	v_add_f32_e32 v62, v62, v78
	v_mul_f32_e32 v62, 0xbfb8aa3b, v62
	v_exp_f32_e32 v62, v62
	v_mul_f32_e32 v58, 0xbfb8aa3b, v58
	v_exp_f32_e32 v58, v58
	v_lshlrev_b32_e32 v91, 16, v66
	v_add_f32_e32 v62, 1.0, v62
	v_rcp_f32_e32 v89, v62
	v_mul_f32_e32 v62, 0xbfb8aa3b, v90
	v_exp_f32_e32 v62, v62
	v_add_f32_e32 v58, 1.0, v58
	v_and_b32_e32 v78, 0xffff0000, v70
	v_add_f32_e32 v62, 1.0, v62
	v_rcp_f32_e32 v88, v62
	s_nop 0
	v_pk_mul_f32 v[88:89], v[88:89], v[90:91]
	v_lshlrev_b32_e32 v90, 16, v72
	v_mul_f32_e32 v92, v88, v89
	v_rcp_f32_e32 v89, v58
	v_mul_f32_e32 v58, 0xbfb8aa3b, v90
	v_exp_f32_e32 v58, v58
	v_lshlrev_b32_e32 v91, 16, v68
	v_add_f32_e32 v58, 1.0, v58
	v_rcp_f32_e32 v88, v58
	v_add_f32_e32 v58, v63, v79
	v_mul_f32_e32 v58, 0xbfb8aa3b, v58
	v_exp_f32_e32 v58, v58
	v_and_b32_e32 v79, 0xffff0000, v66
	v_pk_mul_f32 v[88:89], v[88:89], v[90:91]
	v_add_f32_e32 v58, 1.0, v58
	v_rcp_f32_e32 v63, v58
	v_mul_f32_e32 v58, 0xbfb8aa3b, v78
	v_exp_f32_e32 v58, v58
	v_mul_f32_e32 v88, v88, v89
	v_add_f32_e32 v58, 1.0, v58
	v_rcp_f32_e32 v62, v58
	v_add_f32_e32 v58, v59, v75
	v_mul_f32_e32 v58, 0xbfb8aa3b, v58
	v_exp_f32_e32 v58, v58
	v_pk_mul_f32 v[62:63], v[62:63], v[78:79]
	v_add_f32_e32 v58, 1.0, v58
	v_mul_f32_e32 v66, v62, v63
	v_and_b32_e32 v62, 0xffff0000, v72
	v_rcp_f32_e32 v59, v58
	v_mul_f32_e32 v58, 0xbfb8aa3b, v62
	v_exp_f32_e32 v58, v58
	v_and_b32_e32 v63, 0xffff0000, v68
	v_add_f32_e32 v58, 1.0, v58
	v_rcp_f32_e32 v58, v58
	s_nop 0
	v_pk_mul_f32 v[58:59], v[58:59], v[62:63]
	s_nop 0
	v_mul_f32_e32 v68, v58, v59
	v_add_f32_e32 v58, v64, v80
	v_mul_f32_e32 v58, 0xbfb8aa3b, v58
	v_exp_f32_e32 v58, v58
	v_lshlrev_b32_e32 v62, 16, v71
	v_lshlrev_b32_e32 v63, 16, v67
	v_add_f32_e32 v58, 1.0, v58
	v_rcp_f32_e32 v59, v58
	v_mul_f32_e32 v58, 0xbfb8aa3b, v62
	v_exp_f32_e32 v58, v58
	s_nop 0
	v_add_f32_e32 v58, 1.0, v58
	v_rcp_f32_e32 v58, v58
	s_nop 0
	v_pk_mul_f32 v[58:59], v[58:59], v[62:63]
	s_nop 0
	v_mul_f32_e32 v64, v58, v59
	v_add_f32_e32 v58, v60, v76
	v_mul_f32_e32 v58, 0xbfb8aa3b, v58
	v_exp_f32_e32 v58, v58
	v_lshlrev_b32_e32 v62, 16, v73
	v_lshlrev_b32_e32 v63, 16, v69
	v_and_b32_e32 v60, 0xffff0000, v73
	v_add_f32_e32 v58, 1.0, v58
	v_rcp_f32_e32 v59, v58
	v_mul_f32_e32 v58, 0xbfb8aa3b, v62
	v_exp_f32_e32 v58, v58
	s_nop 0
	v_add_f32_e32 v58, 1.0, v58
	v_rcp_f32_e32 v58, v58
	s_nop 0
	v_pk_mul_f32 v[58:59], v[58:59], v[62:63]
	s_nop 0
	v_mul_f32_e32 v70, v58, v59
	v_add_f32_e32 v58, v65, v81
	v_mul_f32_e32 v58, 0xbfb8aa3b, v58
	v_exp_f32_e32 v58, v58
	v_and_b32_e32 v62, 0xffff0000, v71
	v_and_b32_e32 v63, 0xffff0000, v67
	v_add_f32_e32 v58, 1.0, v58
	v_rcp_f32_e32 v59, v58
	v_mul_f32_e32 v58, 0xbfb8aa3b, v62
	v_exp_f32_e32 v58, v58
	s_nop 0
	v_add_f32_e32 v58, 1.0, v58
	v_rcp_f32_e32 v58, v58
	s_nop 0
	v_pk_mul_f32 v[58:59], v[58:59], v[62:63]
	s_nop 0
	v_mul_f32_e32 v62, v58, v59
	v_add_f32_e32 v58, v61, v77
	v_mul_f32_e32 v58, 0xbfb8aa3b, v58
	v_exp_f32_e32 v58, v58
	v_and_b32_e32 v61, 0xffff0000, v69
	v_add_f32_e32 v58, 1.0, v58
	v_rcp_f32_e32 v59, v58
	v_mul_f32_e32 v58, 0xbfb8aa3b, v60
	v_exp_f32_e32 v58, v58
	s_nop 0
	v_add_f32_e32 v58, 1.0, v58
	v_rcp_f32_e32 v58, v58
	s_nop 0
	v_pk_mul_f32 v[58:59], v[58:59], v[60:61]
	s_nop 0
	v_mul_f32_e32 v61, v58, v59
	v_lshl_add_u64 v[58:59], s[48:49], 0, v[84:85]
	v_lshl_add_u64 v[74:75], v[58:59], 0, v[166:167]
	s_nop 0
	v_cvt_pk_bf16_f32 v58, v92, v66
	s_nop 0
	v_cvt_pk_bf16_f32 v59, v64, v62
	s_nop 0
	v_cvt_pk_bf16_f32 v60, v88, v68
	s_nop 0
	v_cvt_pk_bf16_f32 v61, v70, v61
	global_store_dwordx4 v[74:75], v[58:61], off offset:3072
	global_load_dwordx4 v[62:65], v[82:83], off offset:256
	s_nop 0
	global_load_dwordx4 v[58:61], v[86:87], off offset:256
	global_load_dwordx4 v[66:69], v[168:169], off offset:528
	global_load_dwordx4 v[70:73], v[168:169], off offset:512
	s_waitcnt vmcnt(0)
	v_lshlrev_b32_e32 v79, 16, v62
	v_lshlrev_b32_e32 v78, 16, v58
	v_add_f32_e32 v50, v50, v66
	v_add_f32_e32 v54, v54, v70
	v_mul_f32_e32 v54, 0xbfb8aa3b, v54
	v_exp_f32_e32 v54, v54
	v_mul_f32_e32 v50, 0xbfb8aa3b, v50
	v_exp_f32_e32 v50, v50
	v_and_b32_e32 v70, 0xffff0000, v58
	v_add_f32_e32 v54, 1.0, v54
	v_rcp_f32_e32 v77, v54
	v_mul_f32_e32 v54, 0xbfb8aa3b, v78
	v_exp_f32_e32 v54, v54
	v_add_f32_e32 v50, 1.0, v50
	v_add_f32_e32 v54, 1.0, v54
	v_rcp_f32_e32 v76, v54
	s_nop 0
	v_pk_mul_f32 v[76:77], v[76:77], v[78:79]
	v_lshlrev_b32_e32 v78, 16, v60
	v_mul_f32_e32 v80, v76, v77
	v_rcp_f32_e32 v77, v50
	v_mul_f32_e32 v50, 0xbfb8aa3b, v78
	v_exp_f32_e32 v50, v50
	v_lshlrev_b32_e32 v79, 16, v64
	v_add_f32_e32 v50, 1.0, v50
	v_rcp_f32_e32 v76, v50
	v_add_f32_e32 v50, v55, v71
	v_mul_f32_e32 v50, 0xbfb8aa3b, v50
	v_exp_f32_e32 v50, v50
	v_and_b32_e32 v71, 0xffff0000, v62
	v_pk_mul_f32 v[76:77], v[76:77], v[78:79]
	v_add_f32_e32 v50, 1.0, v50
	v_rcp_f32_e32 v55, v50
	v_mul_f32_e32 v50, 0xbfb8aa3b, v70
	v_exp_f32_e32 v50, v50
	v_mul_f32_e32 v66, v76, v77
	v_add_f32_e32 v50, 1.0, v50
	v_rcp_f32_e32 v54, v50
	v_add_f32_e32 v50, v51, v67
	v_mul_f32_e32 v50, 0xbfb8aa3b, v50
	v_exp_f32_e32 v50, v50
	v_pk_mul_f32 v[54:55], v[54:55], v[70:71]
	v_add_f32_e32 v50, 1.0, v50
	v_mul_f32_e32 v58, v54, v55
	v_and_b32_e32 v54, 0xffff0000, v60
	v_rcp_f32_e32 v51, v50
	v_mul_f32_e32 v50, 0xbfb8aa3b, v54
	v_exp_f32_e32 v50, v50
	v_and_b32_e32 v55, 0xffff0000, v64
	v_add_f32_e32 v50, 1.0, v50
	v_rcp_f32_e32 v50, v50
	s_nop 0
	v_pk_mul_f32 v[50:51], v[50:51], v[54:55]
	s_nop 0
	v_mul_f32_e32 v60, v50, v51
	v_add_f32_e32 v50, v56, v72
	v_mul_f32_e32 v50, 0xbfb8aa3b, v50
	v_exp_f32_e32 v50, v50
	v_lshlrev_b32_e32 v54, 16, v59
	v_lshlrev_b32_e32 v55, 16, v63
; __device__ __forceinline__ float sigmoidf_(float x) { return __builtin_amdgcn_rcpf(1.f + __expf(-x)); }
; __device__ __forceinline__ float siluf_(float x) { return x * sigmoidf_(x); }
;     __device__ __forceinline__ void operator()(AccT& acc, const Unit& u, int wr, int wc, int fr, int fq) const {
;     ...
;             for (int m = 0; m < 4; ++m) { const size_t row = (size_t)(row0 + ai * 128 + m * 16);
; #pragma unroll
;                 for (int bj = 0; bj < 2; ++bj) { const int c = col0 + bj * 128;
;                     float y8[8], z8[8], o8[8]; ld8(yd + row * 512 + c, y8); ld8(proj + row * NP + O_DZ + c, z8);
;                     const f32x4 b0 = *(const f32x4*)(gb + c), b1 = *(const f32x4*)(gb + c + 4);
; #pragma unroll
;                     for (int e = 0; e < 4; ++e) { o8[e] = y8[e] * sigmoidf_(acc[ai][bj][m][0][e] + b0[e]) * siluf_(z8[e]); o8[4 + e] = y8[4 + e] * sigmoidf_(acc[ai][bj][m][1][e] + b1[e]) * siluf_(z8[4 + e]); }
;                     st8(ys + row * DM + 1536 + c, o8); } }
	v_add_f32_e32 v50, 1.0, v50
	v_rcp_f32_e32 v51, v50
	v_mul_f32_e32 v50, 0xbfb8aa3b, v54
	v_exp_f32_e32 v50, v50
	s_nop 0
	v_add_f32_e32 v50, 1.0, v50
	v_rcp_f32_e32 v50, v50
	s_nop 0
	v_pk_mul_f32 v[50:51], v[50:51], v[54:55]
	s_nop 0
	v_mul_f32_e32 v56, v50, v51
	v_add_f32_e32 v50, v52, v68
	v_mul_f32_e32 v50, 0xbfb8aa3b, v50
	v_exp_f32_e32 v50, v50
	v_lshlrev_b32_e32 v54, 16, v61
	v_lshlrev_b32_e32 v55, 16, v65
	v_and_b32_e32 v52, 0xffff0000, v61
	v_add_f32_e32 v50, 1.0, v50
	v_rcp_f32_e32 v51, v50
	v_mul_f32_e32 v50, 0xbfb8aa3b, v54
	v_exp_f32_e32 v50, v50
	s_nop 0
	v_add_f32_e32 v50, 1.0, v50
	v_rcp_f32_e32 v50, v50
	s_nop 0
	v_pk_mul_f32 v[50:51], v[50:51], v[54:55]
	s_nop 0
	v_mul_f32_e32 v62, v50, v51
	v_add_f32_e32 v50, v57, v73
	v_mul_f32_e32 v50, 0xbfb8aa3b, v50
	v_exp_f32_e32 v50, v50
	v_and_b32_e32 v54, 0xffff0000, v59
	v_and_b32_e32 v55, 0xffff0000, v63
	v_add_f32_e32 v50, 1.0, v50
	v_rcp_f32_e32 v51, v50
	v_mul_f32_e32 v50, 0xbfb8aa3b, v54
	v_exp_f32_e32 v50, v50
	s_nop 0
	v_add_f32_e32 v50, 1.0, v50
	v_rcp_f32_e32 v50, v50
	s_nop 0
	v_pk_mul_f32 v[50:51], v[50:51], v[54:55]
	s_nop 0
	v_mul_f32_e32 v54, v50, v51
	v_add_f32_e32 v50, v53, v69
	v_mul_f32_e32 v50, 0xbfb8aa3b, v50
	v_exp_f32_e32 v50, v50
	v_and_b32_e32 v53, 0xffff0000, v65
	v_add_f32_e32 v50, 1.0, v50
	v_rcp_f32_e32 v51, v50
	v_mul_f32_e32 v50, 0xbfb8aa3b, v52
	v_exp_f32_e32 v50, v50
	s_nop 0
	v_add_f32_e32 v50, 1.0, v50
	v_rcp_f32_e32 v50, v50
	s_nop 0
	v_pk_mul_f32 v[50:51], v[50:51], v[52:53]
	s_nop 0
	v_mul_f32_e32 v53, v50, v51
	s_nop 0
	v_cvt_pk_bf16_f32 v50, v80, v58
	s_nop 0
	v_cvt_pk_bf16_f32 v51, v56, v54
	v_add_u32_e32 v54, 0x90, v170
	v_ashrrev_i32_e32 v55, 31, v54
	s_nop 0
	v_cvt_pk_bf16_f32 v52, v66, v60
	s_nop 0
	v_cvt_pk_bf16_f32 v53, v62, v53
	global_store_dwordx4 v[74:75], v[50:53], off offset:3328
	v_lshlrev_b64 v[68:69], 12, v[54:55]
	s_nop 0
	v_lshlrev_b64 v[50:51], 10, v[54:55]
	v_mad_i64_i32 v[54:55], s[6:7], v54, s26, v[172:173]
	v_lshl_add_u64 v[54:55], v[54:55], 0, v[166:167]
	v_lshl_add_u64 v[50:51], s[0:1], 0, v[50:51]
	v_lshl_add_u64 v[70:71], v[54:55], 0, s[20:21]
	v_add_co_u32_e32 v54, vcc, s12, v54
	v_lshl_add_u64 v[66:67], v[50:51], 0, v[166:167]
	s_nop 0
	v_addc_co_u32_e32 v55, vcc, 0, v55, vcc
	global_load_dwordx4 v[50:53], v[66:67], off
	s_nop 0
	global_load_dwordx4 v[54:57], v[54:55], off offset:1296
	s_nop 0
	global_load_dwordx4 v[58:61], v[168:169], off offset:16
	global_load_dwordx4 v[62:65], v[168:169], off
	s_waitcnt vmcnt(0)
	v_lshlrev_b32_e32 v74, 16, v54
	v_add_f32_e32 v42, v42, v58
	v_add_f32_e32 v46, v46, v62
	v_mul_f32_e32 v46, 0xbfb8aa3b, v46
	v_exp_f32_e32 v46, v46
	v_mul_f32_e32 v42, 0xbfb8aa3b, v42
	v_exp_f32_e32 v42, v42
	v_lshlrev_b32_e32 v75, 16, v50
	v_add_f32_e32 v46, 1.0, v46
	v_rcp_f32_e32 v73, v46
	v_mul_f32_e32 v46, 0xbfb8aa3b, v74
	v_exp_f32_e32 v46, v46
	v_add_f32_e32 v42, 1.0, v42
	v_and_b32_e32 v62, 0xffff0000, v54
	v_add_f32_e32 v46, 1.0, v46
	v_rcp_f32_e32 v72, v46
	s_nop 0
	v_pk_mul_f32 v[72:73], v[72:73], v[74:75]
	v_lshlrev_b32_e32 v74, 16, v56
	v_mul_f32_e32 v76, v72, v73
	v_rcp_f32_e32 v73, v42
	v_mul_f32_e32 v42, 0xbfb8aa3b, v74
	v_exp_f32_e32 v42, v42
	v_lshlrev_b32_e32 v75, 16, v52
	v_add_f32_e32 v42, 1.0, v42
	v_rcp_f32_e32 v72, v42
	v_add_f32_e32 v42, v47, v63
	v_mul_f32_e32 v42, 0xbfb8aa3b, v42
	v_exp_f32_e32 v42, v42
	v_and_b32_e32 v63, 0xffff0000, v50
	v_pk_mul_f32 v[72:73], v[72:73], v[74:75]
	v_add_f32_e32 v42, 1.0, v42
	v_rcp_f32_e32 v47, v42
	v_mul_f32_e32 v42, 0xbfb8aa3b, v62
	v_exp_f32_e32 v42, v42
	v_mul_f32_e32 v72, v72, v73
	v_add_f32_e32 v42, 1.0, v42
	v_rcp_f32_e32 v46, v42
	v_add_f32_e32 v42, v43, v59
	v_mul_f32_e32 v42, 0xbfb8aa3b, v42
	v_exp_f32_e32 v42, v42
	v_pk_mul_f32 v[46:47], v[46:47], v[62:63]
	v_add_f32_e32 v42, 1.0, v42
	v_mul_f32_e32 v50, v46, v47
	v_and_b32_e32 v46, 0xffff0000, v56
	v_rcp_f32_e32 v43, v42
	v_mul_f32_e32 v42, 0xbfb8aa3b, v46
	v_exp_f32_e32 v42, v42
	v_and_b32_e32 v47, 0xffff0000, v52
	v_add_f32_e32 v42, 1.0, v42
	v_rcp_f32_e32 v42, v42
	s_nop 0
	v_pk_mul_f32 v[42:43], v[42:43], v[46:47]
	s_nop 0
	v_mul_f32_e32 v52, v42, v43
	v_add_f32_e32 v42, v48, v64
	v_mul_f32_e32 v42, 0xbfb8aa3b, v42
	v_exp_f32_e32 v42, v42
	v_lshlrev_b32_e32 v46, 16, v55
	v_lshlrev_b32_e32 v47, 16, v51
	v_add_f32_e32 v42, 1.0, v42
	v_rcp_f32_e32 v43, v42
	v_mul_f32_e32 v42, 0xbfb8aa3b, v46
	v_exp_f32_e32 v42, v42
	s_nop 0
	v_add_f32_e32 v42, 1.0, v42
	v_rcp_f32_e32 v42, v42
	s_nop 0
	v_pk_mul_f32 v[42:43], v[42:43], v[46:47]
	s_nop 0
	v_mul_f32_e32 v48, v42, v43
	v_add_f32_e32 v42, v44, v60
	v_mul_f32_e32 v42, 0xbfb8aa3b, v42
	v_exp_f32_e32 v42, v42
	v_lshlrev_b32_e32 v46, 16, v57
	v_lshlrev_b32_e32 v47, 16, v53
	v_and_b32_e32 v44, 0xffff0000, v57
	v_add_f32_e32 v42, 1.0, v42
	v_rcp_f32_e32 v43, v42
	v_mul_f32_e32 v42, 0xbfb8aa3b, v46
	v_exp_f32_e32 v42, v42
	s_nop 0
	v_add_f32_e32 v42, 1.0, v42
	v_rcp_f32_e32 v42, v42
	s_nop 0
	v_pk_mul_f32 v[42:43], v[42:43], v[46:47]
	s_nop 0
	v_mul_f32_e32 v54, v42, v43
	v_add_f32_e32 v42, v49, v65
	v_mul_f32_e32 v42, 0xbfb8aa3b, v42
	v_exp_f32_e32 v42, v42
	v_and_b32_e32 v46, 0xffff0000, v55
	v_and_b32_e32 v47, 0xffff0000, v51
	v_add_f32_e32 v42, 1.0, v42
	v_rcp_f32_e32 v43, v42
	v_mul_f32_e32 v42, 0xbfb8aa3b, v46
	v_exp_f32_e32 v42, v42
	s_nop 0
	v_add_f32_e32 v42, 1.0, v42
	v_rcp_f32_e32 v42, v42
	s_nop 0
	v_pk_mul_f32 v[42:43], v[42:43], v[46:47]
	s_nop 0
	v_mul_f32_e32 v46, v42, v43
	v_add_f32_e32 v42, v45, v61
	v_mul_f32_e32 v42, 0xbfb8aa3b, v42
	v_exp_f32_e32 v42, v42
	v_and_b32_e32 v45, 0xffff0000, v53
	v_add_f32_e32 v42, 1.0, v42
	v_rcp_f32_e32 v43, v42
	v_mul_f32_e32 v42, 0xbfb8aa3b, v44
	v_exp_f32_e32 v42, v42
	s_nop 0
	v_add_f32_e32 v42, 1.0, v42
	v_rcp_f32_e32 v42, v42
	s_nop 0
	v_pk_mul_f32 v[42:43], v[42:43], v[44:45]
	s_nop 0
	v_mul_f32_e32 v45, v42, v43
	v_lshl_add_u64 v[42:43], s[48:49], 0, v[68:69]
	v_lshl_add_u64 v[58:59], v[42:43], 0, v[166:167]
	s_nop 0
	v_cvt_pk_bf16_f32 v42, v76, v50
	s_nop 0
	v_cvt_pk_bf16_f32 v43, v48, v46
	s_nop 0
	v_cvt_pk_bf16_f32 v44, v72, v52
	s_nop 0
	v_cvt_pk_bf16_f32 v45, v54, v45
	global_store_dwordx4 v[58:59], v[42:45], off offset:3072
	global_load_dwordx4 v[46:49], v[66:67], off offset:256
	s_nop 0
	global_load_dwordx4 v[42:45], v[70:71], off offset:256
	global_load_dwordx4 v[50:53], v[168:169], off offset:528
	global_load_dwordx4 v[54:57], v[168:169], off offset:512
	s_waitcnt vmcnt(0)
; __device__ __forceinline__ float sigmoidf_(float x) { return __builtin_amdgcn_rcpf(1.f + __expf(-x)); }
; __device__ __forceinline__ float siluf_(float x) { return x * sigmoidf_(x); }
;     __device__ __forceinline__ void operator()(AccT& acc, const Unit& u, int wr, int wc, int fr, int fq) const {
;     ...
;             for (int m = 0; m < 4; ++m) { const size_t row = (size_t)(row0 + ai * 128 + m * 16);
; #pragma unroll
;                 for (int bj = 0; bj < 2; ++bj) { const int c = col0 + bj * 128;
;                     float y8[8], z8[8], o8[8]; ld8(yd + row * 512 + c, y8); ld8(proj + row * NP + O_DZ + c, z8);
;                     const f32x4 b0 = *(const f32x4*)(gb + c), b1 = *(const f32x4*)(gb + c + 4);
; #pragma unroll
;                     for (int e = 0; e < 4; ++e) { o8[e] = y8[e] * sigmoidf_(acc[ai][bj][m][0][e] + b0[e]) * siluf_(z8[e]); o8[4 + e] = y8[4 + e] * sigmoidf_(acc[ai][bj][m][1][e] + b1[e]) * siluf_(z8[4 + e]); }
;                     st8(ys + row * DM + 1536 + c, o8); } }
	v_lshlrev_b32_e32 v63, 16, v46
	v_lshlrev_b32_e32 v62, 16, v42
	v_add_f32_e32 v34, v34, v50
	v_add_f32_e32 v38, v38, v54
	v_mul_f32_e32 v38, 0xbfb8aa3b, v38
	v_exp_f32_e32 v38, v38
	v_mul_f32_e32 v34, 0xbfb8aa3b, v34
	v_exp_f32_e32 v34, v34
	v_and_b32_e32 v54, 0xffff0000, v42
	v_add_f32_e32 v38, 1.0, v38
	v_rcp_f32_e32 v61, v38
	v_mul_f32_e32 v38, 0xbfb8aa3b, v62
	v_exp_f32_e32 v38, v38
	v_add_f32_e32 v34, 1.0, v34
	v_add_f32_e32 v38, 1.0, v38
	v_rcp_f32_e32 v60, v38
	s_nop 0
	v_pk_mul_f32 v[60:61], v[60:61], v[62:63]
	v_lshlrev_b32_e32 v62, 16, v44
	v_mul_f32_e32 v64, v60, v61
	v_rcp_f32_e32 v61, v34
	v_mul_f32_e32 v34, 0xbfb8aa3b, v62
	v_exp_f32_e32 v34, v34
	v_lshlrev_b32_e32 v63, 16, v48
	v_add_f32_e32 v34, 1.0, v34
	v_rcp_f32_e32 v60, v34
	v_add_f32_e32 v34, v39, v55
	v_mul_f32_e32 v34, 0xbfb8aa3b, v34
	v_exp_f32_e32 v34, v34
	v_and_b32_e32 v55, 0xffff0000, v46
	v_pk_mul_f32 v[60:61], v[60:61], v[62:63]
	v_add_f32_e32 v34, 1.0, v34
	v_rcp_f32_e32 v39, v34
	v_mul_f32_e32 v34, 0xbfb8aa3b, v54
	v_exp_f32_e32 v34, v34
	v_mul_f32_e32 v50, v60, v61
	v_add_f32_e32 v34, 1.0, v34
	v_rcp_f32_e32 v38, v34
	v_add_f32_e32 v34, v35, v51
	v_mul_f32_e32 v34, 0xbfb8aa3b, v34
	v_exp_f32_e32 v34, v34
	v_pk_mul_f32 v[38:39], v[38:39], v[54:55]
	v_add_f32_e32 v34, 1.0, v34
	v_mul_f32_e32 v42, v38, v39
	v_and_b32_e32 v38, 0xffff0000, v44
	v_rcp_f32_e32 v35, v34
	v_mul_f32_e32 v34, 0xbfb8aa3b, v38
	v_exp_f32_e32 v34, v34
	v_and_b32_e32 v39, 0xffff0000, v48
	v_add_f32_e32 v34, 1.0, v34
	v_rcp_f32_e32 v34, v34
	s_nop 0
	v_pk_mul_f32 v[34:35], v[34:35], v[38:39]
	s_nop 0
	v_mul_f32_e32 v44, v34, v35
	v_add_f32_e32 v34, v40, v56
	v_mul_f32_e32 v34, 0xbfb8aa3b, v34
	v_exp_f32_e32 v34, v34
	v_lshlrev_b32_e32 v38, 16, v43
	v_lshlrev_b32_e32 v39, 16, v47
	v_add_f32_e32 v34, 1.0, v34
	v_rcp_f32_e32 v35, v34
	v_mul_f32_e32 v34, 0xbfb8aa3b, v38
	v_exp_f32_e32 v34, v34
	s_nop 0
	v_add_f32_e32 v34, 1.0, v34
	v_rcp_f32_e32 v34, v34
	s_nop 0
	v_pk_mul_f32 v[34:35], v[34:35], v[38:39]
	s_nop 0
	v_mul_f32_e32 v40, v34, v35
	v_add_f32_e32 v34, v36, v52
	v_mul_f32_e32 v34, 0xbfb8aa3b, v34
	v_exp_f32_e32 v34, v34
	v_lshlrev_b32_e32 v38, 16, v45
	v_lshlrev_b32_e32 v39, 16, v49
	v_and_b32_e32 v36, 0xffff0000, v45
	v_add_f32_e32 v34, 1.0, v34
	v_rcp_f32_e32 v35, v34
	v_mul_f32_e32 v34, 0xbfb8aa3b, v38
	v_exp_f32_e32 v34, v34
	s_nop 0
	v_add_f32_e32 v34, 1.0, v34
	v_rcp_f32_e32 v34, v34
	s_nop 0
	v_pk_mul_f32 v[34:35], v[34:35], v[38:39]
	s_nop 0
	v_mul_f32_e32 v46, v34, v35
	v_add_f32_e32 v34, v41, v57
	v_mul_f32_e32 v34, 0xbfb8aa3b, v34
	v_exp_f32_e32 v34, v34
	v_and_b32_e32 v38, 0xffff0000, v43
	v_and_b32_e32 v39, 0xffff0000, v47
	v_add_f32_e32 v34, 1.0, v34
	v_rcp_f32_e32 v35, v34
	v_mul_f32_e32 v34, 0xbfb8aa3b, v38
	v_exp_f32_e32 v34, v34
	s_nop 0
	v_add_f32_e32 v34, 1.0, v34
	v_rcp_f32_e32 v34, v34
	s_nop 0
	v_pk_mul_f32 v[34:35], v[34:35], v[38:39]
	s_nop 0
	v_mul_f32_e32 v38, v34, v35
	v_add_f32_e32 v34, v37, v53
	v_mul_f32_e32 v34, 0xbfb8aa3b, v34
	v_exp_f32_e32 v34, v34
	v_and_b32_e32 v37, 0xffff0000, v49
	v_add_f32_e32 v34, 1.0, v34
	v_rcp_f32_e32 v35, v34
	v_mul_f32_e32 v34, 0xbfb8aa3b, v36
	v_exp_f32_e32 v34, v34
	s_nop 0
	v_add_f32_e32 v34, 1.0, v34
	v_rcp_f32_e32 v34, v34
	s_nop 0
	v_pk_mul_f32 v[34:35], v[34:35], v[36:37]
	s_nop 0
	v_mul_f32_e32 v37, v34, v35
	s_nop 0
	v_cvt_pk_bf16_f32 v34, v64, v42
	s_nop 0
	v_cvt_pk_bf16_f32 v35, v40, v38
	v_add_u32_e32 v38, 0xa0, v170
	v_ashrrev_i32_e32 v39, 31, v38
	s_nop 0
	v_cvt_pk_bf16_f32 v36, v50, v44
	s_nop 0
	v_cvt_pk_bf16_f32 v37, v46, v37
	global_store_dwordx4 v[58:59], v[34:37], off offset:3328
	v_lshlrev_b64 v[52:53], 12, v[38:39]
	s_nop 0
	v_lshlrev_b64 v[34:35], 10, v[38:39]
	v_mad_i64_i32 v[38:39], s[6:7], v38, s26, v[172:173]
	v_lshl_add_u64 v[38:39], v[38:39], 0, v[166:167]
	v_lshl_add_u64 v[34:35], s[0:1], 0, v[34:35]
	v_lshl_add_u64 v[54:55], v[38:39], 0, s[20:21]
	v_add_co_u32_e32 v38, vcc, s12, v38
	v_lshl_add_u64 v[50:51], v[34:35], 0, v[166:167]
	s_nop 0
	v_addc_co_u32_e32 v39, vcc, 0, v39, vcc
	global_load_dwordx4 v[34:37], v[50:51], off
	s_nop 0
	global_load_dwordx4 v[38:41], v[38:39], off offset:1296
	s_nop 0
	global_load_dwordx4 v[42:45], v[168:169], off offset:16
	global_load_dwordx4 v[46:49], v[168:169], off
	s_waitcnt vmcnt(0)
; __device__ __forceinline__ float sigmoidf_(float x) { return __builtin_amdgcn_rcpf(1.f + __expf(-x)); }
; __device__ __forceinline__ float siluf_(float x) { return x * sigmoidf_(x); }
;     __device__ __forceinline__ void operator()(AccT& acc, const Unit& u, int wr, int wc, int fr, int fq) const {
;     ...
;             for (int m = 0; m < 4; ++m) { const size_t row = (size_t)(row0 + ai * 128 + m * 16);
; #pragma unroll
;                 for (int bj = 0; bj < 2; ++bj) { const int c = col0 + bj * 128;
;                     float y8[8], z8[8], o8[8]; ld8(yd + row * 512 + c, y8); ld8(proj + row * NP + O_DZ + c, z8);
;                     const f32x4 b0 = *(const f32x4*)(gb + c), b1 = *(const f32x4*)(gb + c + 4);
; #pragma unroll
;                     for (int e = 0; e < 4; ++e) { o8[e] = y8[e] * sigmoidf_(acc[ai][bj][m][0][e] + b0[e]) * siluf_(z8[e]); o8[4 + e] = y8[4 + e] * sigmoidf_(acc[ai][bj][m][1][e] + b1[e]) * siluf_(z8[4 + e]); }
;                     st8(ys + row * DM + 1536 + c, o8); } }
	v_lshlrev_b32_e32 v58, 16, v38
	v_add_f32_e32 v26, v26, v42
	v_add_f32_e32 v30, v30, v46
	v_mul_f32_e32 v30, 0xbfb8aa3b, v30
	v_exp_f32_e32 v30, v30
	v_mul_f32_e32 v26, 0xbfb8aa3b, v26
	v_exp_f32_e32 v26, v26
	v_lshlrev_b32_e32 v59, 16, v34
	v_add_f32_e32 v30, 1.0, v30
	v_rcp_f32_e32 v57, v30
	v_mul_f32_e32 v30, 0xbfb8aa3b, v58
	v_exp_f32_e32 v30, v30
	v_add_f32_e32 v26, 1.0, v26
	v_and_b32_e32 v46, 0xffff0000, v38
	v_add_f32_e32 v30, 1.0, v30
	v_rcp_f32_e32 v56, v30
	s_nop 0
	v_pk_mul_f32 v[56:57], v[56:57], v[58:59]
	v_lshlrev_b32_e32 v58, 16, v40
	v_mul_f32_e32 v60, v56, v57
	v_rcp_f32_e32 v57, v26
	v_mul_f32_e32 v26, 0xbfb8aa3b, v58
	v_exp_f32_e32 v26, v26
	v_lshlrev_b32_e32 v59, 16, v36
	v_add_f32_e32 v26, 1.0, v26
	v_rcp_f32_e32 v56, v26
	v_add_f32_e32 v26, v31, v47
	v_mul_f32_e32 v26, 0xbfb8aa3b, v26
	v_exp_f32_e32 v26, v26
	v_and_b32_e32 v47, 0xffff0000, v34
	v_pk_mul_f32 v[56:57], v[56:57], v[58:59]
	v_add_f32_e32 v26, 1.0, v26
	v_rcp_f32_e32 v31, v26
	v_mul_f32_e32 v26, 0xbfb8aa3b, v46
	v_exp_f32_e32 v26, v26
	v_mul_f32_e32 v56, v56, v57
	v_add_f32_e32 v26, 1.0, v26
	v_rcp_f32_e32 v30, v26
	v_add_f32_e32 v26, v27, v43
	v_mul_f32_e32 v26, 0xbfb8aa3b, v26
	v_exp_f32_e32 v26, v26
	v_pk_mul_f32 v[30:31], v[30:31], v[46:47]
	v_add_f32_e32 v26, 1.0, v26
	v_mul_f32_e32 v34, v30, v31
	v_and_b32_e32 v30, 0xffff0000, v40
	v_rcp_f32_e32 v27, v26
	v_mul_f32_e32 v26, 0xbfb8aa3b, v30
	v_exp_f32_e32 v26, v26
	v_and_b32_e32 v31, 0xffff0000, v36
	v_add_f32_e32 v26, 1.0, v26
	v_rcp_f32_e32 v26, v26
	s_nop 0
	v_pk_mul_f32 v[26:27], v[26:27], v[30:31]
	s_nop 0
	v_mul_f32_e32 v36, v26, v27
	v_add_f32_e32 v26, v32, v48
	v_mul_f32_e32 v26, 0xbfb8aa3b, v26
	v_exp_f32_e32 v26, v26
	v_lshlrev_b32_e32 v30, 16, v39
	v_lshlrev_b32_e32 v31, 16, v35
	v_add_f32_e32 v26, 1.0, v26
	v_rcp_f32_e32 v27, v26
	v_mul_f32_e32 v26, 0xbfb8aa3b, v30
	v_exp_f32_e32 v26, v26
	s_nop 0
	v_add_f32_e32 v26, 1.0, v26
	v_rcp_f32_e32 v26, v26
	s_nop 0
	v_pk_mul_f32 v[26:27], v[26:27], v[30:31]
	s_nop 0
	v_mul_f32_e32 v32, v26, v27
	v_add_f32_e32 v26, v28, v44
	v_mul_f32_e32 v26, 0xbfb8aa3b, v26
	v_exp_f32_e32 v26, v26
	v_lshlrev_b32_e32 v30, 16, v41
	v_lshlrev_b32_e32 v31, 16, v37
	v_and_b32_e32 v28, 0xffff0000, v41
	v_add_f32_e32 v26, 1.0, v26
	v_rcp_f32_e32 v27, v26
	v_mul_f32_e32 v26, 0xbfb8aa3b, v30
	v_exp_f32_e32 v26, v26
	s_nop 0
	v_add_f32_e32 v26, 1.0, v26
	v_rcp_f32_e32 v26, v26
	s_nop 0
	v_pk_mul_f32 v[26:27], v[26:27], v[30:31]
	s_nop 0
	v_mul_f32_e32 v38, v26, v27
	v_add_f32_e32 v26, v33, v49
	v_mul_f32_e32 v26, 0xbfb8aa3b, v26
	v_exp_f32_e32 v26, v26
	v_and_b32_e32 v30, 0xffff0000, v39
	v_and_b32_e32 v31, 0xffff0000, v35
	v_add_f32_e32 v26, 1.0, v26
	v_rcp_f32_e32 v27, v26
	v_mul_f32_e32 v26, 0xbfb8aa3b, v30
	v_exp_f32_e32 v26, v26
	s_nop 0
	v_add_f32_e32 v26, 1.0, v26
	v_rcp_f32_e32 v26, v26
	s_nop 0
	v_pk_mul_f32 v[26:27], v[26:27], v[30:31]
	s_nop 0
	v_mul_f32_e32 v30, v26, v27
	v_add_f32_e32 v26, v29, v45
	v_mul_f32_e32 v26, 0xbfb8aa3b, v26
	v_exp_f32_e32 v26, v26
	v_and_b32_e32 v29, 0xffff0000, v37
	v_add_f32_e32 v26, 1.0, v26
	v_rcp_f32_e32 v27, v26
	v_mul_f32_e32 v26, 0xbfb8aa3b, v28
	v_exp_f32_e32 v26, v26
	s_nop 0
	v_add_f32_e32 v26, 1.0, v26
	v_rcp_f32_e32 v26, v26
	s_nop 0
	v_pk_mul_f32 v[26:27], v[26:27], v[28:29]
	s_nop 0
	v_mul_f32_e32 v29, v26, v27
	v_lshl_add_u64 v[26:27], s[48:49], 0, v[52:53]
	v_lshl_add_u64 v[42:43], v[26:27], 0, v[166:167]
	s_nop 0
	v_cvt_pk_bf16_f32 v26, v60, v34
	s_nop 0
	v_cvt_pk_bf16_f32 v27, v32, v30
	s_nop 0
	v_cvt_pk_bf16_f32 v28, v56, v36
	s_nop 0
	v_cvt_pk_bf16_f32 v29, v38, v29
	global_store_dwordx4 v[42:43], v[26:29], off offset:3072
	global_load_dwordx4 v[30:33], v[50:51], off offset:256
	s_nop 0
	global_load_dwordx4 v[26:29], v[54:55], off offset:256
	global_load_dwordx4 v[34:37], v[168:169], off offset:528
	global_load_dwordx4 v[38:41], v[168:169], off offset:512
	s_waitcnt vmcnt(0)
	v_lshlrev_b32_e32 v47, 16, v30
	v_lshlrev_b32_e32 v46, 16, v26
	v_add_f32_e32 v18, v18, v34
	v_add_f32_e32 v22, v22, v38
	v_mul_f32_e32 v22, 0xbfb8aa3b, v22
	v_exp_f32_e32 v22, v22
	v_mul_f32_e32 v18, 0xbfb8aa3b, v18
	v_exp_f32_e32 v18, v18
	v_and_b32_e32 v38, 0xffff0000, v26
	v_add_f32_e32 v22, 1.0, v22
	v_rcp_f32_e32 v45, v22
	v_mul_f32_e32 v22, 0xbfb8aa3b, v46
	v_exp_f32_e32 v22, v22
	v_add_f32_e32 v18, 1.0, v18
	v_add_f32_e32 v22, 1.0, v22
	v_rcp_f32_e32 v44, v22
	s_nop 0
	v_pk_mul_f32 v[44:45], v[44:45], v[46:47]
	v_lshlrev_b32_e32 v46, 16, v28
	v_mul_f32_e32 v48, v44, v45
	v_rcp_f32_e32 v45, v18
	v_mul_f32_e32 v18, 0xbfb8aa3b, v46
	v_exp_f32_e32 v18, v18
	v_lshlrev_b32_e32 v47, 16, v32
	v_add_f32_e32 v18, 1.0, v18
	v_rcp_f32_e32 v44, v18
	v_add_f32_e32 v18, v23, v39
	v_mul_f32_e32 v18, 0xbfb8aa3b, v18
	v_exp_f32_e32 v18, v18
	v_and_b32_e32 v39, 0xffff0000, v30
	v_pk_mul_f32 v[44:45], v[44:45], v[46:47]
	v_add_f32_e32 v18, 1.0, v18
	v_rcp_f32_e32 v23, v18
	v_mul_f32_e32 v18, 0xbfb8aa3b, v38
	v_exp_f32_e32 v18, v18
	v_mul_f32_e32 v34, v44, v45
	v_add_f32_e32 v18, 1.0, v18
	v_rcp_f32_e32 v22, v18
	v_add_f32_e32 v18, v19, v35
	v_mul_f32_e32 v18, 0xbfb8aa3b, v18
	v_exp_f32_e32 v18, v18
	v_pk_mul_f32 v[22:23], v[22:23], v[38:39]
	v_add_f32_e32 v18, 1.0, v18
	v_mul_f32_e32 v26, v22, v23
	v_and_b32_e32 v22, 0xffff0000, v28
	v_rcp_f32_e32 v19, v18
	v_mul_f32_e32 v18, 0xbfb8aa3b, v22
	v_exp_f32_e32 v18, v18
	v_and_b32_e32 v23, 0xffff0000, v32
	v_add_f32_e32 v18, 1.0, v18
	v_rcp_f32_e32 v18, v18
	s_nop 0
	v_pk_mul_f32 v[18:19], v[18:19], v[22:23]
	s_nop 0
	v_mul_f32_e32 v28, v18, v19
	v_add_f32_e32 v18, v24, v40
	v_mul_f32_e32 v18, 0xbfb8aa3b, v18
	v_exp_f32_e32 v18, v18
	v_lshlrev_b32_e32 v22, 16, v27
	v_lshlrev_b32_e32 v23, 16, v31
; __device__ __forceinline__ float sigmoidf_(float x) { return __builtin_amdgcn_rcpf(1.f + __expf(-x)); }
; __device__ __forceinline__ float siluf_(float x) { return x * sigmoidf_(x); }
; template <class Epi>
; __device__ __forceinline__ void gemm_phase(LAS unsigned char* lds, const Gemm g, const StaticOrder& S, const Epi& E) {
;     ...
;         if (!has_next) break;
; #pragma unroll
;         for (int a = 0; a < 2; ++a)
; #pragma unroll
;             for (int b = 0; b < 2; ++b)
; #pragma unroll
;                 for (int m = 0; m < 4; ++m)
; #pragma unroll
;                     for (int n = 0; n < 2; ++n) acc[a][b][m][n] = (f32x4){0.f, 0.f, 0.f, 0.f};
;         cur = nxt; cA = nA; cB = nB; ++ui;
;     __device__ __forceinline__ void operator()(AccT& acc, const Unit& u, int wr, int wc, int fr, int fq) const {
;     ...
;             for (int m = 0; m < 4; ++m) { const size_t row = (size_t)(row0 + ai * 128 + m * 16);
; #pragma unroll
;                 for (int bj = 0; bj < 2; ++bj) { const int c = col0 + bj * 128;
;                     float y8[8], z8[8], o8[8]; ld8(yd + row * 512 + c, y8); ld8(proj + row * NP + O_DZ + c, z8);
;                     const f32x4 b0 = *(const f32x4*)(gb + c), b1 = *(const f32x4*)(gb + c + 4);
; #pragma unroll
;                     for (int e = 0; e < 4; ++e) { o8[e] = y8[e] * sigmoidf_(acc[ai][bj][m][0][e] + b0[e]) * siluf_(z8[e]); o8[4 + e] = y8[4 + e] * sigmoidf_(acc[ai][bj][m][1][e] + b1[e]) * siluf_(z8[4 + e]); }
;                     st8(ys + row * DM + 1536 + c, o8); } }
;     }
	v_add_f32_e32 v18, 1.0, v18
	v_rcp_f32_e32 v19, v18
	v_mul_f32_e32 v18, 0xbfb8aa3b, v22
	v_exp_f32_e32 v18, v18
	s_nop 0
	v_add_f32_e32 v18, 1.0, v18
	v_rcp_f32_e32 v18, v18
	s_nop 0
	v_pk_mul_f32 v[18:19], v[18:19], v[22:23]
	s_nop 0
	v_mul_f32_e32 v24, v18, v19
	v_add_f32_e32 v18, v20, v36
	v_mul_f32_e32 v18, 0xbfb8aa3b, v18
	v_exp_f32_e32 v18, v18
	v_lshlrev_b32_e32 v22, 16, v29
	v_lshlrev_b32_e32 v23, 16, v33
	v_and_b32_e32 v20, 0xffff0000, v29
	v_add_f32_e32 v18, 1.0, v18
	v_rcp_f32_e32 v19, v18
	v_mul_f32_e32 v18, 0xbfb8aa3b, v22
	v_exp_f32_e32 v18, v18
	s_nop 0
	v_add_f32_e32 v18, 1.0, v18
	v_rcp_f32_e32 v18, v18
	s_nop 0
	v_pk_mul_f32 v[18:19], v[18:19], v[22:23]
	s_nop 0
	v_mul_f32_e32 v30, v18, v19
	v_add_f32_e32 v18, v25, v41
	v_mul_f32_e32 v18, 0xbfb8aa3b, v18
	v_exp_f32_e32 v18, v18
	v_and_b32_e32 v22, 0xffff0000, v27
	v_and_b32_e32 v23, 0xffff0000, v31
	v_add_f32_e32 v18, 1.0, v18
	v_rcp_f32_e32 v19, v18
	v_mul_f32_e32 v18, 0xbfb8aa3b, v22
	v_exp_f32_e32 v18, v18
	s_nop 0
	v_add_f32_e32 v18, 1.0, v18
	v_rcp_f32_e32 v18, v18
	s_nop 0
	v_pk_mul_f32 v[18:19], v[18:19], v[22:23]
	s_nop 0
	v_mul_f32_e32 v22, v18, v19
	v_add_f32_e32 v18, v21, v37
	v_mul_f32_e32 v18, 0xbfb8aa3b, v18
	v_exp_f32_e32 v18, v18
	v_and_b32_e32 v21, 0xffff0000, v33
	v_add_f32_e32 v18, 1.0, v18
	v_rcp_f32_e32 v19, v18
	v_mul_f32_e32 v18, 0xbfb8aa3b, v20
	v_exp_f32_e32 v18, v18
	s_nop 0
	v_add_f32_e32 v18, 1.0, v18
	v_rcp_f32_e32 v18, v18
	s_nop 0
	v_pk_mul_f32 v[18:19], v[18:19], v[20:21]
	s_nop 0
	v_mul_f32_e32 v21, v18, v19
	s_nop 0
	v_cvt_pk_bf16_f32 v18, v48, v26
	s_nop 0
	v_cvt_pk_bf16_f32 v19, v24, v22
	v_add_u32_e32 v22, 0xb0, v170
	v_ashrrev_i32_e32 v23, 31, v22
	s_nop 0
	v_cvt_pk_bf16_f32 v20, v34, v28
	s_nop 0
	v_cvt_pk_bf16_f32 v21, v30, v21
	global_store_dwordx4 v[42:43], v[18:21], off offset:3328
	v_lshlrev_b64 v[36:37], 12, v[22:23]
	s_nop 0
	v_lshlrev_b64 v[18:19], 10, v[22:23]
	v_mad_i64_i32 v[22:23], s[6:7], v22, s26, v[172:173]
	v_lshl_add_u64 v[22:23], v[22:23], 0, v[166:167]
	v_lshl_add_u64 v[18:19], s[0:1], 0, v[18:19]
	v_lshl_add_u64 v[38:39], v[22:23], 0, s[20:21]
	v_add_co_u32_e32 v22, vcc, s12, v22
	v_lshl_add_u64 v[34:35], v[18:19], 0, v[166:167]
	s_nop 0
	v_addc_co_u32_e32 v23, vcc, 0, v23, vcc
	global_load_dwordx4 v[18:21], v[34:35], off
	s_nop 0
	global_load_dwordx4 v[22:25], v[22:23], off offset:1296
	s_nop 0
	global_load_dwordx4 v[26:29], v[168:169], off offset:16
	global_load_dwordx4 v[30:33], v[168:169], off
	s_and_b64 vcc, exec, s[50:51]
	s_mov_b64 s[20:21], s[66:67]
	s_mov_b64 s[6:7], s[62:63]
	s_waitcnt vmcnt(0)
	v_lshlrev_b32_e32 v42, 16, v22
	v_add_f32_e32 v10, v10, v26
	v_add_f32_e32 v14, v14, v30
	v_mul_f32_e32 v14, 0xbfb8aa3b, v14
	v_exp_f32_e32 v14, v14
	v_mul_f32_e32 v10, 0xbfb8aa3b, v10
	v_exp_f32_e32 v10, v10
	v_lshlrev_b32_e32 v43, 16, v18
	v_add_f32_e32 v14, 1.0, v14
	v_rcp_f32_e32 v41, v14
	v_mul_f32_e32 v14, 0xbfb8aa3b, v42
	v_exp_f32_e32 v14, v14
	v_add_f32_e32 v10, 1.0, v10
	v_and_b32_e32 v30, 0xffff0000, v22
	v_add_f32_e32 v14, 1.0, v14
	v_rcp_f32_e32 v40, v14
	s_nop 0
	v_pk_mul_f32 v[40:41], v[40:41], v[42:43]
	v_lshlrev_b32_e32 v42, 16, v24
	v_mul_f32_e32 v44, v40, v41
	v_rcp_f32_e32 v41, v10
	v_mul_f32_e32 v10, 0xbfb8aa3b, v42
	v_exp_f32_e32 v10, v10
	v_lshlrev_b32_e32 v43, 16, v20
	v_add_f32_e32 v10, 1.0, v10
	v_rcp_f32_e32 v40, v10
	v_add_f32_e32 v10, v15, v31
	v_mul_f32_e32 v10, 0xbfb8aa3b, v10
	v_exp_f32_e32 v10, v10
	v_and_b32_e32 v31, 0xffff0000, v18
	v_pk_mul_f32 v[40:41], v[40:41], v[42:43]
	v_add_f32_e32 v10, 1.0, v10
	v_rcp_f32_e32 v15, v10
	v_mul_f32_e32 v10, 0xbfb8aa3b, v30
	v_exp_f32_e32 v10, v10
	v_mul_f32_e32 v40, v40, v41
	v_add_f32_e32 v10, 1.0, v10
	v_rcp_f32_e32 v14, v10
	v_add_f32_e32 v10, v11, v27
	v_mul_f32_e32 v10, 0xbfb8aa3b, v10
	v_exp_f32_e32 v10, v10
	v_pk_mul_f32 v[14:15], v[14:15], v[30:31]
	v_add_f32_e32 v10, 1.0, v10
	v_mul_f32_e32 v18, v14, v15
	v_and_b32_e32 v14, 0xffff0000, v24
	v_rcp_f32_e32 v11, v10
	v_mul_f32_e32 v10, 0xbfb8aa3b, v14
	v_exp_f32_e32 v10, v10
	v_and_b32_e32 v15, 0xffff0000, v20
	v_add_f32_e32 v10, 1.0, v10
	v_rcp_f32_e32 v10, v10
	s_nop 0
	v_pk_mul_f32 v[10:11], v[10:11], v[14:15]
	s_nop 0
	v_mul_f32_e32 v20, v10, v11
	v_add_f32_e32 v10, v16, v32
	v_mul_f32_e32 v10, 0xbfb8aa3b, v10
	v_exp_f32_e32 v10, v10
	v_lshlrev_b32_e32 v14, 16, v23
	v_lshlrev_b32_e32 v15, 16, v19
	v_add_f32_e32 v10, 1.0, v10
	v_rcp_f32_e32 v11, v10
	v_mul_f32_e32 v10, 0xbfb8aa3b, v14
	v_exp_f32_e32 v10, v10
	s_nop 0
	v_add_f32_e32 v10, 1.0, v10
	v_rcp_f32_e32 v10, v10
	s_nop 0
	v_pk_mul_f32 v[10:11], v[10:11], v[14:15]
	s_nop 0
	v_mul_f32_e32 v16, v10, v11
	v_add_f32_e32 v10, v12, v28
	v_mul_f32_e32 v10, 0xbfb8aa3b, v10
	v_exp_f32_e32 v10, v10
	v_lshlrev_b32_e32 v14, 16, v25
	v_lshlrev_b32_e32 v15, 16, v21
	v_and_b32_e32 v12, 0xffff0000, v25
	v_add_f32_e32 v10, 1.0, v10
	v_rcp_f32_e32 v11, v10
	v_mul_f32_e32 v10, 0xbfb8aa3b, v14
	v_exp_f32_e32 v10, v10
	s_nop 0
	v_add_f32_e32 v10, 1.0, v10
	v_rcp_f32_e32 v10, v10
	s_nop 0
	v_pk_mul_f32 v[10:11], v[10:11], v[14:15]
	s_nop 0
	v_mul_f32_e32 v22, v10, v11
	v_add_f32_e32 v10, v17, v33
	v_mul_f32_e32 v10, 0xbfb8aa3b, v10
	v_exp_f32_e32 v10, v10
	v_and_b32_e32 v14, 0xffff0000, v23
	v_and_b32_e32 v15, 0xffff0000, v19
	v_add_f32_e32 v10, 1.0, v10
	v_rcp_f32_e32 v11, v10
	v_mul_f32_e32 v10, 0xbfb8aa3b, v14
	v_exp_f32_e32 v10, v10
	s_nop 0
	v_add_f32_e32 v10, 1.0, v10
	v_rcp_f32_e32 v10, v10
	s_nop 0
	v_pk_mul_f32 v[10:11], v[10:11], v[14:15]
	s_nop 0
	v_mul_f32_e32 v14, v10, v11
	v_add_f32_e32 v10, v13, v29
	v_mul_f32_e32 v10, 0xbfb8aa3b, v10
	v_exp_f32_e32 v10, v10
	v_and_b32_e32 v13, 0xffff0000, v21
	v_add_f32_e32 v10, 1.0, v10
	v_rcp_f32_e32 v11, v10
	v_mul_f32_e32 v10, 0xbfb8aa3b, v12
	v_exp_f32_e32 v10, v10
	s_nop 0
	v_add_f32_e32 v10, 1.0, v10
	v_rcp_f32_e32 v10, v10
	s_nop 0
	v_pk_mul_f32 v[10:11], v[10:11], v[12:13]
	s_nop 0
	v_mul_f32_e32 v13, v10, v11
	v_lshl_add_u64 v[10:11], s[48:49], 0, v[36:37]
	v_lshl_add_u64 v[26:27], v[10:11], 0, v[166:167]
	s_nop 0
	v_cvt_pk_bf16_f32 v10, v44, v18
	s_nop 0
	v_cvt_pk_bf16_f32 v11, v16, v14
	s_nop 0
	v_cvt_pk_bf16_f32 v12, v40, v20
	s_nop 0
	v_cvt_pk_bf16_f32 v13, v22, v13
	global_store_dwordx4 v[26:27], v[10:13], off offset:3072
	global_load_dwordx4 v[14:17], v[34:35], off offset:256
	s_nop 0
	global_load_dwordx4 v[10:13], v[38:39], off offset:256
	global_load_dwordx4 v[18:21], v[168:169], off offset:528
	global_load_dwordx4 v[22:25], v[168:169], off offset:512
	s_waitcnt vmcnt(0)
; __device__ __forceinline__ float sigmoidf_(float x) { return __builtin_amdgcn_rcpf(1.f + __expf(-x)); }
; __device__ __forceinline__ float siluf_(float x) { return x * sigmoidf_(x); }
; #define PG8_WAIT_V(n) asm volatile("s_waitcnt vmcnt(" #n ")" ::: "memory")
; #define PG8_BAR __builtin_amdgcn_s_barrier()
; template <class Epi>
; __device__ __forceinline__ void gemm_phase(LAS unsigned char* lds, const Gemm g, const StaticOrder& S, const Epi& E) {
;     ...
;     PG8_WAIT_V(0);
;     if (wr == 0) PG8_BAR;
;     PG8_BAR;
;     __device__ __forceinline__ void operator()(AccT& acc, const Unit& u, int wr, int wc, int fr, int fq) const {
;     ...
;             for (int m = 0; m < 4; ++m) { const size_t row = (size_t)(row0 + ai * 128 + m * 16);
; #pragma unroll
;                 for (int bj = 0; bj < 2; ++bj) { const int c = col0 + bj * 128;
;                     float y8[8], z8[8], o8[8]; ld8(yd + row * 512 + c, y8); ld8(proj + row * NP + O_DZ + c, z8);
;                     const f32x4 b0 = *(const f32x4*)(gb + c), b1 = *(const f32x4*)(gb + c + 4);
; #pragma unroll
;                     for (int e = 0; e < 4; ++e) { o8[e] = y8[e] * sigmoidf_(acc[ai][bj][m][0][e] + b0[e]) * siluf_(z8[e]); o8[4 + e] = y8[4 + e] * sigmoidf_(acc[ai][bj][m][1][e] + b1[e]) * siluf_(z8[4 + e]); }
;                     st8(ys + row * DM + 1536 + c, o8); } }
;     }
	v_lshlrev_b32_e32 v31, 16, v14
	v_lshlrev_b32_e32 v30, 16, v10
	v_add_f32_e32 v2, v2, v18
	v_add_f32_e32 v6, v6, v22
	v_mul_f32_e32 v6, 0xbfb8aa3b, v6
	v_exp_f32_e32 v6, v6
	v_mul_f32_e32 v2, 0xbfb8aa3b, v2
	v_exp_f32_e32 v2, v2
	v_and_b32_e32 v22, 0xffff0000, v10
	v_add_f32_e32 v6, 1.0, v6
	v_rcp_f32_e32 v29, v6
	v_mul_f32_e32 v6, 0xbfb8aa3b, v30
	v_exp_f32_e32 v6, v6
	v_add_f32_e32 v2, 1.0, v2
	v_add_f32_e32 v6, 1.0, v6
	v_rcp_f32_e32 v28, v6
	s_nop 0
	v_pk_mul_f32 v[28:29], v[28:29], v[30:31]
	v_lshlrev_b32_e32 v30, 16, v12
	v_mul_f32_e32 v32, v28, v29
	v_rcp_f32_e32 v29, v2
	v_mul_f32_e32 v2, 0xbfb8aa3b, v30
	v_exp_f32_e32 v2, v2
	v_lshlrev_b32_e32 v31, 16, v16
	v_add_f32_e32 v2, 1.0, v2
	v_rcp_f32_e32 v28, v2
	v_add_f32_e32 v2, v7, v23
	v_mul_f32_e32 v2, 0xbfb8aa3b, v2
	v_exp_f32_e32 v2, v2
	v_and_b32_e32 v23, 0xffff0000, v14
	v_pk_mul_f32 v[28:29], v[28:29], v[30:31]
	v_add_f32_e32 v2, 1.0, v2
	v_rcp_f32_e32 v7, v2
	v_mul_f32_e32 v2, 0xbfb8aa3b, v22
	v_exp_f32_e32 v2, v2
	v_mul_f32_e32 v18, v28, v29
	v_add_f32_e32 v2, 1.0, v2
	v_rcp_f32_e32 v6, v2
	v_add_f32_e32 v2, v3, v19
	v_mul_f32_e32 v2, 0xbfb8aa3b, v2
	v_exp_f32_e32 v2, v2
	v_pk_mul_f32 v[6:7], v[6:7], v[22:23]
	v_add_f32_e32 v2, 1.0, v2
	v_mul_f32_e32 v10, v6, v7
	v_and_b32_e32 v6, 0xffff0000, v12
	v_rcp_f32_e32 v3, v2
	v_mul_f32_e32 v2, 0xbfb8aa3b, v6
	v_exp_f32_e32 v2, v2
	v_and_b32_e32 v7, 0xffff0000, v16
	v_add_f32_e32 v2, 1.0, v2
	v_rcp_f32_e32 v2, v2
	s_nop 0
	v_pk_mul_f32 v[2:3], v[2:3], v[6:7]
	s_nop 0
	v_mul_f32_e32 v12, v2, v3
	v_add_f32_e32 v2, v8, v24
	v_mul_f32_e32 v2, 0xbfb8aa3b, v2
	v_exp_f32_e32 v2, v2
	v_lshlrev_b32_e32 v6, 16, v11
	v_lshlrev_b32_e32 v7, 16, v15
	v_add_f32_e32 v2, 1.0, v2
	v_rcp_f32_e32 v3, v2
	v_mul_f32_e32 v2, 0xbfb8aa3b, v6
	v_exp_f32_e32 v2, v2
	s_nop 0
	v_add_f32_e32 v2, 1.0, v2
	v_rcp_f32_e32 v2, v2
	s_nop 0
	v_pk_mul_f32 v[2:3], v[2:3], v[6:7]
	s_nop 0
	v_mul_f32_e32 v8, v2, v3
	v_add_f32_e32 v2, v4, v20
	v_mul_f32_e32 v2, 0xbfb8aa3b, v2
	v_exp_f32_e32 v2, v2
	v_lshlrev_b32_e32 v6, 16, v13
	v_lshlrev_b32_e32 v7, 16, v17
	v_and_b32_e32 v4, 0xffff0000, v13
	v_add_f32_e32 v2, 1.0, v2
	v_rcp_f32_e32 v3, v2
	v_mul_f32_e32 v2, 0xbfb8aa3b, v6
	v_exp_f32_e32 v2, v2
	s_nop 0
	v_add_f32_e32 v2, 1.0, v2
	v_rcp_f32_e32 v2, v2
	s_nop 0
	v_pk_mul_f32 v[2:3], v[2:3], v[6:7]
	s_nop 0
	v_mul_f32_e32 v14, v2, v3
	v_add_f32_e32 v2, v9, v25
	v_mul_f32_e32 v2, 0xbfb8aa3b, v2
	v_exp_f32_e32 v2, v2
	v_and_b32_e32 v6, 0xffff0000, v11
	v_and_b32_e32 v7, 0xffff0000, v15
	v_add_f32_e32 v2, 1.0, v2
	v_rcp_f32_e32 v3, v2
	v_mul_f32_e32 v2, 0xbfb8aa3b, v6
	v_exp_f32_e32 v2, v2
	s_nop 0
	v_add_f32_e32 v2, 1.0, v2
	v_rcp_f32_e32 v2, v2
	s_nop 0
	v_pk_mul_f32 v[2:3], v[2:3], v[6:7]
	s_nop 0
	v_mul_f32_e32 v6, v2, v3
	v_add_f32_e32 v2, v5, v21
	v_mul_f32_e32 v2, 0xbfb8aa3b, v2
	v_exp_f32_e32 v2, v2
	v_and_b32_e32 v5, 0xffff0000, v17
	v_add_f32_e32 v2, 1.0, v2
	v_rcp_f32_e32 v3, v2
	v_mul_f32_e32 v2, 0xbfb8aa3b, v4
	v_exp_f32_e32 v2, v2
	s_nop 0
	v_add_f32_e32 v2, 1.0, v2
	v_rcp_f32_e32 v2, v2
	s_nop 0
	v_pk_mul_f32 v[2:3], v[2:3], v[4:5]
	s_nop 0
	v_mul_f32_e32 v5, v2, v3
	s_nop 0
	v_cvt_pk_bf16_f32 v2, v32, v10
	s_nop 0
	v_cvt_pk_bf16_f32 v3, v8, v6
	s_nop 0
	v_cvt_pk_bf16_f32 v4, v18, v12
	s_nop 0
	v_cvt_pk_bf16_f32 v5, v14, v5
	global_store_dwordx4 v[26:27], v[2:5], off offset:3328
	s_cbranch_vccz .LBB0_1295
	s_waitcnt vmcnt(0)
	v_readlane_b32 s52, v255, 42
	v_readlane_b32 s82, v255, 50
	s_cmpk_gt_u32 s23, 0xff
	v_readlane_b32 s51, v255, 41
	v_readlane_b32 s53, v255, 43
	s_mov_b32 s86, 0x3fb8aa3b
	v_readlane_b32 s83, v255, 51
	s_cbranch_scc1 .LBB0_1306
	s_barrier

; template <class Epi>
; __device__ __forceinline__ void gemm_phase(LAS unsigned char* lds, const Gemm g, const StaticOrder& S, const Epi& E) {
;     ...
;         const char* nA = has_next ? (const char*)g.A + (size_t)nxt.pm * tstep : cA; const char* nB = has_next ? (const char*)g.Bt + (size_t)nxt.pn * tstep : cB;
;         for (int t = 0; t < nt; t += 2) {
;             const bool last = (t == nt - 2);
;             const char* a1 = cA + (size_t)(t + 1) * kstep;
;             const char* a2 = last ? nA : cA + (size_t)(t + 2) * kstep; const char* b2 = last ? nB : cB + (size_t)(t + 2) * kstep;
;             const char* a3 = a2 + kstep; const char* b3 = b2 + kstep;
;             if constexpr (Epi::RESCALE) { if (t != 0 && (t & 7) == 0) { const int t2 = fresh_tid(); const int w2 = __builtin_amdgcn_readfirstlane(t2 >> 6); E.rescale(acc, cur, t >> 3, w2 >> 2, w2 & 3, t2 & 15, (t2 >> 4) & 3); } }
;             PG8_LDB(B0, 0, 0); PG8_SCHED; PG8_LDA(At, 0, 0); PG8_STAGE(PG8_SA(1, 1), a1 + hstep);
;             PG8_WAIT_L(8); PG8_BAR; PG8_WAIT_L(0); PG8_MMA(0, 0, At, B0); PG8_BAR; PG8_SCHED;
;             PG8_LDB(B1, 0, 1); PG8_STAGEB(PG8_SB(0, 0), b2);
;             PG8_BAR; PG8_WAIT_L(0); PG8_MMA(0, 1, At, B1); PG8_BAR;
;             PG8_LDA(At, 0, 1); PG8_STAGE(PG8_SA(0, 0), a2);
;             PG8_BAR; PG8_WAIT_L(0); PG8_MMA(1, 0, At, B0); PG8_BAR; PG8_SCHED;
;             PG8_STAGEB(PG8_SB(0, 1), b2 + hstep);
;             PG8_WAIT_V(6); PG8_BAR; PG8_MMA(1, 1, At, B1); PG8_BAR;
;             PG8_LDB(B0, 1, 0); PG8_SCHED; PG8_LDA(At, 1, 0); PG8_STAGE(PG8_SA(0, 1), a2 + hstep);
;             PG8_WAIT_L(8); PG8_BAR; PG8_WAIT_L(0); PG8_MMA(0, 0, At, B0); PG8_BAR; PG8_SCHED;
;             PG8_LDB(B1, 1, 1); PG8_STAGEB(PG8_SB(1, 0), b3);
;             PG8_BAR; PG8_WAIT_L(0); PG8_MMA(0, 1, At, B1); PG8_BAR;
;             PG8_LDA(At, 1, 1); PG8_STAGE(PG8_SA(1, 0), a3);
;             PG8_BAR; PG8_WAIT_L(0); PG8_MMA(1, 0, At, B0); PG8_BAR; PG8_SCHED;
;             PG8_STAGEB(PG8_SB(1, 1), b3 + hstep);
;             PG8_WAIT_V(6); PG8_BAR; PG8_MMA(1, 1, At, B1); PG8_BAR;
;         }
;         { const int t2 = fresh_tid(); const int w2 = __builtin_amdgcn_readfirstlane(t2 >> 6); E(acc, cur, w2 >> 2, w2 & 3, t2 & 15, (t2 >> 4) & 3); }
;         if (!has_next) break;
; #pragma unroll
;         for (int a = 0; a < 2; ++a)
; #pragma unroll
;             for (int b = 0; b < 2; ++b)
.LBB0_1377:
	v_mov_b64_e32 v[2:3], 0x100
	s_ashr_i32 s53, s52, 31
	v_cmp_lt_i64_e32 vcc, s[24:25], v[2:3]
	s_lshl_b64 s[24:25], s[52:53], 20
	s_add_u32 s54, s81, s24
	s_addc_u32 s55, s82, s25
	s_and_b64 s[24:25], vcc, exec
	s_cselect_b32 s24, s55, s21
	s_cselect_b32 s25, s54, s20
	s_ashr_i32 s51, s50, 31
	s_lshl_b64 s[30:31], s[50:51], 20
	s_add_u32 s62, s83, s30
	s_addc_u32 s63, s84, s31
	s_and_b64 s[30:31], vcc, exec
	s_cselect_b32 s51, s63, s7
	s_cselect_b32 s53, s62, s6
	s_lshl_b32 s31, s35, 8
	s_lshl_b32 s30, s34, 8
	s_add_u32 s66, s20, 0x80080
	s_addc_u32 s67, s21, 0
	v_mov_b32_e32 v2, v1
	v_mov_b32_e32 v3, v1
	s_add_u32 s91, s6, 0x100
	v_mov_b32_e32 v0, v1
	v_mov_b64_e32 v[6:7], v[2:3]
	v_mov_b64_e32 v[10:11], v[2:3]
	v_mov_b64_e32 v[22:23], v[2:3]
	v_mov_b64_e32 v[26:27], v[2:3]
	v_mov_b64_e32 v[38:39], v[2:3]
	v_mov_b64_e32 v[42:43], v[2:3]
	s_waitcnt vmcnt(0)
	v_mov_b64_e32 v[54:55], v[2:3]
	v_mov_b64_e32 v[58:59], v[2:3]
	v_mov_b64_e32 v[14:15], v[2:3]
	v_mov_b64_e32 v[18:19], v[2:3]
	v_mov_b64_e32 v[30:31], v[2:3]
	v_mov_b64_e32 v[34:35], v[2:3]
	v_mov_b64_e32 v[46:47], v[2:3]
	v_mov_b64_e32 v[50:51], v[2:3]
	v_mov_b64_e32 v[62:63], v[2:3]
	v_mov_b64_e32 v[66:67], v[2:3]
	v_mov_b64_e32 v[70:71], v[2:3]
	v_mov_b64_e32 v[74:75], v[2:3]
	v_mov_b64_e32 v[86:87], v[2:3]
	v_mov_b64_e32 v[90:91], v[2:3]
	v_mov_b64_e32 v[102:103], v[2:3]
	v_mov_b64_e32 v[106:107], v[2:3]
	v_mov_b64_e32 v[118:119], v[2:3]
	v_mov_b64_e32 v[122:123], v[2:3]
	v_mov_b64_e32 v[78:79], v[2:3]
	v_mov_b64_e32 v[82:83], v[2:3]
	v_mov_b64_e32 v[94:95], v[2:3]
	v_mov_b64_e32 v[98:99], v[2:3]
	v_mov_b64_e32 v[110:111], v[2:3]
	v_mov_b64_e32 v[114:115], v[2:3]
	v_mov_b64_e32 v[126:127], v[2:3]
	v_mov_b64_e32 v[130:131], v[2:3]
	s_addc_u32 s92, s7, 0
	s_mov_b64 s[42:43], 0
	s_mov_b32 s93, -2
	v_mov_b64_e32 v[4:5], v[0:1]
	v_mov_b64_e32 v[8:9], v[0:1]
	v_mov_b64_e32 v[20:21], v[0:1]
	v_mov_b64_e32 v[24:25], v[0:1]
	v_mov_b64_e32 v[36:37], v[0:1]
	v_mov_b64_e32 v[40:41], v[0:1]
	v_mov_b64_e32 v[52:53], v[0:1]
	v_mov_b64_e32 v[56:57], v[0:1]
	v_mov_b64_e32 v[12:13], v[0:1]
	v_mov_b64_e32 v[16:17], v[0:1]
	v_mov_b64_e32 v[28:29], v[0:1]
	v_mov_b64_e32 v[32:33], v[0:1]
	v_mov_b64_e32 v[44:45], v[0:1]
	v_mov_b64_e32 v[48:49], v[0:1]
	v_mov_b64_e32 v[60:61], v[0:1]
	v_mov_b64_e32 v[64:65], v[0:1]
	v_mov_b64_e32 v[68:69], v[0:1]
	v_mov_b64_e32 v[72:73], v[0:1]
	v_mov_b64_e32 v[84:85], v[0:1]
	v_mov_b64_e32 v[88:89], v[0:1]
	v_mov_b64_e32 v[100:101], v[0:1]
	v_mov_b64_e32 v[104:105], v[0:1]
	v_mov_b64_e32 v[116:117], v[0:1]
	v_mov_b64_e32 v[120:121], v[0:1]
	v_mov_b64_e32 v[76:77], v[0:1]
	v_mov_b64_e32 v[80:81], v[0:1]
	v_mov_b64_e32 v[92:93], v[0:1]
	v_mov_b64_e32 v[96:97], v[0:1]
	v_mov_b64_e32 v[108:109], v[0:1]
	v_mov_b64_e32 v[112:113], v[0:1]
	v_mov_b64_e32 v[124:125], v[0:1]
	v_mov_b64_e32 v[128:129], v[0:1]
	v_add_u32_e32 v154, 0x10000, v162
	v_add_u32_e32 v155, 0x14000, v162
	v_add_u32_e32 v182, 0x18000, v162
	v_add_u32_e32 v183, 0x1c000, v162
	s_branch .LBB0_1379
.LBB0_1378:
	s_add_u32 s6, s66, 0xfff80080
	s_addc_u32 s7, s67, -1
	s_cmpk_eq_i32 s42, 0x3c00
	s_cselect_b32 s21, s24, s7
	s_cselect_b32 s20, s25, s6
	s_cselect_b32 s7, s51, s92
	s_cselect_b32 s6, s53, s91
	s_add_u32 s100, s20, s16
	s_addc_u32 s101, s21, s17
	s_add_i32 s34, 0, 0x10000
	ds_read_b128 v[132:135], v154
	ds_read_b128 v[136:139], v154 offset:1024
	ds_read_b128 v[146:149], v154 offset:2048
	ds_read_b128 v[150:153], v154 offset:3072
	s_add_i32 m0, s38, 0xc000
	ds_read_b128 v[164:167], v163
	ds_read_b128 v[168:171], v163 offset:1024
	ds_read_b128 v[172:175], v163 offset:2048
	ds_read_b128 v[176:179], v163 offset:3072
	ds_read_b128 v[188:191], v163 offset:4096
	ds_read_b128 v[192:195], v163 offset:5120
	ds_read_b128 v[196:199], v163 offset:6144
	global_load_lds_dwordx4 v158, s[66:67]
	s_add_i32 m0, s38, 0xe000
	ds_read_b128 v[200:203], v163 offset:7168
	global_load_lds_dwordx4 v160, s[66:67]
	s_waitcnt lgkmcnt(8)
	s_barrier
	s_waitcnt lgkmcnt(0)
	s_setprio 1
	v_mfma_f32_16x16x32_bf16 v[128:131], v[132:135], v[164:167], v[128:131]
	v_mfma_f32_16x16x32_bf16 v[124:127], v[146:149], v[164:167], v[124:127]
	s_add_i32 s58, 0, 0x14000
	v_mfma_f32_16x16x32_bf16 v[112:115], v[132:135], v[172:175], v[112:115]
	s_add_i32 s34, s34, s85
	v_mfma_f32_16x16x32_bf16 v[108:111], v[146:149], v[172:175], v[108:111]
	s_mov_b32 m0, s34
	v_mfma_f32_16x16x32_bf16 v[96:99], v[132:135], v[188:191], v[96:99]
	v_mfma_f32_16x16x32_bf16 v[92:95], v[146:149], v[188:191], v[92:95]
	v_mfma_f32_16x16x32_bf16 v[80:83], v[132:135], v[196:199], v[80:83]
	v_mfma_f32_16x16x32_bf16 v[76:79], v[146:149], v[196:199], v[76:79]
	v_mfma_f32_16x16x32_bf16 v[128:131], v[136:139], v[168:171], v[128:131]
	v_mfma_f32_16x16x32_bf16 v[124:127], v[150:153], v[168:171], v[124:127]
	v_mfma_f32_16x16x32_bf16 v[112:115], v[136:139], v[176:179], v[112:115]
	v_mfma_f32_16x16x32_bf16 v[108:111], v[150:153], v[176:179], v[108:111]
	v_mfma_f32_16x16x32_bf16 v[96:99], v[136:139], v[192:195], v[96:99]
	v_mfma_f32_16x16x32_bf16 v[92:95], v[150:153], v[192:195], v[92:95]
	v_mfma_f32_16x16x32_bf16 v[80:83], v[136:139], v[200:203], v[80:83]
	v_mfma_f32_16x16x32_bf16 v[76:79], v[150:153], v[200:203], v[76:79]
	s_setprio 0
	s_barrier
	ds_read_b128 v[206:209], v155
	ds_read_b128 v[210:213], v155 offset:1024
	ds_read_b128 v[214:217], v155 offset:2048
	global_load_lds_dwordx4 v144, s[6:7]
	s_add_i32 m0, s34, 0x2000
	ds_read_b128 v[218:221], v155 offset:3072
	global_load_lds_dwordx4 v140, s[6:7]
	s_barrier
; #define PG8_STAGE(bufoff, gbase) PG8_STAGE_(bufoff, gbase, voffA)
; #define PG8_STAGEB(bufoff, gbase) PG8_STAGE_(bufoff, gbase, voffB)
; #define PG8_LDA(dst, b, h) do { _Pragma("unroll") for (int m = 0; m < 4; ++m) _Pragma("unroll") for (int k = 0; k < 2; ++k) dst[m][k] = *(const LAS bf16x8*)(lds + PG8_SA(b, h) + aoff + m * 2048 + k * 1024); } while (0)
; #define PG8_LDB(dst, b, h) do { _Pragma("unroll") for (int n = 0; n < 2; ++n) _Pragma("unroll") for (int k = 0; k < 2; ++k) dst[n][k] = *(const LAS bf16x8*)(lds + PG8_SB(b, h) + boff + n * 2048 + k * 1024); } while (0)
; #define PG8_MMA(ai, bj, At, Bt) do { __builtin_amdgcn_s_setprio(1); _Pragma("unroll") for (int m = 0; m < 4; ++m) _Pragma("unroll") for (int n = 0; n < 2; ++n) _Pragma("unroll") for (int k = 0; k < 2; ++k) \
;         acc[ai][bj][m][n] = __builtin_amdgcn_mfma_f32_16x16x32_bf16(Bt[n][k], At[m][k], acc[ai][bj][m][n], 0, 0, 0); __builtin_amdgcn_s_setprio(0); } while (0)
; #define PG8_WAIT_V(n) asm volatile("s_waitcnt vmcnt(" #n ")" ::: "memory")
; #define PG8_WAIT_L(n) asm volatile("s_waitcnt lgkmcnt(" #n ")" ::: "memory")
; #define PG8_BAR __builtin_amdgcn_s_barrier()
; #define PG8_SCHED __builtin_amdgcn_sched_barrier(0)
; template <class Epi>
; __device__ __forceinline__ void gemm_phase(LAS unsigned char* lds, const Gemm g, const StaticOrder& S, const Epi& E) {
;     ...
;             PG8_WAIT_L(8); PG8_BAR; PG8_WAIT_L(0); PG8_MMA(0, 0, At, B0); PG8_BAR; PG8_SCHED;
;             PG8_LDB(B1, 0, 1); PG8_STAGEB(PG8_SB(0, 0), b2);
;             PG8_BAR; PG8_WAIT_L(0); PG8_MMA(0, 1, At, B1); PG8_BAR;
;             PG8_LDA(At, 0, 1); PG8_STAGE(PG8_SA(0, 0), a2);
;             PG8_BAR; PG8_WAIT_L(0); PG8_MMA(1, 0, At, B0); PG8_BAR; PG8_SCHED;
;             PG8_STAGEB(PG8_SB(0, 1), b2 + hstep);
;             PG8_WAIT_V(6); PG8_BAR; PG8_MMA(1, 1, At, B1); PG8_BAR;
;             PG8_LDB(B0, 1, 0); PG8_SCHED; PG8_LDA(At, 1, 0); PG8_STAGE(PG8_SA(0, 1), a2 + hstep);
;             PG8_WAIT_L(8); PG8_BAR; PG8_WAIT_L(0); PG8_MMA(0, 0, At, B0); PG8_BAR; PG8_SCHED;
	s_waitcnt lgkmcnt(0)
	s_setprio 1
	v_mfma_f32_16x16x32_bf16 v[120:123], v[206:209], v[164:167], v[120:123]
	v_mfma_f32_16x16x32_bf16 v[116:119], v[214:217], v[164:167], v[116:119]
	v_mfma_f32_16x16x32_bf16 v[104:107], v[206:209], v[172:175], v[104:107]
	v_mfma_f32_16x16x32_bf16 v[100:103], v[214:217], v[172:175], v[100:103]
	v_mfma_f32_16x16x32_bf16 v[88:91], v[206:209], v[188:191], v[88:91]
	v_mfma_f32_16x16x32_bf16 v[84:87], v[214:217], v[188:191], v[84:87]
	v_mfma_f32_16x16x32_bf16 v[72:75], v[206:209], v[196:199], v[72:75]
	v_mfma_f32_16x16x32_bf16 v[68:71], v[214:217], v[196:199], v[68:71]
	v_mfma_f32_16x16x32_bf16 v[120:123], v[210:213], v[168:171], v[120:123]
	v_mfma_f32_16x16x32_bf16 v[116:119], v[218:221], v[168:171], v[116:119]
	v_mfma_f32_16x16x32_bf16 v[104:107], v[210:213], v[176:179], v[104:107]
	v_mfma_f32_16x16x32_bf16 v[100:103], v[218:221], v[176:179], v[100:103]
	v_mfma_f32_16x16x32_bf16 v[88:91], v[210:213], v[192:195], v[88:91]
	v_mfma_f32_16x16x32_bf16 v[84:87], v[218:221], v[192:195], v[84:87]
	v_mfma_f32_16x16x32_bf16 v[72:75], v[210:213], v[200:203], v[72:75]
	v_mfma_f32_16x16x32_bf16 v[68:71], v[218:221], v[200:203], v[68:71]
	s_setprio 0
	s_mov_b32 m0, s38
	s_barrier
	ds_read_b128 v[164:167], v163 offset:16384
	ds_read_b128 v[168:171], v163 offset:17408
	ds_read_b128 v[172:175], v163 offset:18432
	ds_read_b128 v[176:179], v163 offset:19456
	ds_read_b128 v[188:191], v163 offset:20480
	ds_read_b128 v[192:195], v163 offset:21504
	ds_read_b128 v[196:199], v163 offset:22528
	global_load_lds_dwordx4 v156, s[20:21]
	s_mov_b32 m0, s80
	ds_read_b128 v[200:203], v163 offset:23552
	global_load_lds_dwordx4 v142, s[20:21]
	s_barrier
	s_waitcnt lgkmcnt(0)
	s_setprio 1
	v_mfma_f32_16x16x32_bf16 v[64:67], v[132:135], v[164:167], v[64:67]
	v_mfma_f32_16x16x32_bf16 v[60:63], v[146:149], v[164:167], v[60:63]
	s_add_u32 s34, s6, 0x80000
	v_mfma_f32_16x16x32_bf16 v[48:51], v[132:135], v[172:175], v[48:51]
	s_addc_u32 s35, s7, 0
	v_mfma_f32_16x16x32_bf16 v[44:47], v[146:149], v[172:175], v[44:47]
	s_add_i32 s58, s58, s85
	v_mfma_f32_16x16x32_bf16 v[32:35], v[132:135], v[188:191], v[32:35]
	s_mov_b32 m0, s58
	v_mfma_f32_16x16x32_bf16 v[28:31], v[146:149], v[188:191], v[28:31]
	v_mfma_f32_16x16x32_bf16 v[16:19], v[132:135], v[196:199], v[16:19]
	v_mfma_f32_16x16x32_bf16 v[12:15], v[146:149], v[196:199], v[12:15]
	v_mfma_f32_16x16x32_bf16 v[64:67], v[136:139], v[168:171], v[64:67]
	v_mfma_f32_16x16x32_bf16 v[60:63], v[150:153], v[168:171], v[60:63]
	v_mfma_f32_16x16x32_bf16 v[48:51], v[136:139], v[176:179], v[48:51]
	v_mfma_f32_16x16x32_bf16 v[44:47], v[150:153], v[176:179], v[44:47]
	v_mfma_f32_16x16x32_bf16 v[32:35], v[136:139], v[192:195], v[32:35]
	v_mfma_f32_16x16x32_bf16 v[28:31], v[150:153], v[192:195], v[28:31]
	v_mfma_f32_16x16x32_bf16 v[16:19], v[136:139], v[200:203], v[16:19]
	v_mfma_f32_16x16x32_bf16 v[12:15], v[150:153], v[200:203], v[12:15]
	s_setprio 0
	s_barrier
	global_load_lds_dwordx4 v144, s[34:35]
	s_add_i32 m0, s58, 0x2000
	s_nop 0
	global_load_lds_dwordx4 v140, s[34:35]
	s_waitcnt vmcnt(6)
	s_barrier
	s_setprio 1
	v_mfma_f32_16x16x32_bf16 v[56:59], v[206:209], v[164:167], v[56:59]
	v_mfma_f32_16x16x32_bf16 v[52:55], v[214:217], v[164:167], v[52:55]
	s_add_i32 s34, 0, 0x18000
	v_mfma_f32_16x16x32_bf16 v[40:43], v[206:209], v[172:175], v[40:43]
	s_add_u32 s20, s20, 0x80000
	v_mfma_f32_16x16x32_bf16 v[36:39], v[214:217], v[172:175], v[36:39]
	s_addc_u32 s21, s21, 0
	v_mfma_f32_16x16x32_bf16 v[24:27], v[206:209], v[188:191], v[24:27]
	s_mov_b32 m0, s86
	v_mfma_f32_16x16x32_bf16 v[20:23], v[214:217], v[188:191], v[20:23]
	v_mfma_f32_16x16x32_bf16 v[8:11], v[206:209], v[196:199], v[8:11]
	v_mfma_f32_16x16x32_bf16 v[2:5], v[214:217], v[196:199], v[4:7]
	v_mfma_f32_16x16x32_bf16 v[56:59], v[210:213], v[168:171], v[56:59]
	v_mfma_f32_16x16x32_bf16 v[52:55], v[218:221], v[168:171], v[52:55]
	v_mfma_f32_16x16x32_bf16 v[40:43], v[210:213], v[176:179], v[40:43]
	v_mfma_f32_16x16x32_bf16 v[36:39], v[218:221], v[176:179], v[36:39]
	v_mfma_f32_16x16x32_bf16 v[24:27], v[210:213], v[192:195], v[24:27]
	v_mfma_f32_16x16x32_bf16 v[20:23], v[218:221], v[192:195], v[20:23]
	v_mfma_f32_16x16x32_bf16 v[8:11], v[210:213], v[200:203], v[8:11]
	v_mfma_f32_16x16x32_bf16 v[2:5], v[218:221], v[200:203], v[2:5]
	s_setprio 0
	s_barrier
	ds_read_b128 v[132:135], v182
	ds_read_b128 v[136:139], v182 offset:1024
	ds_read_b128 v[146:149], v182 offset:2048
	ds_read_b128 v[150:153], v182 offset:3072
	ds_read_b128 v[164:167], v163 offset:32768
	ds_read_b128 v[168:171], v163 offset:33792
	ds_read_b128 v[172:175], v163 offset:34816
	ds_read_b128 v[176:179], v163 offset:35840
	ds_read_b128 v[188:191], v163 offset:36864
	ds_read_b128 v[192:195], v163 offset:37888
	ds_read_b128 v[196:199], v163 offset:38912
	global_load_lds_dwordx4 v156, s[20:21]
	s_mov_b32 m0, s87
	ds_read_b128 v[200:203], v163 offset:39936
	global_load_lds_dwordx4 v142, s[20:21]
	s_waitcnt lgkmcnt(8)
	s_barrier
; #define PG8_STAGE(bufoff, gbase) PG8_STAGE_(bufoff, gbase, voffA)
; #define PG8_STAGEB(bufoff, gbase) PG8_STAGE_(bufoff, gbase, voffB)
; #define PG8_LDA(dst, b, h) do { _Pragma("unroll") for (int m = 0; m < 4; ++m) _Pragma("unroll") for (int k = 0; k < 2; ++k) dst[m][k] = *(const LAS bf16x8*)(lds + PG8_SA(b, h) + aoff + m * 2048 + k * 1024); } while (0)
; #define PG8_LDB(dst, b, h) do { _Pragma("unroll") for (int n = 0; n < 2; ++n) _Pragma("unroll") for (int k = 0; k < 2; ++k) dst[n][k] = *(const LAS bf16x8*)(lds + PG8_SB(b, h) + boff + n * 2048 + k * 1024); } while (0)
; #define PG8_MMA(ai, bj, At, Bt) do { __builtin_amdgcn_s_setprio(1); _Pragma("unroll") for (int m = 0; m < 4; ++m) _Pragma("unroll") for (int n = 0; n < 2; ++n) _Pragma("unroll") for (int k = 0; k < 2; ++k) \
;         acc[ai][bj][m][n] = __builtin_amdgcn_mfma_f32_16x16x32_bf16(Bt[n][k], At[m][k], acc[ai][bj][m][n], 0, 0, 0); __builtin_amdgcn_s_setprio(0); } while (0)
; #define PG8_WAIT_V(n) asm volatile("s_waitcnt vmcnt(" #n ")" ::: "memory")
; #define PG8_WAIT_L(n) asm volatile("s_waitcnt lgkmcnt(" #n ")" ::: "memory")
; #define PG8_BAR __builtin_amdgcn_s_barrier()
; #define PG8_SCHED __builtin_amdgcn_sched_barrier(0)
; template <class Epi>
; __device__ __forceinline__ void gemm_phase(LAS unsigned char* lds, const Gemm g, const StaticOrder& S, const Epi& E) {
;     ...
;             PG8_WAIT_L(8); PG8_BAR; PG8_WAIT_L(0); PG8_MMA(0, 0, At, B0); PG8_BAR; PG8_SCHED;
;             PG8_LDB(B1, 1, 1); PG8_STAGEB(PG8_SB(1, 0), b3);
;             PG8_BAR; PG8_WAIT_L(0); PG8_MMA(0, 1, At, B1); PG8_BAR;
;             PG8_LDA(At, 1, 1); PG8_STAGE(PG8_SA(1, 0), a3);
;             PG8_BAR; PG8_WAIT_L(0); PG8_MMA(1, 0, At, B0); PG8_BAR; PG8_SCHED;
;             PG8_STAGEB(PG8_SB(1, 1), b3 + hstep);
;             PG8_WAIT_V(6); PG8_BAR; PG8_MMA(1, 1, At, B1); PG8_BAR;
	s_waitcnt lgkmcnt(0)
	s_setprio 1
	v_mfma_f32_16x16x32_bf16 v[128:131], v[132:135], v[164:167], v[128:131]
	v_mfma_f32_16x16x32_bf16 v[124:127], v[146:149], v[164:167], v[124:127]
	s_add_i32 s20, 0, 0x1c000
	v_mfma_f32_16x16x32_bf16 v[112:115], v[132:135], v[172:175], v[112:115]
	s_add_i32 s21, s34, s85
	v_mfma_f32_16x16x32_bf16 v[108:111], v[146:149], v[172:175], v[108:111]
	s_add_i32 m0, s21, 0xffffff80
	v_mfma_f32_16x16x32_bf16 v[96:99], v[132:135], v[188:191], v[96:99]
	v_mfma_f32_16x16x32_bf16 v[92:95], v[146:149], v[188:191], v[92:95]
	v_mfma_f32_16x16x32_bf16 v[80:83], v[132:135], v[196:199], v[80:83]
	v_mfma_f32_16x16x32_bf16 v[76:79], v[146:149], v[196:199], v[76:79]
	v_mfma_f32_16x16x32_bf16 v[128:131], v[136:139], v[168:171], v[128:131]
	v_mfma_f32_16x16x32_bf16 v[124:127], v[150:153], v[168:171], v[124:127]
	v_mfma_f32_16x16x32_bf16 v[112:115], v[136:139], v[176:179], v[112:115]
	v_mfma_f32_16x16x32_bf16 v[108:111], v[150:153], v[176:179], v[108:111]
	v_mfma_f32_16x16x32_bf16 v[96:99], v[136:139], v[192:195], v[96:99]
	v_mfma_f32_16x16x32_bf16 v[92:95], v[150:153], v[192:195], v[92:95]
	v_mfma_f32_16x16x32_bf16 v[80:83], v[136:139], v[200:203], v[80:83]
	v_mfma_f32_16x16x32_bf16 v[76:79], v[150:153], v[200:203], v[76:79]
	s_setprio 0
	s_barrier
	ds_read_b128 v[206:209], v183
	ds_read_b128 v[210:213], v183 offset:1024
	ds_read_b128 v[214:217], v183 offset:2048
	global_load_lds_dwordx4 v144, s[6:7] offset:128
	s_add_i32 m0, s21, 0x1f80
	ds_read_b128 v[218:221], v183 offset:3072
	global_load_lds_dwordx4 v140, s[6:7] offset:128
	s_barrier
	s_waitcnt lgkmcnt(0)
	s_setprio 1
	v_mfma_f32_16x16x32_bf16 v[120:123], v[206:209], v[164:167], v[120:123]
	v_mfma_f32_16x16x32_bf16 v[116:119], v[214:217], v[164:167], v[116:119]
	v_mfma_f32_16x16x32_bf16 v[104:107], v[206:209], v[172:175], v[104:107]
	v_mfma_f32_16x16x32_bf16 v[100:103], v[214:217], v[172:175], v[100:103]
	v_mfma_f32_16x16x32_bf16 v[88:91], v[206:209], v[188:191], v[88:91]
	v_mfma_f32_16x16x32_bf16 v[84:87], v[214:217], v[188:191], v[84:87]
	v_mfma_f32_16x16x32_bf16 v[72:75], v[206:209], v[196:199], v[72:75]
	v_mfma_f32_16x16x32_bf16 v[68:71], v[214:217], v[196:199], v[68:71]
	v_mfma_f32_16x16x32_bf16 v[120:123], v[210:213], v[168:171], v[120:123]
	v_mfma_f32_16x16x32_bf16 v[116:119], v[218:221], v[168:171], v[116:119]
	v_mfma_f32_16x16x32_bf16 v[104:107], v[210:213], v[176:179], v[104:107]
	v_mfma_f32_16x16x32_bf16 v[100:103], v[218:221], v[176:179], v[100:103]
	v_mfma_f32_16x16x32_bf16 v[88:91], v[210:213], v[192:195], v[88:91]
	v_mfma_f32_16x16x32_bf16 v[84:87], v[218:221], v[192:195], v[84:87]
	v_mfma_f32_16x16x32_bf16 v[72:75], v[210:213], v[200:203], v[72:75]
	v_mfma_f32_16x16x32_bf16 v[68:71], v[218:221], v[200:203], v[68:71]
	s_setprio 0
	s_mov_b32 m0, s88
	s_barrier
	ds_read_b128 v[164:167], v163 offset:49152
	ds_read_b128 v[168:171], v163 offset:50176
	ds_read_b128 v[172:175], v163 offset:51200
	ds_read_b128 v[176:179], v163 offset:52224
	ds_read_b128 v[188:191], v163 offset:53248
	ds_read_b128 v[192:195], v163 offset:54272
	ds_read_b128 v[196:199], v163 offset:55296
	global_load_lds_dwordx4 v156, s[100:101]
	s_mov_b32 m0, s89
	ds_read_b128 v[200:203], v163 offset:56320
	global_load_lds_dwordx4 v142, s[100:101]
	s_barrier
	s_waitcnt lgkmcnt(0)
	s_setprio 1
	v_mfma_f32_16x16x32_bf16 v[64:67], v[132:135], v[164:167], v[64:67]
	v_mfma_f32_16x16x32_bf16 v[60:63], v[146:149], v[164:167], v[60:63]
	s_add_u32 s6, s6, 0x80080
	v_mfma_f32_16x16x32_bf16 v[48:51], v[132:135], v[172:175], v[48:51]
	s_addc_u32 s7, s7, 0
	v_mfma_f32_16x16x32_bf16 v[44:47], v[146:149], v[172:175], v[44:47]
	s_add_i32 s20, s20, s85
	v_mfma_f32_16x16x32_bf16 v[32:35], v[132:135], v[188:191], v[32:35]
	s_mov_b32 m0, s20
	v_mfma_f32_16x16x32_bf16 v[28:31], v[146:149], v[188:191], v[28:31]
	v_mfma_f32_16x16x32_bf16 v[16:19], v[132:135], v[196:199], v[16:19]
	v_mfma_f32_16x16x32_bf16 v[12:15], v[146:149], v[196:199], v[12:15]
	v_mfma_f32_16x16x32_bf16 v[64:67], v[136:139], v[168:171], v[64:67]
	v_mfma_f32_16x16x32_bf16 v[60:63], v[150:153], v[168:171], v[60:63]
	v_mfma_f32_16x16x32_bf16 v[48:51], v[136:139], v[176:179], v[48:51]
	v_mfma_f32_16x16x32_bf16 v[44:47], v[150:153], v[176:179], v[44:47]
	v_mfma_f32_16x16x32_bf16 v[32:35], v[136:139], v[192:195], v[32:35]
	v_mfma_f32_16x16x32_bf16 v[28:31], v[150:153], v[192:195], v[28:31]
	v_mfma_f32_16x16x32_bf16 v[16:19], v[136:139], v[200:203], v[16:19]
	v_mfma_f32_16x16x32_bf16 v[12:15], v[150:153], v[200:203], v[12:15]
	s_setprio 0
	s_barrier
	global_load_lds_dwordx4 v144, s[6:7]
	s_add_i32 m0, s20, 0x2000
	s_nop 0
	global_load_lds_dwordx4 v140, s[6:7]
	s_waitcnt vmcnt(6)
	s_barrier
	s_setprio 1
	v_mfma_f32_16x16x32_bf16 v[56:59], v[206:209], v[164:167], v[56:59]
	v_mfma_f32_16x16x32_bf16 v[52:55], v[214:217], v[164:167], v[52:55]
	s_add_u32 s42, s42, 0x400
	v_mfma_f32_16x16x32_bf16 v[40:43], v[206:209], v[172:175], v[40:43]
	s_addc_u32 s43, s43, 0
	v_mfma_f32_16x16x32_bf16 v[36:39], v[214:217], v[172:175], v[36:39]
	s_add_u32 s66, s66, 0x100
	v_mfma_f32_16x16x32_bf16 v[24:27], v[206:209], v[188:191], v[24:27]
	s_addc_u32 s67, s67, 0
	v_mfma_f32_16x16x32_bf16 v[20:23], v[214:217], v[188:191], v[20:23]
	s_add_u32 s91, s91, 0x100
	v_mfma_f32_16x16x32_bf16 v[6:9], v[206:209], v[196:199], v[8:11]
	s_addc_u32 s92, s92, 0
	v_mfma_f32_16x16x32_bf16 v[2:5], v[214:217], v[196:199], v[2:5]
	v_mfma_f32_16x16x32_bf16 v[56:59], v[210:213], v[168:171], v[56:59]
	v_mfma_f32_16x16x32_bf16 v[52:55], v[218:221], v[168:171], v[52:55]
	v_mfma_f32_16x16x32_bf16 v[40:43], v[210:213], v[176:179], v[40:43]
	v_mfma_f32_16x16x32_bf16 v[36:39], v[218:221], v[176:179], v[36:39]
	v_mfma_f32_16x16x32_bf16 v[24:27], v[210:213], v[192:195], v[24:27]
	v_mfma_f32_16x16x32_bf16 v[20:23], v[218:221], v[192:195], v[20:23]
	v_mfma_f32_16x16x32_bf16 v[8:11], v[210:213], v[200:203], v[6:9]
	v_mfma_f32_16x16x32_bf16 v[4:7], v[218:221], v[200:203], v[2:5]
	s_setprio 0
	s_cmp_gt_u32 s93, 29
	s_barrier
	s_cbranch_scc1 .LBB0_1370

; template <class Epi>
; __device__ __forceinline__ void gemm_phase(LAS unsigned char* lds, const Gemm g, const StaticOrder& S, const Epi& E) {
;     ...
;         const char* nA = has_next ? (const char*)g.A + (size_t)nxt.pm * tstep : cA; const char* nB = has_next ? (const char*)g.Bt + (size_t)nxt.pn * tstep : cB;
;         for (int t = 0; t < nt; t += 2) {
;             const bool last = (t == nt - 2);
;             const char* a1 = cA + (size_t)(t + 1) * kstep;
;             const char* a2 = last ? nA : cA + (size_t)(t + 2) * kstep; const char* b2 = last ? nB : cB + (size_t)(t + 2) * kstep;
;             const char* a3 = a2 + kstep; const char* b3 = b2 + kstep;
;             if constexpr (Epi::RESCALE) { if (t != 0 && (t & 7) == 0) { const int t2 = fresh_tid(); const int w2 = __builtin_amdgcn_readfirstlane(t2 >> 6); E.rescale(acc, cur, t >> 3, w2 >> 2, w2 & 3, t2 & 15, (t2 >> 4) & 3); } }
;             PG8_LDB(B0, 0, 0); PG8_SCHED; PG8_LDA(At, 0, 0); PG8_STAGE(PG8_SA(1, 1), a1 + hstep);
;             PG8_WAIT_L(8); PG8_BAR; PG8_WAIT_L(0); PG8_MMA(0, 0, At, B0); PG8_BAR; PG8_SCHED;
;             PG8_LDB(B1, 0, 1); PG8_STAGEB(PG8_SB(0, 0), b2);
;             PG8_BAR; PG8_WAIT_L(0); PG8_MMA(0, 1, At, B1); PG8_BAR;
;             PG8_LDA(At, 0, 1); PG8_STAGE(PG8_SA(0, 0), a2);
;             PG8_BAR; PG8_WAIT_L(0); PG8_MMA(1, 0, At, B0); PG8_BAR; PG8_SCHED;
;             PG8_STAGEB(PG8_SB(0, 1), b2 + hstep);
;             PG8_WAIT_V(6); PG8_BAR; PG8_MMA(1, 1, At, B1); PG8_BAR;
;             PG8_LDB(B0, 1, 0); PG8_SCHED; PG8_LDA(At, 1, 0); PG8_STAGE(PG8_SA(0, 1), a2 + hstep);
;             PG8_WAIT_L(8); PG8_BAR; PG8_WAIT_L(0); PG8_MMA(0, 0, At, B0); PG8_BAR; PG8_SCHED;
;             PG8_LDB(B1, 1, 1); PG8_STAGEB(PG8_SB(1, 0), b3);
;             PG8_BAR; PG8_WAIT_L(0); PG8_MMA(0, 1, At, B1); PG8_BAR;
;             PG8_LDA(At, 1, 1); PG8_STAGE(PG8_SA(1, 0), a3);
;             PG8_BAR; PG8_WAIT_L(0); PG8_MMA(1, 0, At, B0); PG8_BAR; PG8_SCHED;
;             PG8_STAGEB(PG8_SB(1, 1), b3 + hstep);
;             PG8_WAIT_V(6); PG8_BAR; PG8_MMA(1, 1, At, B1); PG8_BAR;
;         }
;         { const int t2 = fresh_tid(); const int w2 = __builtin_amdgcn_readfirstlane(t2 >> 6); E(acc, cur, w2 >> 2, w2 & 3, t2 & 15, (t2 >> 4) & 3); }
;         if (!has_next) break;
; #pragma unroll
;         for (int a = 0; a < 2; ++a)
; #pragma unroll
;             for (int b = 0; b < 2; ++b)
.LBB0_1446:
	v_mov_b64_e32 v[2:3], 0x100
	s_ashr_i32 s25, s24, 31
	v_cmp_lt_i64_e32 vcc, s[34:35], v[2:3]
	s_lshl_b64 s[34:35], s[24:25], 20
	s_add_u32 s34, s50, s34
	s_addc_u32 s35, s51, s35
	s_and_b64 s[46:47], vcc, exec
	s_cselect_b32 s25, s35, s31
	s_cselect_b32 s84, s34, s30
	s_ashr_i32 s7, s6, 31
	s_lshl_b64 s[46:47], s[6:7], 20
	s_add_u32 s46, s52, s46
	s_addc_u32 s47, s53, s47
	s_and_b64 s[48:49], vcc, exec
	s_cselect_b32 s7, s47, s21
	s_cselect_b32 s85, s46, s20
	s_add_u32 s30, s30, 0x80080
	s_addc_u32 s31, s31, 0
	s_add_u32 s86, s20, 0x100
	v_mov_b32_e32 v2, 0
	s_addc_u32 s87, s21, 0
	s_mov_b32 s88, -2
	v_mov_b32_e32 v3, v2
	v_mov_b32_e32 v4, v2
	v_mov_b32_e32 v5, v2
	v_mov_b32_e32 v6, v2
	v_mov_b32_e32 v7, v2
	v_mov_b32_e32 v8, v2
	v_mov_b32_e32 v9, v2
	v_mov_b32_e32 v18, v2
	v_mov_b32_e32 v19, v2
	v_mov_b32_e32 v20, v2
	v_mov_b32_e32 v21, v2
	v_mov_b32_e32 v22, v2
	v_mov_b32_e32 v23, v2
	v_mov_b32_e32 v24, v2
	v_mov_b32_e32 v25, v2
	v_mov_b32_e32 v34, v2
	v_mov_b32_e32 v35, v2
	v_mov_b32_e32 v36, v2
	v_mov_b32_e32 v37, v2
	v_mov_b32_e32 v38, v2
	v_mov_b32_e32 v39, v2
	v_mov_b32_e32 v40, v2
	v_mov_b32_e32 v41, v2
	v_mov_b32_e32 v50, v2
	v_mov_b32_e32 v51, v2
	v_mov_b32_e32 v52, v2
	v_mov_b32_e32 v53, v2
	s_waitcnt vmcnt(0)
	v_mov_b32_e32 v54, v2
	v_mov_b32_e32 v55, v2
	v_mov_b32_e32 v56, v2
	v_mov_b32_e32 v57, v2
	v_mov_b32_e32 v10, v2
	v_mov_b32_e32 v11, v2
	v_mov_b32_e32 v12, v2
	v_mov_b32_e32 v13, v2
	v_mov_b32_e32 v14, v2
	v_mov_b32_e32 v15, v2
	v_mov_b32_e32 v16, v2
	v_mov_b32_e32 v17, v2
	v_mov_b32_e32 v26, v2
	v_mov_b32_e32 v27, v2
	v_mov_b32_e32 v28, v2
	v_mov_b32_e32 v29, v2
	v_mov_b32_e32 v30, v2
	v_mov_b32_e32 v31, v2
	v_mov_b32_e32 v32, v2
	v_mov_b32_e32 v33, v2
	v_mov_b32_e32 v42, v2
	v_mov_b32_e32 v43, v2
	v_mov_b32_e32 v44, v2
	v_mov_b32_e32 v45, v2
	v_mov_b32_e32 v46, v2
	v_mov_b32_e32 v47, v2
	v_mov_b32_e32 v48, v2
	v_mov_b32_e32 v49, v2
	v_mov_b32_e32 v58, v2
	v_mov_b32_e32 v59, v2
	v_mov_b32_e32 v60, v2
	v_mov_b32_e32 v61, v2
	v_mov_b32_e32 v62, v2
	v_mov_b32_e32 v63, v2
	v_mov_b32_e32 v64, v2
	v_mov_b32_e32 v65, v2
	v_mov_b32_e32 v66, v2
	v_mov_b32_e32 v67, v2
	v_mov_b32_e32 v68, v2
	v_mov_b32_e32 v69, v2
	v_mov_b32_e32 v70, v2
	v_mov_b32_e32 v71, v2
	v_mov_b32_e32 v72, v2
	v_mov_b32_e32 v73, v2
	v_mov_b32_e32 v82, v2
	v_mov_b32_e32 v83, v2
	v_mov_b32_e32 v84, v2
	v_mov_b32_e32 v85, v2
	v_mov_b32_e32 v86, v2
	v_mov_b32_e32 v87, v2
	v_mov_b32_e32 v88, v2
	v_mov_b32_e32 v89, v2
	v_mov_b32_e32 v98, v2
	v_mov_b32_e32 v99, v2
	v_mov_b32_e32 v100, v2
	v_mov_b32_e32 v101, v2
	v_mov_b32_e32 v102, v2
	v_mov_b32_e32 v103, v2
	v_mov_b32_e32 v104, v2
	v_mov_b32_e32 v105, v2
	v_mov_b32_e32 v114, v2
	v_mov_b32_e32 v115, v2
	v_mov_b32_e32 v116, v2
	v_mov_b32_e32 v117, v2
	v_mov_b32_e32 v118, v2
	v_mov_b32_e32 v119, v2
	v_mov_b32_e32 v120, v2
	v_mov_b32_e32 v121, v2
	v_mov_b32_e32 v74, v2
	v_mov_b32_e32 v75, v2
	v_mov_b32_e32 v76, v2
	v_mov_b32_e32 v77, v2
	v_mov_b32_e32 v78, v2
	v_mov_b32_e32 v79, v2
	v_mov_b32_e32 v80, v2
	v_mov_b32_e32 v81, v2
	v_mov_b32_e32 v90, v2
	v_mov_b32_e32 v91, v2
	v_mov_b32_e32 v92, v2
	v_mov_b32_e32 v93, v2
	v_mov_b32_e32 v94, v2
	v_mov_b32_e32 v95, v2
	v_mov_b32_e32 v96, v2
	v_mov_b32_e32 v97, v2
	v_mov_b32_e32 v106, v2
	v_mov_b32_e32 v107, v2
	v_mov_b32_e32 v108, v2
	v_mov_b32_e32 v109, v2
	v_mov_b32_e32 v110, v2
	v_mov_b32_e32 v111, v2
	v_mov_b32_e32 v112, v2
	v_mov_b32_e32 v113, v2
	v_mov_b32_e32 v122, v2
	v_mov_b32_e32 v123, v2
	v_mov_b32_e32 v124, v2
	v_mov_b32_e32 v125, v2
	v_mov_b32_e32 v126, v2
	v_mov_b32_e32 v127, v2
	v_mov_b32_e32 v128, v2
	v_mov_b32_e32 v129, v2
	v_add_u32_e32 v140, 0x10000, v142
	v_add_u32_e32 v141, 0x14000, v142
	v_add_u32_e32 v182, 0x18000, v142
	v_add_u32_e32 v183, 0x1c000, v142
	s_add_u32 s20, s30, 0xfff80080
	s_addc_u32 s21, s31, -1
	s_add_i32 s58, 0, 0x10000
	s_cmp_eq_u32 s88, 28
	s_cselect_b32 s49, s25, s21
	s_cselect_b32 s48, s84, s20
	s_cselect_b32 s21, s7, s87
	s_cselect_b32 s20, s85, s86
	s_add_u32 s100, s48, s16
	s_addc_u32 s101, s49, s17
	s_add_i32 m0, s55, 0xc000
.LBB0_1447:
	ds_read_b128 v[144:147], v140
	ds_read_b128 v[148:151], v140 offset:1024
	ds_read_b128 v[152:155], v140 offset:2048
	ds_read_b128 v[156:159], v140 offset:3072
	ds_read_b128 v[160:163], v143
	ds_read_b128 v[164:167], v143 offset:1024
	ds_read_b128 v[168:171], v143 offset:2048
	ds_read_b128 v[172:175], v143 offset:3072
	ds_read_b128 v[176:179], v143 offset:4096
	ds_read_b128 v[188:191], v143 offset:5120
	ds_read_b128 v[192:195], v143 offset:6144
	global_load_lds_dwordx4 v136, s[30:31]
	s_add_i32 m0, s55, 0xe000
	ds_read_b128 v[196:199], v143 offset:7168
	global_load_lds_dwordx4 v138, s[30:31]
	s_waitcnt lgkmcnt(8)
	s_barrier
	s_waitcnt lgkmcnt(0)
	s_setprio 1
	v_mfma_f32_16x16x32_bf16 v[126:129], v[144:147], v[160:163], v[126:129]
	v_mfma_f32_16x16x32_bf16 v[122:125], v[152:155], v[160:163], v[122:125]
	s_add_i32 s89, 0, 0x14000
	v_mfma_f32_16x16x32_bf16 v[110:113], v[144:147], v[168:171], v[110:113]
	s_add_i32 s58, s58, s54
	v_mfma_f32_16x16x32_bf16 v[106:109], v[152:155], v[168:171], v[106:109]
	s_mov_b32 m0, s58
	v_mfma_f32_16x16x32_bf16 v[94:97], v[144:147], v[176:179], v[94:97]
	v_mfma_f32_16x16x32_bf16 v[90:93], v[152:155], v[176:179], v[90:93]
	v_mfma_f32_16x16x32_bf16 v[78:81], v[144:147], v[192:195], v[78:81]
	v_mfma_f32_16x16x32_bf16 v[74:77], v[152:155], v[192:195], v[74:77]
	v_mfma_f32_16x16x32_bf16 v[126:129], v[148:151], v[164:167], v[126:129]
	v_mfma_f32_16x16x32_bf16 v[122:125], v[156:159], v[164:167], v[122:125]
	v_mfma_f32_16x16x32_bf16 v[110:113], v[148:151], v[172:175], v[110:113]
	v_mfma_f32_16x16x32_bf16 v[106:109], v[156:159], v[172:175], v[106:109]
	v_mfma_f32_16x16x32_bf16 v[94:97], v[148:151], v[188:191], v[94:97]
	v_mfma_f32_16x16x32_bf16 v[90:93], v[156:159], v[188:191], v[90:93]
	v_mfma_f32_16x16x32_bf16 v[78:81], v[148:151], v[196:199], v[78:81]
	v_mfma_f32_16x16x32_bf16 v[74:77], v[156:159], v[196:199], v[74:77]
	s_setprio 0
	s_barrier
; #define PG8_STAGE(bufoff, gbase) PG8_STAGE_(bufoff, gbase, voffA)
; #define PG8_STAGEB(bufoff, gbase) PG8_STAGE_(bufoff, gbase, voffB)
; #define PG8_LDA(dst, b, h) do { _Pragma("unroll") for (int m = 0; m < 4; ++m) _Pragma("unroll") for (int k = 0; k < 2; ++k) dst[m][k] = *(const LAS bf16x8*)(lds + PG8_SA(b, h) + aoff + m * 2048 + k * 1024); } while (0)
; #define PG8_LDB(dst, b, h) do { _Pragma("unroll") for (int n = 0; n < 2; ++n) _Pragma("unroll") for (int k = 0; k < 2; ++k) dst[n][k] = *(const LAS bf16x8*)(lds + PG8_SB(b, h) + boff + n * 2048 + k * 1024); } while (0)
; #define PG8_MMA(ai, bj, At, Bt) do { __builtin_amdgcn_s_setprio(1); _Pragma("unroll") for (int m = 0; m < 4; ++m) _Pragma("unroll") for (int n = 0; n < 2; ++n) _Pragma("unroll") for (int k = 0; k < 2; ++k) \
;         acc[ai][bj][m][n] = __builtin_amdgcn_mfma_f32_16x16x32_bf16(Bt[n][k], At[m][k], acc[ai][bj][m][n], 0, 0, 0); __builtin_amdgcn_s_setprio(0); } while (0)
; #define PG8_WAIT_V(n) asm volatile("s_waitcnt vmcnt(" #n ")" ::: "memory")
; #define PG8_WAIT_L(n) asm volatile("s_waitcnt lgkmcnt(" #n ")" ::: "memory")
; #define PG8_BAR __builtin_amdgcn_s_barrier()
; #define PG8_SCHED __builtin_amdgcn_sched_barrier(0)
; template <class Epi>
; __device__ __forceinline__ void gemm_phase(LAS unsigned char* lds, const Gemm g, const StaticOrder& S, const Epi& E) {
;     ...
;             PG8_LDB(B1, 0, 1); PG8_STAGEB(PG8_SB(0, 0), b2);
;             PG8_BAR; PG8_WAIT_L(0); PG8_MMA(0, 1, At, B1); PG8_BAR;
;             PG8_LDA(At, 0, 1); PG8_STAGE(PG8_SA(0, 0), a2);
;             PG8_BAR; PG8_WAIT_L(0); PG8_MMA(1, 0, At, B0); PG8_BAR; PG8_SCHED;
;             PG8_STAGEB(PG8_SB(0, 1), b2 + hstep);
;             PG8_WAIT_V(6); PG8_BAR; PG8_MMA(1, 1, At, B1); PG8_BAR;
;             PG8_LDB(B0, 1, 0); PG8_SCHED; PG8_LDA(At, 1, 0); PG8_STAGE(PG8_SA(0, 1), a2 + hstep);
;             PG8_WAIT_L(8); PG8_BAR; PG8_WAIT_L(0); PG8_MMA(0, 0, At, B0); PG8_BAR; PG8_SCHED;
	ds_read_b128 v[200:203], v141
	ds_read_b128 v[206:209], v141 offset:1024
	ds_read_b128 v[210:213], v141 offset:2048
	global_load_lds_dwordx4 v0, s[20:21]
	s_add_i32 m0, s58, 0x2000
	ds_read_b128 v[214:217], v141 offset:3072
	global_load_lds_dwordx4 v130, s[20:21]
	s_barrier
	s_waitcnt lgkmcnt(0)
	s_setprio 1
	v_mfma_f32_16x16x32_bf16 v[118:121], v[200:203], v[160:163], v[118:121]
	v_mfma_f32_16x16x32_bf16 v[114:117], v[210:213], v[160:163], v[114:117]
	v_mfma_f32_16x16x32_bf16 v[102:105], v[200:203], v[168:171], v[102:105]
	v_mfma_f32_16x16x32_bf16 v[98:101], v[210:213], v[168:171], v[98:101]
	v_mfma_f32_16x16x32_bf16 v[86:89], v[200:203], v[176:179], v[86:89]
	v_mfma_f32_16x16x32_bf16 v[82:85], v[210:213], v[176:179], v[82:85]
	v_mfma_f32_16x16x32_bf16 v[70:73], v[200:203], v[192:195], v[70:73]
	v_mfma_f32_16x16x32_bf16 v[66:69], v[210:213], v[192:195], v[66:69]
	v_mfma_f32_16x16x32_bf16 v[118:121], v[206:209], v[164:167], v[118:121]
	v_mfma_f32_16x16x32_bf16 v[114:117], v[214:217], v[164:167], v[114:117]
	v_mfma_f32_16x16x32_bf16 v[102:105], v[206:209], v[172:175], v[102:105]
	v_mfma_f32_16x16x32_bf16 v[98:101], v[214:217], v[172:175], v[98:101]
	v_mfma_f32_16x16x32_bf16 v[86:89], v[206:209], v[188:191], v[86:89]
	v_mfma_f32_16x16x32_bf16 v[82:85], v[214:217], v[188:191], v[82:85]
	v_mfma_f32_16x16x32_bf16 v[70:73], v[206:209], v[196:199], v[70:73]
	v_mfma_f32_16x16x32_bf16 v[66:69], v[214:217], v[196:199], v[66:69]
	s_setprio 0
	s_mov_b32 m0, s55
	s_barrier
	ds_read_b128 v[160:163], v143 offset:16384
	ds_read_b128 v[164:167], v143 offset:17408
	ds_read_b128 v[168:171], v143 offset:18432
	ds_read_b128 v[172:175], v143 offset:19456
	ds_read_b128 v[176:179], v143 offset:20480
	ds_read_b128 v[188:191], v143 offset:21504
	ds_read_b128 v[192:195], v143 offset:22528
	global_load_lds_dwordx4 v134, s[48:49]
	s_mov_b32 m0, s62
	ds_read_b128 v[196:199], v143 offset:23552
	global_load_lds_dwordx4 v132, s[48:49]
	s_barrier
	s_waitcnt lgkmcnt(0)
	s_setprio 1
	v_mfma_f32_16x16x32_bf16 v[62:65], v[144:147], v[160:163], v[62:65]
	v_mfma_f32_16x16x32_bf16 v[58:61], v[152:155], v[160:163], v[58:61]
	s_add_u32 s58, s20, 0x80000
	v_mfma_f32_16x16x32_bf16 v[46:49], v[144:147], v[168:171], v[46:49]
	s_addc_u32 s59, s21, 0
	v_mfma_f32_16x16x32_bf16 v[42:45], v[152:155], v[168:171], v[42:45]
	s_add_i32 s89, s89, s54
	v_mfma_f32_16x16x32_bf16 v[30:33], v[144:147], v[176:179], v[30:33]
	s_mov_b32 m0, s89
	v_mfma_f32_16x16x32_bf16 v[26:29], v[152:155], v[176:179], v[26:29]
	v_mfma_f32_16x16x32_bf16 v[14:17], v[144:147], v[192:195], v[14:17]
	v_mfma_f32_16x16x32_bf16 v[10:13], v[152:155], v[192:195], v[10:13]
	v_mfma_f32_16x16x32_bf16 v[62:65], v[148:151], v[164:167], v[62:65]
	v_mfma_f32_16x16x32_bf16 v[58:61], v[156:159], v[164:167], v[58:61]
	v_mfma_f32_16x16x32_bf16 v[46:49], v[148:151], v[172:175], v[46:49]
	v_mfma_f32_16x16x32_bf16 v[42:45], v[156:159], v[172:175], v[42:45]
	v_mfma_f32_16x16x32_bf16 v[30:33], v[148:151], v[188:191], v[30:33]
	v_mfma_f32_16x16x32_bf16 v[26:29], v[156:159], v[188:191], v[26:29]
	v_mfma_f32_16x16x32_bf16 v[14:17], v[148:151], v[196:199], v[14:17]
	v_mfma_f32_16x16x32_bf16 v[10:13], v[156:159], v[196:199], v[10:13]
	s_setprio 0
	s_barrier
	global_load_lds_dwordx4 v0, s[58:59]
	s_add_i32 m0, s89, 0x2000
	s_nop 0
	global_load_lds_dwordx4 v130, s[58:59]
	s_waitcnt vmcnt(6)
	s_barrier
	s_setprio 1
	v_mfma_f32_16x16x32_bf16 v[54:57], v[200:203], v[160:163], v[54:57]
	v_mfma_f32_16x16x32_bf16 v[50:53], v[210:213], v[160:163], v[50:53]
	s_add_i32 s58, 0, 0x18000
	v_mfma_f32_16x16x32_bf16 v[38:41], v[200:203], v[168:171], v[38:41]
	s_add_u32 s48, s48, 0x80000
	v_mfma_f32_16x16x32_bf16 v[34:37], v[210:213], v[168:171], v[34:37]
	s_addc_u32 s49, s49, 0
	v_mfma_f32_16x16x32_bf16 v[22:25], v[200:203], v[176:179], v[22:25]
	s_mov_b32 m0, s63
	v_mfma_f32_16x16x32_bf16 v[18:21], v[210:213], v[176:179], v[18:21]
	v_mfma_f32_16x16x32_bf16 v[6:9], v[200:203], v[192:195], v[6:9]
	v_mfma_f32_16x16x32_bf16 v[2:5], v[210:213], v[192:195], v[2:5]
	v_mfma_f32_16x16x32_bf16 v[54:57], v[206:209], v[164:167], v[54:57]
	v_mfma_f32_16x16x32_bf16 v[50:53], v[214:217], v[164:167], v[50:53]
	v_mfma_f32_16x16x32_bf16 v[38:41], v[206:209], v[172:175], v[38:41]
	v_mfma_f32_16x16x32_bf16 v[34:37], v[214:217], v[172:175], v[34:37]
	v_mfma_f32_16x16x32_bf16 v[22:25], v[206:209], v[188:191], v[22:25]
	v_mfma_f32_16x16x32_bf16 v[18:21], v[214:217], v[188:191], v[18:21]
	v_mfma_f32_16x16x32_bf16 v[6:9], v[206:209], v[196:199], v[6:9]
	v_mfma_f32_16x16x32_bf16 v[2:5], v[214:217], v[196:199], v[2:5]
	s_setprio 0
	s_barrier
	ds_read_b128 v[144:147], v182
	ds_read_b128 v[148:151], v182 offset:1024
	ds_read_b128 v[152:155], v182 offset:2048
	ds_read_b128 v[156:159], v182 offset:3072
	ds_read_b128 v[160:163], v143 offset:32768
	ds_read_b128 v[164:167], v143 offset:33792
	ds_read_b128 v[168:171], v143 offset:34816
	ds_read_b128 v[172:175], v143 offset:35840
	ds_read_b128 v[176:179], v143 offset:36864
	ds_read_b128 v[188:191], v143 offset:37888
	ds_read_b128 v[192:195], v143 offset:38912
	global_load_lds_dwordx4 v134, s[48:49]
	s_mov_b32 m0, s66
	ds_read_b128 v[196:199], v143 offset:39936
	global_load_lds_dwordx4 v132, s[48:49]
	s_waitcnt lgkmcnt(8)
	s_barrier
; __device__ __forceinline__ int fresh_tid() { int t = threadIdx.x; asm volatile("" : "+v"(t)); return t; }
; #define PG8_STAGE(bufoff, gbase) PG8_STAGE_(bufoff, gbase, voffA)
; #define PG8_STAGEB(bufoff, gbase) PG8_STAGE_(bufoff, gbase, voffB)
; #define PG8_LDA(dst, b, h) do { _Pragma("unroll") for (int m = 0; m < 4; ++m) _Pragma("unroll") for (int k = 0; k < 2; ++k) dst[m][k] = *(const LAS bf16x8*)(lds + PG8_SA(b, h) + aoff + m * 2048 + k * 1024); } while (0)
; template <class Epi>
; __device__ __forceinline__ void gemm_phase(LAS unsigned char* lds, const Gemm g, const StaticOrder& S, const Epi& E) {
;     ...
;         for (int t = 0; t < nt; t += 2) {
;             const bool last = (t == nt - 2);
;             const char* a1 = cA + (size_t)(t + 1) * kstep;
;             const char* a2 = last ? nA : cA + (size_t)(t + 2) * kstep; const char* b2 = last ? nB : cB + (size_t)(t + 2) * kstep;
;             const char* a3 = a2 + kstep; const char* b3 = b2 + kstep;
;             if constexpr (Epi::RESCALE) { if (t != 0 && (t & 7) == 0) { const int t2 = fresh_tid(); const int w2 = __builtin_amdgcn_readfirstlane(t2 >> 6); E.rescale(acc, cur, t >> 3, w2 >> 2, w2 & 3, t2 & 15, (t2 >> 4) & 3); } }
;             PG8_LDB(B0, 0, 0); PG8_SCHED; PG8_LDA(At, 0, 0); PG8_STAGE(PG8_SA(1, 1), a1 + hstep);
;             PG8_WAIT_L(8); PG8_BAR; PG8_WAIT_L(0); PG8_MMA(0, 0, At, B0); PG8_BAR; PG8_SCHED;
;             PG8_LDB(B1, 0, 1); PG8_STAGEB(PG8_SB(0, 0), b2);
;             PG8_BAR; PG8_WAIT_L(0); PG8_MMA(0, 1, At, B1); PG8_BAR;
;             PG8_LDA(At, 0, 1); PG8_STAGE(PG8_SA(0, 0), a2);
;             PG8_BAR; PG8_WAIT_L(0); PG8_MMA(1, 0, At, B0); PG8_BAR; PG8_SCHED;
;             PG8_STAGEB(PG8_SB(0, 1), b2 + hstep);
;             PG8_WAIT_V(6); PG8_BAR; PG8_MMA(1, 1, At, B1); PG8_BAR;
;             PG8_LDB(B0, 1, 0); PG8_SCHED; PG8_LDA(At, 1, 0); PG8_STAGE(PG8_SA(0, 1), a2 + hstep);
;             PG8_WAIT_L(8); PG8_BAR; PG8_WAIT_L(0); PG8_MMA(0, 0, At, B0); PG8_BAR; PG8_SCHED;
;             PG8_LDB(B1, 1, 1); PG8_STAGEB(PG8_SB(1, 0), b3);
;             PG8_BAR; PG8_WAIT_L(0); PG8_MMA(0, 1, At, B1); PG8_BAR;
;             PG8_LDA(At, 1, 1); PG8_STAGE(PG8_SA(1, 0), a3);
;             PG8_BAR; PG8_WAIT_L(0); PG8_MMA(1, 0, At, B0); PG8_BAR; PG8_SCHED;
;             PG8_STAGEB(PG8_SB(1, 1), b3 + hstep);
;             PG8_WAIT_V(6); PG8_BAR; PG8_MMA(1, 1, At, B1); PG8_BAR;
	s_waitcnt lgkmcnt(0)
	s_setprio 1
	v_mfma_f32_16x16x32_bf16 v[126:129], v[144:147], v[160:163], v[126:129]
	v_mfma_f32_16x16x32_bf16 v[122:125], v[152:155], v[160:163], v[122:125]
	s_add_i32 s48, 0, 0x1c000
	v_mfma_f32_16x16x32_bf16 v[110:113], v[144:147], v[168:171], v[110:113]
	s_add_i32 s49, s58, s54
	v_mfma_f32_16x16x32_bf16 v[106:109], v[152:155], v[168:171], v[106:109]
	s_add_i32 m0, s49, 0xffffff80
	v_mfma_f32_16x16x32_bf16 v[94:97], v[144:147], v[176:179], v[94:97]
	v_mfma_f32_16x16x32_bf16 v[90:93], v[152:155], v[176:179], v[90:93]
	v_mfma_f32_16x16x32_bf16 v[78:81], v[144:147], v[192:195], v[78:81]
	v_mfma_f32_16x16x32_bf16 v[74:77], v[152:155], v[192:195], v[74:77]
	v_mfma_f32_16x16x32_bf16 v[126:129], v[148:151], v[164:167], v[126:129]
	v_mfma_f32_16x16x32_bf16 v[122:125], v[156:159], v[164:167], v[122:125]
	v_mfma_f32_16x16x32_bf16 v[110:113], v[148:151], v[172:175], v[110:113]
	v_mfma_f32_16x16x32_bf16 v[106:109], v[156:159], v[172:175], v[106:109]
	v_mfma_f32_16x16x32_bf16 v[94:97], v[148:151], v[188:191], v[94:97]
	v_mfma_f32_16x16x32_bf16 v[90:93], v[156:159], v[188:191], v[90:93]
	v_mfma_f32_16x16x32_bf16 v[78:81], v[148:151], v[196:199], v[78:81]
	v_mfma_f32_16x16x32_bf16 v[74:77], v[156:159], v[196:199], v[74:77]
	s_setprio 0
	s_barrier
	ds_read_b128 v[200:203], v183
	ds_read_b128 v[206:209], v183 offset:1024
	ds_read_b128 v[210:213], v183 offset:2048
	global_load_lds_dwordx4 v0, s[20:21] offset:128
	s_add_i32 m0, s49, 0x1f80
	ds_read_b128 v[214:217], v183 offset:3072
	global_load_lds_dwordx4 v130, s[20:21] offset:128
	s_barrier
	s_waitcnt lgkmcnt(0)
	s_setprio 1
	v_mfma_f32_16x16x32_bf16 v[118:121], v[200:203], v[160:163], v[118:121]
	v_mfma_f32_16x16x32_bf16 v[114:117], v[210:213], v[160:163], v[114:117]
	v_mfma_f32_16x16x32_bf16 v[102:105], v[200:203], v[168:171], v[102:105]
	v_mfma_f32_16x16x32_bf16 v[98:101], v[210:213], v[168:171], v[98:101]
	v_mfma_f32_16x16x32_bf16 v[86:89], v[200:203], v[176:179], v[86:89]
	v_mfma_f32_16x16x32_bf16 v[82:85], v[210:213], v[176:179], v[82:85]
	v_mfma_f32_16x16x32_bf16 v[70:73], v[200:203], v[192:195], v[70:73]
	v_mfma_f32_16x16x32_bf16 v[66:69], v[210:213], v[192:195], v[66:69]
	v_mfma_f32_16x16x32_bf16 v[118:121], v[206:209], v[164:167], v[118:121]
	v_mfma_f32_16x16x32_bf16 v[114:117], v[214:217], v[164:167], v[114:117]
	v_mfma_f32_16x16x32_bf16 v[102:105], v[206:209], v[172:175], v[102:105]
	v_mfma_f32_16x16x32_bf16 v[98:101], v[214:217], v[172:175], v[98:101]
	v_mfma_f32_16x16x32_bf16 v[86:89], v[206:209], v[188:191], v[86:89]
	v_mfma_f32_16x16x32_bf16 v[82:85], v[214:217], v[188:191], v[82:85]
	v_mfma_f32_16x16x32_bf16 v[70:73], v[206:209], v[196:199], v[70:73]
	v_mfma_f32_16x16x32_bf16 v[66:69], v[214:217], v[196:199], v[66:69]
	s_setprio 0
	s_mov_b32 m0, s67
	s_barrier
	ds_read_b128 v[160:163], v143 offset:49152
	ds_read_b128 v[164:167], v143 offset:50176
	ds_read_b128 v[168:171], v143 offset:51200
	ds_read_b128 v[172:175], v143 offset:52224
	ds_read_b128 v[176:179], v143 offset:53248
	ds_read_b128 v[188:191], v143 offset:54272
	ds_read_b128 v[192:195], v143 offset:55296
	global_load_lds_dwordx4 v134, s[100:101]
	s_mov_b32 m0, s80
	ds_read_b128 v[196:199], v143 offset:56320
	global_load_lds_dwordx4 v132, s[100:101]
	s_barrier
	s_waitcnt lgkmcnt(0)
	s_setprio 1
	v_mfma_f32_16x16x32_bf16 v[62:65], v[144:147], v[160:163], v[62:65]
	v_mfma_f32_16x16x32_bf16 v[58:61], v[152:155], v[160:163], v[58:61]
	s_add_u32 s20, s20, 0x80080
	v_mfma_f32_16x16x32_bf16 v[46:49], v[144:147], v[168:171], v[46:49]
	s_addc_u32 s21, s21, 0
	v_mfma_f32_16x16x32_bf16 v[42:45], v[152:155], v[168:171], v[42:45]
	s_add_i32 s48, s48, s54
	v_mfma_f32_16x16x32_bf16 v[30:33], v[144:147], v[176:179], v[30:33]
	s_mov_b32 m0, s48
	v_mfma_f32_16x16x32_bf16 v[26:29], v[152:155], v[176:179], v[26:29]
	v_mfma_f32_16x16x32_bf16 v[14:17], v[144:147], v[192:195], v[14:17]
	v_mfma_f32_16x16x32_bf16 v[10:13], v[152:155], v[192:195], v[10:13]
	v_mfma_f32_16x16x32_bf16 v[62:65], v[148:151], v[164:167], v[62:65]
	v_mfma_f32_16x16x32_bf16 v[58:61], v[156:159], v[164:167], v[58:61]
	v_mfma_f32_16x16x32_bf16 v[46:49], v[148:151], v[172:175], v[46:49]
	v_mfma_f32_16x16x32_bf16 v[42:45], v[156:159], v[172:175], v[42:45]
	v_mfma_f32_16x16x32_bf16 v[30:33], v[148:151], v[188:191], v[30:33]
	v_mfma_f32_16x16x32_bf16 v[26:29], v[156:159], v[188:191], v[26:29]
	v_mfma_f32_16x16x32_bf16 v[14:17], v[148:151], v[196:199], v[14:17]
	v_mfma_f32_16x16x32_bf16 v[10:13], v[156:159], v[196:199], v[10:13]
	s_setprio 0
	s_barrier
	global_load_lds_dwordx4 v0, s[20:21]
	s_add_i32 m0, s48, 0x2000
	s_nop 0
	global_load_lds_dwordx4 v130, s[20:21]
	s_waitcnt vmcnt(6)
	s_barrier
	s_setprio 1
	v_mfma_f32_16x16x32_bf16 v[54:57], v[200:203], v[160:163], v[54:57]
	v_mfma_f32_16x16x32_bf16 v[50:53], v[210:213], v[160:163], v[50:53]
	s_add_i32 s88, s88, 2
	v_mfma_f32_16x16x32_bf16 v[38:41], v[200:203], v[168:171], v[38:41]
	s_add_u32 s30, s30, 0x100
	v_mfma_f32_16x16x32_bf16 v[34:37], v[210:213], v[168:171], v[34:37]
	s_addc_u32 s31, s31, 0
	v_mfma_f32_16x16x32_bf16 v[22:25], v[200:203], v[176:179], v[22:25]
	s_add_u32 s86, s86, 0x100
	v_mfma_f32_16x16x32_bf16 v[18:21], v[210:213], v[176:179], v[18:21]
	s_addc_u32 s87, s87, 0
	v_mfma_f32_16x16x32_bf16 v[6:9], v[200:203], v[192:195], v[6:9]
	s_add_u32 s20, s30, 0xfff80080
	v_mfma_f32_16x16x32_bf16 v[2:5], v[210:213], v[192:195], v[2:5]
	s_addc_u32 s21, s31, -1
	v_mfma_f32_16x16x32_bf16 v[54:57], v[206:209], v[164:167], v[54:57]
	s_add_i32 s58, 0, 0x10000
	v_mfma_f32_16x16x32_bf16 v[50:53], v[214:217], v[164:167], v[50:53]
	s_cmp_eq_u32 s88, 28
	v_mfma_f32_16x16x32_bf16 v[38:41], v[206:209], v[172:175], v[38:41]
	s_cselect_b32 s49, s25, s21
	v_mfma_f32_16x16x32_bf16 v[34:37], v[214:217], v[172:175], v[34:37]
	s_cselect_b32 s48, s84, s20
	v_mfma_f32_16x16x32_bf16 v[22:25], v[206:209], v[188:191], v[22:25]
	s_cselect_b32 s21, s7, s87
	v_mfma_f32_16x16x32_bf16 v[18:21], v[214:217], v[188:191], v[18:21]
	s_cselect_b32 s20, s85, s86
	v_mfma_f32_16x16x32_bf16 v[6:9], v[206:209], v[196:199], v[6:9]
	s_add_u32 s100, s48, s16
	v_mfma_f32_16x16x32_bf16 v[2:5], v[214:217], v[196:199], v[2:5]
	s_addc_u32 s101, s49, s17
	s_add_i32 m0, s55, 0xc000
	s_setprio 0
	s_cmp_gt_u32 s88, 29
	s_barrier
;     __device__ __forceinline__ void operator()(AccT& acc, const Unit& u, int wr, int wc, int fr, int fq) const {
;         int row0 = u.pm * 256 + wr * 64 + fr, col0 = u.pn * 256 + wc * 32 + 8 * fq;
;         asm volatile("" : "+v"(row0), "+v"(col0));
; #pragma unroll
;         for (int ai = 0; ai < 2; ++ai)
; #pragma unroll
;             for (int m = 0; m < 4; ++m) { const size_t off = (size_t)(row0 + ai * 128 + m * 16) * DM + col0;
; #pragma unroll
;                 for (int bj = 0; bj < 2; ++bj) { const f32x4 x0 = *(const f32x4*)(xin + off + bj * 128), x1 = *(const f32x4*)(xin + off + bj * 128 + 4);
;                     __builtin_nontemporal_store(x0 + acc[ai][bj][m][0], (f32x4*)(out + off + bj * 128)); __builtin_nontemporal_store(x1 + acc[ai][bj][m][1], (f32x4*)(out + off + bj * 128 + 4)); } }
;     }
	s_cbranch_scc0 .LBB0_1447
	v_mov_b32_e32 v141, v250
	s_lshl_b32 s20, s83, 8
	v_readfirstlane_b32 s7, v141
	s_ashr_i32 s21, s7, 2
	s_andn2_b32 s21, s21, 63
	s_lshr_b32 s7, s7, 1
	s_add_i32 s21, s21, s20
	s_lshl_b32 s20, s82, 8
	s_and_b32 s7, s7, 0x60
	v_and_or_b32 v140, v141, 15, s21
	s_or_b32 s7, s7, s20
	v_lshrrev_b32_e32 v141, 1, v141
	v_and_or_b32 v144, v141, 24, s7
	s_mov_b64 s[20:21], 0x20000
	v_ashrrev_i32_e32 v141, 31, v140
	v_ashrrev_i32_e32 v145, 31, v144
	v_lshlrev_b64 v[140:141], 11, v[140:141]
	v_lshl_add_u64 v[140:141], v[140:141], 0, v[144:145]
	v_lshlrev_b64 v[140:141], 2, v[140:141]
	v_lshl_add_u64 v[152:153], s[0:1], 0, v[140:141]
	global_load_dwordx4 v[144:147], v[152:153], off offset:16
	global_load_dwordx4 v[148:151], v[152:153], off
	s_and_b64 vcc, exec, s[42:43]
	s_mov_b32 s82, s6
	s_mov_b32 s83, s24
	s_mov_b64 s[30:31], s[34:35]
	s_mov_b32 s86, 0x3fb8aa3b
	s_mov_b32 s89, 0x42b17218
	s_waitcnt vmcnt(0)
	v_pk_add_f32 v[124:125], v[124:125], v[146:147]
	v_pk_add_f32 v[128:129], v[128:129], v[150:151]
	v_pk_add_f32 v[126:127], v[126:127], v[148:149]
	v_lshl_add_u64 v[148:149], s[44:45], 0, v[140:141]
	v_pk_add_f32 v[122:123], v[122:123], v[144:145]
	global_store_dwordx4 v[148:149], v[126:129], off nt
	global_store_dwordx4 v[148:149], v[122:125], off offset:16 nt
	global_load_dwordx4 v[122:125], v[152:153], off offset:528
	s_nop 0
	global_load_dwordx4 v[126:129], v[152:153], off offset:512
	s_waitcnt vmcnt(0)
	v_pk_add_f32 v[116:117], v[116:117], v[124:125]
	v_pk_add_f32 v[120:121], v[120:121], v[128:129]
	v_pk_add_f32 v[118:119], v[118:119], v[126:127]
	v_pk_add_f32 v[114:115], v[114:115], v[122:123]
	v_lshl_add_u64 v[122:123], v[140:141], 0, s[20:21]
	global_store_dwordx4 v[148:149], v[118:121], off offset:512 nt
	global_store_dwordx4 v[148:149], v[114:117], off offset:528 nt
	v_lshl_add_u64 v[124:125], s[0:1], 0, v[122:123]
	global_load_dwordx4 v[114:117], v[124:125], off offset:16
	global_load_dwordx4 v[118:121], v[124:125], off
	s_mov_b64 s[20:21], 0x40000
	s_waitcnt vmcnt(0)
	v_pk_add_f32 v[108:109], v[108:109], v[116:117]
	v_pk_add_f32 v[112:113], v[112:113], v[120:121]
	v_pk_add_f32 v[110:111], v[110:111], v[118:119]
	v_lshl_add_u64 v[118:119], s[44:45], 0, v[122:123]
	v_pk_add_f32 v[106:107], v[106:107], v[114:115]
	global_store_dwordx4 v[118:119], v[110:113], off nt
	global_store_dwordx4 v[118:119], v[106:109], off offset:16 nt
	global_load_dwordx4 v[106:109], v[124:125], off offset:528
	s_nop 0
	global_load_dwordx4 v[110:113], v[124:125], off offset:512
	s_waitcnt vmcnt(0)
	v_pk_add_f32 v[100:101], v[100:101], v[108:109]
	v_pk_add_f32 v[104:105], v[104:105], v[112:113]
	v_pk_add_f32 v[102:103], v[102:103], v[110:111]
	v_pk_add_f32 v[98:99], v[98:99], v[106:107]
	v_lshl_add_u64 v[106:107], v[140:141], 0, s[20:21]
	global_store_dwordx4 v[118:119], v[102:105], off offset:512 nt
	global_store_dwordx4 v[118:119], v[98:101], off offset:528 nt
	v_lshl_add_u64 v[108:109], s[0:1], 0, v[106:107]
	global_load_dwordx4 v[98:101], v[108:109], off offset:16
	global_load_dwordx4 v[102:105], v[108:109], off
	s_mov_b64 s[20:21], 0x60000
	s_waitcnt vmcnt(0)
	v_pk_add_f32 v[92:93], v[92:93], v[100:101]
	v_pk_add_f32 v[96:97], v[96:97], v[104:105]
	v_pk_add_f32 v[94:95], v[94:95], v[102:103]
	v_lshl_add_u64 v[102:103], s[44:45], 0, v[106:107]
	v_pk_add_f32 v[90:91], v[90:91], v[98:99]
	global_store_dwordx4 v[102:103], v[94:97], off nt
	global_store_dwordx4 v[102:103], v[90:93], off offset:16 nt
	global_load_dwordx4 v[90:93], v[108:109], off offset:528
	s_nop 0
	global_load_dwordx4 v[94:97], v[108:109], off offset:512
	s_waitcnt vmcnt(0)
	v_pk_add_f32 v[84:85], v[84:85], v[92:93]
	v_pk_add_f32 v[88:89], v[88:89], v[96:97]
	v_pk_add_f32 v[86:87], v[86:87], v[94:95]
	v_pk_add_f32 v[82:83], v[82:83], v[90:91]
	v_lshl_add_u64 v[90:91], v[140:141], 0, s[20:21]
	global_store_dwordx4 v[102:103], v[86:89], off offset:512 nt
	global_store_dwordx4 v[102:103], v[82:85], off offset:528 nt
	v_lshl_add_u64 v[92:93], s[0:1], 0, v[90:91]
	global_load_dwordx4 v[82:85], v[92:93], off offset:16
	global_load_dwordx4 v[86:89], v[92:93], off
	s_mov_b64 s[20:21], 0x100000
	s_waitcnt vmcnt(0)
	v_pk_add_f32 v[76:77], v[76:77], v[84:85]
	v_pk_add_f32 v[80:81], v[80:81], v[88:89]
	v_pk_add_f32 v[78:79], v[78:79], v[86:87]
	v_lshl_add_u64 v[86:87], s[44:45], 0, v[90:91]
	v_pk_add_f32 v[74:75], v[74:75], v[82:83]
	global_store_dwordx4 v[86:87], v[78:81], off nt
	global_store_dwordx4 v[86:87], v[74:77], off offset:16 nt
	global_load_dwordx4 v[74:77], v[92:93], off offset:528
	s_nop 0
	global_load_dwordx4 v[78:81], v[92:93], off offset:512
	s_waitcnt vmcnt(0)
; #define PG8_WAIT_V(n) asm volatile("s_waitcnt vmcnt(" #n ")" ::: "memory")
; #define PG8_BAR __builtin_amdgcn_s_barrier()
; template <class Epi>
; __device__ __forceinline__ void gemm_phase(LAS unsigned char* lds, const Gemm g, const StaticOrder& S, const Epi& E) {
;     ...
;     PG8_WAIT_V(0);
;     if (wr == 0) PG8_BAR;
;     PG8_BAR;
;     __device__ __forceinline__ void operator()(AccT& acc, const Unit& u, int wr, int wc, int fr, int fq) const {
;     ...
;         for (int ai = 0; ai < 2; ++ai)
; #pragma unroll
;             for (int m = 0; m < 4; ++m) { const size_t off = (size_t)(row0 + ai * 128 + m * 16) * DM + col0;
; #pragma unroll
;                 for (int bj = 0; bj < 2; ++bj) { const f32x4 x0 = *(const f32x4*)(xin + off + bj * 128), x1 = *(const f32x4*)(xin + off + bj * 128 + 4);
;                     __builtin_nontemporal_store(x0 + acc[ai][bj][m][0], (f32x4*)(out + off + bj * 128)); __builtin_nontemporal_store(x1 + acc[ai][bj][m][1], (f32x4*)(out + off + bj * 128 + 4)); } }
;     }
	v_pk_add_f32 v[68:69], v[68:69], v[76:77]
	v_pk_add_f32 v[72:73], v[72:73], v[80:81]
	v_pk_add_f32 v[70:71], v[70:71], v[78:79]
	v_pk_add_f32 v[66:67], v[66:67], v[74:75]
	v_lshl_add_u64 v[74:75], v[140:141], 0, s[20:21]
	global_store_dwordx4 v[86:87], v[70:73], off offset:512 nt
	global_store_dwordx4 v[86:87], v[66:69], off offset:528 nt
	v_lshl_add_u64 v[76:77], s[0:1], 0, v[74:75]
	global_load_dwordx4 v[66:69], v[76:77], off offset:16
	global_load_dwordx4 v[70:73], v[76:77], off
	s_mov_b64 s[20:21], 0x120000
	s_waitcnt vmcnt(0)
	v_pk_add_f32 v[60:61], v[60:61], v[68:69]
	v_pk_add_f32 v[64:65], v[64:65], v[72:73]
	v_pk_add_f32 v[62:63], v[62:63], v[70:71]
	v_lshl_add_u64 v[70:71], s[44:45], 0, v[74:75]
	v_pk_add_f32 v[58:59], v[58:59], v[66:67]
	global_store_dwordx4 v[70:71], v[62:65], off nt
	global_store_dwordx4 v[70:71], v[58:61], off offset:16 nt
	global_load_dwordx4 v[58:61], v[76:77], off offset:528
	s_nop 0
	global_load_dwordx4 v[62:65], v[76:77], off offset:512
	s_waitcnt vmcnt(0)
	v_pk_add_f32 v[52:53], v[52:53], v[60:61]
	v_pk_add_f32 v[56:57], v[56:57], v[64:65]
	v_pk_add_f32 v[54:55], v[54:55], v[62:63]
	v_pk_add_f32 v[50:51], v[50:51], v[58:59]
	v_lshl_add_u64 v[58:59], v[140:141], 0, s[20:21]
	global_store_dwordx4 v[70:71], v[54:57], off offset:512 nt
	global_store_dwordx4 v[70:71], v[50:53], off offset:528 nt
	v_lshl_add_u64 v[60:61], s[0:1], 0, v[58:59]
	global_load_dwordx4 v[50:53], v[60:61], off offset:16
	global_load_dwordx4 v[54:57], v[60:61], off
	s_mov_b64 s[20:21], 0x140000
	s_waitcnt vmcnt(0)
	v_pk_add_f32 v[44:45], v[44:45], v[52:53]
	v_pk_add_f32 v[48:49], v[48:49], v[56:57]
	v_pk_add_f32 v[46:47], v[46:47], v[54:55]
	v_lshl_add_u64 v[54:55], s[44:45], 0, v[58:59]
	v_pk_add_f32 v[42:43], v[42:43], v[50:51]
	global_store_dwordx4 v[54:55], v[46:49], off nt
	global_store_dwordx4 v[54:55], v[42:45], off offset:16 nt
	global_load_dwordx4 v[42:45], v[60:61], off offset:528
	s_nop 0
	global_load_dwordx4 v[46:49], v[60:61], off offset:512
	s_waitcnt vmcnt(0)
	v_pk_add_f32 v[36:37], v[36:37], v[44:45]
	v_pk_add_f32 v[40:41], v[40:41], v[48:49]
	v_pk_add_f32 v[38:39], v[38:39], v[46:47]
	v_pk_add_f32 v[34:35], v[34:35], v[42:43]
	v_lshl_add_u64 v[42:43], v[140:141], 0, s[20:21]
	global_store_dwordx4 v[54:55], v[38:41], off offset:512 nt
	global_store_dwordx4 v[54:55], v[34:37], off offset:528 nt
	v_lshl_add_u64 v[44:45], s[0:1], 0, v[42:43]
	global_load_dwordx4 v[34:37], v[44:45], off offset:16
	global_load_dwordx4 v[38:41], v[44:45], off
	s_mov_b64 s[20:21], 0x160000
	s_waitcnt vmcnt(0)
	v_pk_add_f32 v[28:29], v[28:29], v[36:37]
	v_pk_add_f32 v[32:33], v[32:33], v[40:41]
	v_pk_add_f32 v[30:31], v[30:31], v[38:39]
	v_lshl_add_u64 v[38:39], s[44:45], 0, v[42:43]
	v_pk_add_f32 v[26:27], v[26:27], v[34:35]
	global_store_dwordx4 v[38:39], v[30:33], off nt
	global_store_dwordx4 v[38:39], v[26:29], off offset:16 nt
	global_load_dwordx4 v[26:29], v[44:45], off offset:528
	s_nop 0
	global_load_dwordx4 v[30:33], v[44:45], off offset:512
	s_waitcnt vmcnt(0)
	v_pk_add_f32 v[20:21], v[20:21], v[28:29]
	v_pk_add_f32 v[24:25], v[24:25], v[32:33]
	v_pk_add_f32 v[22:23], v[22:23], v[30:31]
	v_pk_add_f32 v[18:19], v[18:19], v[26:27]
	v_lshl_add_u64 v[26:27], v[140:141], 0, s[20:21]
	global_store_dwordx4 v[38:39], v[22:25], off offset:512 nt
	global_store_dwordx4 v[38:39], v[18:21], off offset:528 nt
	v_lshl_add_u64 v[28:29], s[0:1], 0, v[26:27]
	global_load_dwordx4 v[18:21], v[28:29], off offset:16
	global_load_dwordx4 v[22:25], v[28:29], off
	s_mov_b64 s[20:21], s[46:47]
	s_waitcnt vmcnt(0)
	v_pk_add_f32 v[12:13], v[12:13], v[20:21]
	v_pk_add_f32 v[16:17], v[16:17], v[24:25]
	v_pk_add_f32 v[14:15], v[14:15], v[22:23]
	v_lshl_add_u64 v[22:23], s[44:45], 0, v[26:27]
	v_pk_add_f32 v[10:11], v[10:11], v[18:19]
	global_store_dwordx4 v[22:23], v[14:17], off nt
	global_store_dwordx4 v[22:23], v[10:13], off offset:16 nt
	global_load_dwordx4 v[10:13], v[28:29], off offset:528
	s_nop 0
	global_load_dwordx4 v[14:17], v[28:29], off offset:512
	s_waitcnt vmcnt(0)
	v_pk_add_f32 v[4:5], v[4:5], v[12:13]
	v_pk_add_f32 v[8:9], v[8:9], v[16:17]
	v_pk_add_f32 v[6:7], v[6:7], v[14:15]
	v_pk_add_f32 v[2:3], v[2:3], v[10:11]
	global_store_dwordx4 v[22:23], v[6:9], off offset:512 nt
	global_store_dwordx4 v[22:23], v[2:5], off offset:528 nt
	s_cbranch_vccz .LBB0_1440
	s_waitcnt vmcnt(0)
	s_cmpk_gt_u32 s38, 0xff
	s_cbranch_scc1 .LBB0_1451
	s_barrier
